# same static priority raise for waves 4-7 but kept through the GEMM epilogues (no reset at K-loop exit)
# baseline (speedup 1.0000x reference)
; #define PG8_STAGE(bufoff, gbase, voff) do { _Pragma("unroll") for (int _i = 0; _i < 2; ++_i) \
;     __builtin_amdgcn_global_load_lds((const unsigned*)((const char*)(gbase) + (voff)[_i]), (LAS unsigned*)(lds + (bufoff) + ldsw + _i * 8192), 16, 0, 0); } while (0)
; #define PG8_LDA(dst, b, h) do { _Pragma("unroll") for (int m = 0; m < 4; ++m) _Pragma("unroll") for (int k = 0; k < 2; ++k) dst[m][k] = *(const LAS bf16x8*)(lds + PG8_SA(b, h) + aoff + m * 2048 + k * 1024); } while (0)
; #define PG8_LDB(dst, b, h) do { _Pragma("unroll") for (int n = 0; n < 2; ++n) _Pragma("unroll") for (int k = 0; k < 2; ++k) dst[n][k] = *(const LAS bf16x8*)(lds + PG8_SB(b, h) + boff + n * 2048 + k * 1024); } while (0)
; #define PG8_MMA(ai, bj, At, Bt) do { __builtin_amdgcn_s_setprio(1); _Pragma("unroll") for (int m = 0; m < 4; ++m) _Pragma("unroll") for (int n = 0; n < 2; ++n) _Pragma("unroll") for (int k = 0; k < 2; ++k) \
;     acc[ai][bj][m][n] = __builtin_amdgcn_mfma_f32_16x16x32_bf16(Bt[n][k], At[m][k], acc[ai][bj][m][n], 0, 0, 0); __builtin_amdgcn_s_setprio(0); } while (0)
; #define PG8_WAIT_L(n) asm volatile("s_waitcnt lgkmcnt(" #n ")" ::: "memory")
; #define PG8_BAR __builtin_amdgcn_s_barrier()
; #define PG8_SCHED __builtin_amdgcn_sched_barrier(0)
; template <class Epi>
; __device__ __forceinline__ void gemm_phase(LAS unsigned char* lds, const Gemm g, const StaticOrder& S, const Epi& E, int wv0) {
;     ...
;     for (int t = 0; t < nt; t += 2) {
;       const bool last = (t == nt - 2);
;       const char* a1 = cA + (size_t)(t + 1) * kstep;
;       const char* a2 = last ? nA : cA + (size_t)(t + 2) * kstep; const char* b2 = last ? nB : cB + (size_t)(t + 2) * kstep;
;       const char* a3 = a2 + kstep; const char* b3 = b2 + kstep;
;       PG8_LDB(B0, 0, 0); PG8_SCHED; PG8_LDA(At, 0, 0); PG8_STAGE(PG8_SA(1, 1), a1 + hstepA, voffA);
;       PG8_WAIT_L(8); PG8_BAR; PG8_WAIT_L(0); PG8_MMA(0, 0, At, B0); PG8_BAR; PG8_SCHED;
;       PG8_LDB(B1, 0, 1); PG8_STAGE(PG8_SB(0, 0), b2, voffB);
;       PG8_BAR; PG8_WAIT_L(0); PG8_MMA(0, 1, At, B1); PG8_BAR;
;       PG8_LDA(At, 0, 1); PG8_STAGE(PG8_SA(0, 0), a2, voffA);
;       PG8_BAR; PG8_WAIT_L(0); PG8_MMA(1, 0, At, B0); PG8_BAR; PG8_SCHED;
.Lgprio0:
.LBB0_153:
	s_add_u32 s0, s8, 0xfff80080
	s_addc_u32 s24, s9, -1
	s_add_i32 s49, 0, 0x10000
	v_add_u32_e32 v96, s49, v196
	s_waitcnt vmcnt(6)
	ds_read_b128 v[88:91], v96
	ds_read_b128 v[92:95], v96 offset:1024
	ds_read_b128 v[106:109], v96 offset:2048
	ds_read_b128 v[110:113], v96 offset:3072
	s_cmp_eq_u32 s29, 28
	s_cselect_b32 s27, s1, s24
	s_cselect_b32 s26, s5, s0
	s_cselect_b32 s25, s7, s28
	s_cselect_b32 s24, s17, s19
	v_lshl_add_u64 v[190:191], s[8:9], 0, v[170:171]
	s_add_i32 m0, s39, 0xc000
	ds_read_b128 v[122:125], v197
	ds_read_b128 v[126:129], v197 offset:1024
	ds_read_b128 v[138:141], v197 offset:2048
	ds_read_b128 v[142:145], v197 offset:3072
	ds_read_b128 v[174:177], v197 offset:4096
	ds_read_b128 v[178:181], v197 offset:5120
	ds_read_b128 v[182:185], v197 offset:6144
	ds_read_b128 v[186:189], v197 offset:7168
	global_load_lds_dwordx4 v[190:191], off
	v_lshl_add_u64 v[190:191], s[8:9], 0, v[172:173]
	s_add_i32 m0, s39, 0xe000
	s_nop 0
	global_load_lds_dwordx4 v[190:191], off
	s_waitcnt lgkmcnt(8)
	s_barrier
	s_waitcnt lgkmcnt(0)
	s_waitcnt lgkmcnt(0)
	v_mfma_f32_16x16x32_bf16 v[68:71], v[88:91], v[122:125], v[68:71]
	v_mfma_f32_16x16x32_bf16 v[64:67], v[106:109], v[122:125], v[64:67]
	v_mfma_f32_16x16x32_bf16 v[158:161], v[88:91], v[138:141], v[158:161]
	v_mfma_f32_16x16x32_bf16 v[154:157], v[106:109], v[138:141], v[154:157]
	v_mfma_f32_16x16x32_bf16 v[150:153], v[88:91], v[174:177], v[150:153]
	v_mfma_f32_16x16x32_bf16 v[146:149], v[106:109], v[174:177], v[146:149]
	v_mfma_f32_16x16x32_bf16 v[134:137], v[88:91], v[182:185], v[134:137]
	v_mfma_f32_16x16x32_bf16 v[130:133], v[106:109], v[182:185], v[130:133]
	v_mfma_f32_16x16x32_bf16 v[68:71], v[92:95], v[126:129], v[68:71]
	v_mfma_f32_16x16x32_bf16 v[64:67], v[110:113], v[126:129], v[64:67]
	v_mfma_f32_16x16x32_bf16 v[158:161], v[92:95], v[142:145], v[158:161]
	v_mfma_f32_16x16x32_bf16 v[154:157], v[110:113], v[142:145], v[154:157]
	v_mfma_f32_16x16x32_bf16 v[150:153], v[92:95], v[178:181], v[150:153]
	v_mfma_f32_16x16x32_bf16 v[146:149], v[110:113], v[178:181], v[146:149]
	v_mfma_f32_16x16x32_bf16 v[134:137], v[92:95], v[186:189], v[134:137]
	v_mfma_f32_16x16x32_bf16 v[130:133], v[110:113], v[186:189], v[130:133]
	s_barrier
	s_add_i32 s0, 0, 0x14000
	s_add_i32 s49, s49, s38
	v_add_u32_e32 v96, s0, v196
	v_lshl_add_u64 v[210:211], s[24:25], 0, v[164:165]
	s_mov_b32 m0, s49
	ds_read_b128 v[190:193], v96
	ds_read_b128 v[198:201], v96 offset:1024
	ds_read_b128 v[202:205], v96 offset:2048
	ds_read_b128 v[206:209], v96 offset:3072
	global_load_lds_dwordx4 v[210:211], off
	v_lshl_add_u64 v[212:213], s[24:25], 0, v[168:169]
	s_add_i32 m0, s49, 0x2000
	s_nop 0
	global_load_lds_dwordx4 v[212:213], off
	s_barrier
	s_waitcnt lgkmcnt(0)
	s_waitcnt lgkmcnt(0)
	v_mfma_f32_16x16x32_bf16 v[56:59], v[190:193], v[122:125], v[56:59]
	v_mfma_f32_16x16x32_bf16 v[60:63], v[202:205], v[122:125], v[60:63]
	v_mfma_f32_16x16x32_bf16 v[48:51], v[190:193], v[138:141], v[48:51]
	v_mfma_f32_16x16x32_bf16 v[52:55], v[202:205], v[138:141], v[52:55]
	v_mfma_f32_16x16x32_bf16 v[40:43], v[190:193], v[174:177], v[40:43]
	v_mfma_f32_16x16x32_bf16 v[44:47], v[202:205], v[174:177], v[44:47]
	v_mfma_f32_16x16x32_bf16 v[32:35], v[190:193], v[182:185], v[32:35]
	v_mfma_f32_16x16x32_bf16 v[36:39], v[202:205], v[182:185], v[36:39]
	v_mfma_f32_16x16x32_bf16 v[56:59], v[198:201], v[126:129], v[56:59]
	v_mfma_f32_16x16x32_bf16 v[60:63], v[206:209], v[126:129], v[60:63]
	v_mfma_f32_16x16x32_bf16 v[48:51], v[198:201], v[142:145], v[48:51]
	v_mfma_f32_16x16x32_bf16 v[52:55], v[206:209], v[142:145], v[52:55]
	v_mfma_f32_16x16x32_bf16 v[40:43], v[198:201], v[178:181], v[40:43]
	v_mfma_f32_16x16x32_bf16 v[44:47], v[206:209], v[178:181], v[44:47]
	v_mfma_f32_16x16x32_bf16 v[32:35], v[198:201], v[186:189], v[32:35]
	v_mfma_f32_16x16x32_bf16 v[36:39], v[206:209], v[186:189], v[36:39]
	s_mov_b32 m0, s39
	v_lshl_add_u64 v[214:215], s[26:27], 0, v[162:163]
	s_barrier
	ds_read_b128 v[122:125], v197 offset:16384
	ds_read_b128 v[126:129], v197 offset:17408
	ds_read_b128 v[138:141], v197 offset:18432
	ds_read_b128 v[142:145], v197 offset:19456
	ds_read_b128 v[174:177], v197 offset:20480
	ds_read_b128 v[178:181], v197 offset:21504
	ds_read_b128 v[182:185], v197 offset:22528
	ds_read_b128 v[186:189], v197 offset:23552
	global_load_lds_dwordx4 v[214:215], off
	v_lshl_add_u64 v[216:217], s[26:27], 0, v[166:167]
	s_mov_b32 m0, s40
	s_nop 0
	global_load_lds_dwordx4 v[216:217], off
	s_barrier
	s_waitcnt lgkmcnt(0)
	s_waitcnt lgkmcnt(0)
	v_mfma_f32_16x16x32_bf16 v[118:121], v[88:91], v[122:125], v[118:121]
	v_mfma_f32_16x16x32_bf16 v[114:117], v[106:109], v[122:125], v[114:117]
	v_mfma_f32_16x16x32_bf16 v[102:105], v[88:91], v[138:141], v[102:105]
	v_mfma_f32_16x16x32_bf16 v[98:101], v[106:109], v[138:141], v[98:101]
	v_mfma_f32_16x16x32_bf16 v[84:87], v[88:91], v[174:177], v[84:87]
	v_mfma_f32_16x16x32_bf16 v[80:83], v[106:109], v[174:177], v[80:83]
	v_mfma_f32_16x16x32_bf16 v[76:79], v[88:91], v[182:185], v[76:79]
	v_mfma_f32_16x16x32_bf16 v[72:75], v[106:109], v[182:185], v[72:75]
	v_mfma_f32_16x16x32_bf16 v[118:121], v[92:95], v[126:129], v[118:121]
	v_mfma_f32_16x16x32_bf16 v[114:117], v[110:113], v[126:129], v[114:117]
	v_mfma_f32_16x16x32_bf16 v[102:105], v[92:95], v[142:145], v[102:105]
	v_mfma_f32_16x16x32_bf16 v[98:101], v[110:113], v[142:145], v[98:101]
	v_mfma_f32_16x16x32_bf16 v[84:87], v[92:95], v[178:181], v[84:87]
	v_mfma_f32_16x16x32_bf16 v[80:83], v[110:113], v[178:181], v[80:83]
	v_mfma_f32_16x16x32_bf16 v[76:79], v[92:95], v[186:189], v[76:79]
	v_mfma_f32_16x16x32_bf16 v[72:75], v[110:113], v[186:189], v[72:75]
	s_barrier
; #define PG8_STAGE(bufoff, gbase, voff) do { _Pragma("unroll") for (int _i = 0; _i < 2; ++_i) \
;     __builtin_amdgcn_global_load_lds((const unsigned*)((const char*)(gbase) + (voff)[_i]), (LAS unsigned*)(lds + (bufoff) + ldsw + _i * 8192), 16, 0, 0); } while (0)
; #define PG8_LDA(dst, b, h) do { _Pragma("unroll") for (int m = 0; m < 4; ++m) _Pragma("unroll") for (int k = 0; k < 2; ++k) dst[m][k] = *(const LAS bf16x8*)(lds + PG8_SA(b, h) + aoff + m * 2048 + k * 1024); } while (0)
; #define PG8_LDB(dst, b, h) do { _Pragma("unroll") for (int n = 0; n < 2; ++n) _Pragma("unroll") for (int k = 0; k < 2; ++k) dst[n][k] = *(const LAS bf16x8*)(lds + PG8_SB(b, h) + boff + n * 2048 + k * 1024); } while (0)
; #define PG8_MMA(ai, bj, At, Bt) do { __builtin_amdgcn_s_setprio(1); _Pragma("unroll") for (int m = 0; m < 4; ++m) _Pragma("unroll") for (int n = 0; n < 2; ++n) _Pragma("unroll") for (int k = 0; k < 2; ++k) \
;     acc[ai][bj][m][n] = __builtin_amdgcn_mfma_f32_16x16x32_bf16(Bt[n][k], At[m][k], acc[ai][bj][m][n], 0, 0, 0); __builtin_amdgcn_s_setprio(0); } while (0)
; #define PG8_WAIT_V(n) asm volatile("s_waitcnt vmcnt(" #n ")" ::: "memory")
; #define PG8_WAIT_L(n) asm volatile("s_waitcnt lgkmcnt(" #n ")" ::: "memory")
; #define PG8_BAR __builtin_amdgcn_s_barrier()
; #define PG8_SCHED __builtin_amdgcn_sched_barrier(0)
; template <class Epi>
; __device__ __forceinline__ void gemm_phase(LAS unsigned char* lds, const Gemm g, const StaticOrder& S, const Epi& E, int wv0) {
;     ...
;       PG8_STAGE(PG8_SB(0, 1), b2 + hstepB, voffB);
;       PG8_WAIT_V(6); PG8_BAR; PG8_MMA(1, 1, At, B1); PG8_BAR;
;       PG8_LDB(B0, 1, 0); PG8_SCHED; PG8_LDA(At, 1, 0); PG8_STAGE(PG8_SA(0, 1), a2 + hstepA, voffA);
;       PG8_WAIT_L(8); PG8_BAR; PG8_WAIT_L(0); PG8_MMA(0, 0, At, B0); PG8_BAR; PG8_SCHED;
;       PG8_LDB(B1, 1, 1); PG8_STAGE(PG8_SB(1, 0), b3, voffB);
;       PG8_BAR; PG8_WAIT_L(0); PG8_MMA(0, 1, At, B1); PG8_BAR;
	s_add_u32 s50, s24, 0x80000
	s_addc_u32 s51, s25, 0
	s_add_i32 s0, s0, s38
	v_lshl_add_u64 v[88:89], s[50:51], 0, v[164:165]
	s_mov_b32 m0, s0
	s_nop 0
	global_load_lds_dwordx4 v[88:89], off
	v_lshl_add_u64 v[88:89], s[50:51], 0, v[168:169]
	s_add_i32 m0, s0, 0x2000
	s_nop 0
	global_load_lds_dwordx4 v[88:89], off
	s_waitcnt vmcnt(6)
	s_barrier
	v_mfma_f32_16x16x32_bf16 v[24:27], v[190:193], v[122:125], v[24:27]
	v_mfma_f32_16x16x32_bf16 v[28:31], v[202:205], v[122:125], v[28:31]
	v_mfma_f32_16x16x32_bf16 v[16:19], v[190:193], v[138:141], v[16:19]
	v_mfma_f32_16x16x32_bf16 v[20:23], v[202:205], v[138:141], v[20:23]
	v_mfma_f32_16x16x32_bf16 v[8:11], v[190:193], v[174:177], v[8:11]
	v_mfma_f32_16x16x32_bf16 v[12:15], v[202:205], v[174:177], v[12:15]
	v_mfma_f32_16x16x32_bf16 v[0:3], v[190:193], v[182:185], v[0:3]
	v_mfma_f32_16x16x32_bf16 v[4:7], v[202:205], v[182:185], v[4:7]
	v_mfma_f32_16x16x32_bf16 v[24:27], v[198:201], v[126:129], v[24:27]
	v_mfma_f32_16x16x32_bf16 v[28:31], v[206:209], v[126:129], v[28:31]
	v_mfma_f32_16x16x32_bf16 v[16:19], v[198:201], v[142:145], v[16:19]
	v_mfma_f32_16x16x32_bf16 v[20:23], v[206:209], v[142:145], v[20:23]
	v_mfma_f32_16x16x32_bf16 v[8:11], v[198:201], v[178:181], v[8:11]
	v_mfma_f32_16x16x32_bf16 v[12:15], v[206:209], v[178:181], v[12:15]
	v_mfma_f32_16x16x32_bf16 v[0:3], v[198:201], v[186:189], v[0:3]
	v_mfma_f32_16x16x32_bf16 v[4:7], v[206:209], v[186:189], v[4:7]
	s_add_i32 s0, 0, 0x18000
	v_add_u32_e32 v96, s0, v196
	s_barrier
	ds_read_b128 v[88:91], v96
	ds_read_b128 v[92:95], v96 offset:1024
	ds_read_b128 v[106:109], v96 offset:2048
	ds_read_b128 v[110:113], v96 offset:3072
	s_add_u32 s26, s26, 0x80000
	s_addc_u32 s27, s27, 0
	s_mov_b32 m0, s41
	v_lshl_add_u64 v[190:191], s[26:27], 0, v[162:163]
	ds_read_b128 v[122:125], v197 offset:32768
	ds_read_b128 v[126:129], v197 offset:33792
	ds_read_b128 v[138:141], v197 offset:34816
	ds_read_b128 v[142:145], v197 offset:35840
	ds_read_b128 v[174:177], v197 offset:36864
	ds_read_b128 v[178:181], v197 offset:37888
	ds_read_b128 v[182:185], v197 offset:38912
	ds_read_b128 v[186:189], v197 offset:39936
	global_load_lds_dwordx4 v[190:191], off
	v_lshl_add_u64 v[190:191], s[26:27], 0, v[166:167]
	s_mov_b32 m0, s42
	s_nop 0
	global_load_lds_dwordx4 v[190:191], off
	s_waitcnt lgkmcnt(8)
	s_barrier
	s_waitcnt lgkmcnt(0)
	s_waitcnt lgkmcnt(0)
	v_mfma_f32_16x16x32_bf16 v[68:71], v[88:91], v[122:125], v[68:71]
	v_mfma_f32_16x16x32_bf16 v[64:67], v[106:109], v[122:125], v[64:67]
	v_mfma_f32_16x16x32_bf16 v[158:161], v[88:91], v[138:141], v[158:161]
	v_mfma_f32_16x16x32_bf16 v[154:157], v[106:109], v[138:141], v[154:157]
	v_mfma_f32_16x16x32_bf16 v[150:153], v[88:91], v[174:177], v[150:153]
	v_mfma_f32_16x16x32_bf16 v[146:149], v[106:109], v[174:177], v[146:149]
	v_mfma_f32_16x16x32_bf16 v[134:137], v[88:91], v[182:185], v[134:137]
	v_mfma_f32_16x16x32_bf16 v[130:133], v[106:109], v[182:185], v[130:133]
	v_mfma_f32_16x16x32_bf16 v[68:71], v[92:95], v[126:129], v[68:71]
	v_mfma_f32_16x16x32_bf16 v[64:67], v[110:113], v[126:129], v[64:67]
	v_mfma_f32_16x16x32_bf16 v[158:161], v[92:95], v[142:145], v[158:161]
	v_mfma_f32_16x16x32_bf16 v[154:157], v[110:113], v[142:145], v[154:157]
	v_mfma_f32_16x16x32_bf16 v[150:153], v[92:95], v[178:181], v[150:153]
	v_mfma_f32_16x16x32_bf16 v[146:149], v[110:113], v[178:181], v[146:149]
	v_mfma_f32_16x16x32_bf16 v[134:137], v[92:95], v[186:189], v[134:137]
	v_mfma_f32_16x16x32_bf16 v[130:133], v[110:113], v[186:189], v[130:133]
	s_barrier
	s_add_i32 s26, 0, 0x1c000
	s_add_i32 s0, s0, s38
	v_add_u32_e32 v96, s26, v196
	v_lshl_add_u64 v[210:211], v[210:211], 0, s[72:73]
	s_mov_b32 m0, s0
	ds_read_b128 v[190:193], v96
	ds_read_b128 v[198:201], v96 offset:1024
	ds_read_b128 v[202:205], v96 offset:2048
	ds_read_b128 v[206:209], v96 offset:3072
	global_load_lds_dwordx4 v[210:211], off
	v_lshl_add_u64 v[210:211], v[212:213], 0, s[72:73]
	s_add_i32 m0, s0, 0x2000
	s_nop 0
	global_load_lds_dwordx4 v[210:211], off
	s_barrier
; #define PG8_STAGE(bufoff, gbase, voff) do { _Pragma("unroll") for (int _i = 0; _i < 2; ++_i) \
;     __builtin_amdgcn_global_load_lds((const unsigned*)((const char*)(gbase) + (voff)[_i]), (LAS unsigned*)(lds + (bufoff) + ldsw + _i * 8192), 16, 0, 0); } while (0)
; #define PG8_LDA(dst, b, h) do { _Pragma("unroll") for (int m = 0; m < 4; ++m) _Pragma("unroll") for (int k = 0; k < 2; ++k) dst[m][k] = *(const LAS bf16x8*)(lds + PG8_SA(b, h) + aoff + m * 2048 + k * 1024); } while (0)
; #define PG8_MMA(ai, bj, At, Bt) do { __builtin_amdgcn_s_setprio(1); _Pragma("unroll") for (int m = 0; m < 4; ++m) _Pragma("unroll") for (int n = 0; n < 2; ++n) _Pragma("unroll") for (int k = 0; k < 2; ++k) \
;     acc[ai][bj][m][n] = __builtin_amdgcn_mfma_f32_16x16x32_bf16(Bt[n][k], At[m][k], acc[ai][bj][m][n], 0, 0, 0); __builtin_amdgcn_s_setprio(0); } while (0)
; #define PG8_WAIT_V(n) asm volatile("s_waitcnt vmcnt(" #n ")" ::: "memory")
; #define PG8_WAIT_L(n) asm volatile("s_waitcnt lgkmcnt(" #n ")" ::: "memory")
; #define PG8_BAR __builtin_amdgcn_s_barrier()
; #define PG8_SCHED __builtin_amdgcn_sched_barrier(0)
; template <class Epi>
; __device__ __forceinline__ void gemm_phase(LAS unsigned char* lds, const Gemm g, const StaticOrder& S, const Epi& E, int wv0) {
;     ...
;       PG8_BAR; PG8_WAIT_L(0); PG8_MMA(0, 1, At, B1); PG8_BAR;
;       PG8_LDA(At, 1, 1); PG8_STAGE(PG8_SA(1, 0), a3, voffA);
;       PG8_BAR; PG8_WAIT_L(0); PG8_MMA(1, 0, At, B0); PG8_BAR; PG8_SCHED;
;       PG8_STAGE(PG8_SB(1, 1), b3 + hstepB, voffB);
;       PG8_WAIT_V(6); PG8_BAR; PG8_MMA(1, 1, At, B1); PG8_BAR;
;   __device__ __forceinline__ void preload(EpiPre& q, int row, int col) const {
;     if (MODE == E_GATE || MODE == E_UKV) return;
;     if (MODE == E_MAIN) {
;       if (col >= C_KR && col < C_HU) { const float* cs = e.f0 + ((size_t)row * 32 + ((col - C_KR) >> 1)) * 2; q.a0 = *(const f32x4*)cs; q.a1 = *(const f32x4*)(cs + 4); }
	s_waitcnt lgkmcnt(0)
	s_waitcnt lgkmcnt(0)
	v_mfma_f32_16x16x32_bf16 v[56:59], v[190:193], v[122:125], v[56:59]
	v_mfma_f32_16x16x32_bf16 v[60:63], v[202:205], v[122:125], v[60:63]
	v_mfma_f32_16x16x32_bf16 v[48:51], v[190:193], v[138:141], v[48:51]
	v_mfma_f32_16x16x32_bf16 v[52:55], v[202:205], v[138:141], v[52:55]
	v_mfma_f32_16x16x32_bf16 v[40:43], v[190:193], v[174:177], v[40:43]
	v_mfma_f32_16x16x32_bf16 v[44:47], v[202:205], v[174:177], v[44:47]
	v_mfma_f32_16x16x32_bf16 v[32:35], v[190:193], v[182:185], v[32:35]
	v_mfma_f32_16x16x32_bf16 v[36:39], v[202:205], v[182:185], v[36:39]
	v_mfma_f32_16x16x32_bf16 v[56:59], v[198:201], v[126:129], v[56:59]
	v_mfma_f32_16x16x32_bf16 v[60:63], v[206:209], v[126:129], v[60:63]
	v_mfma_f32_16x16x32_bf16 v[48:51], v[198:201], v[142:145], v[48:51]
	v_mfma_f32_16x16x32_bf16 v[52:55], v[206:209], v[142:145], v[52:55]
	v_mfma_f32_16x16x32_bf16 v[40:43], v[198:201], v[178:181], v[40:43]
	v_mfma_f32_16x16x32_bf16 v[44:47], v[206:209], v[178:181], v[44:47]
	v_mfma_f32_16x16x32_bf16 v[32:35], v[198:201], v[186:189], v[32:35]
	v_mfma_f32_16x16x32_bf16 v[36:39], v[206:209], v[186:189], v[36:39]
	s_mov_b32 m0, s44
	v_lshl_add_u64 v[210:211], v[214:215], 0, s[72:73]
	s_barrier
	ds_read_b128 v[122:125], v197 offset:49152
	ds_read_b128 v[126:129], v197 offset:50176
	ds_read_b128 v[138:141], v197 offset:51200
	ds_read_b128 v[142:145], v197 offset:52224
	ds_read_b128 v[174:177], v197 offset:53248
	ds_read_b128 v[178:181], v197 offset:54272
	ds_read_b128 v[182:185], v197 offset:55296
	ds_read_b128 v[186:189], v197 offset:56320
	global_load_lds_dwordx4 v[210:211], off
	v_lshl_add_u64 v[210:211], v[216:217], 0, s[72:73]
	s_mov_b32 m0, s45
	s_nop 0
	global_load_lds_dwordx4 v[210:211], off
	s_barrier
	s_waitcnt lgkmcnt(0)
	s_waitcnt lgkmcnt(0)
	v_mfma_f32_16x16x32_bf16 v[118:121], v[88:91], v[122:125], v[118:121]
	v_mfma_f32_16x16x32_bf16 v[114:117], v[106:109], v[122:125], v[114:117]
	v_mfma_f32_16x16x32_bf16 v[102:105], v[88:91], v[138:141], v[102:105]
	v_mfma_f32_16x16x32_bf16 v[98:101], v[106:109], v[138:141], v[98:101]
	v_mfma_f32_16x16x32_bf16 v[84:87], v[88:91], v[174:177], v[84:87]
	v_mfma_f32_16x16x32_bf16 v[80:83], v[106:109], v[174:177], v[80:83]
	v_mfma_f32_16x16x32_bf16 v[76:79], v[88:91], v[182:185], v[76:79]
	v_mfma_f32_16x16x32_bf16 v[72:75], v[106:109], v[182:185], v[72:75]
	v_mfma_f32_16x16x32_bf16 v[118:121], v[92:95], v[126:129], v[118:121]
	v_mfma_f32_16x16x32_bf16 v[114:117], v[110:113], v[126:129], v[114:117]
	v_mfma_f32_16x16x32_bf16 v[102:105], v[92:95], v[142:145], v[102:105]
	v_mfma_f32_16x16x32_bf16 v[98:101], v[110:113], v[142:145], v[98:101]
	v_mfma_f32_16x16x32_bf16 v[84:87], v[92:95], v[178:181], v[84:87]
	v_mfma_f32_16x16x32_bf16 v[80:83], v[110:113], v[178:181], v[80:83]
	v_mfma_f32_16x16x32_bf16 v[76:79], v[92:95], v[186:189], v[76:79]
	v_mfma_f32_16x16x32_bf16 v[72:75], v[110:113], v[186:189], v[72:75]
	s_barrier
	s_add_u32 s24, s24, 0x80080
	s_addc_u32 s25, s25, 0
	s_add_i32 s0, s26, s38
	v_lshl_add_u64 v[88:89], s[24:25], 0, v[164:165]
	s_mov_b32 m0, s0
	s_nop 0
	global_load_lds_dwordx4 v[88:89], off
	v_lshl_add_u64 v[88:89], s[24:25], 0, v[168:169]
	s_add_i32 m0, s0, 0x2000
	s_nop 0
	global_load_lds_dwordx4 v[88:89], off
	s_waitcnt vmcnt(6)
	s_barrier
	v_mfma_f32_16x16x32_bf16 v[24:27], v[190:193], v[122:125], v[24:27]
	v_mfma_f32_16x16x32_bf16 v[28:31], v[202:205], v[122:125], v[28:31]
	v_mfma_f32_16x16x32_bf16 v[16:19], v[190:193], v[138:141], v[16:19]
	v_mfma_f32_16x16x32_bf16 v[20:23], v[202:205], v[138:141], v[20:23]
	v_mfma_f32_16x16x32_bf16 v[8:11], v[190:193], v[174:177], v[8:11]
	v_mfma_f32_16x16x32_bf16 v[12:15], v[202:205], v[174:177], v[12:15]
	v_mfma_f32_16x16x32_bf16 v[0:3], v[190:193], v[182:185], v[0:3]
	v_mfma_f32_16x16x32_bf16 v[4:7], v[202:205], v[182:185], v[4:7]
	v_mfma_f32_16x16x32_bf16 v[24:27], v[198:201], v[126:129], v[24:27]
	v_mfma_f32_16x16x32_bf16 v[28:31], v[206:209], v[126:129], v[28:31]
	v_mfma_f32_16x16x32_bf16 v[16:19], v[198:201], v[142:145], v[16:19]
	v_mfma_f32_16x16x32_bf16 v[20:23], v[206:209], v[142:145], v[20:23]
	v_mfma_f32_16x16x32_bf16 v[8:11], v[198:201], v[178:181], v[8:11]
	v_mfma_f32_16x16x32_bf16 v[12:15], v[206:209], v[178:181], v[12:15]
	v_mfma_f32_16x16x32_bf16 v[0:3], v[198:201], v[186:189], v[0:3]
	v_mfma_f32_16x16x32_bf16 v[4:7], v[206:209], v[186:189], v[4:7]
	s_add_i32 s29, s29, 2
	s_add_u32 s8, s8, 0x100
	s_addc_u32 s9, s9, 0
	s_add_u32 s19, s19, 0x100
	s_addc_u32 s28, s28, 0
	s_cmp_gt_u32 s29, 29
	s_barrier
	s_cbranch_scc0 .LBB0_153
	s_lshl_b32 s0, s4, 8
	s_or_b32 s17, s0, s43
	s_and_b32 s0, s17, 0xffffff40
	v_bitop3_b32 v88, s17, 56, v195 bitop3:0xc8
	v_lshlrev_b32_e32 v96, 2, v88
	s_cmpk_eq_i32 s0, 0x500
	v_lshl_add_u32 v176, s6, 8, v194
	s_cselect_b64 s[4:5], -1, 0
	s_cmpk_lg_i32 s0, 0x500
	v_lshl_add_u64 v[178:179], s[14:15], 0, v[96:97]
	s_cbranch_scc1 .LBB0_156
	v_ashrrev_i32_e32 v177, 31, v176
	v_lshlrev_b64 v[88:89], 8, v[176:177]
	v_lshl_add_u64 v[88:89], v[178:179], 0, v[88:89]
	global_load_dwordx4 v[138:141], v[88:89], off offset:16
	global_load_dwordx4 v[142:145], v[88:89], off

; #define PG8_STAGE(bufoff, gbase, voff) do { _Pragma("unroll") for (int _i = 0; _i < 2; ++_i) \
;     __builtin_amdgcn_global_load_lds((const unsigned*)((const char*)(gbase) + (voff)[_i]), (LAS unsigned*)(lds + (bufoff) + ldsw + _i * 8192), 16, 0, 0); } while (0)
; #define PG8_LDA(dst, b, h) do { _Pragma("unroll") for (int m = 0; m < 4; ++m) _Pragma("unroll") for (int k = 0; k < 2; ++k) dst[m][k] = *(const LAS bf16x8*)(lds + PG8_SA(b, h) + aoff + m * 2048 + k * 1024); } while (0)
; #define PG8_LDB(dst, b, h) do { _Pragma("unroll") for (int n = 0; n < 2; ++n) _Pragma("unroll") for (int k = 0; k < 2; ++k) dst[n][k] = *(const LAS bf16x8*)(lds + PG8_SB(b, h) + boff + n * 2048 + k * 1024); } while (0)
; #define PG8_MMA(ai, bj, At, Bt) do { __builtin_amdgcn_s_setprio(1); _Pragma("unroll") for (int m = 0; m < 4; ++m) _Pragma("unroll") for (int n = 0; n < 2; ++n) _Pragma("unroll") for (int k = 0; k < 2; ++k) \
;     acc[ai][bj][m][n] = __builtin_amdgcn_mfma_f32_16x16x32_bf16(Bt[n][k], At[m][k], acc[ai][bj][m][n], 0, 0, 0); __builtin_amdgcn_s_setprio(0); } while (0)
; #define PG8_WAIT_V(n) asm volatile("s_waitcnt vmcnt(" #n ")" ::: "memory")
; #define PG8_WAIT_L(n) asm volatile("s_waitcnt lgkmcnt(" #n ")" ::: "memory")
; #define PG8_BAR __builtin_amdgcn_s_barrier()
; #define PG8_SCHED __builtin_amdgcn_sched_barrier(0)
; template <class Epi>
; __device__ __forceinline__ void gemm_phase(LAS unsigned char* lds, const Gemm g, const StaticOrder& S, const Epi& E, int wv0) {
;     ...
;     for (int t = 0; t < nt; t += 2) {
;       const bool last = (t == nt - 2);
;       const char* a1 = cA + (size_t)(t + 1) * kstep;
;       const char* a2 = last ? nA : cA + (size_t)(t + 2) * kstep; const char* b2 = last ? nB : cB + (size_t)(t + 2) * kstep;
;       const char* a3 = a2 + kstep; const char* b3 = b2 + kstep;
;       PG8_LDB(B0, 0, 0); PG8_SCHED; PG8_LDA(At, 0, 0); PG8_STAGE(PG8_SA(1, 1), a1 + hstepA, voffA);
;       PG8_WAIT_L(8); PG8_BAR; PG8_WAIT_L(0); PG8_MMA(0, 0, At, B0); PG8_BAR; PG8_SCHED;
;       PG8_LDB(B1, 0, 1); PG8_STAGE(PG8_SB(0, 0), b2, voffB);
;       PG8_BAR; PG8_WAIT_L(0); PG8_MMA(0, 1, At, B1); PG8_BAR;
;       PG8_LDA(At, 0, 1); PG8_STAGE(PG8_SA(0, 0), a2, voffA);
;       PG8_BAR; PG8_WAIT_L(0); PG8_MMA(1, 0, At, B0); PG8_BAR; PG8_SCHED;
;       PG8_STAGE(PG8_SB(0, 1), b2 + hstepB, voffB);
;       PG8_WAIT_V(6); PG8_BAR; PG8_MMA(1, 1, At, B1); PG8_BAR;
.Lgprio1:
.LBB0_671:
	s_add_u32 s4, s18, 0x100
	s_addc_u32 s5, s19, 0
	s_add_i32 s0, 0, 0x10000
	s_waitcnt vmcnt(6)
	v_add_u32_e32 v80, s0, v253
	ds_read_b128 v[72:75], v80
	ds_read_b128 v[76:79], v80 offset:1024
	ds_read_b128 v[90:93], v80 offset:2048
	ds_read_b128 v[98:101], v80 offset:3072
	s_cmp_eq_u32 s46, 4
	s_cselect_b32 s23, s13, s5
	s_cselect_b32 s22, s12, s4
	s_cselect_b32 s21, s11, s45
	s_cselect_b32 s20, s17, s44
	v_lshl_add_u64 v[80:81], s[18:19], 0, v[230:231]
	s_add_i32 m0, s34, 0xc000
	ds_read_b128 v[110:113], v244
	ds_read_b128 v[114:117], v244 offset:1024
	ds_read_b128 v[118:121], v244 offset:2048
	ds_read_b128 v[122:125], v244 offset:3072
	ds_read_b128 v[136:139], v244 offset:4096
	ds_read_b128 v[140:143], v244 offset:5120
	ds_read_b128 v[144:147], v244 offset:6144
	ds_read_b128 v[148:151], v244 offset:7168
	global_load_lds_dwordx4 v[80:81], off
	v_lshl_add_u64 v[80:81], s[18:19], 0, v[232:233]
	s_add_i32 m0, s34, 0xe000
	s_nop 0
	global_load_lds_dwordx4 v[80:81], off
	s_waitcnt lgkmcnt(8)
	s_barrier
	s_waitcnt lgkmcnt(0)
	s_waitcnt lgkmcnt(0)
	v_mfma_f32_16x16x32_bf16 v[132:135], v[72:75], v[136:139], v[132:135]
	v_mfma_f32_16x16x32_bf16 v[126:129], v[90:93], v[136:139], v[128:131]
	v_mfma_f32_16x16x32_bf16 v[86:89], v[72:75], v[144:147], v[86:89]
	v_mfma_f32_16x16x32_bf16 v[80:83], v[90:93], v[144:147], v[82:85]
	v_mfma_f32_16x16x32_bf16 v[152:155], v[72:75], v[110:113], v[202:205]
	v_mfma_f32_16x16x32_bf16 v[156:159], v[90:93], v[110:113], v[198:201]
	v_mfma_f32_16x16x32_bf16 v[170:173], v[72:75], v[118:121], v[186:189]
	v_mfma_f32_16x16x32_bf16 v[174:177], v[90:93], v[118:121], v[182:185]
	v_mfma_f32_16x16x32_bf16 v[132:135], v[76:79], v[140:143], v[132:135]
	v_mfma_f32_16x16x32_bf16 v[126:129], v[98:101], v[140:143], v[126:129]
	v_mfma_f32_16x16x32_bf16 v[86:89], v[76:79], v[148:151], v[86:89]
	v_mfma_f32_16x16x32_bf16 v[80:83], v[98:101], v[148:151], v[80:83]
	v_mfma_f32_16x16x32_bf16 v[152:155], v[76:79], v[114:117], v[152:155]
	v_mfma_f32_16x16x32_bf16 v[156:159], v[98:101], v[114:117], v[156:159]
	v_mfma_f32_16x16x32_bf16 v[170:173], v[76:79], v[122:125], v[170:173]
	v_mfma_f32_16x16x32_bf16 v[174:177], v[98:101], v[122:125], v[174:177]
	s_barrier
	s_add_i32 s47, 0, 0x14000
	s_add_i32 s0, s0, s31
	v_add_u32_e32 v84, s47, v253
	v_lshl_add_u64 v[214:215], s[20:21], 0, v[224:225]
	s_mov_b32 m0, s0
	ds_read_b128 v[178:181], v84
	ds_read_b128 v[182:185], v84 offset:1024
	ds_read_b128 v[186:189], v84 offset:2048
	ds_read_b128 v[198:201], v84 offset:3072
	global_load_lds_dwordx4 v[214:215], off
	v_lshl_add_u64 v[216:217], s[20:21], 0, v[228:229]
	s_add_i32 m0, s0, 0x2000
	s_nop 0
	global_load_lds_dwordx4 v[216:217], off
	s_barrier
	s_waitcnt lgkmcnt(0)
	s_waitcnt lgkmcnt(0)
	v_mfma_f32_16x16x32_bf16 v[194:197], v[178:181], v[110:113], v[194:197]
	v_mfma_f32_16x16x32_bf16 v[110:113], v[186:189], v[110:113], v[190:193]
	v_mfma_f32_16x16x32_bf16 v[106:109], v[178:181], v[136:139], v[106:109]
	v_mfma_f32_16x16x32_bf16 v[102:105], v[186:189], v[136:139], v[102:105]
	v_mfma_f32_16x16x32_bf16 v[68:71], v[178:181], v[144:147], v[68:71]
	v_mfma_f32_16x16x32_bf16 v[64:67], v[186:189], v[144:147], v[64:67]
	v_mfma_f32_16x16x32_bf16 v[194:197], v[182:185], v[114:117], v[194:197]
	v_mfma_f32_16x16x32_bf16 v[110:113], v[198:201], v[114:117], v[110:113]
	v_mfma_f32_16x16x32_bf16 v[114:117], v[178:181], v[118:121], v[166:169]
	v_mfma_f32_16x16x32_bf16 v[118:121], v[186:189], v[118:121], v[162:165]
	v_mfma_f32_16x16x32_bf16 v[106:109], v[182:185], v[140:143], v[106:109]
	v_mfma_f32_16x16x32_bf16 v[102:105], v[198:201], v[140:143], v[102:105]
	v_mfma_f32_16x16x32_bf16 v[68:71], v[182:185], v[148:151], v[68:71]
	v_mfma_f32_16x16x32_bf16 v[64:67], v[198:201], v[148:151], v[64:67]
	v_mfma_f32_16x16x32_bf16 v[114:117], v[182:185], v[122:125], v[114:117]
	v_mfma_f32_16x16x32_bf16 v[118:121], v[198:201], v[122:125], v[118:121]
	s_mov_b32 m0, s34
	v_lshl_add_u64 v[218:219], s[22:23], 0, v[94:95]
	s_barrier
	ds_read_b128 v[122:125], v244 offset:16384
	ds_read_b128 v[136:139], v244 offset:17408
	ds_read_b128 v[140:143], v244 offset:18432
	ds_read_b128 v[144:147], v244 offset:19456
	ds_read_b128 v[148:151], v244 offset:20480
	ds_read_b128 v[160:163], v244 offset:21504
	ds_read_b128 v[164:167], v244 offset:22528
	ds_read_b128 v[190:193], v244 offset:23552
	global_load_lds_dwordx4 v[218:219], off
	v_lshl_add_u64 v[220:221], s[22:23], 0, v[226:227]
	s_mov_b32 m0, s35
	s_nop 0
	global_load_lds_dwordx4 v[220:221], off
	s_barrier
	s_waitcnt lgkmcnt(0)
	s_waitcnt lgkmcnt(0)
	v_mfma_f32_16x16x32_bf16 v[60:63], v[72:75], v[122:125], v[60:63]
	v_mfma_f32_16x16x32_bf16 v[56:59], v[90:93], v[122:125], v[56:59]
	v_mfma_f32_16x16x32_bf16 v[44:47], v[72:75], v[140:143], v[44:47]
	v_mfma_f32_16x16x32_bf16 v[40:43], v[90:93], v[140:143], v[40:43]
	v_mfma_f32_16x16x32_bf16 v[28:31], v[72:75], v[148:151], v[28:31]
	v_mfma_f32_16x16x32_bf16 v[24:27], v[90:93], v[148:151], v[24:27]
	v_mfma_f32_16x16x32_bf16 v[12:15], v[72:75], v[164:167], v[12:15]
	v_mfma_f32_16x16x32_bf16 v[8:11], v[90:93], v[164:167], v[8:11]
	v_mfma_f32_16x16x32_bf16 v[60:63], v[76:79], v[136:139], v[60:63]
	v_mfma_f32_16x16x32_bf16 v[56:59], v[98:101], v[136:139], v[56:59]
	v_mfma_f32_16x16x32_bf16 v[44:47], v[76:79], v[144:147], v[44:47]
	v_mfma_f32_16x16x32_bf16 v[40:43], v[98:101], v[144:147], v[40:43]
	v_mfma_f32_16x16x32_bf16 v[28:31], v[76:79], v[160:163], v[28:31]
	v_mfma_f32_16x16x32_bf16 v[24:27], v[98:101], v[160:163], v[24:27]
	v_mfma_f32_16x16x32_bf16 v[12:15], v[76:79], v[190:193], v[12:15]
	v_mfma_f32_16x16x32_bf16 v[8:11], v[98:101], v[190:193], v[8:11]
	s_barrier
; #define PG8_STAGE(bufoff, gbase, voff) do { _Pragma("unroll") for (int _i = 0; _i < 2; ++_i) \
;     __builtin_amdgcn_global_load_lds((const unsigned*)((const char*)(gbase) + (voff)[_i]), (LAS unsigned*)(lds + (bufoff) + ldsw + _i * 8192), 16, 0, 0); } while (0)
; #define PG8_LDA(dst, b, h) do { _Pragma("unroll") for (int m = 0; m < 4; ++m) _Pragma("unroll") for (int k = 0; k < 2; ++k) dst[m][k] = *(const LAS bf16x8*)(lds + PG8_SA(b, h) + aoff + m * 2048 + k * 1024); } while (0)
; #define PG8_LDB(dst, b, h) do { _Pragma("unroll") for (int n = 0; n < 2; ++n) _Pragma("unroll") for (int k = 0; k < 2; ++k) dst[n][k] = *(const LAS bf16x8*)(lds + PG8_SB(b, h) + boff + n * 2048 + k * 1024); } while (0)
; #define PG8_MMA(ai, bj, At, Bt) do { __builtin_amdgcn_s_setprio(1); _Pragma("unroll") for (int m = 0; m < 4; ++m) _Pragma("unroll") for (int n = 0; n < 2; ++n) _Pragma("unroll") for (int k = 0; k < 2; ++k) \
;     acc[ai][bj][m][n] = __builtin_amdgcn_mfma_f32_16x16x32_bf16(Bt[n][k], At[m][k], acc[ai][bj][m][n], 0, 0, 0); __builtin_amdgcn_s_setprio(0); } while (0)
; #define PG8_WAIT_V(n) asm volatile("s_waitcnt vmcnt(" #n ")" ::: "memory")
; #define PG8_WAIT_L(n) asm volatile("s_waitcnt lgkmcnt(" #n ")" ::: "memory")
; #define PG8_BAR __builtin_amdgcn_s_barrier()
; #define PG8_SCHED __builtin_amdgcn_sched_barrier(0)
; template <class Epi>
; __device__ __forceinline__ void gemm_phase(LAS unsigned char* lds, const Gemm g, const StaticOrder& S, const Epi& E, int wv0) {
;     ...
;       PG8_WAIT_V(6); PG8_BAR; PG8_MMA(1, 1, At, B1); PG8_BAR;
;       PG8_LDB(B0, 1, 0); PG8_SCHED; PG8_LDA(At, 1, 0); PG8_STAGE(PG8_SA(0, 1), a2 + hstepA, voffA);
;       PG8_WAIT_L(8); PG8_BAR; PG8_WAIT_L(0); PG8_MMA(0, 0, At, B0); PG8_BAR; PG8_SCHED;
;       PG8_LDB(B1, 1, 1); PG8_STAGE(PG8_SB(1, 0), b3, voffB);
;       PG8_BAR; PG8_WAIT_L(0); PG8_MMA(0, 1, At, B1); PG8_BAR;
;       PG8_LDA(At, 1, 1); PG8_STAGE(PG8_SA(1, 0), a3, voffA);
;       PG8_BAR; PG8_WAIT_L(0); PG8_MMA(1, 0, At, B0); PG8_BAR; PG8_SCHED;
	s_add_u32 s18, s20, 0x20000
	s_addc_u32 s19, s21, 0
	s_add_i32 s0, s47, s31
	v_lshl_add_u64 v[72:73], s[18:19], 0, v[224:225]
	s_mov_b32 m0, s0
	s_nop 0
	global_load_lds_dwordx4 v[72:73], off
	v_lshl_add_u64 v[72:73], s[18:19], 0, v[228:229]
	s_add_i32 m0, s0, 0x2000
	s_nop 0
	global_load_lds_dwordx4 v[72:73], off
	s_waitcnt vmcnt(6)
	s_barrier
	v_mfma_f32_16x16x32_bf16 v[52:55], v[178:181], v[122:125], v[52:55]
	v_mfma_f32_16x16x32_bf16 v[48:51], v[186:189], v[122:125], v[48:51]
	v_mfma_f32_16x16x32_bf16 v[36:39], v[178:181], v[140:143], v[36:39]
	v_mfma_f32_16x16x32_bf16 v[32:35], v[186:189], v[140:143], v[32:35]
	v_mfma_f32_16x16x32_bf16 v[20:23], v[178:181], v[148:151], v[20:23]
	v_mfma_f32_16x16x32_bf16 v[16:19], v[186:189], v[148:151], v[16:19]
	v_mfma_f32_16x16x32_bf16 v[4:7], v[178:181], v[164:167], v[4:7]
	v_mfma_f32_16x16x32_bf16 v[0:3], v[186:189], v[164:167], v[0:3]
	v_mfma_f32_16x16x32_bf16 v[52:55], v[182:185], v[136:139], v[52:55]
	v_mfma_f32_16x16x32_bf16 v[48:51], v[198:201], v[136:139], v[48:51]
	v_mfma_f32_16x16x32_bf16 v[36:39], v[182:185], v[144:147], v[36:39]
	v_mfma_f32_16x16x32_bf16 v[32:35], v[198:201], v[144:147], v[32:35]
	v_mfma_f32_16x16x32_bf16 v[20:23], v[182:185], v[160:163], v[20:23]
	v_mfma_f32_16x16x32_bf16 v[16:19], v[198:201], v[160:163], v[16:19]
	v_mfma_f32_16x16x32_bf16 v[4:7], v[182:185], v[190:193], v[4:7]
	v_mfma_f32_16x16x32_bf16 v[0:3], v[198:201], v[190:193], v[0:3]
	s_add_i32 s0, 0, 0x18000
	v_add_u32_e32 v84, s0, v253
	s_barrier
	ds_read_b128 v[72:75], v84
	ds_read_b128 v[76:79], v84 offset:1024
	ds_read_b128 v[90:93], v84 offset:2048
	ds_read_b128 v[98:101], v84 offset:3072
	s_add_u32 s18, s22, 0x114000
	s_addc_u32 s19, s23, 0
	s_mov_b32 m0, s36
	v_lshl_add_u64 v[84:85], s[18:19], 0, v[94:95]
	ds_read_b128 v[122:125], v244 offset:32768
	ds_read_b128 v[136:139], v244 offset:33792
	ds_read_b128 v[140:143], v244 offset:34816
	ds_read_b128 v[144:147], v244 offset:35840
	ds_read_b128 v[148:151], v244 offset:36864
	ds_read_b128 v[178:181], v244 offset:37888
	ds_read_b128 v[206:209], v244 offset:38912
	ds_read_b128 v[210:213], v244 offset:39936
	global_load_lds_dwordx4 v[84:85], off
	v_lshl_add_u64 v[84:85], s[18:19], 0, v[226:227]
	s_mov_b32 m0, s37
	s_nop 0
	global_load_lds_dwordx4 v[84:85], off
	s_waitcnt lgkmcnt(8)
	s_barrier
	s_waitcnt lgkmcnt(0)
	s_waitcnt lgkmcnt(0)
	v_mfma_f32_16x16x32_bf16 v[152:155], v[72:75], v[122:125], v[152:155]
	v_mfma_f32_16x16x32_bf16 v[202:205], v[76:79], v[136:139], v[152:155]
	v_mfma_f32_16x16x32_bf16 v[152:155], v[90:93], v[122:125], v[156:159]
	v_mfma_f32_16x16x32_bf16 v[198:201], v[98:101], v[136:139], v[152:155]
	v_mfma_f32_16x16x32_bf16 v[152:155], v[72:75], v[140:143], v[170:173]
	v_mfma_f32_16x16x32_bf16 v[186:189], v[76:79], v[144:147], v[152:155]
	v_mfma_f32_16x16x32_bf16 v[152:155], v[90:93], v[140:143], v[174:177]
	v_mfma_f32_16x16x32_bf16 v[130:133], v[72:75], v[148:151], v[132:135]
	v_mfma_f32_16x16x32_bf16 v[126:129], v[90:93], v[148:151], v[126:129]
	v_mfma_f32_16x16x32_bf16 v[84:87], v[72:75], v[206:209], v[86:89]
	v_mfma_f32_16x16x32_bf16 v[80:83], v[90:93], v[206:209], v[80:83]
	v_mfma_f32_16x16x32_bf16 v[182:185], v[98:101], v[144:147], v[152:155]
	v_mfma_f32_16x16x32_bf16 v[132:135], v[76:79], v[178:181], v[130:133]
	v_mfma_f32_16x16x32_bf16 v[128:131], v[98:101], v[178:181], v[126:129]
	v_mfma_f32_16x16x32_bf16 v[86:89], v[76:79], v[210:213], v[84:87]
	v_mfma_f32_16x16x32_bf16 v[82:85], v[98:101], v[210:213], v[80:83]
	s_barrier
	s_add_i32 s22, 0, 0x1c000
	v_add_u32_e32 v80, s22, v253
	s_add_i32 s0, s0, s31
	ds_read_b128 v[152:155], v80
	ds_read_b128 v[156:159], v80 offset:1024
	ds_read_b128 v[170:173], v80 offset:2048
	ds_read_b128 v[174:177], v80 offset:3072
	v_lshl_add_u64 v[80:81], v[214:215], 0, s[72:73]
	s_mov_b32 m0, s0
	s_nop 0
	global_load_lds_dwordx4 v[80:81], off
	v_lshl_add_u64 v[80:81], v[216:217], 0, s[72:73]
	s_add_i32 m0, s0, 0x2000
	s_nop 0
	global_load_lds_dwordx4 v[80:81], off
	s_barrier
	s_waitcnt lgkmcnt(0)
	s_waitcnt lgkmcnt(0)
	v_mfma_f32_16x16x32_bf16 v[110:113], v[170:173], v[122:125], v[110:113]
	v_mfma_f32_16x16x32_bf16 v[190:193], v[174:177], v[136:139], v[110:113]
	v_mfma_f32_16x16x32_bf16 v[110:113], v[152:155], v[140:143], v[114:117]
	v_mfma_f32_16x16x32_bf16 v[160:163], v[152:155], v[122:125], v[194:197]
	v_mfma_f32_16x16x32_bf16 v[166:169], v[156:159], v[144:147], v[110:113]
	v_mfma_f32_16x16x32_bf16 v[110:113], v[170:173], v[140:143], v[118:121]
	v_mfma_f32_16x16x32_bf16 v[106:109], v[152:155], v[148:151], v[106:109]
	v_mfma_f32_16x16x32_bf16 v[102:105], v[170:173], v[148:151], v[102:105]
	v_mfma_f32_16x16x32_bf16 v[68:71], v[152:155], v[206:209], v[68:71]
	v_mfma_f32_16x16x32_bf16 v[64:67], v[170:173], v[206:209], v[64:67]
	v_mfma_f32_16x16x32_bf16 v[194:197], v[156:159], v[136:139], v[160:163]
	v_mfma_f32_16x16x32_bf16 v[162:165], v[174:177], v[144:147], v[110:113]
	v_mfma_f32_16x16x32_bf16 v[106:109], v[156:159], v[178:181], v[106:109]
	v_mfma_f32_16x16x32_bf16 v[102:105], v[174:177], v[178:181], v[102:105]
	v_mfma_f32_16x16x32_bf16 v[68:71], v[156:159], v[210:213], v[68:71]
	v_mfma_f32_16x16x32_bf16 v[64:67], v[174:177], v[210:213], v[64:67]
	s_mov_b32 m0, s38
	v_lshl_add_u64 v[80:81], v[218:219], 0, s[72:73]
	s_barrier
; #define PG8_STAGE(bufoff, gbase, voff) do { _Pragma("unroll") for (int _i = 0; _i < 2; ++_i) \
;     __builtin_amdgcn_global_load_lds((const unsigned*)((const char*)(gbase) + (voff)[_i]), (LAS unsigned*)(lds + (bufoff) + ldsw + _i * 8192), 16, 0, 0); } while (0)
; #define PG8_MMA(ai, bj, At, Bt) do { __builtin_amdgcn_s_setprio(1); _Pragma("unroll") for (int m = 0; m < 4; ++m) _Pragma("unroll") for (int n = 0; n < 2; ++n) _Pragma("unroll") for (int k = 0; k < 2; ++k) \
;     acc[ai][bj][m][n] = __builtin_amdgcn_mfma_f32_16x16x32_bf16(Bt[n][k], At[m][k], acc[ai][bj][m][n], 0, 0, 0); __builtin_amdgcn_s_setprio(0); } while (0)
; #define PG8_WAIT_V(n) asm volatile("s_waitcnt vmcnt(" #n ")" ::: "memory")
; #define PG8_WAIT_L(n) asm volatile("s_waitcnt lgkmcnt(" #n ")" ::: "memory")
; #define PG8_BAR __builtin_amdgcn_s_barrier()
; #define PG8_SCHED __builtin_amdgcn_sched_barrier(0)
; template <class Epi>
; __device__ __forceinline__ void gemm_phase(LAS unsigned char* lds, const Gemm g, const StaticOrder& S, const Epi& E, int wv0) {
;     ...
;       PG8_BAR; PG8_WAIT_L(0); PG8_MMA(1, 0, At, B0); PG8_BAR; PG8_SCHED;
;       PG8_STAGE(PG8_SB(1, 1), b3 + hstepB, voffB);
;       PG8_WAIT_V(6); PG8_BAR; PG8_MMA(1, 1, At, B1); PG8_BAR;
;   __device__ __forceinline__ void operator()(const f32x4 (&acc)[2][2][4][2], const pg8::Unit& u, int wr, int wc, int fr, int fq) const {
;     ...
;       for (int m = 0; m < 4; ++m) { hs[ai][m] = 0.f;
;         if (MODE == E_UQ) hs[ai][m] = ((const f32x4*)e.f0)[row0 + ai * 128 + m * 16].x * MLA_QSCALE;
;         if (MODE == E_UKV) hs[ai][m] = ((const f32x4*)e.f0)[row0 + ai * 128 + m * 16].y; }
;     EpiPre q[2][4];
; #pragma unroll
;     for (int i = 0; i < 4; ++i) preload(q[0][i], row0 + (i >> 1) * 16, col0 + (i & 1) * 128);
; #pragma unroll
;     for (int gi = 0; gi < 4; ++gi) {
;       const int ai = gi >> 1, mp = gi & 1;
;       if (gi + 1 < 4) { const int ai2 = (gi + 1) >> 1, mp2 = (gi + 1) & 1;
; #pragma unroll
;         for (int i = 0; i < 4; ++i) preload(q[(gi + 1) & 1][i], row0 + ai2 * 128 + (2 * mp2 + (i >> 1)) * 16, col0 + (i & 1) * 128); }
	ds_read_b128 v[110:113], v244 offset:49152
	ds_read_b128 v[114:117], v244 offset:50176
	ds_read_b128 v[118:121], v244 offset:51200
	ds_read_b128 v[122:125], v244 offset:52224
	ds_read_b128 v[136:139], v244 offset:53248
	ds_read_b128 v[140:143], v244 offset:54272
	ds_read_b128 v[144:147], v244 offset:55296
	ds_read_b128 v[148:151], v244 offset:56320
	global_load_lds_dwordx4 v[80:81], off
	v_lshl_add_u64 v[80:81], v[220:221], 0, s[72:73]
	s_mov_b32 m0, s39
	s_nop 0
	global_load_lds_dwordx4 v[80:81], off
	s_barrier
	s_waitcnt lgkmcnt(0)
	s_waitcnt lgkmcnt(0)
	v_mfma_f32_16x16x32_bf16 v[60:63], v[72:75], v[110:113], v[60:63]
	v_mfma_f32_16x16x32_bf16 v[56:59], v[90:93], v[110:113], v[56:59]
	v_mfma_f32_16x16x32_bf16 v[44:47], v[72:75], v[118:121], v[44:47]
	v_mfma_f32_16x16x32_bf16 v[40:43], v[90:93], v[118:121], v[40:43]
	v_mfma_f32_16x16x32_bf16 v[28:31], v[72:75], v[136:139], v[28:31]
	v_mfma_f32_16x16x32_bf16 v[24:27], v[90:93], v[136:139], v[24:27]
	v_mfma_f32_16x16x32_bf16 v[12:15], v[72:75], v[144:147], v[12:15]
	v_mfma_f32_16x16x32_bf16 v[8:11], v[90:93], v[144:147], v[8:11]
	v_mfma_f32_16x16x32_bf16 v[60:63], v[76:79], v[114:117], v[60:63]
	v_mfma_f32_16x16x32_bf16 v[56:59], v[98:101], v[114:117], v[56:59]
	v_mfma_f32_16x16x32_bf16 v[44:47], v[76:79], v[122:125], v[44:47]
	v_mfma_f32_16x16x32_bf16 v[40:43], v[98:101], v[122:125], v[40:43]
	v_mfma_f32_16x16x32_bf16 v[28:31], v[76:79], v[140:143], v[28:31]
	v_mfma_f32_16x16x32_bf16 v[24:27], v[98:101], v[140:143], v[24:27]
	v_mfma_f32_16x16x32_bf16 v[12:15], v[76:79], v[148:151], v[12:15]
	v_mfma_f32_16x16x32_bf16 v[8:11], v[98:101], v[148:151], v[8:11]
	s_barrier
	s_add_u32 s18, s20, 0x20080
	s_addc_u32 s19, s21, 0
	s_add_i32 s0, s22, s31
	v_lshl_add_u64 v[72:73], s[18:19], 0, v[224:225]
	s_mov_b32 m0, s0
	s_nop 0
	global_load_lds_dwordx4 v[72:73], off
	v_lshl_add_u64 v[72:73], s[18:19], 0, v[228:229]
	s_add_i32 m0, s0, 0x2000
	s_nop 0
	global_load_lds_dwordx4 v[72:73], off
	s_waitcnt vmcnt(6)
	s_barrier
	v_mfma_f32_16x16x32_bf16 v[52:55], v[152:155], v[110:113], v[52:55]
	v_mfma_f32_16x16x32_bf16 v[48:51], v[170:173], v[110:113], v[48:51]
	v_mfma_f32_16x16x32_bf16 v[36:39], v[152:155], v[118:121], v[36:39]
	v_mfma_f32_16x16x32_bf16 v[32:35], v[170:173], v[118:121], v[32:35]
	v_mfma_f32_16x16x32_bf16 v[20:23], v[152:155], v[136:139], v[20:23]
	v_mfma_f32_16x16x32_bf16 v[16:19], v[170:173], v[136:139], v[16:19]
	v_mfma_f32_16x16x32_bf16 v[4:7], v[152:155], v[144:147], v[4:7]
	v_mfma_f32_16x16x32_bf16 v[0:3], v[170:173], v[144:147], v[0:3]
	v_mfma_f32_16x16x32_bf16 v[52:55], v[156:159], v[114:117], v[52:55]
	v_mfma_f32_16x16x32_bf16 v[48:51], v[174:177], v[114:117], v[48:51]
	v_mfma_f32_16x16x32_bf16 v[36:39], v[156:159], v[122:125], v[36:39]
	v_mfma_f32_16x16x32_bf16 v[32:35], v[174:177], v[122:125], v[32:35]
	v_mfma_f32_16x16x32_bf16 v[20:23], v[156:159], v[140:143], v[20:23]
	v_mfma_f32_16x16x32_bf16 v[16:19], v[174:177], v[140:143], v[16:19]
	v_mfma_f32_16x16x32_bf16 v[4:7], v[156:159], v[148:151], v[4:7]
	v_mfma_f32_16x16x32_bf16 v[0:3], v[174:177], v[148:151], v[0:3]
	s_add_i32 s46, s46, 2
	s_add_u32 s44, s44, 0x100
	s_addc_u32 s45, s45, 0
	s_cmp_gt_u32 s46, 5
	s_mov_b64 s[18:19], s[4:5]
	s_barrier
	s_cbranch_scc0 .LBB0_671
	v_lshl_add_u32 v234, s1, 8, v252
	v_or_b32_e32 v238, 32, v234
	v_ashrrev_i32_e32 v239, 31, v238
	v_or_b32_e32 v236, 48, v234
	v_ashrrev_i32_e32 v235, 31, v234
	v_lshl_add_u64 v[76:77], v[238:239], 4, s[68:69]
	v_ashrrev_i32_e32 v237, 31, v236
	v_lshl_add_u64 v[72:73], v[234:235], 4, s[68:69]
	v_lshl_add_u64 v[78:79], v[236:237], 4, s[68:69]
	global_load_dwordx4 v[210:213], v[76:77], off
	global_load_dwordx4 v[206:209], v[78:79], off
	global_load_dwordx4 v[216:219], v[72:73], off
	global_load_dwordx4 v[178:181], v[72:73], off offset:2048
	global_load_dwordx4 v[144:147], v[72:73], off offset:2304
	global_load_dwordx4 v[110:113], v[72:73], off offset:2560
	v_or_b32_e32 v240, 16, v234
	v_ashrrev_i32_e32 v241, 31, v240
	v_lshl_add_u64 v[74:75], v[240:241], 4, s[68:69]
	global_load_dwordx4 v[212:215], v[74:75], off
	s_nop 0
	global_load_dwordx4 v[72:75], v[72:73], off offset:2816
	s_waitcnt vmcnt(0)
	v_lshl_or_b32 v180, s16, 8, v254
	v_mul_hi_i32 v73, v180, s71
	v_lshrrev_b32_e32 v74, 31, v73
	v_lshrrev_b32_e32 v73, 5, v73
	v_add_u32_e32 v73, v73, v74
	v_mul_lo_u32 v73, v73, s59
	v_sub_u32_e32 v96, v180, v73
	v_lshlrev_b64 v[74:75], 8, v[234:235]
	v_cmp_lt_i32_e64 s[4:5], s67, v96
	v_lshl_add_u64 v[74:75], s[8:9], 0, v[74:75]
	s_and_saveexec_b64 s[16:17], s[4:5]
	s_cbranch_execz .LBB0_674
	v_lshl_add_u64 v[76:77], v[96:97], 2, v[74:75]
	global_load_dwordx4 v[170:173], v[76:77], off offset:-496
	global_load_dwordx4 v[174:177], v[76:77], off offset:-512

; #define PG8_STAGE(bufoff, gbase, voff) do { _Pragma("unroll") for (int _i = 0; _i < 2; ++_i) \
;     __builtin_amdgcn_global_load_lds((const unsigned*)((const char*)(gbase) + (voff)[_i]), (LAS unsigned*)(lds + (bufoff) + ldsw + _i * 8192), 16, 0, 0); } while (0)
; #define PG8_LDA(dst, b, h) do { _Pragma("unroll") for (int m = 0; m < 4; ++m) _Pragma("unroll") for (int k = 0; k < 2; ++k) dst[m][k] = *(const LAS bf16x8*)(lds + PG8_SA(b, h) + aoff + m * 2048 + k * 1024); } while (0)
; #define PG8_LDB(dst, b, h) do { _Pragma("unroll") for (int n = 0; n < 2; ++n) _Pragma("unroll") for (int k = 0; k < 2; ++k) dst[n][k] = *(const LAS bf16x8*)(lds + PG8_SB(b, h) + boff + n * 2048 + k * 1024); } while (0)
; #define PG8_MMA(ai, bj, At, Bt) do { __builtin_amdgcn_s_setprio(1); _Pragma("unroll") for (int m = 0; m < 4; ++m) _Pragma("unroll") for (int n = 0; n < 2; ++n) _Pragma("unroll") for (int k = 0; k < 2; ++k) \
;     acc[ai][bj][m][n] = __builtin_amdgcn_mfma_f32_16x16x32_bf16(Bt[n][k], At[m][k], acc[ai][bj][m][n], 0, 0, 0); __builtin_amdgcn_s_setprio(0); } while (0)
; #define PG8_WAIT_V(n) asm volatile("s_waitcnt vmcnt(" #n ")" ::: "memory")
; #define PG8_WAIT_L(n) asm volatile("s_waitcnt lgkmcnt(" #n ")" ::: "memory")
; #define PG8_BAR __builtin_amdgcn_s_barrier()
; #define PG8_SCHED __builtin_amdgcn_sched_barrier(0)
; template <class Epi>
; __device__ __forceinline__ void gemm_phase(LAS unsigned char* lds, const Gemm g, const StaticOrder& S, const Epi& E, int wv0) {
;     ...
;     for (int t = 0; t < nt; t += 2) {
;       const bool last = (t == nt - 2);
;       const char* a1 = cA + (size_t)(t + 1) * kstep;
;       const char* a2 = last ? nA : cA + (size_t)(t + 2) * kstep; const char* b2 = last ? nB : cB + (size_t)(t + 2) * kstep;
;       const char* a3 = a2 + kstep; const char* b3 = b2 + kstep;
;       PG8_LDB(B0, 0, 0); PG8_SCHED; PG8_LDA(At, 0, 0); PG8_STAGE(PG8_SA(1, 1), a1 + hstepA, voffA);
;       PG8_WAIT_L(8); PG8_BAR; PG8_WAIT_L(0); PG8_MMA(0, 0, At, B0); PG8_BAR; PG8_SCHED;
;       PG8_LDB(B1, 0, 1); PG8_STAGE(PG8_SB(0, 0), b2, voffB);
;       PG8_BAR; PG8_WAIT_L(0); PG8_MMA(0, 1, At, B1); PG8_BAR;
;       PG8_LDA(At, 0, 1); PG8_STAGE(PG8_SA(0, 0), a2, voffA);
;       PG8_BAR; PG8_WAIT_L(0); PG8_MMA(1, 0, At, B0); PG8_BAR; PG8_SCHED;
;       PG8_STAGE(PG8_SB(0, 1), b2 + hstepB, voffB);
;       PG8_WAIT_V(6); PG8_BAR; PG8_MMA(1, 1, At, B1); PG8_BAR;
.Lgprio2:
.LBB0_756:
	s_add_u32 s4, s14, 0x100
	s_addc_u32 s5, s15, 0
	s_add_i32 s0, 0, 0x10000
	v_add_u32_e32 v156, s0, v149
	ds_read_b128 v[140:143], v156
	ds_read_b128 v[144:147], v156 offset:1024
	ds_read_b128 v[152:155], v156 offset:2048
	ds_read_b128 v[156:159], v156 offset:3072
	s_cmp_eq_u32 s44, 4
	s_cselect_b32 s19, s11, s5
	s_cselect_b32 s18, s10, s4
	s_cselect_b32 s17, s9, s43
	s_cselect_b32 s16, s41, s42
	v_lshl_add_u64 v[192:193], s[14:15], 0, v[136:137]
	s_add_i32 m0, s29, 0xc000
	ds_read_b128 v[160:163], v151
	ds_read_b128 v[164:167], v151 offset:1024
	ds_read_b128 v[168:171], v151 offset:2048
	ds_read_b128 v[172:175], v151 offset:3072
	ds_read_b128 v[176:179], v151 offset:4096
	ds_read_b128 v[180:183], v151 offset:5120
	ds_read_b128 v[184:187], v151 offset:6144
	ds_read_b128 v[188:191], v151 offset:7168
	global_load_lds_dwordx4 v[192:193], off
	v_lshl_add_u64 v[192:193], s[14:15], 0, v[138:139]
	s_add_i32 m0, s29, 0xe000
	s_nop 0
	global_load_lds_dwordx4 v[192:193], off
	s_waitcnt lgkmcnt(8)
	s_barrier
	s_waitcnt lgkmcnt(0)
	s_waitcnt lgkmcnt(0)
	v_mfma_f32_16x16x32_bf16 v[126:129], v[140:143], v[160:163], v[126:129]
	v_mfma_f32_16x16x32_bf16 v[122:125], v[152:155], v[160:163], v[122:125]
	v_mfma_f32_16x16x32_bf16 v[118:121], v[140:143], v[168:171], v[118:121]
	v_mfma_f32_16x16x32_bf16 v[114:117], v[152:155], v[168:171], v[114:117]
	v_mfma_f32_16x16x32_bf16 v[106:109], v[140:143], v[176:179], v[106:109]
	v_mfma_f32_16x16x32_bf16 v[98:101], v[152:155], v[176:179], v[98:101]
	v_mfma_f32_16x16x32_bf16 v[76:79], v[140:143], v[184:187], v[76:79]
	v_mfma_f32_16x16x32_bf16 v[72:75], v[152:155], v[184:187], v[72:75]
	v_mfma_f32_16x16x32_bf16 v[126:129], v[144:147], v[164:167], v[126:129]
	v_mfma_f32_16x16x32_bf16 v[122:125], v[156:159], v[164:167], v[122:125]
	v_mfma_f32_16x16x32_bf16 v[118:121], v[144:147], v[172:175], v[118:121]
	v_mfma_f32_16x16x32_bf16 v[114:117], v[156:159], v[172:175], v[114:117]
	v_mfma_f32_16x16x32_bf16 v[106:109], v[144:147], v[180:183], v[106:109]
	v_mfma_f32_16x16x32_bf16 v[98:101], v[156:159], v[180:183], v[98:101]
	v_mfma_f32_16x16x32_bf16 v[76:79], v[144:147], v[188:191], v[76:79]
	v_mfma_f32_16x16x32_bf16 v[72:75], v[156:159], v[188:191], v[72:75]
	s_barrier
	s_add_i32 s45, 0, 0x14000
	s_add_i32 s0, s0, s28
	v_add_u32_e32 v204, s45, v149
	v_lshl_add_u64 v[208:209], s[16:17], 0, v[96:97]
	s_mov_b32 m0, s0
	ds_read_b128 v[192:195], v204
	ds_read_b128 v[196:199], v204 offset:1024
	ds_read_b128 v[200:203], v204 offset:2048
	ds_read_b128 v[204:207], v204 offset:3072
	global_load_lds_dwordx4 v[208:209], off
	v_lshl_add_u64 v[210:211], s[16:17], 0, v[134:135]
	s_add_i32 m0, s0, 0x2000
	s_nop 0
	global_load_lds_dwordx4 v[210:211], off
	s_barrier
	s_waitcnt lgkmcnt(0)
	s_waitcnt lgkmcnt(0)
	v_mfma_f32_16x16x32_bf16 v[110:113], v[192:195], v[160:163], v[110:113]
	v_mfma_f32_16x16x32_bf16 v[102:105], v[200:203], v[160:163], v[102:105]
	v_mfma_f32_16x16x32_bf16 v[92:95], v[192:195], v[168:171], v[92:95]
	v_mfma_f32_16x16x32_bf16 v[88:91], v[200:203], v[168:171], v[88:91]
	v_mfma_f32_16x16x32_bf16 v[84:87], v[192:195], v[176:179], v[84:87]
	v_mfma_f32_16x16x32_bf16 v[80:83], v[200:203], v[176:179], v[80:83]
	v_mfma_f32_16x16x32_bf16 v[68:71], v[192:195], v[184:187], v[68:71]
	v_mfma_f32_16x16x32_bf16 v[64:67], v[200:203], v[184:187], v[64:67]
	v_mfma_f32_16x16x32_bf16 v[110:113], v[196:199], v[164:167], v[110:113]
	v_mfma_f32_16x16x32_bf16 v[102:105], v[204:207], v[164:167], v[102:105]
	v_mfma_f32_16x16x32_bf16 v[92:95], v[196:199], v[172:175], v[92:95]
	v_mfma_f32_16x16x32_bf16 v[88:91], v[204:207], v[172:175], v[88:91]
	v_mfma_f32_16x16x32_bf16 v[84:87], v[196:199], v[180:183], v[84:87]
	v_mfma_f32_16x16x32_bf16 v[80:83], v[204:207], v[180:183], v[80:83]
	v_mfma_f32_16x16x32_bf16 v[68:71], v[196:199], v[188:191], v[68:71]
	v_mfma_f32_16x16x32_bf16 v[64:67], v[204:207], v[188:191], v[64:67]
	s_mov_b32 m0, s29
	v_lshl_add_u64 v[212:213], s[18:19], 0, v[130:131]
	s_barrier
	ds_read_b128 v[160:163], v151 offset:16384
	ds_read_b128 v[164:167], v151 offset:17408
	ds_read_b128 v[168:171], v151 offset:18432
	ds_read_b128 v[172:175], v151 offset:19456
	ds_read_b128 v[176:179], v151 offset:20480
	ds_read_b128 v[180:183], v151 offset:21504
	ds_read_b128 v[184:187], v151 offset:22528
	ds_read_b128 v[188:191], v151 offset:23552
	global_load_lds_dwordx4 v[212:213], off
	v_lshl_add_u64 v[214:215], s[18:19], 0, v[132:133]
	s_mov_b32 m0, s30
	s_nop 0
	global_load_lds_dwordx4 v[214:215], off
	s_barrier
	s_waitcnt lgkmcnt(0)
	s_waitcnt lgkmcnt(0)
	v_mfma_f32_16x16x32_bf16 v[60:63], v[140:143], v[160:163], v[60:63]
	v_mfma_f32_16x16x32_bf16 v[56:59], v[152:155], v[160:163], v[56:59]
	v_mfma_f32_16x16x32_bf16 v[52:55], v[140:143], v[168:171], v[52:55]
	v_mfma_f32_16x16x32_bf16 v[44:47], v[152:155], v[168:171], v[44:47]
	v_mfma_f32_16x16x32_bf16 v[36:39], v[140:143], v[176:179], v[36:39]
	v_mfma_f32_16x16x32_bf16 v[28:31], v[152:155], v[176:179], v[28:31]
	v_mfma_f32_16x16x32_bf16 v[20:23], v[140:143], v[184:187], v[20:23]
	v_mfma_f32_16x16x32_bf16 v[12:15], v[152:155], v[184:187], v[12:15]
	v_mfma_f32_16x16x32_bf16 v[60:63], v[144:147], v[164:167], v[60:63]
	v_mfma_f32_16x16x32_bf16 v[56:59], v[156:159], v[164:167], v[56:59]
	v_mfma_f32_16x16x32_bf16 v[52:55], v[144:147], v[172:175], v[52:55]
	v_mfma_f32_16x16x32_bf16 v[44:47], v[156:159], v[172:175], v[44:47]
	v_mfma_f32_16x16x32_bf16 v[36:39], v[144:147], v[180:183], v[36:39]
	v_mfma_f32_16x16x32_bf16 v[28:31], v[156:159], v[180:183], v[28:31]
	v_mfma_f32_16x16x32_bf16 v[20:23], v[144:147], v[188:191], v[20:23]
	v_mfma_f32_16x16x32_bf16 v[12:15], v[156:159], v[188:191], v[12:15]
	s_barrier
; #define PG8_STAGE(bufoff, gbase, voff) do { _Pragma("unroll") for (int _i = 0; _i < 2; ++_i) \
;     __builtin_amdgcn_global_load_lds((const unsigned*)((const char*)(gbase) + (voff)[_i]), (LAS unsigned*)(lds + (bufoff) + ldsw + _i * 8192), 16, 0, 0); } while (0)
; #define PG8_LDA(dst, b, h) do { _Pragma("unroll") for (int m = 0; m < 4; ++m) _Pragma("unroll") for (int k = 0; k < 2; ++k) dst[m][k] = *(const LAS bf16x8*)(lds + PG8_SA(b, h) + aoff + m * 2048 + k * 1024); } while (0)
; #define PG8_LDB(dst, b, h) do { _Pragma("unroll") for (int n = 0; n < 2; ++n) _Pragma("unroll") for (int k = 0; k < 2; ++k) dst[n][k] = *(const LAS bf16x8*)(lds + PG8_SB(b, h) + boff + n * 2048 + k * 1024); } while (0)
; #define PG8_MMA(ai, bj, At, Bt) do { __builtin_amdgcn_s_setprio(1); _Pragma("unroll") for (int m = 0; m < 4; ++m) _Pragma("unroll") for (int n = 0; n < 2; ++n) _Pragma("unroll") for (int k = 0; k < 2; ++k) \
;     acc[ai][bj][m][n] = __builtin_amdgcn_mfma_f32_16x16x32_bf16(Bt[n][k], At[m][k], acc[ai][bj][m][n], 0, 0, 0); __builtin_amdgcn_s_setprio(0); } while (0)
; #define PG8_WAIT_V(n) asm volatile("s_waitcnt vmcnt(" #n ")" ::: "memory")
; #define PG8_WAIT_L(n) asm volatile("s_waitcnt lgkmcnt(" #n ")" ::: "memory")
; #define PG8_BAR __builtin_amdgcn_s_barrier()
; #define PG8_SCHED __builtin_amdgcn_sched_barrier(0)
; template <class Epi>
; __device__ __forceinline__ void gemm_phase(LAS unsigned char* lds, const Gemm g, const StaticOrder& S, const Epi& E, int wv0) {
;     ...
;       PG8_WAIT_V(6); PG8_BAR; PG8_MMA(1, 1, At, B1); PG8_BAR;
;       PG8_LDB(B0, 1, 0); PG8_SCHED; PG8_LDA(At, 1, 0); PG8_STAGE(PG8_SA(0, 1), a2 + hstepA, voffA);
;       PG8_WAIT_L(8); PG8_BAR; PG8_WAIT_L(0); PG8_MMA(0, 0, At, B0); PG8_BAR; PG8_SCHED;
;       PG8_LDB(B1, 1, 1); PG8_STAGE(PG8_SB(1, 0), b3, voffB);
;       PG8_BAR; PG8_WAIT_L(0); PG8_MMA(0, 1, At, B1); PG8_BAR;
;       PG8_LDA(At, 1, 1); PG8_STAGE(PG8_SA(1, 0), a3, voffA);
;       PG8_BAR; PG8_WAIT_L(0); PG8_MMA(1, 0, At, B0); PG8_BAR; PG8_SCHED;
	s_add_u32 s14, s16, 0x20000
	s_addc_u32 s15, s17, 0
	s_add_i32 s0, s45, s28
	v_lshl_add_u64 v[140:141], s[14:15], 0, v[96:97]
	s_mov_b32 m0, s0
	s_nop 0
	global_load_lds_dwordx4 v[140:141], off
	v_lshl_add_u64 v[140:141], s[14:15], 0, v[134:135]
	s_add_i32 m0, s0, 0x2000
	s_nop 0
	global_load_lds_dwordx4 v[140:141], off
	s_waitcnt vmcnt(6)
	s_barrier
	v_mfma_f32_16x16x32_bf16 v[48:51], v[192:195], v[160:163], v[48:51]
	v_mfma_f32_16x16x32_bf16 v[40:43], v[200:203], v[160:163], v[40:43]
	v_mfma_f32_16x16x32_bf16 v[32:35], v[192:195], v[168:171], v[32:35]
	v_mfma_f32_16x16x32_bf16 v[24:27], v[200:203], v[168:171], v[24:27]
	v_mfma_f32_16x16x32_bf16 v[16:19], v[192:195], v[176:179], v[16:19]
	v_mfma_f32_16x16x32_bf16 v[8:11], v[200:203], v[176:179], v[8:11]
	v_mfma_f32_16x16x32_bf16 v[4:7], v[192:195], v[184:187], v[4:7]
	v_mfma_f32_16x16x32_bf16 v[0:3], v[200:203], v[184:187], v[0:3]
	v_mfma_f32_16x16x32_bf16 v[48:51], v[196:199], v[164:167], v[48:51]
	v_mfma_f32_16x16x32_bf16 v[40:43], v[204:207], v[164:167], v[40:43]
	v_mfma_f32_16x16x32_bf16 v[32:35], v[196:199], v[172:175], v[32:35]
	v_mfma_f32_16x16x32_bf16 v[24:27], v[204:207], v[172:175], v[24:27]
	v_mfma_f32_16x16x32_bf16 v[16:19], v[196:199], v[180:183], v[16:19]
	v_mfma_f32_16x16x32_bf16 v[8:11], v[204:207], v[180:183], v[8:11]
	v_mfma_f32_16x16x32_bf16 v[4:7], v[196:199], v[188:191], v[4:7]
	v_mfma_f32_16x16x32_bf16 v[0:3], v[204:207], v[188:191], v[0:3]
	s_add_i32 s0, 0, 0x18000
	v_add_u32_e32 v156, s0, v149
	s_barrier
	ds_read_b128 v[140:143], v156
	ds_read_b128 v[144:147], v156 offset:1024
	ds_read_b128 v[152:155], v156 offset:2048
	ds_read_b128 v[156:159], v156 offset:3072
	s_add_u32 s14, s18, 0x114000
	s_addc_u32 s15, s19, 0
	s_mov_b32 m0, s31
	v_lshl_add_u64 v[192:193], s[14:15], 0, v[130:131]
	ds_read_b128 v[160:163], v151 offset:32768
	ds_read_b128 v[164:167], v151 offset:33792
	ds_read_b128 v[168:171], v151 offset:34816
	ds_read_b128 v[172:175], v151 offset:35840
	ds_read_b128 v[176:179], v151 offset:36864
	ds_read_b128 v[180:183], v151 offset:37888
	ds_read_b128 v[184:187], v151 offset:38912
	ds_read_b128 v[188:191], v151 offset:39936
	global_load_lds_dwordx4 v[192:193], off
	v_lshl_add_u64 v[192:193], s[14:15], 0, v[132:133]
	s_mov_b32 m0, s34
	s_nop 0
	global_load_lds_dwordx4 v[192:193], off
	s_waitcnt lgkmcnt(8)
	s_barrier
	s_waitcnt lgkmcnt(0)
	s_waitcnt lgkmcnt(0)
	v_mfma_f32_16x16x32_bf16 v[126:129], v[140:143], v[160:163], v[126:129]
	v_mfma_f32_16x16x32_bf16 v[122:125], v[152:155], v[160:163], v[122:125]
	v_mfma_f32_16x16x32_bf16 v[118:121], v[140:143], v[168:171], v[118:121]
	v_mfma_f32_16x16x32_bf16 v[114:117], v[152:155], v[168:171], v[114:117]
	v_mfma_f32_16x16x32_bf16 v[106:109], v[140:143], v[176:179], v[106:109]
	v_mfma_f32_16x16x32_bf16 v[98:101], v[152:155], v[176:179], v[98:101]
	v_mfma_f32_16x16x32_bf16 v[76:79], v[140:143], v[184:187], v[76:79]
	v_mfma_f32_16x16x32_bf16 v[72:75], v[152:155], v[184:187], v[72:75]
	v_mfma_f32_16x16x32_bf16 v[126:129], v[144:147], v[164:167], v[126:129]
	v_mfma_f32_16x16x32_bf16 v[122:125], v[156:159], v[164:167], v[122:125]
	v_mfma_f32_16x16x32_bf16 v[118:121], v[144:147], v[172:175], v[118:121]
	v_mfma_f32_16x16x32_bf16 v[114:117], v[156:159], v[172:175], v[114:117]
	v_mfma_f32_16x16x32_bf16 v[106:109], v[144:147], v[180:183], v[106:109]
	v_mfma_f32_16x16x32_bf16 v[98:101], v[156:159], v[180:183], v[98:101]
	v_mfma_f32_16x16x32_bf16 v[76:79], v[144:147], v[188:191], v[76:79]
	v_mfma_f32_16x16x32_bf16 v[72:75], v[156:159], v[188:191], v[72:75]
	s_barrier
	s_add_i32 s18, 0, 0x1c000
	s_add_i32 s0, s0, s28
	v_add_u32_e32 v204, s18, v149
	v_lshl_add_u64 v[208:209], v[208:209], 0, s[72:73]
	s_mov_b32 m0, s0
	ds_read_b128 v[192:195], v204
	ds_read_b128 v[196:199], v204 offset:1024
	ds_read_b128 v[200:203], v204 offset:2048
	ds_read_b128 v[204:207], v204 offset:3072
	global_load_lds_dwordx4 v[208:209], off
	v_lshl_add_u64 v[208:209], v[210:211], 0, s[72:73]
	s_add_i32 m0, s0, 0x2000
	s_nop 0
	global_load_lds_dwordx4 v[208:209], off
	s_barrier
	s_waitcnt lgkmcnt(0)
	s_waitcnt lgkmcnt(0)
	v_mfma_f32_16x16x32_bf16 v[110:113], v[192:195], v[160:163], v[110:113]
	v_mfma_f32_16x16x32_bf16 v[102:105], v[200:203], v[160:163], v[102:105]
	v_mfma_f32_16x16x32_bf16 v[92:95], v[192:195], v[168:171], v[92:95]
	v_mfma_f32_16x16x32_bf16 v[88:91], v[200:203], v[168:171], v[88:91]
	v_mfma_f32_16x16x32_bf16 v[84:87], v[192:195], v[176:179], v[84:87]
	v_mfma_f32_16x16x32_bf16 v[80:83], v[200:203], v[176:179], v[80:83]
	v_mfma_f32_16x16x32_bf16 v[68:71], v[192:195], v[184:187], v[68:71]
	v_mfma_f32_16x16x32_bf16 v[64:67], v[200:203], v[184:187], v[64:67]
	v_mfma_f32_16x16x32_bf16 v[110:113], v[196:199], v[164:167], v[110:113]
	v_mfma_f32_16x16x32_bf16 v[102:105], v[204:207], v[164:167], v[102:105]
	v_mfma_f32_16x16x32_bf16 v[92:95], v[196:199], v[172:175], v[92:95]
	v_mfma_f32_16x16x32_bf16 v[88:91], v[204:207], v[172:175], v[88:91]
	v_mfma_f32_16x16x32_bf16 v[84:87], v[196:199], v[180:183], v[84:87]
	v_mfma_f32_16x16x32_bf16 v[80:83], v[204:207], v[180:183], v[80:83]
	v_mfma_f32_16x16x32_bf16 v[68:71], v[196:199], v[188:191], v[68:71]
	v_mfma_f32_16x16x32_bf16 v[64:67], v[204:207], v[188:191], v[64:67]
	s_mov_b32 m0, s35
	v_lshl_add_u64 v[208:209], v[212:213], 0, s[72:73]
	s_barrier
	ds_read_b128 v[160:163], v151 offset:49152
	ds_read_b128 v[164:167], v151 offset:50176
	ds_read_b128 v[168:171], v151 offset:51200
	ds_read_b128 v[172:175], v151 offset:52224
	ds_read_b128 v[176:179], v151 offset:53248
	ds_read_b128 v[180:183], v151 offset:54272
	ds_read_b128 v[184:187], v151 offset:55296
	ds_read_b128 v[188:191], v151 offset:56320
	global_load_lds_dwordx4 v[208:209], off
	v_lshl_add_u64 v[208:209], v[214:215], 0, s[72:73]
	s_mov_b32 m0, s36
	s_nop 0
	global_load_lds_dwordx4 v[208:209], off
	s_barrier
; #define PG8_STAGE(bufoff, gbase, voff) do { _Pragma("unroll") for (int _i = 0; _i < 2; ++_i) \
;     __builtin_amdgcn_global_load_lds((const unsigned*)((const char*)(gbase) + (voff)[_i]), (LAS unsigned*)(lds + (bufoff) + ldsw + _i * 8192), 16, 0, 0); } while (0)
; #define PG8_MMA(ai, bj, At, Bt) do { __builtin_amdgcn_s_setprio(1); _Pragma("unroll") for (int m = 0; m < 4; ++m) _Pragma("unroll") for (int n = 0; n < 2; ++n) _Pragma("unroll") for (int k = 0; k < 2; ++k) \
;     acc[ai][bj][m][n] = __builtin_amdgcn_mfma_f32_16x16x32_bf16(Bt[n][k], At[m][k], acc[ai][bj][m][n], 0, 0, 0); __builtin_amdgcn_s_setprio(0); } while (0)
; #define PG8_WAIT_V(n) asm volatile("s_waitcnt vmcnt(" #n ")" ::: "memory")
; #define PG8_WAIT_L(n) asm volatile("s_waitcnt lgkmcnt(" #n ")" ::: "memory")
; #define PG8_BAR __builtin_amdgcn_s_barrier()
; #define PG8_SCHED __builtin_amdgcn_sched_barrier(0)
; template <class Epi>
; __device__ __forceinline__ void gemm_phase(LAS unsigned char* lds, const Gemm g, const StaticOrder& S, const Epi& E, int wv0) {
;     ...
;       PG8_BAR; PG8_WAIT_L(0); PG8_MMA(1, 0, At, B0); PG8_BAR; PG8_SCHED;
;       PG8_STAGE(PG8_SB(1, 1), b3 + hstepB, voffB);
;       PG8_WAIT_V(6); PG8_BAR; PG8_MMA(1, 1, At, B1); PG8_BAR;
;   __device__ __forceinline__ void operator()(const f32x4 (&acc)[2][2][4][2], const pg8::Unit& u, int wr, int wc, int fr, int fq) const {
;     ...
;       for (int m = 0; m < 4; ++m) { hs[ai][m] = 0.f;
;         if (MODE == E_UQ) hs[ai][m] = ((const f32x4*)e.f0)[row0 + ai * 128 + m * 16].x * MLA_QSCALE;
;         if (MODE == E_UKV) hs[ai][m] = ((const f32x4*)e.f0)[row0 + ai * 128 + m * 16].y; }
	s_waitcnt lgkmcnt(0)
	s_waitcnt lgkmcnt(0)
	v_mfma_f32_16x16x32_bf16 v[60:63], v[140:143], v[160:163], v[60:63]
	v_mfma_f32_16x16x32_bf16 v[56:59], v[152:155], v[160:163], v[56:59]
	v_mfma_f32_16x16x32_bf16 v[52:55], v[140:143], v[168:171], v[52:55]
	v_mfma_f32_16x16x32_bf16 v[44:47], v[152:155], v[168:171], v[44:47]
	v_mfma_f32_16x16x32_bf16 v[36:39], v[140:143], v[176:179], v[36:39]
	v_mfma_f32_16x16x32_bf16 v[28:31], v[152:155], v[176:179], v[28:31]
	v_mfma_f32_16x16x32_bf16 v[20:23], v[140:143], v[184:187], v[20:23]
	v_mfma_f32_16x16x32_bf16 v[12:15], v[152:155], v[184:187], v[12:15]
	v_mfma_f32_16x16x32_bf16 v[60:63], v[144:147], v[164:167], v[60:63]
	v_mfma_f32_16x16x32_bf16 v[56:59], v[156:159], v[164:167], v[56:59]
	v_mfma_f32_16x16x32_bf16 v[52:55], v[144:147], v[172:175], v[52:55]
	v_mfma_f32_16x16x32_bf16 v[44:47], v[156:159], v[172:175], v[44:47]
	v_mfma_f32_16x16x32_bf16 v[36:39], v[144:147], v[180:183], v[36:39]
	v_mfma_f32_16x16x32_bf16 v[28:31], v[156:159], v[180:183], v[28:31]
	v_mfma_f32_16x16x32_bf16 v[20:23], v[144:147], v[188:191], v[20:23]
	v_mfma_f32_16x16x32_bf16 v[12:15], v[156:159], v[188:191], v[12:15]
	s_barrier
	s_add_u32 s14, s16, 0x20080
	s_addc_u32 s15, s17, 0
	s_add_i32 s0, s18, s28
	v_lshl_add_u64 v[140:141], s[14:15], 0, v[96:97]
	s_mov_b32 m0, s0
	s_nop 0
	global_load_lds_dwordx4 v[140:141], off
	v_lshl_add_u64 v[140:141], s[14:15], 0, v[134:135]
	s_add_i32 m0, s0, 0x2000
	s_nop 0
	global_load_lds_dwordx4 v[140:141], off
	s_waitcnt vmcnt(6)
	s_barrier
	v_mfma_f32_16x16x32_bf16 v[48:51], v[192:195], v[160:163], v[48:51]
	v_mfma_f32_16x16x32_bf16 v[40:43], v[200:203], v[160:163], v[40:43]
	v_mfma_f32_16x16x32_bf16 v[32:35], v[192:195], v[168:171], v[32:35]
	v_mfma_f32_16x16x32_bf16 v[24:27], v[200:203], v[168:171], v[24:27]
	v_mfma_f32_16x16x32_bf16 v[16:19], v[192:195], v[176:179], v[16:19]
	v_mfma_f32_16x16x32_bf16 v[8:11], v[200:203], v[176:179], v[8:11]
	v_mfma_f32_16x16x32_bf16 v[4:7], v[192:195], v[184:187], v[4:7]
	v_mfma_f32_16x16x32_bf16 v[0:3], v[200:203], v[184:187], v[0:3]
	v_mfma_f32_16x16x32_bf16 v[48:51], v[196:199], v[164:167], v[48:51]
	v_mfma_f32_16x16x32_bf16 v[40:43], v[204:207], v[164:167], v[40:43]
	v_mfma_f32_16x16x32_bf16 v[32:35], v[196:199], v[172:175], v[32:35]
	v_mfma_f32_16x16x32_bf16 v[24:27], v[204:207], v[172:175], v[24:27]
	v_mfma_f32_16x16x32_bf16 v[16:19], v[196:199], v[180:183], v[16:19]
	v_mfma_f32_16x16x32_bf16 v[8:11], v[204:207], v[180:183], v[8:11]
	v_mfma_f32_16x16x32_bf16 v[4:7], v[196:199], v[188:191], v[4:7]
	v_mfma_f32_16x16x32_bf16 v[0:3], v[204:207], v[188:191], v[0:3]
	s_add_i32 s44, s44, 2
	s_add_u32 s42, s42, 0x100
	s_addc_u32 s43, s43, 0
	s_cmp_gt_u32 s44, 5
	s_mov_b64 s[14:15], s[4:5]
	s_barrier
	s_cbranch_scc0 .LBB0_756
	v_lshl_add_u32 v140, s39, 8, v148
	v_or_b32_e32 v146, 16, v140
	v_ashrrev_i32_e32 v141, 31, v140
	v_ashrrev_i32_e32 v147, 31, v146
	v_or_b32_e32 v156, 32, v140
	v_lshl_add_u64 v[142:143], v[140:141], 4, s[68:69]
	v_lshl_add_u64 v[144:145], v[146:147], 4, s[68:69]
	v_ashrrev_i32_e32 v157, 31, v156
	v_or_b32_e32 v160, 48, v140
	global_load_dwordx2 v[152:153], v[142:143], off
	global_load_dwordx2 v[154:155], v[144:145], off
	v_lshl_add_u64 v[144:145], v[156:157], 4, s[68:69]
	v_ashrrev_i32_e32 v161, 31, v160
	global_load_dwordx2 v[158:159], v[144:145], off
	v_lshl_add_u64 v[144:145], v[160:161], 4, s[68:69]
	global_load_dwordx2 v[162:163], v[144:145], off
	v_lshl_or_b32 v144, s40, 8, v150
	v_ashrrev_i32_e32 v145, 31, v144
	v_lshlrev_b64 v[164:165], 13, v[140:141]
	v_lshlrev_b64 v[166:167], 1, v[144:145]
	global_load_dwordx2 v[168:169], v[142:143], off offset:2048
	global_load_dwordx2 v[144:145], v[142:143], off offset:2304
	global_load_dwordx2 v[140:141], v[142:143], off offset:2560
	v_lshl_add_u64 v[164:165], s[6:7], 0, v[164:165]
	global_load_dwordx2 v[142:143], v[142:143], off offset:2816
	v_lshlrev_b64 v[170:171], 13, v[146:147]
	v_lshl_add_u64 v[146:147], v[164:165], 0, v[166:167]
	v_lshl_add_u64 v[164:165], s[6:7], 0, v[170:171]
	v_lshl_add_u64 v[164:165], v[164:165], 0, v[166:167]
	v_lshlrev_b64 v[156:157], 13, v[156:157]
	v_lshl_add_u64 v[156:157], s[6:7], 0, v[156:157]
	v_lshl_add_u64 v[156:157], v[156:157], 0, v[166:167]
	s_mov_b64 s[4:5], 0x100000
	s_mov_b32 s0, 0x140000
	s_mov_b32 s40, s8
	s_mov_b32 s39, s1
	s_mov_b64 s[16:17], s[12:13]
	s_mov_b64 s[14:15], s[10:11]
	s_waitcnt vmcnt(0)
;   __device__ __forceinline__ void emit(const EpiPre& q0, int row, int col, f32x4 a, f32x4 b, const f32x4 (&hb)[2][2], const float (&hs)[2][4], int ai_, int m_, int bj_) const {
;     ...
;     } else if (MODE == E_UKV) {
; #pragma unroll
;       for (int j = 0; j < 8; ++j) v[j] *= q.s;
;       store8bf((bf16_t*)e.out + (size_t)row * NKV + col, v);
	v_pk_mul_f32 v[126:127], v[126:127], v[152:153] op_sel:[0,1]
	v_pk_mul_f32 v[128:129], v[128:129], v[152:153] op_sel:[0,1]
	v_pk_mul_f32 v[122:123], v[122:123], v[152:153] op_sel:[0,1]
	v_pk_mul_f32 v[124:125], v[124:125], v[152:153] op_sel:[0,1]
	v_pk_mul_f32 v[118:119], v[118:119], v[154:155] op_sel:[0,1]
	v_pk_mul_f32 v[120:121], v[120:121], v[154:155] op_sel:[0,1]
	v_pk_mul_f32 v[114:115], v[114:115], v[154:155] op_sel:[0,1]
	v_pk_mul_f32 v[116:117], v[116:117], v[154:155] op_sel:[0,1]
	v_pk_mul_f32 v[110:111], v[110:111], v[152:153] op_sel:[0,1]
	v_pk_mul_f32 v[112:113], v[112:113], v[152:153] op_sel:[0,1]
	v_pk_mul_f32 v[170:171], v[102:103], v[152:153] op_sel:[0,1]
	v_pk_mul_f32 v[152:153], v[104:105], v[152:153] op_sel:[0,1]
	v_cvt_pk_bf16_f32 v102, v126, v127
	v_cvt_pk_bf16_f32 v103, v128, v129
	v_cvt_pk_bf16_f32 v104, v122, v123
	v_cvt_pk_bf16_f32 v105, v124, v125
	v_pk_mul_f32 v[92:93], v[92:93], v[154:155] op_sel:[0,1]
	v_pk_mul_f32 v[94:95], v[94:95], v[154:155] op_sel:[0,1]
	v_pk_mul_f32 v[88:89], v[88:89], v[154:155] op_sel:[0,1]
	v_pk_mul_f32 v[90:91], v[90:91], v[154:155] op_sel:[0,1]
	v_pk_mul_f32 v[126:127], v[80:81], v[158:159] op_sel:[0,1]
	v_pk_mul_f32 v[128:129], v[82:83], v[158:159] op_sel:[0,1]
	v_cvt_pk_bf16_f32 v80, v118, v119
	v_cvt_pk_bf16_f32 v81, v120, v121
	v_cvt_pk_bf16_f32 v82, v114, v115
	v_cvt_pk_bf16_f32 v83, v116, v117
	v_cvt_pk_bf16_f32 v110, v110, v111
	v_cvt_pk_bf16_f32 v111, v112, v113
	v_cvt_pk_bf16_f32 v112, v170, v171
	v_cvt_pk_bf16_f32 v113, v152, v153
	v_pk_mul_f32 v[122:123], v[84:85], v[158:159] op_sel:[0,1]
	v_pk_mul_f32 v[124:125], v[86:87], v[158:159] op_sel:[0,1]
	global_store_dwordx4 v[146:147], v[102:105], off
	global_store_dwordx4 v[146:147], v[110:113], off offset:256
	v_cvt_pk_bf16_f32 v84, v92, v93
	v_cvt_pk_bf16_f32 v85, v94, v95
	v_cvt_pk_bf16_f32 v86, v88, v89
	v_cvt_pk_bf16_f32 v87, v90, v91
	global_store_dwordx4 v[164:165], v[80:83], off
	global_store_dwordx4 v[164:165], v[84:87], off offset:256
	v_pk_mul_f32 v[106:107], v[106:107], v[158:159] op_sel:[0,1]
	v_pk_mul_f32 v[80:81], v[72:73], v[162:163] op_sel:[0,1]
	v_lshlrev_b64 v[72:73], 13, v[160:161]
	v_pk_mul_f32 v[108:109], v[108:109], v[158:159] op_sel:[0,1]
	v_pk_mul_f32 v[98:99], v[98:99], v[158:159] op_sel:[0,1]
	v_pk_mul_f32 v[100:101], v[100:101], v[158:159] op_sel:[0,1]
	v_pk_mul_f32 v[76:77], v[76:77], v[162:163] op_sel:[0,1]
	v_pk_mul_f32 v[78:79], v[78:79], v[162:163] op_sel:[0,1]
	v_pk_mul_f32 v[82:83], v[74:75], v[162:163] op_sel:[0,1]
	v_lshl_add_u64 v[72:73], s[6:7], 0, v[72:73]
	v_cvt_pk_bf16_f32 v88, v106, v107
	v_cvt_pk_bf16_f32 v89, v108, v109
	v_cvt_pk_bf16_f32 v90, v98, v99
	v_cvt_pk_bf16_f32 v91, v100, v101
	v_lshl_add_u64 v[84:85], v[72:73], 0, v[166:167]
	v_cvt_pk_bf16_f32 v72, v76, v77
	v_cvt_pk_bf16_f32 v73, v78, v79
	v_cvt_pk_bf16_f32 v74, v80, v81
	v_cvt_pk_bf16_f32 v75, v82, v83
	v_cvt_pk_bf16_f32 v92, v122, v123
	v_cvt_pk_bf16_f32 v93, v124, v125
	v_cvt_pk_bf16_f32 v94, v126, v127
	v_cvt_pk_bf16_f32 v95, v128, v129
	global_store_dwordx4 v[156:157], v[88:91], off
	global_store_dwordx4 v[156:157], v[92:95], off offset:256
	global_store_dwordx4 v[84:85], v[72:75], off
	v_pk_mul_f32 v[68:69], v[68:69], v[162:163] op_sel:[0,1]
	v_pk_mul_f32 v[70:71], v[70:71], v[162:163] op_sel:[0,1]
	v_pk_mul_f32 v[72:73], v[64:65], v[162:163] op_sel:[0,1]
	v_pk_mul_f32 v[74:75], v[66:67], v[162:163] op_sel:[0,1]
	v_cvt_pk_bf16_f32 v64, v68, v69
	v_cvt_pk_bf16_f32 v65, v70, v71
	v_cvt_pk_bf16_f32 v66, v72, v73
	v_cvt_pk_bf16_f32 v67, v74, v75
	v_pk_mul_f32 v[60:61], v[60:61], v[168:169] op_sel:[0,1]
	global_store_dwordx4 v[84:85], v[64:67], off offset:256
	v_pk_mul_f32 v[62:63], v[62:63], v[168:169] op_sel:[0,1]
	v_pk_mul_f32 v[48:49], v[48:49], v[168:169] op_sel:[0,1]
	v_pk_mul_f32 v[64:65], v[56:57], v[168:169] op_sel:[0,1]
; #define PG8_WAIT_V(n) asm volatile("s_waitcnt vmcnt(" #n ")" ::: "memory")
; #define PG8_BAR __builtin_amdgcn_s_barrier()
; template <class Epi>
; __device__ __forceinline__ void gemm_phase(LAS unsigned char* lds, const Gemm g, const StaticOrder& S, const Epi& E, int wv0) {
;     ...
;     if (!has_next) break;
; #pragma unroll
;     for (int a = 0; a < 2; ++a)
; #pragma unroll
;       for (int b = 0; b < 2; ++b)
; #pragma unroll
;         for (int m = 0; m < 4; ++m)
; #pragma unroll
;           for (int n = 0; n < 2; ++n) acc[a][b][m][n] = (f32x4){0.f, 0.f, 0.f, 0.f};
;     cur = nxt; cA = nA; cB = nB; ++ui;
;   }
;   PG8_WAIT_V(0);
;   if (wr == 0) PG8_BAR;
;   PG8_BAR;
;   __device__ __forceinline__ void emit(const EpiPre& q0, int row, int col, f32x4 a, f32x4 b, const f32x4 (&hb)[2][2], const float (&hs)[2][4], int ai_, int m_, int bj_) const {
;     ...
;     } else if (MODE == E_UKV) {
; #pragma unroll
;       for (int j = 0; j < 8; ++j) v[j] *= q.s;
;       store8bf((bf16_t*)e.out + (size_t)row * NKV + col, v);
	v_pk_mul_f32 v[66:67], v[58:59], v[168:169] op_sel:[0,1]
	v_cvt_pk_bf16_f32 v56, v60, v61
	v_add_co_u32_e32 v60, vcc, s94, v146
	v_cvt_pk_bf16_f32 v57, v62, v63
	v_cvt_pk_bf16_f32 v58, v64, v65
	v_cvt_pk_bf16_f32 v59, v66, v67
	v_addc_co_u32_e32 v61, vcc, 0, v147, vcc
	global_store_dwordx4 v[60:61], v[56:59], off
	v_pk_mul_f32 v[50:51], v[50:51], v[168:169] op_sel:[0,1]
	v_lshl_add_u64 v[68:69], v[146:147], 0, s[4:5]
	v_pk_mul_f32 v[56:57], v[40:41], v[168:169] op_sel:[0,1]
	v_pk_mul_f32 v[58:59], v[42:43], v[168:169] op_sel:[0,1]
	v_cvt_pk_bf16_f32 v40, v48, v49
	v_cvt_pk_bf16_f32 v41, v50, v51
	v_cvt_pk_bf16_f32 v42, v56, v57
	v_cvt_pk_bf16_f32 v43, v58, v59
	global_store_dwordx4 v[68:69], v[40:43], off offset:256
	v_pk_mul_f32 v[44:45], v[44:45], v[144:145] op_sel:[0,1]
	v_pk_mul_f32 v[46:47], v[46:47], v[144:145] op_sel:[0,1]
	v_pk_mul_f32 v[40:41], v[52:53], v[144:145] op_sel:[0,1]
	v_pk_mul_f32 v[42:43], v[54:55], v[144:145] op_sel:[0,1]
	v_cvt_pk_bf16_f32 v40, v40, v41
	v_cvt_pk_bf16_f32 v41, v42, v43
	v_cvt_pk_bf16_f32 v42, v44, v45
	v_add_co_u32_e32 v44, vcc, s95, v146
	v_cvt_pk_bf16_f32 v43, v46, v47
	s_nop 0
	v_addc_co_u32_e32 v45, vcc, 0, v147, vcc
	s_mov_b64 s[4:5], 0x120000
	global_store_dwordx4 v[44:45], v[40:43], off
	v_pk_mul_f32 v[32:33], v[32:33], v[144:145] op_sel:[0,1]
	v_pk_mul_f32 v[34:35], v[34:35], v[144:145] op_sel:[0,1]
	v_pk_mul_f32 v[40:41], v[24:25], v[144:145] op_sel:[0,1]
	v_pk_mul_f32 v[42:43], v[26:27], v[144:145] op_sel:[0,1]
	v_lshl_add_u64 v[48:49], v[146:147], 0, s[4:5]
	v_cvt_pk_bf16_f32 v24, v32, v33
	v_cvt_pk_bf16_f32 v25, v34, v35
	v_cvt_pk_bf16_f32 v26, v40, v41
	v_cvt_pk_bf16_f32 v27, v42, v43
	global_store_dwordx4 v[48:49], v[24:27], off offset:256
	v_pk_mul_f32 v[28:29], v[28:29], v[140:141] op_sel:[0,1]
	v_pk_mul_f32 v[30:31], v[30:31], v[140:141] op_sel:[0,1]
	v_pk_mul_f32 v[24:25], v[36:37], v[140:141] op_sel:[0,1]
	v_pk_mul_f32 v[26:27], v[38:39], v[140:141] op_sel:[0,1]
	v_cvt_pk_bf16_f32 v24, v24, v25
	v_cvt_pk_bf16_f32 v25, v26, v27
	v_cvt_pk_bf16_f32 v26, v28, v29
	v_add_co_u32_e32 v28, vcc, s0, v146
	v_cvt_pk_bf16_f32 v27, v30, v31
	s_nop 0
	v_addc_co_u32_e32 v29, vcc, 0, v147, vcc
	s_mov_b64 s[4:5], 0x140000
	global_store_dwordx4 v[28:29], v[24:27], off
	v_pk_mul_f32 v[16:17], v[16:17], v[140:141] op_sel:[0,1]
	v_pk_mul_f32 v[18:19], v[18:19], v[140:141] op_sel:[0,1]
	v_pk_mul_f32 v[24:25], v[8:9], v[140:141] op_sel:[0,1]
	v_pk_mul_f32 v[26:27], v[10:11], v[140:141] op_sel:[0,1]
	v_lshl_add_u64 v[32:33], v[146:147], 0, s[4:5]
	v_cvt_pk_bf16_f32 v8, v16, v17
	v_cvt_pk_bf16_f32 v9, v18, v19
	v_cvt_pk_bf16_f32 v10, v24, v25
	v_cvt_pk_bf16_f32 v11, v26, v27
	global_store_dwordx4 v[32:33], v[8:11], off offset:256
	v_pk_mul_f32 v[12:13], v[12:13], v[142:143] op_sel:[0,1]
	s_mov_b32 s0, 0x160000
	v_pk_mul_f32 v[8:9], v[20:21], v[142:143] op_sel:[0,1]
	v_pk_mul_f32 v[10:11], v[22:23], v[142:143] op_sel:[0,1]
	v_pk_mul_f32 v[14:15], v[14:15], v[142:143] op_sel:[0,1]
	v_cvt_pk_bf16_f32 v8, v8, v9
	v_cvt_pk_bf16_f32 v9, v10, v11
	v_cvt_pk_bf16_f32 v10, v12, v13
	v_add_co_u32_e32 v12, vcc, s0, v146
	v_cvt_pk_bf16_f32 v11, v14, v15
	s_nop 0
	v_addc_co_u32_e32 v13, vcc, 0, v147, vcc
	s_mov_b64 s[4:5], 0x160000
	global_store_dwordx4 v[12:13], v[8:11], off
	v_pk_mul_f32 v[4:5], v[4:5], v[142:143] op_sel:[0,1]
	v_pk_mul_f32 v[6:7], v[6:7], v[142:143] op_sel:[0,1]
	v_pk_mul_f32 v[8:9], v[0:1], v[142:143] op_sel:[0,1]
	v_pk_mul_f32 v[10:11], v[2:3], v[142:143] op_sel:[0,1]
	v_lshl_add_u64 v[16:17], v[146:147], 0, s[4:5]
	v_cvt_pk_bf16_f32 v0, v4, v5
	v_cvt_pk_bf16_f32 v1, v6, v7
	v_cvt_pk_bf16_f32 v2, v8, v9
	v_cvt_pk_bf16_f32 v3, v10, v11
	global_store_dwordx4 v[16:17], v[0:3], off offset:256
	s_and_b64 vcc, exec, s[2:3]
	s_cbranch_vccz .LBB0_747
	s_waitcnt vmcnt(0)
	s_cmpk_gt_u32 s22, 0xff
	s_cbranch_scc1 .LBB0_760
	s_barrier

; #define PG8_STAGE(bufoff, gbase, voff) do { _Pragma("unroll") for (int _i = 0; _i < 2; ++_i) \
;     __builtin_amdgcn_global_load_lds((const unsigned*)((const char*)(gbase) + (voff)[_i]), (LAS unsigned*)(lds + (bufoff) + ldsw + _i * 8192), 16, 0, 0); } while (0)
; #define PG8_LDA(dst, b, h) do { _Pragma("unroll") for (int m = 0; m < 4; ++m) _Pragma("unroll") for (int k = 0; k < 2; ++k) dst[m][k] = *(const LAS bf16x8*)(lds + PG8_SA(b, h) + aoff + m * 2048 + k * 1024); } while (0)
; #define PG8_LDB(dst, b, h) do { _Pragma("unroll") for (int n = 0; n < 2; ++n) _Pragma("unroll") for (int k = 0; k < 2; ++k) dst[n][k] = *(const LAS bf16x8*)(lds + PG8_SB(b, h) + boff + n * 2048 + k * 1024); } while (0)
; #define PG8_MMA(ai, bj, At, Bt) do { __builtin_amdgcn_s_setprio(1); _Pragma("unroll") for (int m = 0; m < 4; ++m) _Pragma("unroll") for (int n = 0; n < 2; ++n) _Pragma("unroll") for (int k = 0; k < 2; ++k) \
;     acc[ai][bj][m][n] = __builtin_amdgcn_mfma_f32_16x16x32_bf16(Bt[n][k], At[m][k], acc[ai][bj][m][n], 0, 0, 0); __builtin_amdgcn_s_setprio(0); } while (0)
; #define PG8_WAIT_V(n) asm volatile("s_waitcnt vmcnt(" #n ")" ::: "memory")
; #define PG8_WAIT_L(n) asm volatile("s_waitcnt lgkmcnt(" #n ")" ::: "memory")
; #define PG8_BAR __builtin_amdgcn_s_barrier()
; #define PG8_SCHED __builtin_amdgcn_sched_barrier(0)
; template <class Epi>
; __device__ __forceinline__ void gemm_phase(LAS unsigned char* lds, const Gemm g, const StaticOrder& S, const Epi& E, int wv0) {
;     ...
;     for (int t = 0; t < nt; t += 2) {
;       const bool last = (t == nt - 2);
;       const char* a1 = cA + (size_t)(t + 1) * kstep;
;       const char* a2 = last ? nA : cA + (size_t)(t + 2) * kstep; const char* b2 = last ? nB : cB + (size_t)(t + 2) * kstep;
;       const char* a3 = a2 + kstep; const char* b3 = b2 + kstep;
;       PG8_LDB(B0, 0, 0); PG8_SCHED; PG8_LDA(At, 0, 0); PG8_STAGE(PG8_SA(1, 1), a1 + hstepA, voffA);
;       PG8_WAIT_L(8); PG8_BAR; PG8_WAIT_L(0); PG8_MMA(0, 0, At, B0); PG8_BAR; PG8_SCHED;
;       PG8_LDB(B1, 0, 1); PG8_STAGE(PG8_SB(0, 0), b2, voffB);
;       PG8_BAR; PG8_WAIT_L(0); PG8_MMA(0, 1, At, B1); PG8_BAR;
;       PG8_LDA(At, 0, 1); PG8_STAGE(PG8_SA(0, 0), a2, voffA);
;       PG8_BAR; PG8_WAIT_L(0); PG8_MMA(1, 0, At, B0); PG8_BAR; PG8_SCHED;
;       PG8_STAGE(PG8_SB(0, 1), b2 + hstepB, voffB);
;       PG8_WAIT_V(6); PG8_BAR; PG8_MMA(1, 1, At, B1); PG8_BAR;
.Lgprio3:
.LBB0_906:
	s_add_u32 s0, s20, 0xfff80080
	s_addc_u32 s22, s21, -1
	s_add_i32 s50, 0, 0x10000
	v_add_u32_e32 v152, s50, v157
	ds_read_b128 v[140:143], v152
	ds_read_b128 v[144:147], v152 offset:1024
	ds_read_b128 v[148:151], v152 offset:2048
	ds_read_b128 v[152:155], v152 offset:3072
	s_cmp_eq_u32 s49, 28
	s_cselect_b32 s25, s13, s22
	s_cselect_b32 s24, s45, s0
	s_cselect_b32 s23, s11, s48
	s_cselect_b32 s22, s46, s47
	v_lshl_add_u64 v[192:193], s[20:21], 0, v[136:137]
	s_add_i32 m0, s19, 0xc000
	ds_read_b128 v[160:163], v159
	ds_read_b128 v[164:167], v159 offset:1024
	ds_read_b128 v[168:171], v159 offset:2048
	ds_read_b128 v[172:175], v159 offset:3072
	ds_read_b128 v[176:179], v159 offset:4096
	ds_read_b128 v[180:183], v159 offset:5120
	ds_read_b128 v[184:187], v159 offset:6144
	ds_read_b128 v[188:191], v159 offset:7168
	global_load_lds_dwordx4 v[192:193], off
	v_lshl_add_u64 v[192:193], s[20:21], 0, v[138:139]
	s_add_i32 m0, s19, 0xe000
	s_nop 0
	global_load_lds_dwordx4 v[192:193], off
	s_waitcnt lgkmcnt(8)
	s_barrier
	s_waitcnt lgkmcnt(0)
	s_waitcnt lgkmcnt(0)
	v_mfma_f32_16x16x32_bf16 v[126:129], v[140:143], v[160:163], v[126:129]
	v_mfma_f32_16x16x32_bf16 v[122:125], v[148:151], v[160:163], v[122:125]
	v_mfma_f32_16x16x32_bf16 v[110:113], v[140:143], v[168:171], v[110:113]
	v_mfma_f32_16x16x32_bf16 v[106:109], v[148:151], v[168:171], v[106:109]
	v_mfma_f32_16x16x32_bf16 v[92:95], v[140:143], v[176:179], v[92:95]
	v_mfma_f32_16x16x32_bf16 v[88:91], v[148:151], v[176:179], v[88:91]
	v_mfma_f32_16x16x32_bf16 v[76:79], v[140:143], v[184:187], v[76:79]
	v_mfma_f32_16x16x32_bf16 v[72:75], v[148:151], v[184:187], v[72:75]
	v_mfma_f32_16x16x32_bf16 v[126:129], v[144:147], v[164:167], v[126:129]
	v_mfma_f32_16x16x32_bf16 v[122:125], v[152:155], v[164:167], v[122:125]
	v_mfma_f32_16x16x32_bf16 v[110:113], v[144:147], v[172:175], v[110:113]
	v_mfma_f32_16x16x32_bf16 v[106:109], v[152:155], v[172:175], v[106:109]
	v_mfma_f32_16x16x32_bf16 v[92:95], v[144:147], v[180:183], v[92:95]
	v_mfma_f32_16x16x32_bf16 v[88:91], v[152:155], v[180:183], v[88:91]
	v_mfma_f32_16x16x32_bf16 v[76:79], v[144:147], v[188:191], v[76:79]
	v_mfma_f32_16x16x32_bf16 v[72:75], v[152:155], v[188:191], v[72:75]
	s_barrier
	s_add_i32 s0, 0, 0x14000
	s_add_i32 s50, s50, s36
	v_add_u32_e32 v204, s0, v157
	v_lshl_add_u64 v[208:209], s[22:23], 0, v[96:97]
	s_mov_b32 m0, s50
	ds_read_b128 v[192:195], v204
	ds_read_b128 v[196:199], v204 offset:1024
	ds_read_b128 v[200:203], v204 offset:2048
	ds_read_b128 v[204:207], v204 offset:3072
	global_load_lds_dwordx4 v[208:209], off
	v_lshl_add_u64 v[210:211], s[22:23], 0, v[130:131]
	s_add_i32 m0, s50, 0x2000
	s_nop 0
	global_load_lds_dwordx4 v[210:211], off
	s_barrier
	s_waitcnt lgkmcnt(0)
	s_waitcnt lgkmcnt(0)
	v_mfma_f32_16x16x32_bf16 v[118:121], v[192:195], v[160:163], v[118:121]
	v_mfma_f32_16x16x32_bf16 v[114:117], v[200:203], v[160:163], v[114:117]
	v_mfma_f32_16x16x32_bf16 v[102:105], v[192:195], v[168:171], v[102:105]
	v_mfma_f32_16x16x32_bf16 v[98:101], v[200:203], v[168:171], v[98:101]
	v_mfma_f32_16x16x32_bf16 v[84:87], v[192:195], v[176:179], v[84:87]
	v_mfma_f32_16x16x32_bf16 v[80:83], v[200:203], v[176:179], v[80:83]
	v_mfma_f32_16x16x32_bf16 v[68:71], v[192:195], v[184:187], v[68:71]
	v_mfma_f32_16x16x32_bf16 v[64:67], v[200:203], v[184:187], v[64:67]
	v_mfma_f32_16x16x32_bf16 v[118:121], v[196:199], v[164:167], v[118:121]
	v_mfma_f32_16x16x32_bf16 v[114:117], v[204:207], v[164:167], v[114:117]
	v_mfma_f32_16x16x32_bf16 v[102:105], v[196:199], v[172:175], v[102:105]
	v_mfma_f32_16x16x32_bf16 v[98:101], v[204:207], v[172:175], v[98:101]
	v_mfma_f32_16x16x32_bf16 v[84:87], v[196:199], v[180:183], v[84:87]
	v_mfma_f32_16x16x32_bf16 v[80:83], v[204:207], v[180:183], v[80:83]
	v_mfma_f32_16x16x32_bf16 v[68:71], v[196:199], v[188:191], v[68:71]
	v_mfma_f32_16x16x32_bf16 v[64:67], v[204:207], v[188:191], v[64:67]
	s_mov_b32 m0, s19
	v_lshl_add_u64 v[212:213], s[24:25], 0, v[134:135]
	s_barrier
	ds_read_b128 v[160:163], v159 offset:16384
	ds_read_b128 v[164:167], v159 offset:17408
	ds_read_b128 v[168:171], v159 offset:18432
	ds_read_b128 v[172:175], v159 offset:19456
	ds_read_b128 v[176:179], v159 offset:20480
	ds_read_b128 v[180:183], v159 offset:21504
	ds_read_b128 v[184:187], v159 offset:22528
	ds_read_b128 v[188:191], v159 offset:23552
	global_load_lds_dwordx4 v[212:213], off
	v_lshl_add_u64 v[214:215], s[24:25], 0, v[132:133]
	s_mov_b32 m0, s38
	s_nop 0
	global_load_lds_dwordx4 v[214:215], off
	s_barrier
	s_waitcnt lgkmcnt(0)
	s_waitcnt lgkmcnt(0)
	v_mfma_f32_16x16x32_bf16 v[60:63], v[140:143], v[160:163], v[60:63]
	v_mfma_f32_16x16x32_bf16 v[56:59], v[148:151], v[160:163], v[56:59]
	v_mfma_f32_16x16x32_bf16 v[44:47], v[140:143], v[168:171], v[44:47]
	v_mfma_f32_16x16x32_bf16 v[40:43], v[148:151], v[168:171], v[40:43]
	v_mfma_f32_16x16x32_bf16 v[28:31], v[140:143], v[176:179], v[28:31]
	v_mfma_f32_16x16x32_bf16 v[24:27], v[148:151], v[176:179], v[24:27]
	v_mfma_f32_16x16x32_bf16 v[12:15], v[140:143], v[184:187], v[12:15]
	v_mfma_f32_16x16x32_bf16 v[8:11], v[148:151], v[184:187], v[8:11]
	v_mfma_f32_16x16x32_bf16 v[60:63], v[144:147], v[164:167], v[60:63]
	v_mfma_f32_16x16x32_bf16 v[56:59], v[152:155], v[164:167], v[56:59]
	v_mfma_f32_16x16x32_bf16 v[44:47], v[144:147], v[172:175], v[44:47]
	v_mfma_f32_16x16x32_bf16 v[40:43], v[152:155], v[172:175], v[40:43]
	v_mfma_f32_16x16x32_bf16 v[28:31], v[144:147], v[180:183], v[28:31]
	v_mfma_f32_16x16x32_bf16 v[24:27], v[152:155], v[180:183], v[24:27]
	v_mfma_f32_16x16x32_bf16 v[12:15], v[144:147], v[188:191], v[12:15]
	v_mfma_f32_16x16x32_bf16 v[8:11], v[152:155], v[188:191], v[8:11]
	s_barrier
; #define PG8_STAGE(bufoff, gbase, voff) do { _Pragma("unroll") for (int _i = 0; _i < 2; ++_i) \
;     __builtin_amdgcn_global_load_lds((const unsigned*)((const char*)(gbase) + (voff)[_i]), (LAS unsigned*)(lds + (bufoff) + ldsw + _i * 8192), 16, 0, 0); } while (0)
; #define PG8_LDA(dst, b, h) do { _Pragma("unroll") for (int m = 0; m < 4; ++m) _Pragma("unroll") for (int k = 0; k < 2; ++k) dst[m][k] = *(const LAS bf16x8*)(lds + PG8_SA(b, h) + aoff + m * 2048 + k * 1024); } while (0)
; #define PG8_LDB(dst, b, h) do { _Pragma("unroll") for (int n = 0; n < 2; ++n) _Pragma("unroll") for (int k = 0; k < 2; ++k) dst[n][k] = *(const LAS bf16x8*)(lds + PG8_SB(b, h) + boff + n * 2048 + k * 1024); } while (0)
; #define PG8_MMA(ai, bj, At, Bt) do { __builtin_amdgcn_s_setprio(1); _Pragma("unroll") for (int m = 0; m < 4; ++m) _Pragma("unroll") for (int n = 0; n < 2; ++n) _Pragma("unroll") for (int k = 0; k < 2; ++k) \
;     acc[ai][bj][m][n] = __builtin_amdgcn_mfma_f32_16x16x32_bf16(Bt[n][k], At[m][k], acc[ai][bj][m][n], 0, 0, 0); __builtin_amdgcn_s_setprio(0); } while (0)
; #define PG8_WAIT_V(n) asm volatile("s_waitcnt vmcnt(" #n ")" ::: "memory")
; #define PG8_WAIT_L(n) asm volatile("s_waitcnt lgkmcnt(" #n ")" ::: "memory")
; #define PG8_BAR __builtin_amdgcn_s_barrier()
; #define PG8_SCHED __builtin_amdgcn_sched_barrier(0)
; template <class Epi>
; __device__ __forceinline__ void gemm_phase(LAS unsigned char* lds, const Gemm g, const StaticOrder& S, const Epi& E, int wv0) {
;     ...
;       PG8_WAIT_V(6); PG8_BAR; PG8_MMA(1, 1, At, B1); PG8_BAR;
;       PG8_LDB(B0, 1, 0); PG8_SCHED; PG8_LDA(At, 1, 0); PG8_STAGE(PG8_SA(0, 1), a2 + hstepA, voffA);
;       PG8_WAIT_L(8); PG8_BAR; PG8_WAIT_L(0); PG8_MMA(0, 0, At, B0); PG8_BAR; PG8_SCHED;
;       PG8_LDB(B1, 1, 1); PG8_STAGE(PG8_SB(1, 0), b3, voffB);
;       PG8_BAR; PG8_WAIT_L(0); PG8_MMA(0, 1, At, B1); PG8_BAR;
;       PG8_LDA(At, 1, 1); PG8_STAGE(PG8_SA(1, 0), a3, voffA);
;       PG8_BAR; PG8_WAIT_L(0); PG8_MMA(1, 0, At, B0); PG8_BAR; PG8_SCHED;
	s_add_u32 s50, s22, 0x80000
	s_addc_u32 s51, s23, 0
	s_add_i32 s0, s0, s36
	v_lshl_add_u64 v[140:141], s[50:51], 0, v[96:97]
	s_mov_b32 m0, s0
	s_nop 0
	global_load_lds_dwordx4 v[140:141], off
	v_lshl_add_u64 v[140:141], s[50:51], 0, v[130:131]
	s_add_i32 m0, s0, 0x2000
	s_nop 0
	global_load_lds_dwordx4 v[140:141], off
	s_waitcnt vmcnt(6)
	s_barrier
	v_mfma_f32_16x16x32_bf16 v[52:55], v[192:195], v[160:163], v[52:55]
	v_mfma_f32_16x16x32_bf16 v[48:51], v[200:203], v[160:163], v[48:51]
	v_mfma_f32_16x16x32_bf16 v[36:39], v[192:195], v[168:171], v[36:39]
	v_mfma_f32_16x16x32_bf16 v[32:35], v[200:203], v[168:171], v[32:35]
	v_mfma_f32_16x16x32_bf16 v[20:23], v[192:195], v[176:179], v[20:23]
	v_mfma_f32_16x16x32_bf16 v[16:19], v[200:203], v[176:179], v[16:19]
	v_mfma_f32_16x16x32_bf16 v[4:7], v[192:195], v[184:187], v[4:7]
	v_mfma_f32_16x16x32_bf16 v[0:3], v[200:203], v[184:187], v[0:3]
	v_mfma_f32_16x16x32_bf16 v[52:55], v[196:199], v[164:167], v[52:55]
	v_mfma_f32_16x16x32_bf16 v[48:51], v[204:207], v[164:167], v[48:51]
	v_mfma_f32_16x16x32_bf16 v[36:39], v[196:199], v[172:175], v[36:39]
	v_mfma_f32_16x16x32_bf16 v[32:35], v[204:207], v[172:175], v[32:35]
	v_mfma_f32_16x16x32_bf16 v[20:23], v[196:199], v[180:183], v[20:23]
	v_mfma_f32_16x16x32_bf16 v[16:19], v[204:207], v[180:183], v[16:19]
	v_mfma_f32_16x16x32_bf16 v[4:7], v[196:199], v[188:191], v[4:7]
	v_mfma_f32_16x16x32_bf16 v[0:3], v[204:207], v[188:191], v[0:3]
	s_add_i32 s0, 0, 0x18000
	v_add_u32_e32 v152, s0, v157
	s_barrier
	ds_read_b128 v[140:143], v152
	ds_read_b128 v[144:147], v152 offset:1024
	ds_read_b128 v[148:151], v152 offset:2048
	ds_read_b128 v[152:155], v152 offset:3072
	s_add_u32 s24, s24, 0x80000
	s_addc_u32 s25, s25, 0
	s_mov_b32 m0, s39
	v_lshl_add_u64 v[192:193], s[24:25], 0, v[134:135]
	ds_read_b128 v[160:163], v159 offset:32768
	ds_read_b128 v[164:167], v159 offset:33792
	ds_read_b128 v[168:171], v159 offset:34816
	ds_read_b128 v[172:175], v159 offset:35840
	ds_read_b128 v[176:179], v159 offset:36864
	ds_read_b128 v[180:183], v159 offset:37888
	ds_read_b128 v[184:187], v159 offset:38912
	ds_read_b128 v[188:191], v159 offset:39936
	global_load_lds_dwordx4 v[192:193], off
	v_lshl_add_u64 v[192:193], s[24:25], 0, v[132:133]
	s_mov_b32 m0, s40
	s_nop 0
	global_load_lds_dwordx4 v[192:193], off
	s_waitcnt lgkmcnt(8)
	s_barrier
	s_waitcnt lgkmcnt(0)
	s_waitcnt lgkmcnt(0)
	v_mfma_f32_16x16x32_bf16 v[126:129], v[140:143], v[160:163], v[126:129]
	v_mfma_f32_16x16x32_bf16 v[122:125], v[148:151], v[160:163], v[122:125]
	v_mfma_f32_16x16x32_bf16 v[110:113], v[140:143], v[168:171], v[110:113]
	v_mfma_f32_16x16x32_bf16 v[106:109], v[148:151], v[168:171], v[106:109]
	v_mfma_f32_16x16x32_bf16 v[92:95], v[140:143], v[176:179], v[92:95]
	v_mfma_f32_16x16x32_bf16 v[88:91], v[148:151], v[176:179], v[88:91]
	v_mfma_f32_16x16x32_bf16 v[76:79], v[140:143], v[184:187], v[76:79]
	v_mfma_f32_16x16x32_bf16 v[72:75], v[148:151], v[184:187], v[72:75]
	v_mfma_f32_16x16x32_bf16 v[126:129], v[144:147], v[164:167], v[126:129]
	v_mfma_f32_16x16x32_bf16 v[122:125], v[152:155], v[164:167], v[122:125]
	v_mfma_f32_16x16x32_bf16 v[110:113], v[144:147], v[172:175], v[110:113]
	v_mfma_f32_16x16x32_bf16 v[106:109], v[152:155], v[172:175], v[106:109]
	v_mfma_f32_16x16x32_bf16 v[92:95], v[144:147], v[180:183], v[92:95]
	v_mfma_f32_16x16x32_bf16 v[88:91], v[152:155], v[180:183], v[88:91]
	v_mfma_f32_16x16x32_bf16 v[76:79], v[144:147], v[188:191], v[76:79]
	v_mfma_f32_16x16x32_bf16 v[72:75], v[152:155], v[188:191], v[72:75]
	s_barrier
	s_add_i32 s24, 0, 0x1c000
	s_add_i32 s0, s0, s36
	v_add_u32_e32 v204, s24, v157
	v_lshl_add_u64 v[208:209], v[208:209], 0, s[72:73]
	s_mov_b32 m0, s0
	ds_read_b128 v[192:195], v204
	ds_read_b128 v[196:199], v204 offset:1024
	ds_read_b128 v[200:203], v204 offset:2048
	ds_read_b128 v[204:207], v204 offset:3072
	global_load_lds_dwordx4 v[208:209], off
	v_lshl_add_u64 v[208:209], v[210:211], 0, s[72:73]
	s_add_i32 m0, s0, 0x2000
	s_nop 0
	global_load_lds_dwordx4 v[208:209], off
	s_barrier
	s_waitcnt lgkmcnt(0)
	s_waitcnt lgkmcnt(0)
	v_mfma_f32_16x16x32_bf16 v[118:121], v[192:195], v[160:163], v[118:121]
	v_mfma_f32_16x16x32_bf16 v[114:117], v[200:203], v[160:163], v[114:117]
	v_mfma_f32_16x16x32_bf16 v[102:105], v[192:195], v[168:171], v[102:105]
	v_mfma_f32_16x16x32_bf16 v[98:101], v[200:203], v[168:171], v[98:101]
	v_mfma_f32_16x16x32_bf16 v[84:87], v[192:195], v[176:179], v[84:87]
	v_mfma_f32_16x16x32_bf16 v[80:83], v[200:203], v[176:179], v[80:83]
	v_mfma_f32_16x16x32_bf16 v[68:71], v[192:195], v[184:187], v[68:71]
	v_mfma_f32_16x16x32_bf16 v[64:67], v[200:203], v[184:187], v[64:67]
	v_mfma_f32_16x16x32_bf16 v[118:121], v[196:199], v[164:167], v[118:121]
	v_mfma_f32_16x16x32_bf16 v[114:117], v[204:207], v[164:167], v[114:117]
	v_mfma_f32_16x16x32_bf16 v[102:105], v[196:199], v[172:175], v[102:105]
	v_mfma_f32_16x16x32_bf16 v[98:101], v[204:207], v[172:175], v[98:101]
	v_mfma_f32_16x16x32_bf16 v[84:87], v[196:199], v[180:183], v[84:87]
	v_mfma_f32_16x16x32_bf16 v[80:83], v[204:207], v[180:183], v[80:83]
	v_mfma_f32_16x16x32_bf16 v[68:71], v[196:199], v[188:191], v[68:71]
	v_mfma_f32_16x16x32_bf16 v[64:67], v[204:207], v[188:191], v[64:67]
	s_mov_b32 m0, s41
	v_lshl_add_u64 v[208:209], v[212:213], 0, s[72:73]
	s_barrier
	ds_read_b128 v[160:163], v159 offset:49152
	ds_read_b128 v[164:167], v159 offset:50176
	ds_read_b128 v[168:171], v159 offset:51200
	ds_read_b128 v[172:175], v159 offset:52224
	ds_read_b128 v[176:179], v159 offset:53248
	ds_read_b128 v[180:183], v159 offset:54272
	ds_read_b128 v[184:187], v159 offset:55296
	ds_read_b128 v[188:191], v159 offset:56320
	global_load_lds_dwordx4 v[208:209], off
	v_lshl_add_u64 v[208:209], v[214:215], 0, s[72:73]
	s_mov_b32 m0, s42
	s_nop 0
	global_load_lds_dwordx4 v[208:209], off
	s_barrier
; __device__ __forceinline__ float fexp2(float x) { return __builtin_amdgcn_exp2f(x); }
; __device__ __forceinline__ float frcp(float x) { return __builtin_amdgcn_rcpf(x); }
; #define PG8_STAGE(bufoff, gbase, voff) do { _Pragma("unroll") for (int _i = 0; _i < 2; ++_i) \
;     __builtin_amdgcn_global_load_lds((const unsigned*)((const char*)(gbase) + (voff)[_i]), (LAS unsigned*)(lds + (bufoff) + ldsw + _i * 8192), 16, 0, 0); } while (0)
; #define PG8_MMA(ai, bj, At, Bt) do { __builtin_amdgcn_s_setprio(1); _Pragma("unroll") for (int m = 0; m < 4; ++m) _Pragma("unroll") for (int n = 0; n < 2; ++n) _Pragma("unroll") for (int k = 0; k < 2; ++k) \
;     acc[ai][bj][m][n] = __builtin_amdgcn_mfma_f32_16x16x32_bf16(Bt[n][k], At[m][k], acc[ai][bj][m][n], 0, 0, 0); __builtin_amdgcn_s_setprio(0); } while (0)
; #define PG8_WAIT_V(n) asm volatile("s_waitcnt vmcnt(" #n ")" ::: "memory")
; #define PG8_WAIT_L(n) asm volatile("s_waitcnt lgkmcnt(" #n ")" ::: "memory")
; #define PG8_BAR __builtin_amdgcn_s_barrier()
; #define PG8_SCHED __builtin_amdgcn_sched_barrier(0)
; template <class Epi>
; __device__ __forceinline__ void gemm_phase(LAS unsigned char* lds, const Gemm g, const StaticOrder& S, const Epi& E, int wv0) {
;     ...
;       PG8_BAR; PG8_WAIT_L(0); PG8_MMA(1, 0, At, B0); PG8_BAR; PG8_SCHED;
;       PG8_STAGE(PG8_SB(1, 1), b3 + hstepB, voffB);
;       PG8_WAIT_V(6); PG8_BAR; PG8_MMA(1, 1, At, B1); PG8_BAR;
;   __device__ __forceinline__ void emit(const EpiPre& q0, int row, int col, f32x4 a, f32x4 b, const f32x4 (&hb)[2][2], const float (&hs)[2][4], int ai_, int m_, int bj_) const {
;     ...
;     } else if (MODE == E_GATE) {
;       const float bb[8] = {q.a0[0], q.a0[1], q.a0[2], q.a0[3], q.a1[0], q.a1[1], q.a1[2], q.a1[3]};
; #pragma unroll
;       for (int j = 0; j < 8; ++j) v[j] = frcp(1.0f + fexp2(__builtin_fmaf(v[j], -LOG2E, bb[j])));
;       store8bf((bf16_t*)e.out + (size_t)row * NG + col, v);
	s_waitcnt lgkmcnt(0)
	s_waitcnt lgkmcnt(0)
	v_mfma_f32_16x16x32_bf16 v[60:63], v[140:143], v[160:163], v[60:63]
	v_mfma_f32_16x16x32_bf16 v[56:59], v[148:151], v[160:163], v[56:59]
	v_mfma_f32_16x16x32_bf16 v[44:47], v[140:143], v[168:171], v[44:47]
	v_mfma_f32_16x16x32_bf16 v[40:43], v[148:151], v[168:171], v[40:43]
	v_mfma_f32_16x16x32_bf16 v[28:31], v[140:143], v[176:179], v[28:31]
	v_mfma_f32_16x16x32_bf16 v[24:27], v[148:151], v[176:179], v[24:27]
	v_mfma_f32_16x16x32_bf16 v[12:15], v[140:143], v[184:187], v[12:15]
	v_mfma_f32_16x16x32_bf16 v[8:11], v[148:151], v[184:187], v[8:11]
	v_mfma_f32_16x16x32_bf16 v[60:63], v[144:147], v[164:167], v[60:63]
	v_mfma_f32_16x16x32_bf16 v[56:59], v[152:155], v[164:167], v[56:59]
	v_mfma_f32_16x16x32_bf16 v[44:47], v[144:147], v[172:175], v[44:47]
	v_mfma_f32_16x16x32_bf16 v[40:43], v[152:155], v[172:175], v[40:43]
	v_mfma_f32_16x16x32_bf16 v[28:31], v[144:147], v[180:183], v[28:31]
	v_mfma_f32_16x16x32_bf16 v[24:27], v[152:155], v[180:183], v[24:27]
	v_mfma_f32_16x16x32_bf16 v[12:15], v[144:147], v[188:191], v[12:15]
	v_mfma_f32_16x16x32_bf16 v[8:11], v[152:155], v[188:191], v[8:11]
	s_barrier
	s_add_u32 s22, s22, 0x80080
	s_addc_u32 s23, s23, 0
	s_add_i32 s0, s24, s36
	v_lshl_add_u64 v[140:141], s[22:23], 0, v[96:97]
	s_mov_b32 m0, s0
	s_nop 0
	global_load_lds_dwordx4 v[140:141], off
	v_lshl_add_u64 v[140:141], s[22:23], 0, v[130:131]
	s_add_i32 m0, s0, 0x2000
	s_nop 0
	global_load_lds_dwordx4 v[140:141], off
	s_waitcnt vmcnt(6)
	s_barrier
	v_mfma_f32_16x16x32_bf16 v[52:55], v[192:195], v[160:163], v[52:55]
	v_mfma_f32_16x16x32_bf16 v[48:51], v[200:203], v[160:163], v[48:51]
	v_mfma_f32_16x16x32_bf16 v[36:39], v[192:195], v[168:171], v[36:39]
	v_mfma_f32_16x16x32_bf16 v[32:35], v[200:203], v[168:171], v[32:35]
	v_mfma_f32_16x16x32_bf16 v[20:23], v[192:195], v[176:179], v[20:23]
	v_mfma_f32_16x16x32_bf16 v[16:19], v[200:203], v[176:179], v[16:19]
	v_mfma_f32_16x16x32_bf16 v[4:7], v[192:195], v[184:187], v[4:7]
	v_mfma_f32_16x16x32_bf16 v[0:3], v[200:203], v[184:187], v[0:3]
	v_mfma_f32_16x16x32_bf16 v[52:55], v[196:199], v[164:167], v[52:55]
	v_mfma_f32_16x16x32_bf16 v[48:51], v[204:207], v[164:167], v[48:51]
	v_mfma_f32_16x16x32_bf16 v[36:39], v[196:199], v[172:175], v[36:39]
	v_mfma_f32_16x16x32_bf16 v[32:35], v[204:207], v[172:175], v[32:35]
	v_mfma_f32_16x16x32_bf16 v[20:23], v[196:199], v[180:183], v[20:23]
	v_mfma_f32_16x16x32_bf16 v[16:19], v[204:207], v[180:183], v[16:19]
	v_mfma_f32_16x16x32_bf16 v[4:7], v[196:199], v[188:191], v[4:7]
	v_mfma_f32_16x16x32_bf16 v[0:3], v[204:207], v[188:191], v[0:3]
	s_add_i32 s49, s49, 2
	s_add_u32 s20, s20, 0x100
	s_addc_u32 s21, s21, 0
	s_add_u32 s47, s47, 0x100
	s_addc_u32 s48, s48, 0
	s_cmp_gt_u32 s49, 29
	s_barrier
	s_cbranch_scc0 .LBB0_906
	v_lshl_or_b32 v164, s1, 8, v158
	v_ashrrev_i32_e32 v165, 31, v164
	v_lshl_add_u64 v[166:167], v[164:165], 2, s[8:9]
	global_load_dwordx4 v[140:143], v[166:167], off offset:16
	global_load_dwordx4 v[144:147], v[166:167], off
	s_mov_b32 s0, 0xbfb8aa3b
	s_and_b64 vcc, exec, s[2:3]
	s_mov_b64 s[22:23], s[16:17]
	s_mov_b64 s[20:21], s[14:15]
	s_waitcnt vmcnt(0)
	v_pk_mul_f32 v[148:149], v[142:143], s[0:1] op_sel_hi:[1,0]
	v_pk_mul_f32 v[150:151], v[140:141], s[0:1] op_sel_hi:[1,0]
	global_load_dwordx4 v[160:163], v[166:167], off offset:528
	global_load_dwordx4 v[140:143], v[166:167], off offset:512
	v_pk_mul_f32 v[154:155], v[144:145], s[0:1] op_sel_hi:[1,0]
	v_pk_mul_f32 v[152:153], v[146:147], s[0:1] op_sel_hi:[1,0]
	v_fmamk_f32 v126, v126, 0xbfb8aa3b, v154
	v_exp_f32_e32 v126, v126
	v_fmamk_f32 v122, v122, 0xbfb8aa3b, v150
	v_exp_f32_e32 v122, v122
	v_fmamk_f32 v110, v110, 0xbfb8aa3b, v154
	v_add_f32_e32 v126, 1.0, v126
	v_fmamk_f32 v106, v106, 0xbfb8aa3b, v150
	v_add_f32_e32 v122, 1.0, v122
	v_rcp_f32_e32 v166, v122
	v_fmamk_f32 v122, v123, 0xbfb8aa3b, v151
	v_exp_f32_e32 v122, v122
	v_exp_f32_e32 v110, v110
	v_exp_f32_e32 v106, v106
	v_add_f32_e32 v122, 1.0, v122
	v_rcp_f32_e32 v167, v122
	v_fmamk_f32 v122, v124, 0xbfb8aa3b, v148
	v_exp_f32_e32 v122, v122
	v_add_f32_e32 v110, 1.0, v110
	v_add_f32_e32 v106, 1.0, v106
	v_fmamk_f32 v92, v92, 0xbfb8aa3b, v154
	v_add_f32_e32 v122, 1.0, v122
	v_rcp_f32_e32 v168, v122
	v_fmamk_f32 v122, v125, 0xbfb8aa3b, v149
	v_exp_f32_e32 v122, v122
	v_lshlrev_b64 v[124:125], 1, v[164:165]
	v_fmamk_f32 v88, v88, 0xbfb8aa3b, v150
	v_exp_f32_e32 v92, v92
	v_add_f32_e32 v122, 1.0, v122
	v_rcp_f32_e32 v169, v122
	v_mov_b64_e32 v[122:123], s[6:7]
	v_exp_f32_e32 v88, v88
	v_add_f32_e32 v92, 1.0, v92
	v_cvt_pk_bf16_f32 v164, v166, v167
	v_cvt_pk_bf16_f32 v165, v168, v169
	v_add_f32_e32 v88, 1.0, v88
	v_fmamk_f32 v76, v76, 0xbfb8aa3b, v154
	v_fmamk_f32 v72, v72, 0xbfb8aa3b, v150
	v_exp_f32_e32 v76, v76
	v_exp_f32_e32 v72, v72
	v_fmamk_f32 v60, v60, 0xbfb8aa3b, v154
	v_fmamk_f32 v56, v56, 0xbfb8aa3b, v150
	v_add_f32_e32 v76, 1.0, v76
	v_add_f32_e32 v72, 1.0, v72
	v_exp_f32_e32 v60, v60
	v_exp_f32_e32 v56, v56
	v_fmamk_f32 v44, v44, 0xbfb8aa3b, v154
	v_fmamk_f32 v40, v40, 0xbfb8aa3b, v150
	v_add_f32_e32 v60, 1.0, v60
	v_add_f32_e32 v56, 1.0, v56
	v_exp_f32_e32 v44, v44
	v_exp_f32_e32 v40, v40
	v_fmamk_f32 v28, v28, 0xbfb8aa3b, v154
	v_fmamk_f32 v24, v24, 0xbfb8aa3b, v150
	v_add_f32_e32 v44, 1.0, v44
	v_add_f32_e32 v40, 1.0, v40
	v_exp_f32_e32 v28, v28
	v_exp_f32_e32 v24, v24
	v_fmamk_f32 v12, v12, 0xbfb8aa3b, v154
	v_fmamk_f32 v8, v8, 0xbfb8aa3b, v150
	v_add_f32_e32 v28, 1.0, v28
	v_add_f32_e32 v24, 1.0, v24
	v_exp_f32_e32 v12, v12
	v_exp_f32_e32 v8, v8
	v_add_f32_e32 v12, 1.0, v12
	v_add_f32_e32 v8, 1.0, v8
	s_waitcnt vmcnt(0)
; __device__ __forceinline__ float fexp2(float x) { return __builtin_amdgcn_exp2f(x); }
; __device__ __forceinline__ float frcp(float x) { return __builtin_amdgcn_rcpf(x); }
;   __device__ __forceinline__ void emit(const EpiPre& q0, int row, int col, f32x4 a, f32x4 b, const f32x4 (&hb)[2][2], const float (&hs)[2][4], int ai_, int m_, int bj_) const {
;     ...
;     } else if (MODE == E_GATE) {
;       const float bb[8] = {q.a0[0], q.a0[1], q.a0[2], q.a0[3], q.a1[0], q.a1[1], q.a1[2], q.a1[3]};
; #pragma unroll
;       for (int j = 0; j < 8; ++j) v[j] = frcp(1.0f + fexp2(__builtin_fmaf(v[j], -LOG2E, bb[j])));
;       store8bf((bf16_t*)e.out + (size_t)row * NG + col, v);
;   __device__ __forceinline__ void operator()(const f32x4 (&acc)[2][2][4][2], const pg8::Unit& u, int wr, int wc, int fr, int fq) const {
;     ...
;     for (int gi = 0; gi < 4; ++gi) {
;       const int ai = gi >> 1, mp = gi & 1;
;       if (gi + 1 < 4) { const int ai2 = (gi + 1) >> 1, mp2 = (gi + 1) & 1;
; #pragma unroll
;         for (int i = 0; i < 4; ++i) preload(q[(gi + 1) & 1][i], row0 + ai2 * 128 + (2 * mp2 + (i >> 1)) * 16, col0 + (i & 1) * 128); }
;       asm volatile("" ::: "memory");
; #pragma unroll
;       for (int i = 0; i < 4; ++i) { const int m = 2 * mp + (i >> 1), bj = i & 1; emit(q[gi & 1][i], row0 + ai * 128 + m * 16, col0 + bj * 128, acc[ai][bj][m][0], acc[ai][bj][m][1], hb, hs, ai, m, bj); }
;       asm volatile("" ::: "memory");
	v_pk_mul_f32 v[144:145], v[142:143], s[0:1] op_sel_hi:[1,0]
	v_pk_mul_f32 v[142:143], v[160:161], s[0:1] op_sel_hi:[1,0]
	v_rcp_f32_e32 v161, v126
	v_fmamk_f32 v126, v127, 0xbfb8aa3b, v155
	v_exp_f32_e32 v126, v126
	v_pk_mul_f32 v[146:147], v[140:141], s[0:1] op_sel_hi:[1,0]
	v_pk_mul_f32 v[140:141], v[162:163], s[0:1] op_sel_hi:[1,0]
	v_fmamk_f32 v114, v114, 0xbfb8aa3b, v142
	v_add_f32_e32 v126, 1.0, v126
	v_rcp_f32_e32 v162, v126
	v_fmamk_f32 v126, v128, 0xbfb8aa3b, v152
	v_exp_f32_e32 v126, v126
	v_exp_f32_e32 v114, v114
	v_cvt_pk_bf16_f32 v162, v161, v162
	v_fmamk_f32 v118, v118, 0xbfb8aa3b, v146
	v_add_f32_e32 v126, 1.0, v126
	v_rcp_f32_e32 v128, v126
	v_fmamk_f32 v126, v129, 0xbfb8aa3b, v153
	v_exp_f32_e32 v126, v126
	v_add_f32_e32 v114, 1.0, v114
	v_fmamk_f32 v119, v119, 0xbfb8aa3b, v147
	v_fmamk_f32 v120, v120, 0xbfb8aa3b, v144
	v_add_f32_e32 v126, 1.0, v126
	v_rcp_f32_e32 v129, v126
	v_fmamk_f32 v121, v121, 0xbfb8aa3b, v145
	v_exp_f32_e32 v118, v118
	v_exp_f32_e32 v119, v119
	v_cvt_pk_bf16_f32 v163, v128, v129
	v_rcp_f32_e32 v128, v114
	v_fmamk_f32 v114, v115, 0xbfb8aa3b, v143
	v_exp_f32_e32 v114, v114
	v_exp_f32_e32 v120, v120
	v_exp_f32_e32 v121, v121
	v_add_f32_e32 v118, 1.0, v118
	v_add_f32_e32 v114, 1.0, v114
	v_rcp_f32_e32 v129, v114
	v_fmamk_f32 v114, v116, 0xbfb8aa3b, v140
	v_exp_f32_e32 v114, v114
	v_add_f32_e32 v119, 1.0, v119
	v_add_f32_e32 v120, 1.0, v120
	v_add_f32_e32 v121, 1.0, v121
	v_add_f32_e32 v114, 1.0, v114
	v_rcp_f32_e32 v161, v114
	v_fmamk_f32 v114, v117, 0xbfb8aa3b, v141
	v_exp_f32_e32 v114, v114
	v_rcp_f32_e32 v118, v118
	v_rcp_f32_e32 v119, v119
	v_rcp_f32_e32 v120, v120
	v_add_f32_e32 v114, 1.0, v114
	v_rcp_f32_e32 v121, v121
	v_rcp_f32_e32 v117, v114
	v_lshl_add_u32 v160, s18, 8, v156
	v_mad_i64_i32 v[126:127], s[0:1], v160, s33, v[122:123]
	v_lshl_add_u64 v[126:127], v[126:127], 0, v[124:125]
	v_cvt_pk_bf16_f32 v114, v118, v119
	v_cvt_pk_bf16_f32 v115, v120, v121
	v_cvt_pk_bf16_f32 v116, v128, v129
	v_cvt_pk_bf16_f32 v117, v161, v117
	global_store_dwordx4 v[126:127], v[114:117], off offset:256
	v_fmamk_f32 v98, v98, 0xbfb8aa3b, v142
	v_exp_f32_e32 v98, v98
	v_rcp_f32_e32 v115, v110
	v_fmamk_f32 v110, v111, 0xbfb8aa3b, v155
	v_rcp_f32_e32 v117, v106
	v_fmamk_f32 v106, v107, 0xbfb8aa3b, v151
	v_exp_f32_e32 v110, v110
	v_exp_f32_e32 v106, v106
	v_or_b32_e32 v114, 16, v160
	v_add_f32_e32 v98, 1.0, v98
	v_add_f32_e32 v110, 1.0, v110
	v_add_f32_e32 v106, 1.0, v106
	v_rcp_f32_e32 v116, v110
	v_fmamk_f32 v110, v112, 0xbfb8aa3b, v152
	v_rcp_f32_e32 v118, v106
	v_fmamk_f32 v106, v108, 0xbfb8aa3b, v148
	v_exp_f32_e32 v110, v110
	v_exp_f32_e32 v106, v106
	v_cvt_pk_bf16_f32 v108, v117, v118
	v_fmamk_f32 v102, v102, 0xbfb8aa3b, v146
	v_add_f32_e32 v110, 1.0, v110
	v_add_f32_e32 v106, 1.0, v106
	v_rcp_f32_e32 v112, v110
	v_fmamk_f32 v110, v113, 0xbfb8aa3b, v153
	v_rcp_f32_e32 v119, v106
	v_fmamk_f32 v106, v109, 0xbfb8aa3b, v149
	v_exp_f32_e32 v110, v110
	v_exp_f32_e32 v106, v106
	v_fmamk_f32 v103, v103, 0xbfb8aa3b, v147
	v_fmamk_f32 v104, v104, 0xbfb8aa3b, v144
	v_add_f32_e32 v110, 1.0, v110
	v_add_f32_e32 v106, 1.0, v106
	v_rcp_f32_e32 v113, v110
	v_rcp_f32_e32 v109, v106
	v_mad_i64_i32 v[106:107], s[0:1], v114, s33, v[122:123]
	v_lshl_add_u64 v[110:111], v[106:107], 0, v[124:125]
	v_cvt_pk_bf16_f32 v106, v115, v116
	v_cvt_pk_bf16_f32 v107, v112, v113
	v_cvt_pk_bf16_f32 v109, v119, v109
	global_store_dwordx4 v[110:111], v[106:109], off
	v_fmamk_f32 v105, v105, 0xbfb8aa3b, v145
	v_exp_f32_e32 v102, v102
	v_rcp_f32_e32 v106, v98
	v_fmamk_f32 v98, v99, 0xbfb8aa3b, v143
	v_exp_f32_e32 v98, v98
	v_exp_f32_e32 v103, v103
	v_exp_f32_e32 v104, v104
	v_exp_f32_e32 v105, v105
	v_add_f32_e32 v98, 1.0, v98
	v_rcp_f32_e32 v107, v98
	v_fmamk_f32 v98, v100, 0xbfb8aa3b, v140
	v_exp_f32_e32 v98, v98
	v_add_f32_e32 v102, 1.0, v102
	v_add_f32_e32 v103, 1.0, v103
	v_add_f32_e32 v104, 1.0, v104
	v_add_f32_e32 v98, 1.0, v98
	v_rcp_f32_e32 v108, v98
	v_fmamk_f32 v98, v101, 0xbfb8aa3b, v141
	v_exp_f32_e32 v98, v98
	v_add_f32_e32 v105, 1.0, v105
	v_rcp_f32_e32 v102, v102
	v_rcp_f32_e32 v103, v103
	v_add_f32_e32 v98, 1.0, v98
	v_rcp_f32_e32 v104, v104
	v_rcp_f32_e32 v105, v105
	v_rcp_f32_e32 v101, v98
	v_cvt_pk_bf16_f32 v98, v102, v103
	v_cvt_pk_bf16_f32 v100, v106, v107
	v_cvt_pk_bf16_f32 v99, v104, v105
	v_cvt_pk_bf16_f32 v101, v108, v101
	global_store_dwordx4 v[110:111], v[98:101], off offset:256
	v_fmamk_f32 v80, v80, 0xbfb8aa3b, v142
	v_exp_f32_e32 v80, v80
	v_rcp_f32_e32 v99, v92
	v_fmamk_f32 v92, v93, 0xbfb8aa3b, v155
	v_rcp_f32_e32 v101, v88
	v_fmamk_f32 v88, v89, 0xbfb8aa3b, v151
	v_exp_f32_e32 v92, v92
	v_exp_f32_e32 v88, v88
	v_or_b32_e32 v98, 32, v160
	global_store_dwordx4 v[126:127], v[162:165], off
	v_add_f32_e32 v92, 1.0, v92
	v_add_f32_e32 v88, 1.0, v88
	v_rcp_f32_e32 v100, v92
	v_fmamk_f32 v92, v94, 0xbfb8aa3b, v152
	v_rcp_f32_e32 v102, v88
	v_fmamk_f32 v88, v90, 0xbfb8aa3b, v148
	v_exp_f32_e32 v92, v92
	v_exp_f32_e32 v88, v88
	v_cvt_pk_bf16_f32 v90, v101, v102
	v_add_f32_e32 v92, 1.0, v92
	v_add_f32_e32 v88, 1.0, v88
	v_rcp_f32_e32 v94, v92
	v_fmamk_f32 v92, v95, 0xbfb8aa3b, v153
	v_rcp_f32_e32 v103, v88
	v_fmamk_f32 v88, v91, 0xbfb8aa3b, v149
	v_exp_f32_e32 v92, v92
	v_exp_f32_e32 v88, v88
	v_add_f32_e32 v80, 1.0, v80
	v_add_f32_e32 v92, 1.0, v92
	v_add_f32_e32 v88, 1.0, v88
	v_rcp_f32_e32 v95, v92
	v_rcp_f32_e32 v91, v88
	v_mad_i64_i32 v[88:89], s[0:1], v98, s33, v[122:123]
	v_lshl_add_u64 v[92:93], v[88:89], 0, v[124:125]
	v_cvt_pk_bf16_f32 v88, v99, v100
	v_cvt_pk_bf16_f32 v89, v94, v95
	v_cvt_pk_bf16_f32 v91, v103, v91
	global_store_dwordx4 v[92:93], v[88:91], off
	v_fmamk_f32 v84, v84, 0xbfb8aa3b, v146
; __device__ __forceinline__ float fexp2(float x) { return __builtin_amdgcn_exp2f(x); }
; __device__ __forceinline__ float frcp(float x) { return __builtin_amdgcn_rcpf(x); }
;   __device__ __forceinline__ void emit(const EpiPre& q0, int row, int col, f32x4 a, f32x4 b, const f32x4 (&hb)[2][2], const float (&hs)[2][4], int ai_, int m_, int bj_) const {
;     ...
;     } else if (MODE == E_GATE) {
;       const float bb[8] = {q.a0[0], q.a0[1], q.a0[2], q.a0[3], q.a1[0], q.a1[1], q.a1[2], q.a1[3]};
; #pragma unroll
;       for (int j = 0; j < 8; ++j) v[j] = frcp(1.0f + fexp2(__builtin_fmaf(v[j], -LOG2E, bb[j])));
;       store8bf((bf16_t*)e.out + (size_t)row * NG + col, v);
;   __device__ __forceinline__ void operator()(const f32x4 (&acc)[2][2][4][2], const pg8::Unit& u, int wr, int wc, int fr, int fq) const {
;     ...
;     for (int gi = 0; gi < 4; ++gi) {
;       const int ai = gi >> 1, mp = gi & 1;
;       if (gi + 1 < 4) { const int ai2 = (gi + 1) >> 1, mp2 = (gi + 1) & 1;
; #pragma unroll
;         for (int i = 0; i < 4; ++i) preload(q[(gi + 1) & 1][i], row0 + ai2 * 128 + (2 * mp2 + (i >> 1)) * 16, col0 + (i & 1) * 128); }
;       asm volatile("" ::: "memory");
; #pragma unroll
;       for (int i = 0; i < 4; ++i) { const int m = 2 * mp + (i >> 1), bj = i & 1; emit(q[gi & 1][i], row0 + ai * 128 + m * 16, col0 + bj * 128, acc[ai][bj][m][0], acc[ai][bj][m][1], hb, hs, ai, m, bj); }
;       asm volatile("" ::: "memory");
	v_fmamk_f32 v85, v85, 0xbfb8aa3b, v147
	v_rcp_f32_e32 v88, v80
	v_fmamk_f32 v80, v81, 0xbfb8aa3b, v143
	v_exp_f32_e32 v80, v80
	v_fmamk_f32 v86, v86, 0xbfb8aa3b, v144
	v_fmamk_f32 v87, v87, 0xbfb8aa3b, v145
	v_exp_f32_e32 v84, v84
	v_add_f32_e32 v80, 1.0, v80
	v_rcp_f32_e32 v89, v80
	v_fmamk_f32 v80, v82, 0xbfb8aa3b, v140
	v_exp_f32_e32 v80, v80
	v_exp_f32_e32 v85, v85
	v_exp_f32_e32 v86, v86
	v_exp_f32_e32 v87, v87
	v_add_f32_e32 v80, 1.0, v80
	v_rcp_f32_e32 v90, v80
	v_fmamk_f32 v80, v83, 0xbfb8aa3b, v141
	v_exp_f32_e32 v80, v80
	v_add_f32_e32 v84, 1.0, v84
	v_add_f32_e32 v85, 1.0, v85
	v_add_f32_e32 v86, 1.0, v86
	v_add_f32_e32 v87, 1.0, v87
	v_add_f32_e32 v80, 1.0, v80
	v_rcp_f32_e32 v84, v84
	v_rcp_f32_e32 v85, v85
	v_rcp_f32_e32 v86, v86
	v_rcp_f32_e32 v87, v87
	v_rcp_f32_e32 v83, v80
	v_cvt_pk_bf16_f32 v80, v84, v85
	v_cvt_pk_bf16_f32 v82, v88, v89
	v_cvt_pk_bf16_f32 v81, v86, v87
	v_cvt_pk_bf16_f32 v83, v90, v83
	global_store_dwordx4 v[92:93], v[80:83], off offset:256
	v_fmamk_f32 v64, v64, 0xbfb8aa3b, v142
	v_exp_f32_e32 v64, v64
	v_rcp_f32_e32 v81, v76
	v_fmamk_f32 v76, v77, 0xbfb8aa3b, v155
	v_rcp_f32_e32 v83, v72
	v_fmamk_f32 v72, v73, 0xbfb8aa3b, v151
	v_exp_f32_e32 v76, v76
	v_exp_f32_e32 v72, v72
	v_or_b32_e32 v80, 48, v160
	v_add_f32_e32 v64, 1.0, v64
	v_add_f32_e32 v76, 1.0, v76
	v_add_f32_e32 v72, 1.0, v72
	v_rcp_f32_e32 v82, v76
	v_fmamk_f32 v76, v78, 0xbfb8aa3b, v152
	v_rcp_f32_e32 v84, v72
	v_fmamk_f32 v72, v74, 0xbfb8aa3b, v148
	v_exp_f32_e32 v76, v76
	v_exp_f32_e32 v72, v72
	v_cvt_pk_bf16_f32 v74, v83, v84
	v_fmamk_f32 v68, v68, 0xbfb8aa3b, v146
	v_add_f32_e32 v76, 1.0, v76
	v_add_f32_e32 v72, 1.0, v72
	v_rcp_f32_e32 v78, v76
	v_fmamk_f32 v76, v79, 0xbfb8aa3b, v153
	v_rcp_f32_e32 v85, v72
	v_fmamk_f32 v72, v75, 0xbfb8aa3b, v149
	v_exp_f32_e32 v76, v76
	v_exp_f32_e32 v72, v72
	v_fmamk_f32 v69, v69, 0xbfb8aa3b, v147
	v_fmamk_f32 v70, v70, 0xbfb8aa3b, v144
	v_add_f32_e32 v76, 1.0, v76
	v_add_f32_e32 v72, 1.0, v72
	v_rcp_f32_e32 v79, v76
	v_rcp_f32_e32 v75, v72
	v_mad_i64_i32 v[72:73], s[0:1], v80, s33, v[122:123]
	v_lshl_add_u64 v[76:77], v[72:73], 0, v[124:125]
	v_cvt_pk_bf16_f32 v72, v81, v82
	v_cvt_pk_bf16_f32 v73, v78, v79
	v_cvt_pk_bf16_f32 v75, v85, v75
	global_store_dwordx4 v[76:77], v[72:75], off
	v_fmamk_f32 v71, v71, 0xbfb8aa3b, v145
	v_exp_f32_e32 v68, v68
	v_rcp_f32_e32 v72, v64
	v_fmamk_f32 v64, v65, 0xbfb8aa3b, v143
	v_exp_f32_e32 v64, v64
	v_exp_f32_e32 v69, v69
	v_exp_f32_e32 v70, v70
	v_exp_f32_e32 v71, v71
	v_add_f32_e32 v64, 1.0, v64
	v_rcp_f32_e32 v73, v64
	v_fmamk_f32 v64, v66, 0xbfb8aa3b, v140
	v_exp_f32_e32 v64, v64
	v_add_f32_e32 v68, 1.0, v68
	v_add_f32_e32 v69, 1.0, v69
	v_add_f32_e32 v70, 1.0, v70
	v_add_f32_e32 v64, 1.0, v64
	v_rcp_f32_e32 v74, v64
	v_fmamk_f32 v64, v67, 0xbfb8aa3b, v141
	v_exp_f32_e32 v64, v64
	v_add_f32_e32 v71, 1.0, v71
	v_rcp_f32_e32 v68, v68
	v_rcp_f32_e32 v69, v69
	v_add_f32_e32 v64, 1.0, v64
	v_rcp_f32_e32 v70, v70
	v_rcp_f32_e32 v71, v71
	v_rcp_f32_e32 v67, v64
	v_cvt_pk_bf16_f32 v64, v68, v69
	v_cvt_pk_bf16_f32 v66, v72, v73
	v_cvt_pk_bf16_f32 v65, v70, v71
	v_cvt_pk_bf16_f32 v67, v74, v67
	global_store_dwordx4 v[76:77], v[64:67], off offset:256
	v_fmamk_f32 v48, v48, 0xbfb8aa3b, v142
	v_exp_f32_e32 v48, v48
	v_rcp_f32_e32 v65, v60
	v_fmamk_f32 v60, v61, 0xbfb8aa3b, v155
	v_rcp_f32_e32 v67, v56
	v_fmamk_f32 v56, v57, 0xbfb8aa3b, v151
	v_exp_f32_e32 v60, v60
	v_exp_f32_e32 v56, v56
	v_add_u32_e32 v64, 0x80, v160
	v_add_f32_e32 v60, 1.0, v60
	v_add_f32_e32 v56, 1.0, v56
	v_rcp_f32_e32 v66, v60
	v_fmamk_f32 v60, v62, 0xbfb8aa3b, v152
	v_rcp_f32_e32 v68, v56
	v_fmamk_f32 v56, v58, 0xbfb8aa3b, v148
	v_exp_f32_e32 v60, v60
	v_exp_f32_e32 v56, v56
	v_cvt_pk_bf16_f32 v58, v67, v68
	v_add_f32_e32 v48, 1.0, v48
	v_add_f32_e32 v60, 1.0, v60
	v_add_f32_e32 v56, 1.0, v56
	v_rcp_f32_e32 v62, v60
	v_fmamk_f32 v60, v63, 0xbfb8aa3b, v153
	v_rcp_f32_e32 v69, v56
	v_fmamk_f32 v56, v59, 0xbfb8aa3b, v149
	v_exp_f32_e32 v60, v60
	v_exp_f32_e32 v56, v56
	v_fmamk_f32 v52, v52, 0xbfb8aa3b, v146
	v_add_f32_e32 v60, 1.0, v60
	v_add_f32_e32 v56, 1.0, v56
	v_rcp_f32_e32 v63, v60
	v_rcp_f32_e32 v59, v56
	v_mad_i64_i32 v[56:57], s[0:1], v64, s33, v[122:123]
	v_lshl_add_u64 v[60:61], v[56:57], 0, v[124:125]
	v_cvt_pk_bf16_f32 v56, v65, v66
	v_cvt_pk_bf16_f32 v57, v62, v63
	v_cvt_pk_bf16_f32 v59, v69, v59
	global_store_dwordx4 v[60:61], v[56:59], off
	v_fmamk_f32 v53, v53, 0xbfb8aa3b, v147
	v_fmamk_f32 v54, v54, 0xbfb8aa3b, v144
	v_rcp_f32_e32 v56, v48
	v_fmamk_f32 v48, v49, 0xbfb8aa3b, v143
	v_exp_f32_e32 v48, v48
	v_fmamk_f32 v55, v55, 0xbfb8aa3b, v145
	v_exp_f32_e32 v52, v52
	v_exp_f32_e32 v53, v53
	v_add_f32_e32 v48, 1.0, v48
	v_rcp_f32_e32 v57, v48
	v_fmamk_f32 v48, v50, 0xbfb8aa3b, v140
	v_exp_f32_e32 v48, v48
	v_exp_f32_e32 v54, v54
	v_exp_f32_e32 v55, v55
	v_add_f32_e32 v52, 1.0, v52
	v_add_f32_e32 v48, 1.0, v48
	v_rcp_f32_e32 v58, v48
	v_fmamk_f32 v48, v51, 0xbfb8aa3b, v141
	v_exp_f32_e32 v48, v48
	v_add_f32_e32 v53, 1.0, v53
	v_add_f32_e32 v54, 1.0, v54
	v_add_f32_e32 v55, 1.0, v55
	v_add_f32_e32 v48, 1.0, v48
	v_rcp_f32_e32 v52, v52
	v_rcp_f32_e32 v53, v53
	v_rcp_f32_e32 v54, v54
	v_rcp_f32_e32 v55, v55
	v_rcp_f32_e32 v51, v48
	v_cvt_pk_bf16_f32 v48, v52, v53
	v_cvt_pk_bf16_f32 v50, v56, v57
	v_cvt_pk_bf16_f32 v49, v54, v55
	v_cvt_pk_bf16_f32 v51, v58, v51
	global_store_dwordx4 v[60:61], v[48:51], off offset:256
	v_fmamk_f32 v32, v32, 0xbfb8aa3b, v142
	v_exp_f32_e32 v32, v32
	v_rcp_f32_e32 v49, v44
	v_fmamk_f32 v44, v45, 0xbfb8aa3b, v155
	v_rcp_f32_e32 v51, v40
	v_fmamk_f32 v40, v41, 0xbfb8aa3b, v151
	v_exp_f32_e32 v44, v44
	v_exp_f32_e32 v40, v40
	v_add_u32_e32 v48, 0x90, v160
; __device__ __forceinline__ float fexp2(float x) { return __builtin_amdgcn_exp2f(x); }
; __device__ __forceinline__ float frcp(float x) { return __builtin_amdgcn_rcpf(x); }
; #define PG8_WAIT_V(n) asm volatile("s_waitcnt vmcnt(" #n ")" ::: "memory")
; #define PG8_BAR __builtin_amdgcn_s_barrier()
; template <class Epi>
; __device__ __forceinline__ void gemm_phase(LAS unsigned char* lds, const Gemm g, const StaticOrder& S, const Epi& E, int wv0) {
;     ...
;     if (!has_next) break;
; #pragma unroll
;     for (int a = 0; a < 2; ++a)
; #pragma unroll
;       for (int b = 0; b < 2; ++b)
; #pragma unroll
;         for (int m = 0; m < 4; ++m)
; #pragma unroll
;           for (int n = 0; n < 2; ++n) acc[a][b][m][n] = (f32x4){0.f, 0.f, 0.f, 0.f};
;     cur = nxt; cA = nA; cB = nB; ++ui;
;   }
;   PG8_WAIT_V(0);
;   if (wr == 0) PG8_BAR;
;   PG8_BAR;
;   __device__ __forceinline__ void emit(const EpiPre& q0, int row, int col, f32x4 a, f32x4 b, const f32x4 (&hb)[2][2], const float (&hs)[2][4], int ai_, int m_, int bj_) const {
;     ...
;     } else if (MODE == E_GATE) {
;       const float bb[8] = {q.a0[0], q.a0[1], q.a0[2], q.a0[3], q.a1[0], q.a1[1], q.a1[2], q.a1[3]};
; #pragma unroll
;       for (int j = 0; j < 8; ++j) v[j] = frcp(1.0f + fexp2(__builtin_fmaf(v[j], -LOG2E, bb[j])));
;       store8bf((bf16_t*)e.out + (size_t)row * NG + col, v);
	v_add_f32_e32 v32, 1.0, v32
	v_add_f32_e32 v44, 1.0, v44
	v_add_f32_e32 v40, 1.0, v40
	v_rcp_f32_e32 v50, v44
	v_fmamk_f32 v44, v46, 0xbfb8aa3b, v152
	v_rcp_f32_e32 v52, v40
	v_fmamk_f32 v40, v42, 0xbfb8aa3b, v148
	v_exp_f32_e32 v44, v44
	v_exp_f32_e32 v40, v40
	v_cvt_pk_bf16_f32 v42, v51, v52
	v_fmamk_f32 v36, v36, 0xbfb8aa3b, v146
	v_add_f32_e32 v44, 1.0, v44
	v_add_f32_e32 v40, 1.0, v40
	v_rcp_f32_e32 v46, v44
	v_fmamk_f32 v44, v47, 0xbfb8aa3b, v153
	v_rcp_f32_e32 v53, v40
	v_fmamk_f32 v40, v43, 0xbfb8aa3b, v149
	v_exp_f32_e32 v44, v44
	v_exp_f32_e32 v40, v40
	v_fmamk_f32 v37, v37, 0xbfb8aa3b, v147
	v_fmamk_f32 v38, v38, 0xbfb8aa3b, v144
	v_add_f32_e32 v44, 1.0, v44
	v_add_f32_e32 v40, 1.0, v40
	v_rcp_f32_e32 v47, v44
	v_rcp_f32_e32 v43, v40
	v_mad_i64_i32 v[40:41], s[0:1], v48, s33, v[122:123]
	v_lshl_add_u64 v[44:45], v[40:41], 0, v[124:125]
	v_cvt_pk_bf16_f32 v40, v49, v50
	v_cvt_pk_bf16_f32 v41, v46, v47
	v_cvt_pk_bf16_f32 v43, v53, v43
	global_store_dwordx4 v[44:45], v[40:43], off
	v_fmamk_f32 v39, v39, 0xbfb8aa3b, v145
	v_exp_f32_e32 v36, v36
	v_rcp_f32_e32 v40, v32
	v_fmamk_f32 v32, v33, 0xbfb8aa3b, v143
	v_exp_f32_e32 v32, v32
	v_exp_f32_e32 v37, v37
	v_exp_f32_e32 v38, v38
	v_exp_f32_e32 v39, v39
	v_add_f32_e32 v32, 1.0, v32
	v_rcp_f32_e32 v41, v32
	v_fmamk_f32 v32, v34, 0xbfb8aa3b, v140
	v_exp_f32_e32 v32, v32
	v_add_f32_e32 v36, 1.0, v36
	v_add_f32_e32 v37, 1.0, v37
	v_add_f32_e32 v38, 1.0, v38
	v_add_f32_e32 v32, 1.0, v32
	v_rcp_f32_e32 v42, v32
	v_fmamk_f32 v32, v35, 0xbfb8aa3b, v141
	v_exp_f32_e32 v32, v32
	v_add_f32_e32 v39, 1.0, v39
	v_rcp_f32_e32 v36, v36
	v_rcp_f32_e32 v37, v37
	v_add_f32_e32 v32, 1.0, v32
	v_rcp_f32_e32 v38, v38
	v_rcp_f32_e32 v39, v39
	v_rcp_f32_e32 v35, v32
	v_cvt_pk_bf16_f32 v32, v36, v37
	v_cvt_pk_bf16_f32 v34, v40, v41
	v_cvt_pk_bf16_f32 v33, v38, v39
	v_cvt_pk_bf16_f32 v35, v42, v35
	global_store_dwordx4 v[44:45], v[32:35], off offset:256
	v_fmamk_f32 v16, v16, 0xbfb8aa3b, v142
	v_exp_f32_e32 v16, v16
	v_rcp_f32_e32 v33, v28
	v_fmamk_f32 v28, v29, 0xbfb8aa3b, v155
	v_rcp_f32_e32 v35, v24
	v_fmamk_f32 v24, v25, 0xbfb8aa3b, v151
	v_exp_f32_e32 v28, v28
	v_exp_f32_e32 v24, v24
	v_add_u32_e32 v32, 0xa0, v160
	v_add_f32_e32 v28, 1.0, v28
	v_add_f32_e32 v24, 1.0, v24
	v_rcp_f32_e32 v34, v28
	v_fmamk_f32 v28, v30, 0xbfb8aa3b, v152
	v_rcp_f32_e32 v36, v24
	v_fmamk_f32 v24, v26, 0xbfb8aa3b, v148
	v_exp_f32_e32 v28, v28
	v_exp_f32_e32 v24, v24
	v_cvt_pk_bf16_f32 v26, v35, v36
	v_add_f32_e32 v16, 1.0, v16
	v_add_f32_e32 v28, 1.0, v28
	v_add_f32_e32 v24, 1.0, v24
	v_rcp_f32_e32 v30, v28
	v_fmamk_f32 v28, v31, 0xbfb8aa3b, v153
	v_rcp_f32_e32 v37, v24
	v_fmamk_f32 v24, v27, 0xbfb8aa3b, v149
	v_exp_f32_e32 v28, v28
	v_exp_f32_e32 v24, v24
	v_fmamk_f32 v20, v20, 0xbfb8aa3b, v146
	v_add_f32_e32 v28, 1.0, v28
	v_add_f32_e32 v24, 1.0, v24
	v_rcp_f32_e32 v31, v28
	v_rcp_f32_e32 v27, v24
	v_mad_i64_i32 v[24:25], s[0:1], v32, s33, v[122:123]
	v_lshl_add_u64 v[28:29], v[24:25], 0, v[124:125]
	v_cvt_pk_bf16_f32 v24, v33, v34
	v_cvt_pk_bf16_f32 v25, v30, v31
	v_cvt_pk_bf16_f32 v27, v37, v27
	global_store_dwordx4 v[28:29], v[24:27], off
	v_fmamk_f32 v21, v21, 0xbfb8aa3b, v147
	v_fmamk_f32 v22, v22, 0xbfb8aa3b, v144
	v_rcp_f32_e32 v24, v16
	v_fmamk_f32 v16, v17, 0xbfb8aa3b, v143
	v_exp_f32_e32 v16, v16
	v_fmamk_f32 v23, v23, 0xbfb8aa3b, v145
	v_exp_f32_e32 v20, v20
	v_exp_f32_e32 v21, v21
	v_add_f32_e32 v16, 1.0, v16
	v_rcp_f32_e32 v25, v16
	v_fmamk_f32 v16, v18, 0xbfb8aa3b, v140
	v_exp_f32_e32 v16, v16
	v_exp_f32_e32 v22, v22
	v_exp_f32_e32 v23, v23
	v_add_f32_e32 v20, 1.0, v20
	v_add_f32_e32 v16, 1.0, v16
	v_rcp_f32_e32 v26, v16
	v_fmamk_f32 v16, v19, 0xbfb8aa3b, v141
	v_exp_f32_e32 v16, v16
	v_add_f32_e32 v21, 1.0, v21
	v_add_f32_e32 v22, 1.0, v22
	v_add_f32_e32 v23, 1.0, v23
	v_add_f32_e32 v16, 1.0, v16
	v_rcp_f32_e32 v20, v20
	v_rcp_f32_e32 v21, v21
	v_rcp_f32_e32 v22, v22
	v_rcp_f32_e32 v23, v23
	v_rcp_f32_e32 v19, v16
	v_cvt_pk_bf16_f32 v16, v20, v21
	v_cvt_pk_bf16_f32 v18, v24, v25
	v_cvt_pk_bf16_f32 v17, v22, v23
	v_cvt_pk_bf16_f32 v19, v26, v19
	v_fmac_f32_e32 v155, 0xbfb8aa3b, v13
	v_fmac_f32_e32 v151, 0xbfb8aa3b, v9
	global_store_dwordx4 v[28:29], v[16:19], off offset:256
	v_fmac_f32_e32 v153, 0xbfb8aa3b, v15
	v_fmac_f32_e32 v149, 0xbfb8aa3b, v11
	v_rcp_f32_e32 v17, v12
	v_exp_f32_e32 v12, v155
	v_rcp_f32_e32 v19, v8
	v_exp_f32_e32 v8, v151
	v_fmamk_f32 v0, v0, 0xbfb8aa3b, v142
	v_add_f32_e32 v12, 1.0, v12
	v_rcp_f32_e32 v18, v12
	v_add_f32_e32 v8, 1.0, v8
	v_fmamk_f32 v12, v14, 0xbfb8aa3b, v152
	v_rcp_f32_e32 v20, v8
	v_fmamk_f32 v8, v10, 0xbfb8aa3b, v148
	v_exp_f32_e32 v12, v12
	v_exp_f32_e32 v8, v8
	v_exp_f32_e32 v0, v0
	v_add_u32_e32 v16, 0xb0, v160
	v_add_f32_e32 v12, 1.0, v12
	v_add_f32_e32 v8, 1.0, v8
	v_rcp_f32_e32 v14, v12
	v_exp_f32_e32 v12, v153
	v_rcp_f32_e32 v21, v8
	v_exp_f32_e32 v8, v149
	v_cvt_pk_bf16_f32 v10, v19, v20
	v_add_f32_e32 v12, 1.0, v12
	v_rcp_f32_e32 v15, v12
	v_add_f32_e32 v8, 1.0, v8
	v_rcp_f32_e32 v11, v8
	v_mad_i64_i32 v[8:9], s[0:1], v16, s33, v[122:123]
	v_lshl_add_u64 v[12:13], v[8:9], 0, v[124:125]
	v_cvt_pk_bf16_f32 v8, v17, v18
	v_cvt_pk_bf16_f32 v9, v14, v15
	v_cvt_pk_bf16_f32 v11, v21, v11
	v_add_f32_e32 v0, 1.0, v0
	v_fmac_f32_e32 v143, 0xbfb8aa3b, v1
	global_store_dwordx4 v[12:13], v[8:11], off
	v_fmamk_f32 v4, v4, 0xbfb8aa3b, v146
	v_fmac_f32_e32 v147, 0xbfb8aa3b, v5
	v_rcp_f32_e32 v8, v0
	v_exp_f32_e32 v0, v143
	v_fmamk_f32 v6, v6, 0xbfb8aa3b, v144
	v_fmac_f32_e32 v145, 0xbfb8aa3b, v7
	v_fmac_f32_e32 v141, 0xbfb8aa3b, v3
	v_add_f32_e32 v0, 1.0, v0
	v_rcp_f32_e32 v9, v0
	v_fmamk_f32 v0, v2, 0xbfb8aa3b, v140
	v_exp_f32_e32 v0, v0
	v_exp_f32_e32 v4, v4
	v_exp_f32_e32 v5, v147
	v_exp_f32_e32 v6, v6
	v_add_f32_e32 v0, 1.0, v0
	v_exp_f32_e32 v7, v145
	v_rcp_f32_e32 v10, v0
	v_exp_f32_e32 v0, v141
	v_add_f32_e32 v4, 1.0, v4
	v_add_f32_e32 v5, 1.0, v5
	v_add_f32_e32 v6, 1.0, v6
	v_add_f32_e32 v7, 1.0, v7
	v_add_f32_e32 v0, 1.0, v0
	v_rcp_f32_e32 v4, v4
	v_rcp_f32_e32 v5, v5
	v_rcp_f32_e32 v6, v6
	v_rcp_f32_e32 v7, v7
	v_rcp_f32_e32 v3, v0
	v_cvt_pk_bf16_f32 v0, v4, v5
	v_cvt_pk_bf16_f32 v2, v8, v9
	v_cvt_pk_bf16_f32 v1, v6, v7
	v_cvt_pk_bf16_f32 v3, v10, v3
	global_store_dwordx4 v[12:13], v[0:3], off offset:256
	s_mov_b32 s1, s10
	s_mov_b32 s18, s12
	s_cbranch_vccz .LBB0_903
	s_waitcnt vmcnt(0)
	s_cmpk_gt_u32 s29, 0xff
	s_cbranch_scc1 .LBB0_910
	s_barrier

; #define PG8_STAGE(bufoff, gbase, voff) do { _Pragma("unroll") for (int _i = 0; _i < 2; ++_i) \
;     __builtin_amdgcn_global_load_lds((const unsigned*)((const char*)(gbase) + (voff)[_i]), (LAS unsigned*)(lds + (bufoff) + ldsw + _i * 8192), 16, 0, 0); } while (0)
; #define PG8_LDA(dst, b, h) do { _Pragma("unroll") for (int m = 0; m < 4; ++m) _Pragma("unroll") for (int k = 0; k < 2; ++k) dst[m][k] = *(const LAS bf16x8*)(lds + PG8_SA(b, h) + aoff + m * 2048 + k * 1024); } while (0)
; #define PG8_LDB(dst, b, h) do { _Pragma("unroll") for (int n = 0; n < 2; ++n) _Pragma("unroll") for (int k = 0; k < 2; ++k) dst[n][k] = *(const LAS bf16x8*)(lds + PG8_SB(b, h) + boff + n * 2048 + k * 1024); } while (0)
; #define PG8_MMA(ai, bj, At, Bt) do { __builtin_amdgcn_s_setprio(1); _Pragma("unroll") for (int m = 0; m < 4; ++m) _Pragma("unroll") for (int n = 0; n < 2; ++n) _Pragma("unroll") for (int k = 0; k < 2; ++k) \
;     acc[ai][bj][m][n] = __builtin_amdgcn_mfma_f32_16x16x32_bf16(Bt[n][k], At[m][k], acc[ai][bj][m][n], 0, 0, 0); __builtin_amdgcn_s_setprio(0); } while (0)
; #define PG8_WAIT_V(n) asm volatile("s_waitcnt vmcnt(" #n ")" ::: "memory")
; #define PG8_WAIT_L(n) asm volatile("s_waitcnt lgkmcnt(" #n ")" ::: "memory")
; #define PG8_BAR __builtin_amdgcn_s_barrier()
; #define PG8_SCHED __builtin_amdgcn_sched_barrier(0)
; template <class Epi>
; __device__ __forceinline__ void gemm_phase(LAS unsigned char* lds, const Gemm g, const StaticOrder& S, const Epi& E, int wv0) {
;     ...
;       PG8_LDB(B0, 0, 0); PG8_SCHED; PG8_LDA(At, 0, 0); PG8_STAGE(PG8_SA(1, 1), a1 + hstepA, voffA);
;       PG8_WAIT_L(8); PG8_BAR; PG8_WAIT_L(0); PG8_MMA(0, 0, At, B0); PG8_BAR; PG8_SCHED;
;       PG8_LDB(B1, 0, 1); PG8_STAGE(PG8_SB(0, 0), b2, voffB);
;       PG8_BAR; PG8_WAIT_L(0); PG8_MMA(0, 1, At, B1); PG8_BAR;
;       PG8_LDA(At, 0, 1); PG8_STAGE(PG8_SA(0, 0), a2, voffA);
;       PG8_BAR; PG8_WAIT_L(0); PG8_MMA(1, 0, At, B0); PG8_BAR; PG8_SCHED;
;       PG8_STAGE(PG8_SB(0, 1), b2 + hstepB, voffB);
;       PG8_WAIT_V(6); PG8_BAR; PG8_MMA(1, 1, At, B1); PG8_BAR;
.Lgprio4:
.LBB0_981:
	s_add_u32 s4, s18, 0x100
	s_addc_u32 s5, s19, 0
	s_add_i32 s0, 0, 0x10000
	v_add_u32_e32 v142, s0, v173
	ds_read_b128 v[130:133], v142
	ds_read_b128 v[134:137], v142 offset:1024
	ds_read_b128 v[138:141], v142 offset:2048
	ds_read_b128 v[142:145], v142 offset:3072
	s_cmp_eq_u32 s49, 12
	s_cselect_b32 s23, s15, s5
	s_cselect_b32 s22, s14, s4
	s_cselect_b32 s21, s13, s48
	s_cselect_b32 s20, s46, s47
	v_lshl_add_u64 v[192:193], s[18:19], 0, v[156:157]
	s_add_i32 m0, s36, 0xc000
	ds_read_b128 v[146:149], v175
	ds_read_b128 v[160:163], v175 offset:1024
	ds_read_b128 v[164:167], v175 offset:2048
	ds_read_b128 v[168:171], v175 offset:3072
	ds_read_b128 v[176:179], v175 offset:4096
	ds_read_b128 v[180:183], v175 offset:5120
	ds_read_b128 v[184:187], v175 offset:6144
	ds_read_b128 v[188:191], v175 offset:7168
	global_load_lds_dwordx4 v[192:193], off
	v_lshl_add_u64 v[192:193], s[18:19], 0, v[158:159]
	s_add_i32 m0, s36, 0xe000
	s_nop 0
	global_load_lds_dwordx4 v[192:193], off
	s_waitcnt lgkmcnt(8)
	s_barrier
	s_waitcnt lgkmcnt(0)
	s_waitcnt lgkmcnt(0)
	v_mfma_f32_16x16x32_bf16 v[126:129], v[130:133], v[146:149], v[126:129]
	v_mfma_f32_16x16x32_bf16 v[122:125], v[138:141], v[146:149], v[122:125]
	v_mfma_f32_16x16x32_bf16 v[118:121], v[130:133], v[164:167], v[118:121]
	v_mfma_f32_16x16x32_bf16 v[110:113], v[138:141], v[164:167], v[110:113]
	v_mfma_f32_16x16x32_bf16 v[92:95], v[130:133], v[176:179], v[92:95]
	v_mfma_f32_16x16x32_bf16 v[88:91], v[138:141], v[176:179], v[88:91]
	v_mfma_f32_16x16x32_bf16 v[80:83], v[130:133], v[184:187], v[80:83]
	v_mfma_f32_16x16x32_bf16 v[72:75], v[138:141], v[184:187], v[72:75]
	v_mfma_f32_16x16x32_bf16 v[126:129], v[134:137], v[160:163], v[126:129]
	v_mfma_f32_16x16x32_bf16 v[122:125], v[142:145], v[160:163], v[122:125]
	v_mfma_f32_16x16x32_bf16 v[118:121], v[134:137], v[168:171], v[118:121]
	v_mfma_f32_16x16x32_bf16 v[110:113], v[142:145], v[168:171], v[110:113]
	v_mfma_f32_16x16x32_bf16 v[92:95], v[134:137], v[180:183], v[92:95]
	v_mfma_f32_16x16x32_bf16 v[88:91], v[142:145], v[180:183], v[88:91]
	v_mfma_f32_16x16x32_bf16 v[80:83], v[134:137], v[188:191], v[80:83]
	v_mfma_f32_16x16x32_bf16 v[72:75], v[142:145], v[188:191], v[72:75]
	s_barrier
	s_add_i32 s50, 0, 0x14000
	s_add_i32 s0, s0, s35
	v_add_u32_e32 v204, s50, v173
	v_lshl_add_u64 v[208:209], s[20:21], 0, v[96:97]
	s_mov_b32 m0, s0
	ds_read_b128 v[192:195], v204
	ds_read_b128 v[196:199], v204 offset:1024
	ds_read_b128 v[200:203], v204 offset:2048
	ds_read_b128 v[204:207], v204 offset:3072
	global_load_lds_dwordx4 v[208:209], off
	v_lshl_add_u64 v[210:211], s[20:21], 0, v[154:155]
	s_add_i32 m0, s0, 0x2000
	s_nop 0
	global_load_lds_dwordx4 v[210:211], off
	s_barrier
	s_waitcnt lgkmcnt(0)
	s_waitcnt lgkmcnt(0)
	v_mfma_f32_16x16x32_bf16 v[114:117], v[192:195], v[146:149], v[114:117]
	v_mfma_f32_16x16x32_bf16 v[106:109], v[200:203], v[146:149], v[106:109]
	v_mfma_f32_16x16x32_bf16 v[102:105], v[192:195], v[164:167], v[102:105]
	v_mfma_f32_16x16x32_bf16 v[98:101], v[200:203], v[164:167], v[98:101]
	v_mfma_f32_16x16x32_bf16 v[84:87], v[192:195], v[176:179], v[84:87]
	v_mfma_f32_16x16x32_bf16 v[76:79], v[200:203], v[176:179], v[76:79]
	v_mfma_f32_16x16x32_bf16 v[68:71], v[192:195], v[184:187], v[68:71]
	v_mfma_f32_16x16x32_bf16 v[64:67], v[200:203], v[184:187], v[64:67]
	v_mfma_f32_16x16x32_bf16 v[114:117], v[196:199], v[160:163], v[114:117]
	v_mfma_f32_16x16x32_bf16 v[106:109], v[204:207], v[160:163], v[106:109]
	v_mfma_f32_16x16x32_bf16 v[102:105], v[196:199], v[168:171], v[102:105]
	v_mfma_f32_16x16x32_bf16 v[98:101], v[204:207], v[168:171], v[98:101]
	v_mfma_f32_16x16x32_bf16 v[84:87], v[196:199], v[180:183], v[84:87]
	v_mfma_f32_16x16x32_bf16 v[76:79], v[204:207], v[180:183], v[76:79]
	v_mfma_f32_16x16x32_bf16 v[68:71], v[196:199], v[188:191], v[68:71]
	v_mfma_f32_16x16x32_bf16 v[64:67], v[204:207], v[188:191], v[64:67]
	s_mov_b32 m0, s36
	v_lshl_add_u64 v[212:213], s[22:23], 0, v[150:151]
	s_barrier
	ds_read_b128 v[146:149], v175 offset:16384
	ds_read_b128 v[160:163], v175 offset:17408
	ds_read_b128 v[164:167], v175 offset:18432
	ds_read_b128 v[168:171], v175 offset:19456
	ds_read_b128 v[176:179], v175 offset:20480
	ds_read_b128 v[180:183], v175 offset:21504
	ds_read_b128 v[184:187], v175 offset:22528
	ds_read_b128 v[188:191], v175 offset:23552
	global_load_lds_dwordx4 v[212:213], off
	v_lshl_add_u64 v[214:215], s[22:23], 0, v[152:153]
	s_mov_b32 m0, s37
	s_nop 0
	global_load_lds_dwordx4 v[214:215], off
	s_barrier
	s_waitcnt lgkmcnt(0)
	s_waitcnt lgkmcnt(0)
	v_mfma_f32_16x16x32_bf16 v[60:63], v[130:133], v[146:149], v[60:63]
	v_mfma_f32_16x16x32_bf16 v[56:59], v[138:141], v[146:149], v[56:59]
	v_mfma_f32_16x16x32_bf16 v[48:51], v[130:133], v[164:167], v[48:51]
	v_mfma_f32_16x16x32_bf16 v[40:43], v[138:141], v[164:167], v[40:43]
	v_mfma_f32_16x16x32_bf16 v[32:35], v[130:133], v[176:179], v[32:35]
	v_mfma_f32_16x16x32_bf16 v[24:27], v[138:141], v[176:179], v[24:27]
	v_mfma_f32_16x16x32_bf16 v[16:19], v[130:133], v[184:187], v[16:19]
	v_mfma_f32_16x16x32_bf16 v[8:11], v[138:141], v[184:187], v[8:11]
	v_mfma_f32_16x16x32_bf16 v[60:63], v[134:137], v[160:163], v[60:63]
	v_mfma_f32_16x16x32_bf16 v[56:59], v[142:145], v[160:163], v[56:59]
	v_mfma_f32_16x16x32_bf16 v[48:51], v[134:137], v[168:171], v[48:51]
	v_mfma_f32_16x16x32_bf16 v[40:43], v[142:145], v[168:171], v[40:43]
	v_mfma_f32_16x16x32_bf16 v[32:35], v[134:137], v[180:183], v[32:35]
	v_mfma_f32_16x16x32_bf16 v[24:27], v[142:145], v[180:183], v[24:27]
	v_mfma_f32_16x16x32_bf16 v[16:19], v[134:137], v[188:191], v[16:19]
	v_mfma_f32_16x16x32_bf16 v[8:11], v[142:145], v[188:191], v[8:11]
	s_barrier
; #define PG8_STAGE(bufoff, gbase, voff) do { _Pragma("unroll") for (int _i = 0; _i < 2; ++_i) \
;     __builtin_amdgcn_global_load_lds((const unsigned*)((const char*)(gbase) + (voff)[_i]), (LAS unsigned*)(lds + (bufoff) + ldsw + _i * 8192), 16, 0, 0); } while (0)
; #define PG8_LDA(dst, b, h) do { _Pragma("unroll") for (int m = 0; m < 4; ++m) _Pragma("unroll") for (int k = 0; k < 2; ++k) dst[m][k] = *(const LAS bf16x8*)(lds + PG8_SA(b, h) + aoff + m * 2048 + k * 1024); } while (0)
; #define PG8_LDB(dst, b, h) do { _Pragma("unroll") for (int n = 0; n < 2; ++n) _Pragma("unroll") for (int k = 0; k < 2; ++k) dst[n][k] = *(const LAS bf16x8*)(lds + PG8_SB(b, h) + boff + n * 2048 + k * 1024); } while (0)
; #define PG8_MMA(ai, bj, At, Bt) do { __builtin_amdgcn_s_setprio(1); _Pragma("unroll") for (int m = 0; m < 4; ++m) _Pragma("unroll") for (int n = 0; n < 2; ++n) _Pragma("unroll") for (int k = 0; k < 2; ++k) \
;     acc[ai][bj][m][n] = __builtin_amdgcn_mfma_f32_16x16x32_bf16(Bt[n][k], At[m][k], acc[ai][bj][m][n], 0, 0, 0); __builtin_amdgcn_s_setprio(0); } while (0)
; #define PG8_WAIT_V(n) asm volatile("s_waitcnt vmcnt(" #n ")" ::: "memory")
; #define PG8_WAIT_L(n) asm volatile("s_waitcnt lgkmcnt(" #n ")" ::: "memory")
; #define PG8_BAR __builtin_amdgcn_s_barrier()
; #define PG8_SCHED __builtin_amdgcn_sched_barrier(0)
; template <class Epi>
; __device__ __forceinline__ void gemm_phase(LAS unsigned char* lds, const Gemm g, const StaticOrder& S, const Epi& E, int wv0) {
;     ...
;       PG8_WAIT_V(6); PG8_BAR; PG8_MMA(1, 1, At, B1); PG8_BAR;
;       PG8_LDB(B0, 1, 0); PG8_SCHED; PG8_LDA(At, 1, 0); PG8_STAGE(PG8_SA(0, 1), a2 + hstepA, voffA);
;       PG8_WAIT_L(8); PG8_BAR; PG8_WAIT_L(0); PG8_MMA(0, 0, At, B0); PG8_BAR; PG8_SCHED;
;       PG8_LDB(B1, 1, 1); PG8_STAGE(PG8_SB(1, 0), b3, voffB);
;       PG8_BAR; PG8_WAIT_L(0); PG8_MMA(0, 1, At, B1); PG8_BAR;
;       PG8_LDA(At, 1, 1); PG8_STAGE(PG8_SA(1, 0), a3, voffA);
;       PG8_BAR; PG8_WAIT_L(0); PG8_MMA(1, 0, At, B0); PG8_BAR; PG8_SCHED;
	s_add_u32 s18, s20, 0x40000
	s_addc_u32 s19, s21, 0
	s_add_i32 s0, s50, s35
	v_lshl_add_u64 v[130:131], s[18:19], 0, v[96:97]
	s_mov_b32 m0, s0
	s_nop 0
	global_load_lds_dwordx4 v[130:131], off
	v_lshl_add_u64 v[130:131], s[18:19], 0, v[154:155]
	s_add_i32 m0, s0, 0x2000
	s_nop 0
	global_load_lds_dwordx4 v[130:131], off
	s_waitcnt vmcnt(6)
	s_barrier
	v_mfma_f32_16x16x32_bf16 v[52:55], v[192:195], v[146:149], v[52:55]
	v_mfma_f32_16x16x32_bf16 v[44:47], v[200:203], v[146:149], v[44:47]
	v_mfma_f32_16x16x32_bf16 v[36:39], v[192:195], v[164:167], v[36:39]
	v_mfma_f32_16x16x32_bf16 v[28:31], v[200:203], v[164:167], v[28:31]
	v_mfma_f32_16x16x32_bf16 v[20:23], v[192:195], v[176:179], v[20:23]
	v_mfma_f32_16x16x32_bf16 v[12:15], v[200:203], v[176:179], v[12:15]
	v_mfma_f32_16x16x32_bf16 v[4:7], v[192:195], v[184:187], v[4:7]
	v_mfma_f32_16x16x32_bf16 v[0:3], v[200:203], v[184:187], v[0:3]
	v_mfma_f32_16x16x32_bf16 v[52:55], v[196:199], v[160:163], v[52:55]
	v_mfma_f32_16x16x32_bf16 v[44:47], v[204:207], v[160:163], v[44:47]
	v_mfma_f32_16x16x32_bf16 v[36:39], v[196:199], v[168:171], v[36:39]
	v_mfma_f32_16x16x32_bf16 v[28:31], v[204:207], v[168:171], v[28:31]
	v_mfma_f32_16x16x32_bf16 v[20:23], v[196:199], v[180:183], v[20:23]
	v_mfma_f32_16x16x32_bf16 v[12:15], v[204:207], v[180:183], v[12:15]
	v_mfma_f32_16x16x32_bf16 v[4:7], v[196:199], v[188:191], v[4:7]
	v_mfma_f32_16x16x32_bf16 v[0:3], v[204:207], v[188:191], v[0:3]
	s_add_i32 s0, 0, 0x18000
	v_add_u32_e32 v142, s0, v173
	s_barrier
	ds_read_b128 v[130:133], v142
	ds_read_b128 v[134:137], v142 offset:1024
	ds_read_b128 v[138:141], v142 offset:2048
	ds_read_b128 v[142:145], v142 offset:3072
	s_add_u32 s18, s22, 0x114000
	s_addc_u32 s19, s23, 0
	s_mov_b32 m0, s38
	v_lshl_add_u64 v[192:193], s[18:19], 0, v[150:151]
	ds_read_b128 v[146:149], v175 offset:32768
	ds_read_b128 v[160:163], v175 offset:33792
	ds_read_b128 v[164:167], v175 offset:34816
	ds_read_b128 v[168:171], v175 offset:35840
	ds_read_b128 v[176:179], v175 offset:36864
	ds_read_b128 v[180:183], v175 offset:37888
	ds_read_b128 v[184:187], v175 offset:38912
	ds_read_b128 v[188:191], v175 offset:39936
	global_load_lds_dwordx4 v[192:193], off
	v_lshl_add_u64 v[192:193], s[18:19], 0, v[152:153]
	s_mov_b32 m0, s39
	s_nop 0
	global_load_lds_dwordx4 v[192:193], off
	s_waitcnt lgkmcnt(8)
	s_barrier
	s_waitcnt lgkmcnt(0)
	s_waitcnt lgkmcnt(0)
	v_mfma_f32_16x16x32_bf16 v[126:129], v[130:133], v[146:149], v[126:129]
	v_mfma_f32_16x16x32_bf16 v[122:125], v[138:141], v[146:149], v[122:125]
	v_mfma_f32_16x16x32_bf16 v[118:121], v[130:133], v[164:167], v[118:121]
	v_mfma_f32_16x16x32_bf16 v[110:113], v[138:141], v[164:167], v[110:113]
	v_mfma_f32_16x16x32_bf16 v[92:95], v[130:133], v[176:179], v[92:95]
	v_mfma_f32_16x16x32_bf16 v[88:91], v[138:141], v[176:179], v[88:91]
	v_mfma_f32_16x16x32_bf16 v[80:83], v[130:133], v[184:187], v[80:83]
	v_mfma_f32_16x16x32_bf16 v[72:75], v[138:141], v[184:187], v[72:75]
	v_mfma_f32_16x16x32_bf16 v[126:129], v[134:137], v[160:163], v[126:129]
	v_mfma_f32_16x16x32_bf16 v[122:125], v[142:145], v[160:163], v[122:125]
	v_mfma_f32_16x16x32_bf16 v[118:121], v[134:137], v[168:171], v[118:121]
	v_mfma_f32_16x16x32_bf16 v[110:113], v[142:145], v[168:171], v[110:113]
	v_mfma_f32_16x16x32_bf16 v[92:95], v[134:137], v[180:183], v[92:95]
	v_mfma_f32_16x16x32_bf16 v[88:91], v[142:145], v[180:183], v[88:91]
	v_mfma_f32_16x16x32_bf16 v[80:83], v[134:137], v[188:191], v[80:83]
	v_mfma_f32_16x16x32_bf16 v[72:75], v[142:145], v[188:191], v[72:75]
	s_barrier
	s_add_i32 s22, 0, 0x1c000
	s_add_i32 s0, s0, s35
	v_add_u32_e32 v204, s22, v173
	v_lshl_add_u64 v[208:209], v[208:209], 0, s[72:73]
	s_mov_b32 m0, s0
	ds_read_b128 v[192:195], v204
	ds_read_b128 v[196:199], v204 offset:1024
	ds_read_b128 v[200:203], v204 offset:2048
	ds_read_b128 v[204:207], v204 offset:3072
	global_load_lds_dwordx4 v[208:209], off
	v_lshl_add_u64 v[208:209], v[210:211], 0, s[72:73]
	s_add_i32 m0, s0, 0x2000
	s_nop 0
	global_load_lds_dwordx4 v[208:209], off
	s_barrier
	s_waitcnt lgkmcnt(0)
	s_waitcnt lgkmcnt(0)
	v_mfma_f32_16x16x32_bf16 v[114:117], v[192:195], v[146:149], v[114:117]
	v_mfma_f32_16x16x32_bf16 v[106:109], v[200:203], v[146:149], v[106:109]
	v_mfma_f32_16x16x32_bf16 v[102:105], v[192:195], v[164:167], v[102:105]
	v_mfma_f32_16x16x32_bf16 v[98:101], v[200:203], v[164:167], v[98:101]
	v_mfma_f32_16x16x32_bf16 v[84:87], v[192:195], v[176:179], v[84:87]
	v_mfma_f32_16x16x32_bf16 v[76:79], v[200:203], v[176:179], v[76:79]
	v_mfma_f32_16x16x32_bf16 v[68:71], v[192:195], v[184:187], v[68:71]
	v_mfma_f32_16x16x32_bf16 v[64:67], v[200:203], v[184:187], v[64:67]
	v_mfma_f32_16x16x32_bf16 v[114:117], v[196:199], v[160:163], v[114:117]
	v_mfma_f32_16x16x32_bf16 v[106:109], v[204:207], v[160:163], v[106:109]
	v_mfma_f32_16x16x32_bf16 v[102:105], v[196:199], v[168:171], v[102:105]
	v_mfma_f32_16x16x32_bf16 v[98:101], v[204:207], v[168:171], v[98:101]
	v_mfma_f32_16x16x32_bf16 v[84:87], v[196:199], v[180:183], v[84:87]
	v_mfma_f32_16x16x32_bf16 v[76:79], v[204:207], v[180:183], v[76:79]
	v_mfma_f32_16x16x32_bf16 v[68:71], v[196:199], v[188:191], v[68:71]
	v_mfma_f32_16x16x32_bf16 v[64:67], v[204:207], v[188:191], v[64:67]
	s_mov_b32 m0, s40
	v_lshl_add_u64 v[208:209], v[212:213], 0, s[72:73]
	s_barrier
	ds_read_b128 v[146:149], v175 offset:49152
	ds_read_b128 v[160:163], v175 offset:50176
	ds_read_b128 v[164:167], v175 offset:51200
	ds_read_b128 v[168:171], v175 offset:52224
	ds_read_b128 v[176:179], v175 offset:53248
	ds_read_b128 v[180:183], v175 offset:54272
	ds_read_b128 v[184:187], v175 offset:55296
	ds_read_b128 v[188:191], v175 offset:56320
	global_load_lds_dwordx4 v[208:209], off
	v_lshl_add_u64 v[208:209], v[214:215], 0, s[72:73]
	s_mov_b32 m0, s41
	s_nop 0
	global_load_lds_dwordx4 v[208:209], off
	s_barrier
; __device__ __forceinline__ float bf_lo(unsigned u) { return __uint_as_float(u << 16); }
; __device__ __forceinline__ float bf_hi(unsigned u) { return __uint_as_float(u & 0xffff0000u); }
; #define PG8_STAGE(bufoff, gbase, voff) do { _Pragma("unroll") for (int _i = 0; _i < 2; ++_i) \
;     __builtin_amdgcn_global_load_lds((const unsigned*)((const char*)(gbase) + (voff)[_i]), (LAS unsigned*)(lds + (bufoff) + ldsw + _i * 8192), 16, 0, 0); } while (0)
; #define PG8_MMA(ai, bj, At, Bt) do { __builtin_amdgcn_s_setprio(1); _Pragma("unroll") for (int m = 0; m < 4; ++m) _Pragma("unroll") for (int n = 0; n < 2; ++n) _Pragma("unroll") for (int k = 0; k < 2; ++k) \
;     acc[ai][bj][m][n] = __builtin_amdgcn_mfma_f32_16x16x32_bf16(Bt[n][k], At[m][k], acc[ai][bj][m][n], 0, 0, 0); __builtin_amdgcn_s_setprio(0); } while (0)
; #define PG8_WAIT_V(n) asm volatile("s_waitcnt vmcnt(" #n ")" ::: "memory")
; #define PG8_BAR __builtin_amdgcn_s_barrier()
; template <class Epi>
; __device__ __forceinline__ void gemm_phase(LAS unsigned char* lds, const Gemm g, const StaticOrder& S, const Epi& E, int wv0) {
;     ...
;       PG8_STAGE(PG8_SB(1, 1), b3 + hstepB, voffB);
;       PG8_WAIT_V(6); PG8_BAR; PG8_MMA(1, 1, At, B1); PG8_BAR;
;     }
;     E(acc, cur, wr, wc, fr, fq);
;     if (!has_next) break;
;   __device__ __forceinline__ void emit(const EpiPre& q0, int row, int col, f32x4 a, f32x4 b, const f32x4 (&hb)[2][2], const float (&hs)[2][4], int ai_, int m_, int bj_) const {
;     ...
;     } else if (MODE == E_PROJ) {
;       const int br = e.aux; const u32x4 gw = q.u0;
;       v[0] *= bf_lo(gw.x); v[1] *= bf_hi(gw.x); v[2] *= bf_lo(gw.y); v[3] *= bf_hi(gw.y);
;       v[4] *= bf_lo(gw.z); v[5] *= bf_hi(gw.z); v[6] *= bf_lo(gw.w); v[7] *= bf_hi(gw.w);
;       bf16_t* fa = (bf16_t*)e.facc + (size_t)row * DM + col;
;       if (br > 0) { const u32x4 pw = q.u1;
;         v[0] += bf_lo(pw.x); v[1] += bf_hi(pw.x); v[2] += bf_lo(pw.y); v[3] += bf_hi(pw.y); v[4] += bf_lo(pw.z); v[5] += bf_hi(pw.z); v[6] += bf_lo(pw.w); v[7] += bf_hi(pw.w); }
;       if (br == 2) store8bf((bf16_t*)e.out + (size_t)row * DM + col, v);
;       else store8bf(fa, v);
	s_waitcnt lgkmcnt(0)
	s_waitcnt lgkmcnt(0)
	v_mfma_f32_16x16x32_bf16 v[60:63], v[130:133], v[146:149], v[60:63]
	v_mfma_f32_16x16x32_bf16 v[56:59], v[138:141], v[146:149], v[56:59]
	v_mfma_f32_16x16x32_bf16 v[48:51], v[130:133], v[164:167], v[48:51]
	v_mfma_f32_16x16x32_bf16 v[40:43], v[138:141], v[164:167], v[40:43]
	v_mfma_f32_16x16x32_bf16 v[32:35], v[130:133], v[176:179], v[32:35]
	v_mfma_f32_16x16x32_bf16 v[24:27], v[138:141], v[176:179], v[24:27]
	v_mfma_f32_16x16x32_bf16 v[16:19], v[130:133], v[184:187], v[16:19]
	v_mfma_f32_16x16x32_bf16 v[8:11], v[138:141], v[184:187], v[8:11]
	v_mfma_f32_16x16x32_bf16 v[60:63], v[134:137], v[160:163], v[60:63]
	v_mfma_f32_16x16x32_bf16 v[56:59], v[142:145], v[160:163], v[56:59]
	v_mfma_f32_16x16x32_bf16 v[48:51], v[134:137], v[168:171], v[48:51]
	v_mfma_f32_16x16x32_bf16 v[40:43], v[142:145], v[168:171], v[40:43]
	v_mfma_f32_16x16x32_bf16 v[32:35], v[134:137], v[180:183], v[32:35]
	v_mfma_f32_16x16x32_bf16 v[24:27], v[142:145], v[180:183], v[24:27]
	v_mfma_f32_16x16x32_bf16 v[16:19], v[134:137], v[188:191], v[16:19]
	v_mfma_f32_16x16x32_bf16 v[8:11], v[142:145], v[188:191], v[8:11]
	s_barrier
	s_add_u32 s18, s20, 0x40080
	s_addc_u32 s19, s21, 0
	s_add_i32 s0, s22, s35
	v_lshl_add_u64 v[130:131], s[18:19], 0, v[96:97]
	s_mov_b32 m0, s0
	s_nop 0
	global_load_lds_dwordx4 v[130:131], off
	v_lshl_add_u64 v[130:131], s[18:19], 0, v[154:155]
	s_add_i32 m0, s0, 0x2000
	s_nop 0
	global_load_lds_dwordx4 v[130:131], off
	s_waitcnt vmcnt(6)
	s_barrier
	v_mfma_f32_16x16x32_bf16 v[52:55], v[192:195], v[146:149], v[52:55]
	v_mfma_f32_16x16x32_bf16 v[44:47], v[200:203], v[146:149], v[44:47]
	v_mfma_f32_16x16x32_bf16 v[36:39], v[192:195], v[164:167], v[36:39]
	v_mfma_f32_16x16x32_bf16 v[28:31], v[200:203], v[164:167], v[28:31]
	v_mfma_f32_16x16x32_bf16 v[20:23], v[192:195], v[176:179], v[20:23]
	v_mfma_f32_16x16x32_bf16 v[12:15], v[200:203], v[176:179], v[12:15]
	v_mfma_f32_16x16x32_bf16 v[4:7], v[192:195], v[184:187], v[4:7]
	v_mfma_f32_16x16x32_bf16 v[0:3], v[200:203], v[184:187], v[0:3]
	v_mfma_f32_16x16x32_bf16 v[52:55], v[196:199], v[160:163], v[52:55]
	v_mfma_f32_16x16x32_bf16 v[44:47], v[204:207], v[160:163], v[44:47]
	v_mfma_f32_16x16x32_bf16 v[36:39], v[196:199], v[168:171], v[36:39]
	v_mfma_f32_16x16x32_bf16 v[28:31], v[204:207], v[168:171], v[28:31]
	v_mfma_f32_16x16x32_bf16 v[20:23], v[196:199], v[180:183], v[20:23]
	v_mfma_f32_16x16x32_bf16 v[12:15], v[204:207], v[180:183], v[12:15]
	v_mfma_f32_16x16x32_bf16 v[4:7], v[196:199], v[188:191], v[4:7]
	v_mfma_f32_16x16x32_bf16 v[0:3], v[204:207], v[188:191], v[0:3]
	s_add_i32 s49, s49, 2
	s_add_u32 s47, s47, 0x100
	s_addc_u32 s48, s48, 0
	s_cmp_gt_u32 s49, 13
	s_mov_b64 s[18:19], s[4:5]
	s_barrier
	s_cbranch_scc0 .LBB0_981
	v_lshl_add_u32 v213, s1, 8, v172
	v_lshl_or_b32 v214, s45, 8, v174
	v_mul_u32_u24_e32 v212, 0x3000, v213
	v_lshlrev_b32_e32 v213, 12, v213
	v_lshl_add_u32 v212, v214, 1, v212
	v_lshl_add_u32 v213, v214, 1, v213
	v_add_u32_e32 v214, 0x0, v212
	global_load_dwordx4 v[130:133], v214, s[6:7]
	global_load_dwordx4 v[134:137], v214, s[6:7] offset:256
	v_add_u32_e32 v214, 0x30000, v212
	global_load_dwordx4 v[138:141], v214, s[6:7]
	global_load_dwordx4 v[142:145], v214, s[6:7] offset:256
	v_add_u32_e32 v214, 0x60000, v212
	global_load_dwordx4 v[146:149], v214, s[6:7]
	global_load_dwordx4 v[160:163], v214, s[6:7] offset:256
	v_add_u32_e32 v214, 0x90000, v212
	global_load_dwordx4 v[164:167], v214, s[6:7]
	global_load_dwordx4 v[168:171], v214, s[6:7] offset:256
	v_add_u32_e32 v214, 0x180000, v212
	global_load_dwordx4 v[176:179], v214, s[6:7]
	global_load_dwordx4 v[180:183], v214, s[6:7] offset:256
	v_add_u32_e32 v214, 0x1b0000, v212
	global_load_dwordx4 v[184:187], v214, s[6:7]
	global_load_dwordx4 v[188:191], v214, s[6:7] offset:256
	v_add_u32_e32 v214, 0x1e0000, v212
	global_load_dwordx4 v[192:195], v214, s[6:7]
	global_load_dwordx4 v[196:199], v214, s[6:7] offset:256
	v_add_u32_e32 v214, 0x210000, v212
	global_load_dwordx4 v[200:203], v214, s[6:7]
	global_load_dwordx4 v[204:207], v214, s[6:7] offset:256
	s_waitcnt vmcnt(15)
	v_lshlrev_b32_e32 v208, 16, v130
	v_and_b32_e32 v209, 0xffff0000, v130
	v_pk_mul_f32 v[126:127], v[126:127], v[208:209]
	v_lshlrev_b32_e32 v208, 16, v131
	v_and_b32_e32 v209, 0xffff0000, v131
	v_pk_mul_f32 v[128:129], v[128:129], v[208:209]
	v_lshlrev_b32_e32 v208, 16, v132
	v_and_b32_e32 v209, 0xffff0000, v132
	v_pk_mul_f32 v[122:123], v[122:123], v[208:209]
	v_lshlrev_b32_e32 v208, 16, v133
	v_and_b32_e32 v209, 0xffff0000, v133
	v_pk_mul_f32 v[124:125], v[124:125], v[208:209]
	v_cvt_pk_bf16_f32 v126, v126, v127
	v_cvt_pk_bf16_f32 v127, v128, v129
	v_cvt_pk_bf16_f32 v128, v122, v123
	v_cvt_pk_bf16_f32 v129, v124, v125
	v_add_u32_e32 v215, 0x0, v213
	global_store_dwordx4 v215, v[126:129], s[8:9]
	s_waitcnt vmcnt(15)
	v_lshlrev_b32_e32 v208, 16, v134
	v_and_b32_e32 v209, 0xffff0000, v134
	v_pk_mul_f32 v[114:115], v[114:115], v[208:209]
	v_lshlrev_b32_e32 v208, 16, v135
	v_and_b32_e32 v209, 0xffff0000, v135
	v_pk_mul_f32 v[116:117], v[116:117], v[208:209]
	v_lshlrev_b32_e32 v208, 16, v136
	v_and_b32_e32 v209, 0xffff0000, v136
	v_pk_mul_f32 v[106:107], v[106:107], v[208:209]
	v_lshlrev_b32_e32 v208, 16, v137
	v_and_b32_e32 v209, 0xffff0000, v137
	v_pk_mul_f32 v[108:109], v[108:109], v[208:209]
	v_cvt_pk_bf16_f32 v114, v114, v115
	v_cvt_pk_bf16_f32 v115, v116, v117
	v_cvt_pk_bf16_f32 v116, v106, v107
	v_cvt_pk_bf16_f32 v117, v108, v109
	global_store_dwordx4 v215, v[114:117], s[8:9] offset:256
	s_waitcnt vmcnt(15)
; __device__ __forceinline__ float bf_lo(unsigned u) { return __uint_as_float(u << 16); }
; __device__ __forceinline__ float bf_hi(unsigned u) { return __uint_as_float(u & 0xffff0000u); }
;   __device__ __forceinline__ void emit(const EpiPre& q0, int row, int col, f32x4 a, f32x4 b, const f32x4 (&hb)[2][2], const float (&hs)[2][4], int ai_, int m_, int bj_) const {
;     ...
;     } else if (MODE == E_PROJ) {
;       const int br = e.aux; const u32x4 gw = q.u0;
;       v[0] *= bf_lo(gw.x); v[1] *= bf_hi(gw.x); v[2] *= bf_lo(gw.y); v[3] *= bf_hi(gw.y);
;       v[4] *= bf_lo(gw.z); v[5] *= bf_hi(gw.z); v[6] *= bf_lo(gw.w); v[7] *= bf_hi(gw.w);
;       bf16_t* fa = (bf16_t*)e.facc + (size_t)row * DM + col;
;       if (br > 0) { const u32x4 pw = q.u1;
;         v[0] += bf_lo(pw.x); v[1] += bf_hi(pw.x); v[2] += bf_lo(pw.y); v[3] += bf_hi(pw.y); v[4] += bf_lo(pw.z); v[5] += bf_hi(pw.z); v[6] += bf_lo(pw.w); v[7] += bf_hi(pw.w); }
;       if (br == 2) store8bf((bf16_t*)e.out + (size_t)row * DM + col, v);
;       else store8bf(fa, v);
	v_lshlrev_b32_e32 v208, 16, v138
	v_and_b32_e32 v209, 0xffff0000, v138
	v_pk_mul_f32 v[118:119], v[118:119], v[208:209]
	v_lshlrev_b32_e32 v208, 16, v139
	v_and_b32_e32 v209, 0xffff0000, v139
	v_pk_mul_f32 v[120:121], v[120:121], v[208:209]
	v_lshlrev_b32_e32 v208, 16, v140
	v_and_b32_e32 v209, 0xffff0000, v140
	v_pk_mul_f32 v[110:111], v[110:111], v[208:209]
	v_lshlrev_b32_e32 v208, 16, v141
	v_and_b32_e32 v209, 0xffff0000, v141
	v_pk_mul_f32 v[112:113], v[112:113], v[208:209]
	v_cvt_pk_bf16_f32 v118, v118, v119
	v_cvt_pk_bf16_f32 v119, v120, v121
	v_cvt_pk_bf16_f32 v120, v110, v111
	v_cvt_pk_bf16_f32 v121, v112, v113
	v_add_u32_e32 v215, 0x10000, v213
	global_store_dwordx4 v215, v[118:121], s[8:9]
	s_waitcnt vmcnt(15)
	v_lshlrev_b32_e32 v208, 16, v142
	v_and_b32_e32 v209, 0xffff0000, v142
	v_pk_mul_f32 v[102:103], v[102:103], v[208:209]
	v_lshlrev_b32_e32 v208, 16, v143
	v_and_b32_e32 v209, 0xffff0000, v143
	v_pk_mul_f32 v[104:105], v[104:105], v[208:209]
	v_lshlrev_b32_e32 v208, 16, v144
	v_and_b32_e32 v209, 0xffff0000, v144
	v_pk_mul_f32 v[98:99], v[98:99], v[208:209]
	v_lshlrev_b32_e32 v208, 16, v145
	v_and_b32_e32 v209, 0xffff0000, v145
	v_pk_mul_f32 v[100:101], v[100:101], v[208:209]
	v_cvt_pk_bf16_f32 v102, v102, v103
	v_cvt_pk_bf16_f32 v103, v104, v105
	v_cvt_pk_bf16_f32 v104, v98, v99
	v_cvt_pk_bf16_f32 v105, v100, v101
	global_store_dwordx4 v215, v[102:105], s[8:9] offset:256
	s_waitcnt vmcnt(15)
	v_lshlrev_b32_e32 v208, 16, v146
	v_and_b32_e32 v209, 0xffff0000, v146
	v_pk_mul_f32 v[92:93], v[92:93], v[208:209]
	v_lshlrev_b32_e32 v208, 16, v147
	v_and_b32_e32 v209, 0xffff0000, v147
	v_pk_mul_f32 v[94:95], v[94:95], v[208:209]
	v_lshlrev_b32_e32 v208, 16, v148
	v_and_b32_e32 v209, 0xffff0000, v148
	v_pk_mul_f32 v[88:89], v[88:89], v[208:209]
	v_lshlrev_b32_e32 v208, 16, v149
	v_and_b32_e32 v209, 0xffff0000, v149
	v_pk_mul_f32 v[90:91], v[90:91], v[208:209]
	v_cvt_pk_bf16_f32 v92, v92, v93
	v_cvt_pk_bf16_f32 v93, v94, v95
	v_cvt_pk_bf16_f32 v94, v88, v89
	v_cvt_pk_bf16_f32 v95, v90, v91
	v_add_u32_e32 v215, 0x20000, v213
	global_store_dwordx4 v215, v[92:95], s[8:9]
	s_waitcnt vmcnt(15)
	v_lshlrev_b32_e32 v208, 16, v160
	v_and_b32_e32 v209, 0xffff0000, v160
	v_pk_mul_f32 v[84:85], v[84:85], v[208:209]
	v_lshlrev_b32_e32 v208, 16, v161
	v_and_b32_e32 v209, 0xffff0000, v161
	v_pk_mul_f32 v[86:87], v[86:87], v[208:209]
	v_lshlrev_b32_e32 v208, 16, v162
	v_and_b32_e32 v209, 0xffff0000, v162
	v_pk_mul_f32 v[76:77], v[76:77], v[208:209]
	v_lshlrev_b32_e32 v208, 16, v163
	v_and_b32_e32 v209, 0xffff0000, v163
	v_pk_mul_f32 v[78:79], v[78:79], v[208:209]
	v_cvt_pk_bf16_f32 v84, v84, v85
	v_cvt_pk_bf16_f32 v85, v86, v87
	v_cvt_pk_bf16_f32 v86, v76, v77
	v_cvt_pk_bf16_f32 v87, v78, v79
	global_store_dwordx4 v215, v[84:87], s[8:9] offset:256
	s_waitcnt vmcnt(15)
	v_lshlrev_b32_e32 v208, 16, v164
	v_and_b32_e32 v209, 0xffff0000, v164
	v_pk_mul_f32 v[80:81], v[80:81], v[208:209]
	v_lshlrev_b32_e32 v208, 16, v165
	v_and_b32_e32 v209, 0xffff0000, v165
	v_pk_mul_f32 v[82:83], v[82:83], v[208:209]
	v_lshlrev_b32_e32 v208, 16, v166
	v_and_b32_e32 v209, 0xffff0000, v166
	v_pk_mul_f32 v[72:73], v[72:73], v[208:209]
	v_lshlrev_b32_e32 v208, 16, v167
	v_and_b32_e32 v209, 0xffff0000, v167
	v_pk_mul_f32 v[74:75], v[74:75], v[208:209]
	v_cvt_pk_bf16_f32 v80, v80, v81
	v_cvt_pk_bf16_f32 v81, v82, v83
	v_cvt_pk_bf16_f32 v82, v72, v73
	v_cvt_pk_bf16_f32 v83, v74, v75
	v_add_u32_e32 v215, 0x30000, v213
	global_store_dwordx4 v215, v[80:83], s[8:9]
	s_waitcnt vmcnt(15)
	v_lshlrev_b32_e32 v208, 16, v168
	v_and_b32_e32 v209, 0xffff0000, v168
	v_pk_mul_f32 v[68:69], v[68:69], v[208:209]
	v_lshlrev_b32_e32 v208, 16, v169
	v_and_b32_e32 v209, 0xffff0000, v169
	v_pk_mul_f32 v[70:71], v[70:71], v[208:209]
	v_lshlrev_b32_e32 v208, 16, v170
	v_and_b32_e32 v209, 0xffff0000, v170
	v_pk_mul_f32 v[64:65], v[64:65], v[208:209]
	v_lshlrev_b32_e32 v208, 16, v171
	v_and_b32_e32 v209, 0xffff0000, v171
	v_pk_mul_f32 v[66:67], v[66:67], v[208:209]
	v_cvt_pk_bf16_f32 v68, v68, v69
	v_cvt_pk_bf16_f32 v69, v70, v71
	v_cvt_pk_bf16_f32 v70, v64, v65
	v_cvt_pk_bf16_f32 v71, v66, v67
	global_store_dwordx4 v215, v[68:71], s[8:9] offset:256
	s_waitcnt vmcnt(15)
	v_lshlrev_b32_e32 v208, 16, v176
	v_and_b32_e32 v209, 0xffff0000, v176
	v_pk_mul_f32 v[60:61], v[60:61], v[208:209]
	v_lshlrev_b32_e32 v208, 16, v177
	v_and_b32_e32 v209, 0xffff0000, v177
	v_pk_mul_f32 v[62:63], v[62:63], v[208:209]
	v_lshlrev_b32_e32 v208, 16, v178
	v_and_b32_e32 v209, 0xffff0000, v178
	v_pk_mul_f32 v[56:57], v[56:57], v[208:209]
	v_lshlrev_b32_e32 v208, 16, v179
	v_and_b32_e32 v209, 0xffff0000, v179
	v_pk_mul_f32 v[58:59], v[58:59], v[208:209]
	v_cvt_pk_bf16_f32 v60, v60, v61
	v_cvt_pk_bf16_f32 v61, v62, v63
	v_cvt_pk_bf16_f32 v62, v56, v57
	v_cvt_pk_bf16_f32 v63, v58, v59
	v_add_u32_e32 v215, 0x80000, v213
	global_store_dwordx4 v215, v[60:63], s[8:9]
	s_waitcnt vmcnt(15)
; __device__ __forceinline__ float bf_lo(unsigned u) { return __uint_as_float(u << 16); }
; __device__ __forceinline__ float bf_hi(unsigned u) { return __uint_as_float(u & 0xffff0000u); }
; #define PG8_WAIT_V(n) asm volatile("s_waitcnt vmcnt(" #n ")" ::: "memory")
; #define PG8_BAR __builtin_amdgcn_s_barrier()
; template <class Epi>
; __device__ __forceinline__ void gemm_phase(LAS unsigned char* lds, const Gemm g, const StaticOrder& S, const Epi& E, int wv0) {
;     ...
;     if (!has_next) break;
; #pragma unroll
;     for (int a = 0; a < 2; ++a)
; #pragma unroll
;       for (int b = 0; b < 2; ++b)
; #pragma unroll
;         for (int m = 0; m < 4; ++m)
; #pragma unroll
;           for (int n = 0; n < 2; ++n) acc[a][b][m][n] = (f32x4){0.f, 0.f, 0.f, 0.f};
;     cur = nxt; cA = nA; cB = nB; ++ui;
;   }
;   PG8_WAIT_V(0);
;   if (wr == 0) PG8_BAR;
;   PG8_BAR;
;   __device__ __forceinline__ void emit(const EpiPre& q0, int row, int col, f32x4 a, f32x4 b, const f32x4 (&hb)[2][2], const float (&hs)[2][4], int ai_, int m_, int bj_) const {
;     ...
;     } else if (MODE == E_PROJ) {
;       const int br = e.aux; const u32x4 gw = q.u0;
;       v[0] *= bf_lo(gw.x); v[1] *= bf_hi(gw.x); v[2] *= bf_lo(gw.y); v[3] *= bf_hi(gw.y);
;       v[4] *= bf_lo(gw.z); v[5] *= bf_hi(gw.z); v[6] *= bf_lo(gw.w); v[7] *= bf_hi(gw.w);
;       bf16_t* fa = (bf16_t*)e.facc + (size_t)row * DM + col;
;       if (br > 0) { const u32x4 pw = q.u1;
;         v[0] += bf_lo(pw.x); v[1] += bf_hi(pw.x); v[2] += bf_lo(pw.y); v[3] += bf_hi(pw.y); v[4] += bf_lo(pw.z); v[5] += bf_hi(pw.z); v[6] += bf_lo(pw.w); v[7] += bf_hi(pw.w); }
;       if (br == 2) store8bf((bf16_t*)e.out + (size_t)row * DM + col, v);
;       else store8bf(fa, v);
	v_lshlrev_b32_e32 v208, 16, v180
	v_and_b32_e32 v209, 0xffff0000, v180
	v_pk_mul_f32 v[52:53], v[52:53], v[208:209]
	v_lshlrev_b32_e32 v208, 16, v181
	v_and_b32_e32 v209, 0xffff0000, v181
	v_pk_mul_f32 v[54:55], v[54:55], v[208:209]
	v_lshlrev_b32_e32 v208, 16, v182
	v_and_b32_e32 v209, 0xffff0000, v182
	v_pk_mul_f32 v[44:45], v[44:45], v[208:209]
	v_lshlrev_b32_e32 v208, 16, v183
	v_and_b32_e32 v209, 0xffff0000, v183
	v_pk_mul_f32 v[46:47], v[46:47], v[208:209]
	v_cvt_pk_bf16_f32 v52, v52, v53
	v_cvt_pk_bf16_f32 v53, v54, v55
	v_cvt_pk_bf16_f32 v54, v44, v45
	v_cvt_pk_bf16_f32 v55, v46, v47
	global_store_dwordx4 v215, v[52:55], s[8:9] offset:256
	s_waitcnt vmcnt(15)
	v_lshlrev_b32_e32 v208, 16, v184
	v_and_b32_e32 v209, 0xffff0000, v184
	v_pk_mul_f32 v[48:49], v[48:49], v[208:209]
	v_lshlrev_b32_e32 v208, 16, v185
	v_and_b32_e32 v209, 0xffff0000, v185
	v_pk_mul_f32 v[50:51], v[50:51], v[208:209]
	v_lshlrev_b32_e32 v208, 16, v186
	v_and_b32_e32 v209, 0xffff0000, v186
	v_pk_mul_f32 v[40:41], v[40:41], v[208:209]
	v_lshlrev_b32_e32 v208, 16, v187
	v_and_b32_e32 v209, 0xffff0000, v187
	v_pk_mul_f32 v[42:43], v[42:43], v[208:209]
	v_cvt_pk_bf16_f32 v48, v48, v49
	v_cvt_pk_bf16_f32 v49, v50, v51
	v_cvt_pk_bf16_f32 v50, v40, v41
	v_cvt_pk_bf16_f32 v51, v42, v43
	v_add_u32_e32 v215, 0x90000, v213
	global_store_dwordx4 v215, v[48:51], s[8:9]
	s_waitcnt vmcnt(15)
	v_lshlrev_b32_e32 v208, 16, v188
	v_and_b32_e32 v209, 0xffff0000, v188
	v_pk_mul_f32 v[36:37], v[36:37], v[208:209]
	v_lshlrev_b32_e32 v208, 16, v189
	v_and_b32_e32 v209, 0xffff0000, v189
	v_pk_mul_f32 v[38:39], v[38:39], v[208:209]
	v_lshlrev_b32_e32 v208, 16, v190
	v_and_b32_e32 v209, 0xffff0000, v190
	v_pk_mul_f32 v[28:29], v[28:29], v[208:209]
	v_lshlrev_b32_e32 v208, 16, v191
	v_and_b32_e32 v209, 0xffff0000, v191
	v_pk_mul_f32 v[30:31], v[30:31], v[208:209]
	v_cvt_pk_bf16_f32 v36, v36, v37
	v_cvt_pk_bf16_f32 v37, v38, v39
	v_cvt_pk_bf16_f32 v38, v28, v29
	v_cvt_pk_bf16_f32 v39, v30, v31
	global_store_dwordx4 v215, v[36:39], s[8:9] offset:256
	s_waitcnt vmcnt(15)
	v_lshlrev_b32_e32 v208, 16, v192
	v_and_b32_e32 v209, 0xffff0000, v192
	v_pk_mul_f32 v[32:33], v[32:33], v[208:209]
	v_lshlrev_b32_e32 v208, 16, v193
	v_and_b32_e32 v209, 0xffff0000, v193
	v_pk_mul_f32 v[34:35], v[34:35], v[208:209]
	v_lshlrev_b32_e32 v208, 16, v194
	v_and_b32_e32 v209, 0xffff0000, v194
	v_pk_mul_f32 v[24:25], v[24:25], v[208:209]
	v_lshlrev_b32_e32 v208, 16, v195
	v_and_b32_e32 v209, 0xffff0000, v195
	v_pk_mul_f32 v[26:27], v[26:27], v[208:209]
	v_cvt_pk_bf16_f32 v32, v32, v33
	v_cvt_pk_bf16_f32 v33, v34, v35
	v_cvt_pk_bf16_f32 v34, v24, v25
	v_cvt_pk_bf16_f32 v35, v26, v27
	v_add_u32_e32 v215, 0xa0000, v213
	global_store_dwordx4 v215, v[32:35], s[8:9]
	s_waitcnt vmcnt(15)
	v_lshlrev_b32_e32 v208, 16, v196
	v_and_b32_e32 v209, 0xffff0000, v196
	v_pk_mul_f32 v[20:21], v[20:21], v[208:209]
	v_lshlrev_b32_e32 v208, 16, v197
	v_and_b32_e32 v209, 0xffff0000, v197
	v_pk_mul_f32 v[22:23], v[22:23], v[208:209]
	v_lshlrev_b32_e32 v208, 16, v198
	v_and_b32_e32 v209, 0xffff0000, v198
	v_pk_mul_f32 v[12:13], v[12:13], v[208:209]
	v_lshlrev_b32_e32 v208, 16, v199
	v_and_b32_e32 v209, 0xffff0000, v199
	v_pk_mul_f32 v[14:15], v[14:15], v[208:209]
	v_cvt_pk_bf16_f32 v20, v20, v21
	v_cvt_pk_bf16_f32 v21, v22, v23
	v_cvt_pk_bf16_f32 v22, v12, v13
	v_cvt_pk_bf16_f32 v23, v14, v15
	global_store_dwordx4 v215, v[20:23], s[8:9] offset:256
	s_waitcnt vmcnt(15)
	v_lshlrev_b32_e32 v208, 16, v200
	v_and_b32_e32 v209, 0xffff0000, v200
	v_pk_mul_f32 v[16:17], v[16:17], v[208:209]
	v_lshlrev_b32_e32 v208, 16, v201
	v_and_b32_e32 v209, 0xffff0000, v201
	v_pk_mul_f32 v[18:19], v[18:19], v[208:209]
	v_lshlrev_b32_e32 v208, 16, v202
	v_and_b32_e32 v209, 0xffff0000, v202
	v_pk_mul_f32 v[8:9], v[8:9], v[208:209]
	v_lshlrev_b32_e32 v208, 16, v203
	v_and_b32_e32 v209, 0xffff0000, v203
	v_pk_mul_f32 v[10:11], v[10:11], v[208:209]
	v_cvt_pk_bf16_f32 v16, v16, v17
	v_cvt_pk_bf16_f32 v17, v18, v19
	v_cvt_pk_bf16_f32 v18, v8, v9
	v_cvt_pk_bf16_f32 v19, v10, v11
	v_add_u32_e32 v215, 0xb0000, v213
	global_store_dwordx4 v215, v[16:19], s[8:9]
	s_waitcnt vmcnt(15)
	v_lshlrev_b32_e32 v208, 16, v204
	v_and_b32_e32 v209, 0xffff0000, v204
	v_pk_mul_f32 v[4:5], v[4:5], v[208:209]
	v_lshlrev_b32_e32 v208, 16, v205
	v_and_b32_e32 v209, 0xffff0000, v205
	v_pk_mul_f32 v[6:7], v[6:7], v[208:209]
	v_lshlrev_b32_e32 v208, 16, v206
	v_and_b32_e32 v209, 0xffff0000, v206
	v_pk_mul_f32 v[0:1], v[0:1], v[208:209]
	v_lshlrev_b32_e32 v208, 16, v207
	v_and_b32_e32 v209, 0xffff0000, v207
	v_pk_mul_f32 v[2:3], v[2:3], v[208:209]
	v_cvt_pk_bf16_f32 v4, v4, v5
	v_cvt_pk_bf16_f32 v5, v6, v7
	v_cvt_pk_bf16_f32 v6, v0, v1
	v_cvt_pk_bf16_f32 v7, v2, v3
	global_store_dwordx4 v215, v[4:7], s[8:9] offset:256
	s_mov_b32 s45, s12
	s_mov_b64 s[20:21], s[16:17]
	s_mov_b64 s[18:19], s[14:15]
	s_and_b64 vcc, exec, s[2:3]
	s_mov_b32 s1, s44
	s_cbranch_vccz .LBB0_972
	s_waitcnt vmcnt(0)
	s_cmpk_gt_u32 s27, 0xff
	s_cbranch_scc1 .LBB0_985
	s_barrier

; #define PG8_STAGE(bufoff, gbase, voff) do { _Pragma("unroll") for (int _i = 0; _i < 2; ++_i) \
;     __builtin_amdgcn_global_load_lds((const unsigned*)((const char*)(gbase) + (voff)[_i]), (LAS unsigned*)(lds + (bufoff) + ldsw + _i * 8192), 16, 0, 0); } while (0)
; #define PG8_LDA(dst, b, h) do { _Pragma("unroll") for (int m = 0; m < 4; ++m) _Pragma("unroll") for (int k = 0; k < 2; ++k) dst[m][k] = *(const LAS bf16x8*)(lds + PG8_SA(b, h) + aoff + m * 2048 + k * 1024); } while (0)
; #define PG8_LDB(dst, b, h) do { _Pragma("unroll") for (int n = 0; n < 2; ++n) _Pragma("unroll") for (int k = 0; k < 2; ++k) dst[n][k] = *(const LAS bf16x8*)(lds + PG8_SB(b, h) + boff + n * 2048 + k * 1024); } while (0)
; #define PG8_MMA(ai, bj, At, Bt) do { __builtin_amdgcn_s_setprio(1); _Pragma("unroll") for (int m = 0; m < 4; ++m) _Pragma("unroll") for (int n = 0; n < 2; ++n) _Pragma("unroll") for (int k = 0; k < 2; ++k) \
;     acc[ai][bj][m][n] = __builtin_amdgcn_mfma_f32_16x16x32_bf16(Bt[n][k], At[m][k], acc[ai][bj][m][n], 0, 0, 0); __builtin_amdgcn_s_setprio(0); } while (0)
; #define PG8_WAIT_V(n) asm volatile("s_waitcnt vmcnt(" #n ")" ::: "memory")
; #define PG8_WAIT_L(n) asm volatile("s_waitcnt lgkmcnt(" #n ")" ::: "memory")
; #define PG8_BAR __builtin_amdgcn_s_barrier()
; #define PG8_SCHED __builtin_amdgcn_sched_barrier(0)
; template <class Epi>
; __device__ __forceinline__ void gemm_phase(LAS unsigned char* lds, const Gemm g, const StaticOrder& S, const Epi& E, int wv0) {
;     ...
;       PG8_LDB(B0, 0, 0); PG8_SCHED; PG8_LDA(At, 0, 0); PG8_STAGE(PG8_SA(1, 1), a1 + hstepA, voffA);
;       PG8_WAIT_L(8); PG8_BAR; PG8_WAIT_L(0); PG8_MMA(0, 0, At, B0); PG8_BAR; PG8_SCHED;
;       PG8_LDB(B1, 0, 1); PG8_STAGE(PG8_SB(0, 0), b2, voffB);
;       PG8_BAR; PG8_WAIT_L(0); PG8_MMA(0, 1, At, B1); PG8_BAR;
;       PG8_LDA(At, 0, 1); PG8_STAGE(PG8_SA(0, 0), a2, voffA);
;       PG8_BAR; PG8_WAIT_L(0); PG8_MMA(1, 0, At, B0); PG8_BAR; PG8_SCHED;
;       PG8_STAGE(PG8_SB(0, 1), b2 + hstepB, voffB);
;       PG8_WAIT_V(6); PG8_BAR; PG8_MMA(1, 1, At, B1); PG8_BAR;
.Lgprio5:
.LBB0_1003:
	s_add_u32 s4, s18, 0x100
	s_addc_u32 s5, s19, 0
	s_add_i32 s0, 0, 0x10000
	v_add_u32_e32 v142, s0, v219
	ds_read_b128 v[130:133], v142
	ds_read_b128 v[134:137], v142 offset:1024
	ds_read_b128 v[138:141], v142 offset:2048
	ds_read_b128 v[142:145], v142 offset:3072
	s_cmp_eq_u32 s49, 28
	s_cselect_b32 s23, s15, s5
	s_cselect_b32 s22, s14, s4
	s_cselect_b32 s21, s13, s48
	s_cselect_b32 s20, s46, s47
	v_lshl_add_u64 v[178:179], s[18:19], 0, v[200:201]
	s_add_i32 m0, s36, 0xc000
	ds_read_b128 v[146:149], v225
	ds_read_b128 v[150:153], v225 offset:1024
	ds_read_b128 v[154:157], v225 offset:2048
	ds_read_b128 v[158:161], v225 offset:3072
	ds_read_b128 v[162:165], v225 offset:4096
	ds_read_b128 v[166:169], v225 offset:5120
	ds_read_b128 v[170:173], v225 offset:6144
	ds_read_b128 v[174:177], v225 offset:7168
	global_load_lds_dwordx4 v[178:179], off
	v_lshl_add_u64 v[178:179], s[18:19], 0, v[202:203]
	s_add_i32 m0, s36, 0xe000
	s_nop 0
	global_load_lds_dwordx4 v[178:179], off
	s_waitcnt lgkmcnt(8)
	s_barrier
	s_waitcnt lgkmcnt(0)
	s_waitcnt lgkmcnt(0)
	v_mfma_f32_16x16x32_bf16 v[126:129], v[130:133], v[146:149], v[126:129]
	v_mfma_f32_16x16x32_bf16 v[122:125], v[138:141], v[146:149], v[122:125]
	v_mfma_f32_16x16x32_bf16 v[110:113], v[130:133], v[154:157], v[110:113]
	v_mfma_f32_16x16x32_bf16 v[106:109], v[138:141], v[154:157], v[106:109]
	v_mfma_f32_16x16x32_bf16 v[92:95], v[130:133], v[162:165], v[92:95]
	v_mfma_f32_16x16x32_bf16 v[88:91], v[138:141], v[162:165], v[88:91]
	v_mfma_f32_16x16x32_bf16 v[76:79], v[130:133], v[170:173], v[76:79]
	v_mfma_f32_16x16x32_bf16 v[72:75], v[138:141], v[170:173], v[72:75]
	v_mfma_f32_16x16x32_bf16 v[126:129], v[134:137], v[150:153], v[126:129]
	v_mfma_f32_16x16x32_bf16 v[122:125], v[142:145], v[150:153], v[122:125]
	v_mfma_f32_16x16x32_bf16 v[110:113], v[134:137], v[158:161], v[110:113]
	v_mfma_f32_16x16x32_bf16 v[106:109], v[142:145], v[158:161], v[106:109]
	v_mfma_f32_16x16x32_bf16 v[92:95], v[134:137], v[166:169], v[92:95]
	v_mfma_f32_16x16x32_bf16 v[88:91], v[142:145], v[166:169], v[88:91]
	v_mfma_f32_16x16x32_bf16 v[76:79], v[134:137], v[174:177], v[76:79]
	v_mfma_f32_16x16x32_bf16 v[72:75], v[142:145], v[174:177], v[72:75]
	s_barrier
	s_add_i32 s50, 0, 0x14000
	s_add_i32 s0, s0, s35
	v_add_u32_e32 v190, s50, v219
	v_lshl_add_u64 v[204:205], s[20:21], 0, v[96:97]
	s_mov_b32 m0, s0
	ds_read_b128 v[178:181], v190
	ds_read_b128 v[182:185], v190 offset:1024
	ds_read_b128 v[186:189], v190 offset:2048
	ds_read_b128 v[190:193], v190 offset:3072
	global_load_lds_dwordx4 v[204:205], off
	v_lshl_add_u64 v[206:207], s[20:21], 0, v[198:199]
	s_add_i32 m0, s0, 0x2000
	s_nop 0
	global_load_lds_dwordx4 v[206:207], off
	s_barrier
	s_waitcnt lgkmcnt(0)
	s_waitcnt lgkmcnt(0)
	v_mfma_f32_16x16x32_bf16 v[118:121], v[178:181], v[146:149], v[118:121]
	v_mfma_f32_16x16x32_bf16 v[114:117], v[186:189], v[146:149], v[114:117]
	v_mfma_f32_16x16x32_bf16 v[102:105], v[178:181], v[154:157], v[102:105]
	v_mfma_f32_16x16x32_bf16 v[98:101], v[186:189], v[154:157], v[98:101]
	v_mfma_f32_16x16x32_bf16 v[84:87], v[178:181], v[162:165], v[84:87]
	v_mfma_f32_16x16x32_bf16 v[80:83], v[186:189], v[162:165], v[80:83]
	v_mfma_f32_16x16x32_bf16 v[68:71], v[178:181], v[170:173], v[68:71]
	v_mfma_f32_16x16x32_bf16 v[64:67], v[186:189], v[170:173], v[64:67]
	v_mfma_f32_16x16x32_bf16 v[118:121], v[182:185], v[150:153], v[118:121]
	v_mfma_f32_16x16x32_bf16 v[114:117], v[190:193], v[150:153], v[114:117]
	v_mfma_f32_16x16x32_bf16 v[102:105], v[182:185], v[158:161], v[102:105]
	v_mfma_f32_16x16x32_bf16 v[98:101], v[190:193], v[158:161], v[98:101]
	v_mfma_f32_16x16x32_bf16 v[84:87], v[182:185], v[166:169], v[84:87]
	v_mfma_f32_16x16x32_bf16 v[80:83], v[190:193], v[166:169], v[80:83]
	v_mfma_f32_16x16x32_bf16 v[68:71], v[182:185], v[174:177], v[68:71]
	v_mfma_f32_16x16x32_bf16 v[64:67], v[190:193], v[174:177], v[64:67]
	s_mov_b32 m0, s36
	v_lshl_add_u64 v[208:209], s[22:23], 0, v[194:195]
	s_barrier
	ds_read_b128 v[146:149], v225 offset:16384
	ds_read_b128 v[150:153], v225 offset:17408
	ds_read_b128 v[154:157], v225 offset:18432
	ds_read_b128 v[158:161], v225 offset:19456
	ds_read_b128 v[162:165], v225 offset:20480
	ds_read_b128 v[166:169], v225 offset:21504
	ds_read_b128 v[170:173], v225 offset:22528
	ds_read_b128 v[174:177], v225 offset:23552
	global_load_lds_dwordx4 v[208:209], off
	v_lshl_add_u64 v[210:211], s[22:23], 0, v[196:197]
	s_mov_b32 m0, s37
	s_nop 0
	global_load_lds_dwordx4 v[210:211], off
	s_barrier
	s_waitcnt lgkmcnt(0)
	s_waitcnt lgkmcnt(0)
	v_mfma_f32_16x16x32_bf16 v[60:63], v[130:133], v[146:149], v[60:63]
	v_mfma_f32_16x16x32_bf16 v[56:59], v[138:141], v[146:149], v[56:59]
	v_mfma_f32_16x16x32_bf16 v[44:47], v[130:133], v[154:157], v[44:47]
	v_mfma_f32_16x16x32_bf16 v[40:43], v[138:141], v[154:157], v[40:43]
	v_mfma_f32_16x16x32_bf16 v[28:31], v[130:133], v[162:165], v[28:31]
	v_mfma_f32_16x16x32_bf16 v[24:27], v[138:141], v[162:165], v[24:27]
	v_mfma_f32_16x16x32_bf16 v[12:15], v[130:133], v[170:173], v[12:15]
	v_mfma_f32_16x16x32_bf16 v[8:11], v[138:141], v[170:173], v[8:11]
	v_mfma_f32_16x16x32_bf16 v[60:63], v[134:137], v[150:153], v[60:63]
	v_mfma_f32_16x16x32_bf16 v[56:59], v[142:145], v[150:153], v[56:59]
	v_mfma_f32_16x16x32_bf16 v[44:47], v[134:137], v[158:161], v[44:47]
	v_mfma_f32_16x16x32_bf16 v[40:43], v[142:145], v[158:161], v[40:43]
	v_mfma_f32_16x16x32_bf16 v[28:31], v[134:137], v[166:169], v[28:31]
	v_mfma_f32_16x16x32_bf16 v[24:27], v[142:145], v[166:169], v[24:27]
	v_mfma_f32_16x16x32_bf16 v[12:15], v[134:137], v[174:177], v[12:15]
	v_mfma_f32_16x16x32_bf16 v[8:11], v[142:145], v[174:177], v[8:11]
	s_barrier
; #define PG8_STAGE(bufoff, gbase, voff) do { _Pragma("unroll") for (int _i = 0; _i < 2; ++_i) \
;     __builtin_amdgcn_global_load_lds((const unsigned*)((const char*)(gbase) + (voff)[_i]), (LAS unsigned*)(lds + (bufoff) + ldsw + _i * 8192), 16, 0, 0); } while (0)
; #define PG8_LDA(dst, b, h) do { _Pragma("unroll") for (int m = 0; m < 4; ++m) _Pragma("unroll") for (int k = 0; k < 2; ++k) dst[m][k] = *(const LAS bf16x8*)(lds + PG8_SA(b, h) + aoff + m * 2048 + k * 1024); } while (0)
; #define PG8_LDB(dst, b, h) do { _Pragma("unroll") for (int n = 0; n < 2; ++n) _Pragma("unroll") for (int k = 0; k < 2; ++k) dst[n][k] = *(const LAS bf16x8*)(lds + PG8_SB(b, h) + boff + n * 2048 + k * 1024); } while (0)
; #define PG8_MMA(ai, bj, At, Bt) do { __builtin_amdgcn_s_setprio(1); _Pragma("unroll") for (int m = 0; m < 4; ++m) _Pragma("unroll") for (int n = 0; n < 2; ++n) _Pragma("unroll") for (int k = 0; k < 2; ++k) \
;     acc[ai][bj][m][n] = __builtin_amdgcn_mfma_f32_16x16x32_bf16(Bt[n][k], At[m][k], acc[ai][bj][m][n], 0, 0, 0); __builtin_amdgcn_s_setprio(0); } while (0)
; #define PG8_WAIT_V(n) asm volatile("s_waitcnt vmcnt(" #n ")" ::: "memory")
; #define PG8_WAIT_L(n) asm volatile("s_waitcnt lgkmcnt(" #n ")" ::: "memory")
; #define PG8_BAR __builtin_amdgcn_s_barrier()
; #define PG8_SCHED __builtin_amdgcn_sched_barrier(0)
; template <class Epi>
; __device__ __forceinline__ void gemm_phase(LAS unsigned char* lds, const Gemm g, const StaticOrder& S, const Epi& E, int wv0) {
;     ...
;       PG8_WAIT_V(6); PG8_BAR; PG8_MMA(1, 1, At, B1); PG8_BAR;
;       PG8_LDB(B0, 1, 0); PG8_SCHED; PG8_LDA(At, 1, 0); PG8_STAGE(PG8_SA(0, 1), a2 + hstepA, voffA);
;       PG8_WAIT_L(8); PG8_BAR; PG8_WAIT_L(0); PG8_MMA(0, 0, At, B0); PG8_BAR; PG8_SCHED;
;       PG8_LDB(B1, 1, 1); PG8_STAGE(PG8_SB(1, 0), b3, voffB);
;       PG8_BAR; PG8_WAIT_L(0); PG8_MMA(0, 1, At, B1); PG8_BAR;
;       PG8_LDA(At, 1, 1); PG8_STAGE(PG8_SA(1, 0), a3, voffA);
;       PG8_BAR; PG8_WAIT_L(0); PG8_MMA(1, 0, At, B0); PG8_BAR; PG8_SCHED;
	s_add_u32 s18, s20, 0x80000
	s_addc_u32 s19, s21, 0
	s_add_i32 s0, s50, s35
	v_lshl_add_u64 v[130:131], s[18:19], 0, v[96:97]
	s_mov_b32 m0, s0
	s_nop 0
	global_load_lds_dwordx4 v[130:131], off
	v_lshl_add_u64 v[130:131], s[18:19], 0, v[198:199]
	s_add_i32 m0, s0, 0x2000
	s_nop 0
	global_load_lds_dwordx4 v[130:131], off
	s_waitcnt vmcnt(6)
	s_barrier
	v_mfma_f32_16x16x32_bf16 v[52:55], v[178:181], v[146:149], v[52:55]
	v_mfma_f32_16x16x32_bf16 v[48:51], v[186:189], v[146:149], v[48:51]
	v_mfma_f32_16x16x32_bf16 v[36:39], v[178:181], v[154:157], v[36:39]
	v_mfma_f32_16x16x32_bf16 v[32:35], v[186:189], v[154:157], v[32:35]
	v_mfma_f32_16x16x32_bf16 v[20:23], v[178:181], v[162:165], v[20:23]
	v_mfma_f32_16x16x32_bf16 v[16:19], v[186:189], v[162:165], v[16:19]
	v_mfma_f32_16x16x32_bf16 v[4:7], v[178:181], v[170:173], v[4:7]
	v_mfma_f32_16x16x32_bf16 v[0:3], v[186:189], v[170:173], v[0:3]
	v_mfma_f32_16x16x32_bf16 v[52:55], v[182:185], v[150:153], v[52:55]
	v_mfma_f32_16x16x32_bf16 v[48:51], v[190:193], v[150:153], v[48:51]
	v_mfma_f32_16x16x32_bf16 v[36:39], v[182:185], v[158:161], v[36:39]
	v_mfma_f32_16x16x32_bf16 v[32:35], v[190:193], v[158:161], v[32:35]
	v_mfma_f32_16x16x32_bf16 v[20:23], v[182:185], v[166:169], v[20:23]
	v_mfma_f32_16x16x32_bf16 v[16:19], v[190:193], v[166:169], v[16:19]
	v_mfma_f32_16x16x32_bf16 v[4:7], v[182:185], v[174:177], v[4:7]
	v_mfma_f32_16x16x32_bf16 v[0:3], v[190:193], v[174:177], v[0:3]
	s_add_i32 s0, 0, 0x18000
	v_add_u32_e32 v142, s0, v219
	s_barrier
	ds_read_b128 v[130:133], v142
	ds_read_b128 v[134:137], v142 offset:1024
	ds_read_b128 v[138:141], v142 offset:2048
	ds_read_b128 v[142:145], v142 offset:3072
	s_add_u32 s18, s22, 0x114000
	s_addc_u32 s19, s23, 0
	s_mov_b32 m0, s38
	v_lshl_add_u64 v[178:179], s[18:19], 0, v[194:195]
	ds_read_b128 v[146:149], v225 offset:32768
	ds_read_b128 v[150:153], v225 offset:33792
	ds_read_b128 v[154:157], v225 offset:34816
	ds_read_b128 v[158:161], v225 offset:35840
	ds_read_b128 v[162:165], v225 offset:36864
	ds_read_b128 v[166:169], v225 offset:37888
	ds_read_b128 v[170:173], v225 offset:38912
	ds_read_b128 v[174:177], v225 offset:39936
	global_load_lds_dwordx4 v[178:179], off
	v_lshl_add_u64 v[178:179], s[18:19], 0, v[196:197]
	s_mov_b32 m0, s39
	s_nop 0
	global_load_lds_dwordx4 v[178:179], off
	s_waitcnt lgkmcnt(8)
	s_barrier
	s_waitcnt lgkmcnt(0)
	s_waitcnt lgkmcnt(0)
	v_mfma_f32_16x16x32_bf16 v[126:129], v[130:133], v[146:149], v[126:129]
	v_mfma_f32_16x16x32_bf16 v[122:125], v[138:141], v[146:149], v[122:125]
	v_mfma_f32_16x16x32_bf16 v[110:113], v[130:133], v[154:157], v[110:113]
	v_mfma_f32_16x16x32_bf16 v[106:109], v[138:141], v[154:157], v[106:109]
	v_mfma_f32_16x16x32_bf16 v[92:95], v[130:133], v[162:165], v[92:95]
	v_mfma_f32_16x16x32_bf16 v[88:91], v[138:141], v[162:165], v[88:91]
	v_mfma_f32_16x16x32_bf16 v[76:79], v[130:133], v[170:173], v[76:79]
	v_mfma_f32_16x16x32_bf16 v[72:75], v[138:141], v[170:173], v[72:75]
	v_mfma_f32_16x16x32_bf16 v[126:129], v[134:137], v[150:153], v[126:129]
	v_mfma_f32_16x16x32_bf16 v[122:125], v[142:145], v[150:153], v[122:125]
	v_mfma_f32_16x16x32_bf16 v[110:113], v[134:137], v[158:161], v[110:113]
	v_mfma_f32_16x16x32_bf16 v[106:109], v[142:145], v[158:161], v[106:109]
	v_mfma_f32_16x16x32_bf16 v[92:95], v[134:137], v[166:169], v[92:95]
	v_mfma_f32_16x16x32_bf16 v[88:91], v[142:145], v[166:169], v[88:91]
	v_mfma_f32_16x16x32_bf16 v[76:79], v[134:137], v[174:177], v[76:79]
	v_mfma_f32_16x16x32_bf16 v[72:75], v[142:145], v[174:177], v[72:75]
	s_barrier
	s_add_i32 s22, 0, 0x1c000
	s_add_i32 s0, s0, s35
	v_add_u32_e32 v190, s22, v219
	v_lshl_add_u64 v[204:205], v[204:205], 0, s[72:73]
	s_mov_b32 m0, s0
	ds_read_b128 v[178:181], v190
	ds_read_b128 v[182:185], v190 offset:1024
	ds_read_b128 v[186:189], v190 offset:2048
	ds_read_b128 v[190:193], v190 offset:3072
	global_load_lds_dwordx4 v[204:205], off
	v_lshl_add_u64 v[204:205], v[206:207], 0, s[72:73]
	s_add_i32 m0, s0, 0x2000
	s_nop 0
	global_load_lds_dwordx4 v[204:205], off
	s_barrier
	s_waitcnt lgkmcnt(0)
	s_waitcnt lgkmcnt(0)
	v_mfma_f32_16x16x32_bf16 v[118:121], v[178:181], v[146:149], v[118:121]
	v_mfma_f32_16x16x32_bf16 v[114:117], v[186:189], v[146:149], v[114:117]
	v_mfma_f32_16x16x32_bf16 v[102:105], v[178:181], v[154:157], v[102:105]
	v_mfma_f32_16x16x32_bf16 v[98:101], v[186:189], v[154:157], v[98:101]
	v_mfma_f32_16x16x32_bf16 v[84:87], v[178:181], v[162:165], v[84:87]
	v_mfma_f32_16x16x32_bf16 v[80:83], v[186:189], v[162:165], v[80:83]
	v_mfma_f32_16x16x32_bf16 v[68:71], v[178:181], v[170:173], v[68:71]
	v_mfma_f32_16x16x32_bf16 v[64:67], v[186:189], v[170:173], v[64:67]
	v_mfma_f32_16x16x32_bf16 v[118:121], v[182:185], v[150:153], v[118:121]
	v_mfma_f32_16x16x32_bf16 v[114:117], v[190:193], v[150:153], v[114:117]
	v_mfma_f32_16x16x32_bf16 v[102:105], v[182:185], v[158:161], v[102:105]
	v_mfma_f32_16x16x32_bf16 v[98:101], v[190:193], v[158:161], v[98:101]
	v_mfma_f32_16x16x32_bf16 v[84:87], v[182:185], v[166:169], v[84:87]
	v_mfma_f32_16x16x32_bf16 v[80:83], v[190:193], v[166:169], v[80:83]
	v_mfma_f32_16x16x32_bf16 v[68:71], v[182:185], v[174:177], v[68:71]
	v_mfma_f32_16x16x32_bf16 v[64:67], v[190:193], v[174:177], v[64:67]
	s_mov_b32 m0, s40
	v_lshl_add_u64 v[204:205], v[208:209], 0, s[72:73]
	s_barrier
	ds_read_b128 v[146:149], v225 offset:49152
	ds_read_b128 v[150:153], v225 offset:50176
	ds_read_b128 v[154:157], v225 offset:51200
	ds_read_b128 v[158:161], v225 offset:52224
	ds_read_b128 v[162:165], v225 offset:53248
	ds_read_b128 v[166:169], v225 offset:54272
	ds_read_b128 v[170:173], v225 offset:55296
	ds_read_b128 v[174:177], v225 offset:56320
	global_load_lds_dwordx4 v[204:205], off
	v_lshl_add_u64 v[204:205], v[210:211], 0, s[72:73]
	s_mov_b32 m0, s41
	s_nop 0
	global_load_lds_dwordx4 v[204:205], off
	s_barrier
; __device__ __forceinline__ float bf_lo(unsigned u) { return __uint_as_float(u << 16); }
; __device__ __forceinline__ float bf_hi(unsigned u) { return __uint_as_float(u & 0xffff0000u); }
; #define PG8_STAGE(bufoff, gbase, voff) do { _Pragma("unroll") for (int _i = 0; _i < 2; ++_i) \
;     __builtin_amdgcn_global_load_lds((const unsigned*)((const char*)(gbase) + (voff)[_i]), (LAS unsigned*)(lds + (bufoff) + ldsw + _i * 8192), 16, 0, 0); } while (0)
; #define PG8_MMA(ai, bj, At, Bt) do { __builtin_amdgcn_s_setprio(1); _Pragma("unroll") for (int m = 0; m < 4; ++m) _Pragma("unroll") for (int n = 0; n < 2; ++n) _Pragma("unroll") for (int k = 0; k < 2; ++k) \
;     acc[ai][bj][m][n] = __builtin_amdgcn_mfma_f32_16x16x32_bf16(Bt[n][k], At[m][k], acc[ai][bj][m][n], 0, 0, 0); __builtin_amdgcn_s_setprio(0); } while (0)
; #define PG8_WAIT_V(n) asm volatile("s_waitcnt vmcnt(" #n ")" ::: "memory")
; #define PG8_BAR __builtin_amdgcn_s_barrier()
; template <class Epi>
; __device__ __forceinline__ void gemm_phase(LAS unsigned char* lds, const Gemm g, const StaticOrder& S, const Epi& E, int wv0) {
;     ...
;       PG8_STAGE(PG8_SB(1, 1), b3 + hstepB, voffB);
;       PG8_WAIT_V(6); PG8_BAR; PG8_MMA(1, 1, At, B1); PG8_BAR;
;     }
;     E(acc, cur, wr, wc, fr, fq);
;     if (!has_next) break;
;   __device__ __forceinline__ void emit(const EpiPre& q0, int row, int col, f32x4 a, f32x4 b, const f32x4 (&hb)[2][2], const float (&hs)[2][4], int ai_, int m_, int bj_) const {
;     ...
;     } else if (MODE == E_PROJ) {
;       const int br = e.aux; const u32x4 gw = q.u0;
;       v[0] *= bf_lo(gw.x); v[1] *= bf_hi(gw.x); v[2] *= bf_lo(gw.y); v[3] *= bf_hi(gw.y);
;       v[4] *= bf_lo(gw.z); v[5] *= bf_hi(gw.z); v[6] *= bf_lo(gw.w); v[7] *= bf_hi(gw.w);
;       bf16_t* fa = (bf16_t*)e.facc + (size_t)row * DM + col;
;       if (br > 0) { const u32x4 pw = q.u1;
;         v[0] += bf_lo(pw.x); v[1] += bf_hi(pw.x); v[2] += bf_lo(pw.y); v[3] += bf_hi(pw.y); v[4] += bf_lo(pw.z); v[5] += bf_hi(pw.z); v[6] += bf_lo(pw.w); v[7] += bf_hi(pw.w); }
;       if (br == 2) store8bf((bf16_t*)e.out + (size_t)row * DM + col, v);
;       else store8bf(fa, v);
	s_waitcnt lgkmcnt(0)
	s_waitcnt lgkmcnt(0)
	v_mfma_f32_16x16x32_bf16 v[60:63], v[130:133], v[146:149], v[60:63]
	v_mfma_f32_16x16x32_bf16 v[56:59], v[138:141], v[146:149], v[56:59]
	v_mfma_f32_16x16x32_bf16 v[44:47], v[130:133], v[154:157], v[44:47]
	v_mfma_f32_16x16x32_bf16 v[40:43], v[138:141], v[154:157], v[40:43]
	v_mfma_f32_16x16x32_bf16 v[28:31], v[130:133], v[162:165], v[28:31]
	v_mfma_f32_16x16x32_bf16 v[24:27], v[138:141], v[162:165], v[24:27]
	v_mfma_f32_16x16x32_bf16 v[12:15], v[130:133], v[170:173], v[12:15]
	v_mfma_f32_16x16x32_bf16 v[8:11], v[138:141], v[170:173], v[8:11]
	v_mfma_f32_16x16x32_bf16 v[60:63], v[134:137], v[150:153], v[60:63]
	v_mfma_f32_16x16x32_bf16 v[56:59], v[142:145], v[150:153], v[56:59]
	v_mfma_f32_16x16x32_bf16 v[44:47], v[134:137], v[158:161], v[44:47]
	v_mfma_f32_16x16x32_bf16 v[40:43], v[142:145], v[158:161], v[40:43]
	v_mfma_f32_16x16x32_bf16 v[28:31], v[134:137], v[166:169], v[28:31]
	v_mfma_f32_16x16x32_bf16 v[24:27], v[142:145], v[166:169], v[24:27]
	v_mfma_f32_16x16x32_bf16 v[12:15], v[134:137], v[174:177], v[12:15]
	v_mfma_f32_16x16x32_bf16 v[8:11], v[142:145], v[174:177], v[8:11]
	s_barrier
	s_add_u32 s18, s20, 0x80080
	s_addc_u32 s19, s21, 0
	s_add_i32 s0, s22, s35
	v_lshl_add_u64 v[130:131], s[18:19], 0, v[96:97]
	s_mov_b32 m0, s0
	s_nop 0
	global_load_lds_dwordx4 v[130:131], off
	v_lshl_add_u64 v[130:131], s[18:19], 0, v[198:199]
	s_add_i32 m0, s0, 0x2000
	s_nop 0
	global_load_lds_dwordx4 v[130:131], off
	s_waitcnt vmcnt(6)
	s_barrier
	v_mfma_f32_16x16x32_bf16 v[52:55], v[178:181], v[146:149], v[52:55]
	v_mfma_f32_16x16x32_bf16 v[48:51], v[186:189], v[146:149], v[48:51]
	v_mfma_f32_16x16x32_bf16 v[36:39], v[178:181], v[154:157], v[36:39]
	v_mfma_f32_16x16x32_bf16 v[32:35], v[186:189], v[154:157], v[32:35]
	v_mfma_f32_16x16x32_bf16 v[20:23], v[178:181], v[162:165], v[20:23]
	v_mfma_f32_16x16x32_bf16 v[16:19], v[186:189], v[162:165], v[16:19]
	v_mfma_f32_16x16x32_bf16 v[4:7], v[178:181], v[170:173], v[4:7]
	v_mfma_f32_16x16x32_bf16 v[0:3], v[186:189], v[170:173], v[0:3]
	v_mfma_f32_16x16x32_bf16 v[52:55], v[182:185], v[150:153], v[52:55]
	v_mfma_f32_16x16x32_bf16 v[48:51], v[190:193], v[150:153], v[48:51]
	v_mfma_f32_16x16x32_bf16 v[36:39], v[182:185], v[158:161], v[36:39]
	v_mfma_f32_16x16x32_bf16 v[32:35], v[190:193], v[158:161], v[32:35]
	v_mfma_f32_16x16x32_bf16 v[20:23], v[182:185], v[166:169], v[20:23]
	v_mfma_f32_16x16x32_bf16 v[16:19], v[190:193], v[166:169], v[16:19]
	v_mfma_f32_16x16x32_bf16 v[4:7], v[182:185], v[174:177], v[4:7]
	v_mfma_f32_16x16x32_bf16 v[0:3], v[190:193], v[174:177], v[0:3]
	s_add_i32 s49, s49, 2
	s_add_u32 s47, s47, 0x100
	s_addc_u32 s48, s48, 0
	s_cmp_gt_u32 s49, 29
	s_mov_b64 s[18:19], s[4:5]
	s_barrier
	s_cbranch_scc0 .LBB0_1003
	v_lshl_add_u32 v209, s1, 8, v218
	v_lshl_or_b32 v211, s45, 8, v224
	v_mul_u32_u24_e32 v208, 0x3000, v209
	v_lshlrev_b32_e32 v209, 12, v209
	v_lshl_add_u32 v208, v211, 1, v208
	v_lshl_add_u32 v209, v211, 1, v209
	v_add_u32_e32 v211, 0x0, v208
	global_load_dwordx4 v[130:133], v211, s[8:9]
	v_add_u32_e32 v212, 0x0, v209
	global_load_dwordx4 v[134:137], v212, s[6:7]
	global_load_dwordx4 v[138:141], v211, s[8:9] offset:256
	global_load_dwordx4 v[142:145], v212, s[6:7] offset:256
	v_add_u32_e32 v211, 0x30000, v208
	global_load_dwordx4 v[146:149], v211, s[8:9]
	v_add_u32_e32 v212, 0x10000, v209
	global_load_dwordx4 v[150:153], v212, s[6:7]
	global_load_dwordx4 v[154:157], v211, s[8:9] offset:256
	global_load_dwordx4 v[158:161], v212, s[6:7] offset:256
	v_add_u32_e32 v211, 0x60000, v208
	global_load_dwordx4 v[162:165], v211, s[8:9]
	v_add_u32_e32 v212, 0x20000, v209
	global_load_dwordx4 v[166:169], v212, s[6:7]
	global_load_dwordx4 v[170:173], v211, s[8:9] offset:256
	global_load_dwordx4 v[174:177], v212, s[6:7] offset:256
	v_add_u32_e32 v211, 0x90000, v208
	global_load_dwordx4 v[178:181], v211, s[8:9]
	v_add_u32_e32 v212, 0x30000, v209
	global_load_dwordx4 v[182:185], v212, s[6:7]
	global_load_dwordx4 v[186:189], v211, s[8:9] offset:256
	global_load_dwordx4 v[190:193], v212, s[6:7] offset:256
	s_waitcnt vmcnt(14)
	v_lshlrev_b32_e32 v204, 16, v130
	v_and_b32_e32 v205, 0xffff0000, v130
	v_lshlrev_b32_e32 v206, 16, v134
	v_and_b32_e32 v207, 0xffff0000, v134
	v_pk_fma_f32 v[126:127], v[126:127], v[204:205], v[206:207]
	v_lshlrev_b32_e32 v204, 16, v131
	v_and_b32_e32 v205, 0xffff0000, v131
	v_lshlrev_b32_e32 v206, 16, v135
	v_and_b32_e32 v207, 0xffff0000, v135
	v_pk_fma_f32 v[128:129], v[128:129], v[204:205], v[206:207]
	v_lshlrev_b32_e32 v204, 16, v132
	v_and_b32_e32 v205, 0xffff0000, v132
	v_lshlrev_b32_e32 v206, 16, v136
	v_and_b32_e32 v207, 0xffff0000, v136
	v_pk_fma_f32 v[122:123], v[122:123], v[204:205], v[206:207]
	v_lshlrev_b32_e32 v204, 16, v133
	v_and_b32_e32 v205, 0xffff0000, v133
	v_lshlrev_b32_e32 v206, 16, v137
	v_and_b32_e32 v207, 0xffff0000, v137
	v_pk_fma_f32 v[124:125], v[124:125], v[204:205], v[206:207]
	v_cvt_pk_bf16_f32 v126, v126, v127
	v_cvt_pk_bf16_f32 v127, v128, v129
	v_cvt_pk_bf16_f32 v128, v122, v123
	v_cvt_pk_bf16_f32 v129, v124, v125
	v_add_u32_e32 v211, 0x180000, v208
	global_load_dwordx4 v[130:133], v211, s[8:9]
	v_add_u32_e32 v212, 0x80000, v209
	global_load_dwordx4 v[134:137], v212, s[6:7]
	s_waitcnt vmcnt(14)
; __device__ __forceinline__ float bf_lo(unsigned u) { return __uint_as_float(u << 16); }
; __device__ __forceinline__ float bf_hi(unsigned u) { return __uint_as_float(u & 0xffff0000u); }
;   __device__ __forceinline__ void emit(const EpiPre& q0, int row, int col, f32x4 a, f32x4 b, const f32x4 (&hb)[2][2], const float (&hs)[2][4], int ai_, int m_, int bj_) const {
;     ...
;     } else if (MODE == E_PROJ) {
;       const int br = e.aux; const u32x4 gw = q.u0;
;       v[0] *= bf_lo(gw.x); v[1] *= bf_hi(gw.x); v[2] *= bf_lo(gw.y); v[3] *= bf_hi(gw.y);
;       v[4] *= bf_lo(gw.z); v[5] *= bf_hi(gw.z); v[6] *= bf_lo(gw.w); v[7] *= bf_hi(gw.w);
;       bf16_t* fa = (bf16_t*)e.facc + (size_t)row * DM + col;
;       if (br > 0) { const u32x4 pw = q.u1;
;         v[0] += bf_lo(pw.x); v[1] += bf_hi(pw.x); v[2] += bf_lo(pw.y); v[3] += bf_hi(pw.y); v[4] += bf_lo(pw.z); v[5] += bf_hi(pw.z); v[6] += bf_lo(pw.w); v[7] += bf_hi(pw.w); }
;       if (br == 2) store8bf((bf16_t*)e.out + (size_t)row * DM + col, v);
;       else store8bf(fa, v);
	v_lshlrev_b32_e32 v204, 16, v138
	v_and_b32_e32 v205, 0xffff0000, v138
	v_lshlrev_b32_e32 v206, 16, v142
	v_and_b32_e32 v207, 0xffff0000, v142
	v_pk_fma_f32 v[118:119], v[118:119], v[204:205], v[206:207]
	v_lshlrev_b32_e32 v204, 16, v139
	v_and_b32_e32 v205, 0xffff0000, v139
	v_lshlrev_b32_e32 v206, 16, v143
	v_and_b32_e32 v207, 0xffff0000, v143
	v_pk_fma_f32 v[120:121], v[120:121], v[204:205], v[206:207]
	v_lshlrev_b32_e32 v204, 16, v140
	v_and_b32_e32 v205, 0xffff0000, v140
	v_lshlrev_b32_e32 v206, 16, v144
	v_and_b32_e32 v207, 0xffff0000, v144
	v_pk_fma_f32 v[114:115], v[114:115], v[204:205], v[206:207]
	v_lshlrev_b32_e32 v204, 16, v141
	v_and_b32_e32 v205, 0xffff0000, v141
	v_lshlrev_b32_e32 v206, 16, v145
	v_and_b32_e32 v207, 0xffff0000, v145
	v_pk_fma_f32 v[116:117], v[116:117], v[204:205], v[206:207]
	v_cvt_pk_bf16_f32 v118, v118, v119
	v_cvt_pk_bf16_f32 v119, v120, v121
	v_cvt_pk_bf16_f32 v120, v114, v115
	v_cvt_pk_bf16_f32 v121, v116, v117
	global_load_dwordx4 v[138:141], v211, s[8:9] offset:256
	global_load_dwordx4 v[142:145], v212, s[6:7] offset:256
	s_waitcnt vmcnt(14)
	v_lshlrev_b32_e32 v204, 16, v146
	v_and_b32_e32 v205, 0xffff0000, v146
	v_lshlrev_b32_e32 v206, 16, v150
	v_and_b32_e32 v207, 0xffff0000, v150
	v_pk_fma_f32 v[110:111], v[110:111], v[204:205], v[206:207]
	v_lshlrev_b32_e32 v204, 16, v147
	v_and_b32_e32 v205, 0xffff0000, v147
	v_lshlrev_b32_e32 v206, 16, v151
	v_and_b32_e32 v207, 0xffff0000, v151
	v_pk_fma_f32 v[112:113], v[112:113], v[204:205], v[206:207]
	v_lshlrev_b32_e32 v204, 16, v148
	v_and_b32_e32 v205, 0xffff0000, v148
	v_lshlrev_b32_e32 v206, 16, v152
	v_and_b32_e32 v207, 0xffff0000, v152
	v_pk_fma_f32 v[106:107], v[106:107], v[204:205], v[206:207]
	v_lshlrev_b32_e32 v204, 16, v149
	v_and_b32_e32 v205, 0xffff0000, v149
	v_lshlrev_b32_e32 v206, 16, v153
	v_and_b32_e32 v207, 0xffff0000, v153
	v_pk_fma_f32 v[108:109], v[108:109], v[204:205], v[206:207]
	v_cvt_pk_bf16_f32 v110, v110, v111
	v_cvt_pk_bf16_f32 v111, v112, v113
	v_cvt_pk_bf16_f32 v112, v106, v107
	v_cvt_pk_bf16_f32 v113, v108, v109
	v_add_u32_e32 v211, 0x1b0000, v208
	global_load_dwordx4 v[146:149], v211, s[8:9]
	v_add_u32_e32 v212, 0x90000, v209
	global_load_dwordx4 v[150:153], v212, s[6:7]
	s_waitcnt vmcnt(14)
	v_lshlrev_b32_e32 v204, 16, v154
	v_and_b32_e32 v205, 0xffff0000, v154
	v_lshlrev_b32_e32 v206, 16, v158
	v_and_b32_e32 v207, 0xffff0000, v158
	v_pk_fma_f32 v[102:103], v[102:103], v[204:205], v[206:207]
	v_lshlrev_b32_e32 v204, 16, v155
	v_and_b32_e32 v205, 0xffff0000, v155
	v_lshlrev_b32_e32 v206, 16, v159
	v_and_b32_e32 v207, 0xffff0000, v159
	v_pk_fma_f32 v[104:105], v[104:105], v[204:205], v[206:207]
	v_lshlrev_b32_e32 v204, 16, v156
	v_and_b32_e32 v205, 0xffff0000, v156
	v_lshlrev_b32_e32 v206, 16, v160
	v_and_b32_e32 v207, 0xffff0000, v160
	v_pk_fma_f32 v[98:99], v[98:99], v[204:205], v[206:207]
	v_lshlrev_b32_e32 v204, 16, v157
	v_and_b32_e32 v205, 0xffff0000, v157
	v_lshlrev_b32_e32 v206, 16, v161
	v_and_b32_e32 v207, 0xffff0000, v161
	v_pk_fma_f32 v[100:101], v[100:101], v[204:205], v[206:207]
	v_cvt_pk_bf16_f32 v102, v102, v103
	v_cvt_pk_bf16_f32 v103, v104, v105
	v_cvt_pk_bf16_f32 v104, v98, v99
	v_cvt_pk_bf16_f32 v105, v100, v101
	global_load_dwordx4 v[154:157], v211, s[8:9] offset:256
	global_load_dwordx4 v[158:161], v212, s[6:7] offset:256
	s_waitcnt vmcnt(14)
	v_lshlrev_b32_e32 v204, 16, v162
	v_and_b32_e32 v205, 0xffff0000, v162
	v_lshlrev_b32_e32 v206, 16, v166
	v_and_b32_e32 v207, 0xffff0000, v166
	v_pk_fma_f32 v[92:93], v[92:93], v[204:205], v[206:207]
	v_lshlrev_b32_e32 v204, 16, v163
	v_and_b32_e32 v205, 0xffff0000, v163
	v_lshlrev_b32_e32 v206, 16, v167
	v_and_b32_e32 v207, 0xffff0000, v167
	v_pk_fma_f32 v[94:95], v[94:95], v[204:205], v[206:207]
	v_lshlrev_b32_e32 v204, 16, v164
	v_and_b32_e32 v205, 0xffff0000, v164
	v_lshlrev_b32_e32 v206, 16, v168
	v_and_b32_e32 v207, 0xffff0000, v168
	v_pk_fma_f32 v[88:89], v[88:89], v[204:205], v[206:207]
	v_lshlrev_b32_e32 v204, 16, v165
	v_and_b32_e32 v205, 0xffff0000, v165
	v_lshlrev_b32_e32 v206, 16, v169
	v_and_b32_e32 v207, 0xffff0000, v169
	v_pk_fma_f32 v[90:91], v[90:91], v[204:205], v[206:207]
	v_cvt_pk_bf16_f32 v92, v92, v93
	v_cvt_pk_bf16_f32 v93, v94, v95
	v_cvt_pk_bf16_f32 v94, v88, v89
	v_cvt_pk_bf16_f32 v95, v90, v91
	v_add_u32_e32 v211, 0x1e0000, v208
	global_load_dwordx4 v[162:165], v211, s[8:9]
	v_add_u32_e32 v212, 0xa0000, v209
	global_load_dwordx4 v[166:169], v212, s[6:7]
	s_waitcnt vmcnt(14)
	v_lshlrev_b32_e32 v204, 16, v170
	v_and_b32_e32 v205, 0xffff0000, v170
	v_lshlrev_b32_e32 v206, 16, v174
	v_and_b32_e32 v207, 0xffff0000, v174
	v_pk_fma_f32 v[84:85], v[84:85], v[204:205], v[206:207]
	v_lshlrev_b32_e32 v204, 16, v171
	v_and_b32_e32 v205, 0xffff0000, v171
	v_lshlrev_b32_e32 v206, 16, v175
	v_and_b32_e32 v207, 0xffff0000, v175
	v_pk_fma_f32 v[86:87], v[86:87], v[204:205], v[206:207]
	v_lshlrev_b32_e32 v204, 16, v172
	v_and_b32_e32 v205, 0xffff0000, v172
	v_lshlrev_b32_e32 v206, 16, v176
	v_and_b32_e32 v207, 0xffff0000, v176
	v_pk_fma_f32 v[80:81], v[80:81], v[204:205], v[206:207]
	v_lshlrev_b32_e32 v204, 16, v173
	v_and_b32_e32 v205, 0xffff0000, v173
	v_lshlrev_b32_e32 v206, 16, v177
	v_and_b32_e32 v207, 0xffff0000, v177
	v_pk_fma_f32 v[82:83], v[82:83], v[204:205], v[206:207]
	v_cvt_pk_bf16_f32 v84, v84, v85
	v_cvt_pk_bf16_f32 v85, v86, v87
	v_cvt_pk_bf16_f32 v86, v80, v81
	v_cvt_pk_bf16_f32 v87, v82, v83
	global_load_dwordx4 v[170:173], v211, s[8:9] offset:256
	global_load_dwordx4 v[174:177], v212, s[6:7] offset:256
	s_waitcnt vmcnt(14)
; __device__ __forceinline__ float bf_lo(unsigned u) { return __uint_as_float(u << 16); }
; __device__ __forceinline__ float bf_hi(unsigned u) { return __uint_as_float(u & 0xffff0000u); }
;   __device__ __forceinline__ void emit(const EpiPre& q0, int row, int col, f32x4 a, f32x4 b, const f32x4 (&hb)[2][2], const float (&hs)[2][4], int ai_, int m_, int bj_) const {
;     ...
;     } else if (MODE == E_PROJ) {
;       const int br = e.aux; const u32x4 gw = q.u0;
;       v[0] *= bf_lo(gw.x); v[1] *= bf_hi(gw.x); v[2] *= bf_lo(gw.y); v[3] *= bf_hi(gw.y);
;       v[4] *= bf_lo(gw.z); v[5] *= bf_hi(gw.z); v[6] *= bf_lo(gw.w); v[7] *= bf_hi(gw.w);
;       bf16_t* fa = (bf16_t*)e.facc + (size_t)row * DM + col;
;       if (br > 0) { const u32x4 pw = q.u1;
;         v[0] += bf_lo(pw.x); v[1] += bf_hi(pw.x); v[2] += bf_lo(pw.y); v[3] += bf_hi(pw.y); v[4] += bf_lo(pw.z); v[5] += bf_hi(pw.z); v[6] += bf_lo(pw.w); v[7] += bf_hi(pw.w); }
;       if (br == 2) store8bf((bf16_t*)e.out + (size_t)row * DM + col, v);
;       else store8bf(fa, v);
	v_lshlrev_b32_e32 v204, 16, v178
	v_and_b32_e32 v205, 0xffff0000, v178
	v_lshlrev_b32_e32 v206, 16, v182
	v_and_b32_e32 v207, 0xffff0000, v182
	v_pk_fma_f32 v[76:77], v[76:77], v[204:205], v[206:207]
	v_lshlrev_b32_e32 v204, 16, v179
	v_and_b32_e32 v205, 0xffff0000, v179
	v_lshlrev_b32_e32 v206, 16, v183
	v_and_b32_e32 v207, 0xffff0000, v183
	v_pk_fma_f32 v[78:79], v[78:79], v[204:205], v[206:207]
	v_lshlrev_b32_e32 v204, 16, v180
	v_and_b32_e32 v205, 0xffff0000, v180
	v_lshlrev_b32_e32 v206, 16, v184
	v_and_b32_e32 v207, 0xffff0000, v184
	v_pk_fma_f32 v[72:73], v[72:73], v[204:205], v[206:207]
	v_lshlrev_b32_e32 v204, 16, v181
	v_and_b32_e32 v205, 0xffff0000, v181
	v_lshlrev_b32_e32 v206, 16, v185
	v_and_b32_e32 v207, 0xffff0000, v185
	v_pk_fma_f32 v[74:75], v[74:75], v[204:205], v[206:207]
	v_cvt_pk_bf16_f32 v76, v76, v77
	v_cvt_pk_bf16_f32 v77, v78, v79
	v_cvt_pk_bf16_f32 v78, v72, v73
	v_cvt_pk_bf16_f32 v79, v74, v75
	v_add_u32_e32 v211, 0x210000, v208
	global_load_dwordx4 v[178:181], v211, s[8:9]
	v_add_u32_e32 v212, 0xb0000, v209
	global_load_dwordx4 v[182:185], v212, s[6:7]
	s_waitcnt vmcnt(14)
	v_lshlrev_b32_e32 v204, 16, v186
	v_and_b32_e32 v205, 0xffff0000, v186
	v_lshlrev_b32_e32 v206, 16, v190
	v_and_b32_e32 v207, 0xffff0000, v190
	v_pk_fma_f32 v[68:69], v[68:69], v[204:205], v[206:207]
	v_lshlrev_b32_e32 v204, 16, v187
	v_and_b32_e32 v205, 0xffff0000, v187
	v_lshlrev_b32_e32 v206, 16, v191
	v_and_b32_e32 v207, 0xffff0000, v191
	v_pk_fma_f32 v[70:71], v[70:71], v[204:205], v[206:207]
	v_lshlrev_b32_e32 v204, 16, v188
	v_and_b32_e32 v205, 0xffff0000, v188
	v_lshlrev_b32_e32 v206, 16, v192
	v_and_b32_e32 v207, 0xffff0000, v192
	v_pk_fma_f32 v[64:65], v[64:65], v[204:205], v[206:207]
	v_lshlrev_b32_e32 v204, 16, v189
	v_and_b32_e32 v205, 0xffff0000, v189
	v_lshlrev_b32_e32 v206, 16, v193
	v_and_b32_e32 v207, 0xffff0000, v193
	v_pk_fma_f32 v[66:67], v[66:67], v[204:205], v[206:207]
	v_cvt_pk_bf16_f32 v68, v68, v69
	v_cvt_pk_bf16_f32 v69, v70, v71
	v_cvt_pk_bf16_f32 v70, v64, v65
	v_cvt_pk_bf16_f32 v71, v66, v67
	global_load_dwordx4 v[186:189], v211, s[8:9] offset:256
	global_load_dwordx4 v[190:193], v212, s[6:7] offset:256
	v_add_u32_e32 v212, 0x0, v209
	global_store_dwordx4 v212, v[126:129], s[6:7]
	global_store_dwordx4 v212, v[118:121], s[6:7] offset:256
	v_add_u32_e32 v212, 0x10000, v209
	global_store_dwordx4 v212, v[110:113], s[6:7]
	global_store_dwordx4 v212, v[102:105], s[6:7] offset:256
	v_add_u32_e32 v212, 0x20000, v209
	global_store_dwordx4 v212, v[92:95], s[6:7]
	global_store_dwordx4 v212, v[84:87], s[6:7] offset:256
	v_add_u32_e32 v212, 0x30000, v209
	global_store_dwordx4 v212, v[76:79], s[6:7]
	global_store_dwordx4 v212, v[68:71], s[6:7] offset:256
	s_waitcnt vmcnt(22)
	v_lshlrev_b32_e32 v204, 16, v130
	v_and_b32_e32 v205, 0xffff0000, v130
	v_lshlrev_b32_e32 v206, 16, v134
	v_and_b32_e32 v207, 0xffff0000, v134
	v_pk_fma_f32 v[60:61], v[60:61], v[204:205], v[206:207]
	v_lshlrev_b32_e32 v204, 16, v131
	v_and_b32_e32 v205, 0xffff0000, v131
	v_lshlrev_b32_e32 v206, 16, v135
	v_and_b32_e32 v207, 0xffff0000, v135
	v_pk_fma_f32 v[62:63], v[62:63], v[204:205], v[206:207]
	v_lshlrev_b32_e32 v204, 16, v132
	v_and_b32_e32 v205, 0xffff0000, v132
	v_lshlrev_b32_e32 v206, 16, v136
	v_and_b32_e32 v207, 0xffff0000, v136
	v_pk_fma_f32 v[56:57], v[56:57], v[204:205], v[206:207]
	v_lshlrev_b32_e32 v204, 16, v133
	v_and_b32_e32 v205, 0xffff0000, v133
	v_lshlrev_b32_e32 v206, 16, v137
	v_and_b32_e32 v207, 0xffff0000, v137
	v_pk_fma_f32 v[58:59], v[58:59], v[204:205], v[206:207]
	v_cvt_pk_bf16_f32 v60, v60, v61
	v_cvt_pk_bf16_f32 v61, v62, v63
	v_cvt_pk_bf16_f32 v62, v56, v57
	v_cvt_pk_bf16_f32 v63, v58, v59
	v_add_u32_e32 v212, 0x80000, v209
	global_store_dwordx4 v212, v[60:63], s[6:7]
	s_waitcnt vmcnt(21)
	v_lshlrev_b32_e32 v204, 16, v138
	v_and_b32_e32 v205, 0xffff0000, v138
	v_lshlrev_b32_e32 v206, 16, v142
	v_and_b32_e32 v207, 0xffff0000, v142
	v_pk_fma_f32 v[52:53], v[52:53], v[204:205], v[206:207]
	v_lshlrev_b32_e32 v204, 16, v139
	v_and_b32_e32 v205, 0xffff0000, v139
	v_lshlrev_b32_e32 v206, 16, v143
	v_and_b32_e32 v207, 0xffff0000, v143
	v_pk_fma_f32 v[54:55], v[54:55], v[204:205], v[206:207]
	v_lshlrev_b32_e32 v204, 16, v140
	v_and_b32_e32 v205, 0xffff0000, v140
	v_lshlrev_b32_e32 v206, 16, v144
	v_and_b32_e32 v207, 0xffff0000, v144
	v_pk_fma_f32 v[48:49], v[48:49], v[204:205], v[206:207]
	v_lshlrev_b32_e32 v204, 16, v141
	v_and_b32_e32 v205, 0xffff0000, v141
	v_lshlrev_b32_e32 v206, 16, v145
	v_and_b32_e32 v207, 0xffff0000, v145
	v_pk_fma_f32 v[50:51], v[50:51], v[204:205], v[206:207]
	v_cvt_pk_bf16_f32 v52, v52, v53
	v_cvt_pk_bf16_f32 v53, v54, v55
	v_cvt_pk_bf16_f32 v54, v48, v49
	v_cvt_pk_bf16_f32 v55, v50, v51
	global_store_dwordx4 v212, v[52:55], s[6:7] offset:256
	s_waitcnt vmcnt(20)
	v_lshlrev_b32_e32 v204, 16, v146
	v_and_b32_e32 v205, 0xffff0000, v146
	v_lshlrev_b32_e32 v206, 16, v150
	v_and_b32_e32 v207, 0xffff0000, v150
	v_pk_fma_f32 v[44:45], v[44:45], v[204:205], v[206:207]
	v_lshlrev_b32_e32 v204, 16, v147
	v_and_b32_e32 v205, 0xffff0000, v147
	v_lshlrev_b32_e32 v206, 16, v151
	v_and_b32_e32 v207, 0xffff0000, v151
	v_pk_fma_f32 v[46:47], v[46:47], v[204:205], v[206:207]
	v_lshlrev_b32_e32 v204, 16, v148
	v_and_b32_e32 v205, 0xffff0000, v148
	v_lshlrev_b32_e32 v206, 16, v152
	v_and_b32_e32 v207, 0xffff0000, v152
	v_pk_fma_f32 v[40:41], v[40:41], v[204:205], v[206:207]
	v_lshlrev_b32_e32 v204, 16, v149
	v_and_b32_e32 v205, 0xffff0000, v149
	v_lshlrev_b32_e32 v206, 16, v153
	v_and_b32_e32 v207, 0xffff0000, v153
	v_pk_fma_f32 v[42:43], v[42:43], v[204:205], v[206:207]
	v_cvt_pk_bf16_f32 v44, v44, v45
	v_cvt_pk_bf16_f32 v45, v46, v47
	v_cvt_pk_bf16_f32 v46, v40, v41
	v_cvt_pk_bf16_f32 v47, v42, v43
	v_add_u32_e32 v212, 0x90000, v209
	global_store_dwordx4 v212, v[44:47], s[6:7]
	s_waitcnt vmcnt(19)
; __device__ __forceinline__ float bf_lo(unsigned u) { return __uint_as_float(u << 16); }
; __device__ __forceinline__ float bf_hi(unsigned u) { return __uint_as_float(u & 0xffff0000u); }
; #define PG8_WAIT_V(n) asm volatile("s_waitcnt vmcnt(" #n ")" ::: "memory")
; #define PG8_BAR __builtin_amdgcn_s_barrier()
; template <class Epi>
; __device__ __forceinline__ void gemm_phase(LAS unsigned char* lds, const Gemm g, const StaticOrder& S, const Epi& E, int wv0) {
;     ...
;     if (!has_next) break;
; #pragma unroll
;     for (int a = 0; a < 2; ++a)
; #pragma unroll
;       for (int b = 0; b < 2; ++b)
; #pragma unroll
;         for (int m = 0; m < 4; ++m)
; #pragma unroll
;           for (int n = 0; n < 2; ++n) acc[a][b][m][n] = (f32x4){0.f, 0.f, 0.f, 0.f};
;     cur = nxt; cA = nA; cB = nB; ++ui;
;   }
;   PG8_WAIT_V(0);
;   if (wr == 0) PG8_BAR;
;   PG8_BAR;
;   __device__ __forceinline__ void emit(const EpiPre& q0, int row, int col, f32x4 a, f32x4 b, const f32x4 (&hb)[2][2], const float (&hs)[2][4], int ai_, int m_, int bj_) const {
;     ...
;     } else if (MODE == E_PROJ) {
;       const int br = e.aux; const u32x4 gw = q.u0;
;       v[0] *= bf_lo(gw.x); v[1] *= bf_hi(gw.x); v[2] *= bf_lo(gw.y); v[3] *= bf_hi(gw.y);
;       v[4] *= bf_lo(gw.z); v[5] *= bf_hi(gw.z); v[6] *= bf_lo(gw.w); v[7] *= bf_hi(gw.w);
;       bf16_t* fa = (bf16_t*)e.facc + (size_t)row * DM + col;
;       if (br > 0) { const u32x4 pw = q.u1;
;         v[0] += bf_lo(pw.x); v[1] += bf_hi(pw.x); v[2] += bf_lo(pw.y); v[3] += bf_hi(pw.y); v[4] += bf_lo(pw.z); v[5] += bf_hi(pw.z); v[6] += bf_lo(pw.w); v[7] += bf_hi(pw.w); }
;       if (br == 2) store8bf((bf16_t*)e.out + (size_t)row * DM + col, v);
;       else store8bf(fa, v);
	v_lshlrev_b32_e32 v204, 16, v154
	v_and_b32_e32 v205, 0xffff0000, v154
	v_lshlrev_b32_e32 v206, 16, v158
	v_and_b32_e32 v207, 0xffff0000, v158
	v_pk_fma_f32 v[36:37], v[36:37], v[204:205], v[206:207]
	v_lshlrev_b32_e32 v204, 16, v155
	v_and_b32_e32 v205, 0xffff0000, v155
	v_lshlrev_b32_e32 v206, 16, v159
	v_and_b32_e32 v207, 0xffff0000, v159
	v_pk_fma_f32 v[38:39], v[38:39], v[204:205], v[206:207]
	v_lshlrev_b32_e32 v204, 16, v156
	v_and_b32_e32 v205, 0xffff0000, v156
	v_lshlrev_b32_e32 v206, 16, v160
	v_and_b32_e32 v207, 0xffff0000, v160
	v_pk_fma_f32 v[32:33], v[32:33], v[204:205], v[206:207]
	v_lshlrev_b32_e32 v204, 16, v157
	v_and_b32_e32 v205, 0xffff0000, v157
	v_lshlrev_b32_e32 v206, 16, v161
	v_and_b32_e32 v207, 0xffff0000, v161
	v_pk_fma_f32 v[34:35], v[34:35], v[204:205], v[206:207]
	v_cvt_pk_bf16_f32 v36, v36, v37
	v_cvt_pk_bf16_f32 v37, v38, v39
	v_cvt_pk_bf16_f32 v38, v32, v33
	v_cvt_pk_bf16_f32 v39, v34, v35
	global_store_dwordx4 v212, v[36:39], s[6:7] offset:256
	s_waitcnt vmcnt(18)
	v_lshlrev_b32_e32 v204, 16, v162
	v_and_b32_e32 v205, 0xffff0000, v162
	v_lshlrev_b32_e32 v206, 16, v166
	v_and_b32_e32 v207, 0xffff0000, v166
	v_pk_fma_f32 v[28:29], v[28:29], v[204:205], v[206:207]
	v_lshlrev_b32_e32 v204, 16, v163
	v_and_b32_e32 v205, 0xffff0000, v163
	v_lshlrev_b32_e32 v206, 16, v167
	v_and_b32_e32 v207, 0xffff0000, v167
	v_pk_fma_f32 v[30:31], v[30:31], v[204:205], v[206:207]
	v_lshlrev_b32_e32 v204, 16, v164
	v_and_b32_e32 v205, 0xffff0000, v164
	v_lshlrev_b32_e32 v206, 16, v168
	v_and_b32_e32 v207, 0xffff0000, v168
	v_pk_fma_f32 v[24:25], v[24:25], v[204:205], v[206:207]
	v_lshlrev_b32_e32 v204, 16, v165
	v_and_b32_e32 v205, 0xffff0000, v165
	v_lshlrev_b32_e32 v206, 16, v169
	v_and_b32_e32 v207, 0xffff0000, v169
	v_pk_fma_f32 v[26:27], v[26:27], v[204:205], v[206:207]
	v_cvt_pk_bf16_f32 v28, v28, v29
	v_cvt_pk_bf16_f32 v29, v30, v31
	v_cvt_pk_bf16_f32 v30, v24, v25
	v_cvt_pk_bf16_f32 v31, v26, v27
	v_add_u32_e32 v212, 0xa0000, v209
	global_store_dwordx4 v212, v[28:31], s[6:7]
	s_waitcnt vmcnt(17)
	v_lshlrev_b32_e32 v204, 16, v170
	v_and_b32_e32 v205, 0xffff0000, v170
	v_lshlrev_b32_e32 v206, 16, v174
	v_and_b32_e32 v207, 0xffff0000, v174
	v_pk_fma_f32 v[20:21], v[20:21], v[204:205], v[206:207]
	v_lshlrev_b32_e32 v204, 16, v171
	v_and_b32_e32 v205, 0xffff0000, v171
	v_lshlrev_b32_e32 v206, 16, v175
	v_and_b32_e32 v207, 0xffff0000, v175
	v_pk_fma_f32 v[22:23], v[22:23], v[204:205], v[206:207]
	v_lshlrev_b32_e32 v204, 16, v172
	v_and_b32_e32 v205, 0xffff0000, v172
	v_lshlrev_b32_e32 v206, 16, v176
	v_and_b32_e32 v207, 0xffff0000, v176
	v_pk_fma_f32 v[16:17], v[16:17], v[204:205], v[206:207]
	v_lshlrev_b32_e32 v204, 16, v173
	v_and_b32_e32 v205, 0xffff0000, v173
	v_lshlrev_b32_e32 v206, 16, v177
	v_and_b32_e32 v207, 0xffff0000, v177
	v_pk_fma_f32 v[18:19], v[18:19], v[204:205], v[206:207]
	v_cvt_pk_bf16_f32 v20, v20, v21
	v_cvt_pk_bf16_f32 v21, v22, v23
	v_cvt_pk_bf16_f32 v22, v16, v17
	v_cvt_pk_bf16_f32 v23, v18, v19
	global_store_dwordx4 v212, v[20:23], s[6:7] offset:256
	s_waitcnt vmcnt(16)
	v_lshlrev_b32_e32 v204, 16, v178
	v_and_b32_e32 v205, 0xffff0000, v178
	v_lshlrev_b32_e32 v206, 16, v182
	v_and_b32_e32 v207, 0xffff0000, v182
	v_pk_fma_f32 v[12:13], v[12:13], v[204:205], v[206:207]
	v_lshlrev_b32_e32 v204, 16, v179
	v_and_b32_e32 v205, 0xffff0000, v179
	v_lshlrev_b32_e32 v206, 16, v183
	v_and_b32_e32 v207, 0xffff0000, v183
	v_pk_fma_f32 v[14:15], v[14:15], v[204:205], v[206:207]
	v_lshlrev_b32_e32 v204, 16, v180
	v_and_b32_e32 v205, 0xffff0000, v180
	v_lshlrev_b32_e32 v206, 16, v184
	v_and_b32_e32 v207, 0xffff0000, v184
	v_pk_fma_f32 v[8:9], v[8:9], v[204:205], v[206:207]
	v_lshlrev_b32_e32 v204, 16, v181
	v_and_b32_e32 v205, 0xffff0000, v181
	v_lshlrev_b32_e32 v206, 16, v185
	v_and_b32_e32 v207, 0xffff0000, v185
	v_pk_fma_f32 v[10:11], v[10:11], v[204:205], v[206:207]
	v_cvt_pk_bf16_f32 v12, v12, v13
	v_cvt_pk_bf16_f32 v13, v14, v15
	v_cvt_pk_bf16_f32 v14, v8, v9
	v_cvt_pk_bf16_f32 v15, v10, v11
	v_add_u32_e32 v212, 0xb0000, v209
	global_store_dwordx4 v212, v[12:15], s[6:7]
	s_waitcnt vmcnt(15)
	v_lshlrev_b32_e32 v204, 16, v186
	v_and_b32_e32 v205, 0xffff0000, v186
	v_lshlrev_b32_e32 v206, 16, v190
	v_and_b32_e32 v207, 0xffff0000, v190
	v_pk_fma_f32 v[4:5], v[4:5], v[204:205], v[206:207]
	v_lshlrev_b32_e32 v204, 16, v187
	v_and_b32_e32 v205, 0xffff0000, v187
	v_lshlrev_b32_e32 v206, 16, v191
	v_and_b32_e32 v207, 0xffff0000, v191
	v_pk_fma_f32 v[6:7], v[6:7], v[204:205], v[206:207]
	v_lshlrev_b32_e32 v204, 16, v188
	v_and_b32_e32 v205, 0xffff0000, v188
	v_lshlrev_b32_e32 v206, 16, v192
	v_and_b32_e32 v207, 0xffff0000, v192
	v_pk_fma_f32 v[0:1], v[0:1], v[204:205], v[206:207]
	v_lshlrev_b32_e32 v204, 16, v189
	v_and_b32_e32 v205, 0xffff0000, v189
	v_lshlrev_b32_e32 v206, 16, v193
	v_and_b32_e32 v207, 0xffff0000, v193
	v_pk_fma_f32 v[2:3], v[2:3], v[204:205], v[206:207]
	v_cvt_pk_bf16_f32 v4, v4, v5
	v_cvt_pk_bf16_f32 v5, v6, v7
	v_cvt_pk_bf16_f32 v6, v0, v1
	v_cvt_pk_bf16_f32 v7, v2, v3
	global_store_dwordx4 v212, v[4:7], s[6:7] offset:256
	s_and_b64 vcc, exec, s[2:3]
	s_mov_b32 s45, s12
	s_mov_b64 s[20:21], s[16:17]
	s_mov_b64 s[18:19], s[14:15]
	s_mov_b32 s1, s44
	s_cbranch_vccz .LBB0_994
	s_waitcnt vmcnt(0)
	s_cmpk_gt_u32 s27, 0xff
	s_cbranch_scc1 .LBB0_1007
	s_barrier

; #define PG8_STAGE(bufoff, gbase, voff) do { _Pragma("unroll") for (int _i = 0; _i < 2; ++_i) \
;     __builtin_amdgcn_global_load_lds((const unsigned*)((const char*)(gbase) + (voff)[_i]), (LAS unsigned*)(lds + (bufoff) + ldsw + _i * 8192), 16, 0, 0); } while (0)
; #define PG8_LDA(dst, b, h) do { _Pragma("unroll") for (int m = 0; m < 4; ++m) _Pragma("unroll") for (int k = 0; k < 2; ++k) dst[m][k] = *(const LAS bf16x8*)(lds + PG8_SA(b, h) + aoff + m * 2048 + k * 1024); } while (0)
; #define PG8_LDB(dst, b, h) do { _Pragma("unroll") for (int n = 0; n < 2; ++n) _Pragma("unroll") for (int k = 0; k < 2; ++k) dst[n][k] = *(const LAS bf16x8*)(lds + PG8_SB(b, h) + boff + n * 2048 + k * 1024); } while (0)
; #define PG8_MMA(ai, bj, At, Bt) do { __builtin_amdgcn_s_setprio(1); _Pragma("unroll") for (int m = 0; m < 4; ++m) _Pragma("unroll") for (int n = 0; n < 2; ++n) _Pragma("unroll") for (int k = 0; k < 2; ++k) \
;     acc[ai][bj][m][n] = __builtin_amdgcn_mfma_f32_16x16x32_bf16(Bt[n][k], At[m][k], acc[ai][bj][m][n], 0, 0, 0); __builtin_amdgcn_s_setprio(0); } while (0)
; #define PG8_WAIT_V(n) asm volatile("s_waitcnt vmcnt(" #n ")" ::: "memory")
; #define PG8_WAIT_L(n) asm volatile("s_waitcnt lgkmcnt(" #n ")" ::: "memory")
; #define PG8_BAR __builtin_amdgcn_s_barrier()
; #define PG8_SCHED __builtin_amdgcn_sched_barrier(0)
; template <class Epi>
; __device__ __forceinline__ void gemm_phase(LAS unsigned char* lds, const Gemm g, const StaticOrder& S, const Epi& E, int wv0) {
;     ...
;       PG8_LDB(B0, 0, 0); PG8_SCHED; PG8_LDA(At, 0, 0); PG8_STAGE(PG8_SA(1, 1), a1 + hstepA, voffA);
;       PG8_WAIT_L(8); PG8_BAR; PG8_WAIT_L(0); PG8_MMA(0, 0, At, B0); PG8_BAR; PG8_SCHED;
;       PG8_LDB(B1, 0, 1); PG8_STAGE(PG8_SB(0, 0), b2, voffB);
;       PG8_BAR; PG8_WAIT_L(0); PG8_MMA(0, 1, At, B1); PG8_BAR;
;       PG8_LDA(At, 0, 1); PG8_STAGE(PG8_SA(0, 0), a2, voffA);
;       PG8_BAR; PG8_WAIT_L(0); PG8_MMA(1, 0, At, B0); PG8_BAR; PG8_SCHED;
;       PG8_STAGE(PG8_SB(0, 1), b2 + hstepB, voffB);
;       PG8_WAIT_V(6); PG8_BAR; PG8_MMA(1, 1, At, B1); PG8_BAR;
.Lgprio6:
.LBB0_1025:
	s_add_u32 s4, s20, 0x100
	s_addc_u32 s5, s21, 0
	s_add_i32 s0, 0, 0x10000
	v_add_u32_e32 v142, s0, v211
	ds_read_b128 v[130:133], v142
	ds_read_b128 v[134:137], v142 offset:1024
	ds_read_b128 v[138:141], v142 offset:2048
	ds_read_b128 v[142:145], v142 offset:3072
	s_cmp_eq_u32 s51, 12
	s_cselect_b32 s25, s17, s5
	s_cselect_b32 s24, s16, s4
	s_cselect_b32 s23, s15, s50
	s_cselect_b32 s22, s48, s49
	v_lshl_add_u64 v[178:179], s[20:21], 0, v[192:193]
	s_add_i32 m0, s38, 0xc000
	ds_read_b128 v[146:149], v213
	ds_read_b128 v[150:153], v213 offset:1024
	ds_read_b128 v[154:157], v213 offset:2048
	ds_read_b128 v[158:161], v213 offset:3072
	ds_read_b128 v[162:165], v213 offset:4096
	ds_read_b128 v[166:169], v213 offset:5120
	ds_read_b128 v[170:173], v213 offset:6144
	ds_read_b128 v[174:177], v213 offset:7168
	global_load_lds_dwordx4 v[178:179], off
	v_lshl_add_u64 v[178:179], s[20:21], 0, v[194:195]
	s_add_i32 m0, s38, 0xe000
	s_nop 0
	global_load_lds_dwordx4 v[178:179], off
	s_waitcnt lgkmcnt(8)
	s_barrier
	s_waitcnt lgkmcnt(0)
	s_waitcnt lgkmcnt(0)
	v_mfma_f32_16x16x32_bf16 v[126:129], v[130:133], v[146:149], v[126:129]
	v_mfma_f32_16x16x32_bf16 v[122:125], v[138:141], v[146:149], v[122:125]
	v_mfma_f32_16x16x32_bf16 v[110:113], v[130:133], v[154:157], v[110:113]
	v_mfma_f32_16x16x32_bf16 v[106:109], v[138:141], v[154:157], v[106:109]
	v_mfma_f32_16x16x32_bf16 v[92:95], v[130:133], v[162:165], v[92:95]
	v_mfma_f32_16x16x32_bf16 v[88:91], v[138:141], v[162:165], v[88:91]
	v_mfma_f32_16x16x32_bf16 v[76:79], v[130:133], v[170:173], v[76:79]
	v_mfma_f32_16x16x32_bf16 v[72:75], v[138:141], v[170:173], v[72:75]
	v_mfma_f32_16x16x32_bf16 v[126:129], v[134:137], v[150:153], v[126:129]
	v_mfma_f32_16x16x32_bf16 v[122:125], v[142:145], v[150:153], v[122:125]
	v_mfma_f32_16x16x32_bf16 v[110:113], v[134:137], v[158:161], v[110:113]
	v_mfma_f32_16x16x32_bf16 v[106:109], v[142:145], v[158:161], v[106:109]
	v_mfma_f32_16x16x32_bf16 v[92:95], v[134:137], v[166:169], v[92:95]
	v_mfma_f32_16x16x32_bf16 v[88:91], v[142:145], v[166:169], v[88:91]
	v_mfma_f32_16x16x32_bf16 v[76:79], v[134:137], v[174:177], v[76:79]
	v_mfma_f32_16x16x32_bf16 v[72:75], v[142:145], v[174:177], v[72:75]
	s_barrier
	s_add_i32 s52, 0, 0x14000
	s_add_i32 s0, s0, s37
	v_add_u32_e32 v200, s52, v211
	v_lshl_add_u64 v[204:205], s[22:23], 0, v[96:97]
	s_mov_b32 m0, s0
	ds_read_b128 v[178:181], v200
	ds_read_b128 v[182:185], v200 offset:1024
	ds_read_b128 v[196:199], v200 offset:2048
	ds_read_b128 v[200:203], v200 offset:3072
	global_load_lds_dwordx4 v[204:205], off
	v_lshl_add_u64 v[206:207], s[22:23], 0, v[190:191]
	s_add_i32 m0, s0, 0x2000
	s_nop 0
	global_load_lds_dwordx4 v[206:207], off
	s_barrier
	s_waitcnt lgkmcnt(0)
	s_waitcnt lgkmcnt(0)
	v_mfma_f32_16x16x32_bf16 v[118:121], v[178:181], v[146:149], v[118:121]
	v_mfma_f32_16x16x32_bf16 v[114:117], v[196:199], v[146:149], v[114:117]
	v_mfma_f32_16x16x32_bf16 v[102:105], v[178:181], v[154:157], v[102:105]
	v_mfma_f32_16x16x32_bf16 v[98:101], v[196:199], v[154:157], v[98:101]
	v_mfma_f32_16x16x32_bf16 v[84:87], v[178:181], v[162:165], v[84:87]
	v_mfma_f32_16x16x32_bf16 v[80:83], v[196:199], v[162:165], v[80:83]
	v_mfma_f32_16x16x32_bf16 v[68:71], v[178:181], v[170:173], v[68:71]
	v_mfma_f32_16x16x32_bf16 v[64:67], v[196:199], v[170:173], v[64:67]
	v_mfma_f32_16x16x32_bf16 v[118:121], v[182:185], v[150:153], v[118:121]
	v_mfma_f32_16x16x32_bf16 v[114:117], v[200:203], v[150:153], v[114:117]
	v_mfma_f32_16x16x32_bf16 v[102:105], v[182:185], v[158:161], v[102:105]
	v_mfma_f32_16x16x32_bf16 v[98:101], v[200:203], v[158:161], v[98:101]
	v_mfma_f32_16x16x32_bf16 v[84:87], v[182:185], v[166:169], v[84:87]
	v_mfma_f32_16x16x32_bf16 v[80:83], v[200:203], v[166:169], v[80:83]
	v_mfma_f32_16x16x32_bf16 v[68:71], v[182:185], v[174:177], v[68:71]
	v_mfma_f32_16x16x32_bf16 v[64:67], v[200:203], v[174:177], v[64:67]
	s_mov_b32 m0, s38
	v_lshl_add_u64 v[208:209], s[24:25], 0, v[186:187]
	s_barrier
	ds_read_b128 v[146:149], v213 offset:16384
	ds_read_b128 v[150:153], v213 offset:17408
	ds_read_b128 v[154:157], v213 offset:18432
	ds_read_b128 v[158:161], v213 offset:19456
	ds_read_b128 v[162:165], v213 offset:20480
	ds_read_b128 v[166:169], v213 offset:21504
	ds_read_b128 v[170:173], v213 offset:22528
	ds_read_b128 v[174:177], v213 offset:23552
	global_load_lds_dwordx4 v[208:209], off
	v_lshl_add_u64 v[214:215], s[24:25], 0, v[188:189]
	s_mov_b32 m0, s39
	s_nop 0
	global_load_lds_dwordx4 v[214:215], off
	s_barrier
	s_waitcnt lgkmcnt(0)
	s_waitcnt lgkmcnt(0)
	v_mfma_f32_16x16x32_bf16 v[60:63], v[130:133], v[146:149], v[60:63]
	v_mfma_f32_16x16x32_bf16 v[56:59], v[138:141], v[146:149], v[56:59]
	v_mfma_f32_16x16x32_bf16 v[44:47], v[130:133], v[154:157], v[44:47]
	v_mfma_f32_16x16x32_bf16 v[40:43], v[138:141], v[154:157], v[40:43]
	v_mfma_f32_16x16x32_bf16 v[28:31], v[130:133], v[162:165], v[28:31]
	v_mfma_f32_16x16x32_bf16 v[24:27], v[138:141], v[162:165], v[24:27]
	v_mfma_f32_16x16x32_bf16 v[12:15], v[130:133], v[170:173], v[12:15]
	v_mfma_f32_16x16x32_bf16 v[8:11], v[138:141], v[170:173], v[8:11]
	v_mfma_f32_16x16x32_bf16 v[60:63], v[134:137], v[150:153], v[60:63]
	v_mfma_f32_16x16x32_bf16 v[56:59], v[142:145], v[150:153], v[56:59]
	v_mfma_f32_16x16x32_bf16 v[44:47], v[134:137], v[158:161], v[44:47]
	v_mfma_f32_16x16x32_bf16 v[40:43], v[142:145], v[158:161], v[40:43]
	v_mfma_f32_16x16x32_bf16 v[28:31], v[134:137], v[166:169], v[28:31]
	v_mfma_f32_16x16x32_bf16 v[24:27], v[142:145], v[166:169], v[24:27]
	v_mfma_f32_16x16x32_bf16 v[12:15], v[134:137], v[174:177], v[12:15]
	v_mfma_f32_16x16x32_bf16 v[8:11], v[142:145], v[174:177], v[8:11]
	s_barrier
; #define PG8_STAGE(bufoff, gbase, voff) do { _Pragma("unroll") for (int _i = 0; _i < 2; ++_i) \
;     __builtin_amdgcn_global_load_lds((const unsigned*)((const char*)(gbase) + (voff)[_i]), (LAS unsigned*)(lds + (bufoff) + ldsw + _i * 8192), 16, 0, 0); } while (0)
; #define PG8_LDA(dst, b, h) do { _Pragma("unroll") for (int m = 0; m < 4; ++m) _Pragma("unroll") for (int k = 0; k < 2; ++k) dst[m][k] = *(const LAS bf16x8*)(lds + PG8_SA(b, h) + aoff + m * 2048 + k * 1024); } while (0)
; #define PG8_LDB(dst, b, h) do { _Pragma("unroll") for (int n = 0; n < 2; ++n) _Pragma("unroll") for (int k = 0; k < 2; ++k) dst[n][k] = *(const LAS bf16x8*)(lds + PG8_SB(b, h) + boff + n * 2048 + k * 1024); } while (0)
; #define PG8_MMA(ai, bj, At, Bt) do { __builtin_amdgcn_s_setprio(1); _Pragma("unroll") for (int m = 0; m < 4; ++m) _Pragma("unroll") for (int n = 0; n < 2; ++n) _Pragma("unroll") for (int k = 0; k < 2; ++k) \
;     acc[ai][bj][m][n] = __builtin_amdgcn_mfma_f32_16x16x32_bf16(Bt[n][k], At[m][k], acc[ai][bj][m][n], 0, 0, 0); __builtin_amdgcn_s_setprio(0); } while (0)
; #define PG8_WAIT_V(n) asm volatile("s_waitcnt vmcnt(" #n ")" ::: "memory")
; #define PG8_WAIT_L(n) asm volatile("s_waitcnt lgkmcnt(" #n ")" ::: "memory")
; #define PG8_BAR __builtin_amdgcn_s_barrier()
; #define PG8_SCHED __builtin_amdgcn_sched_barrier(0)
; template <class Epi>
; __device__ __forceinline__ void gemm_phase(LAS unsigned char* lds, const Gemm g, const StaticOrder& S, const Epi& E, int wv0) {
;     ...
;       PG8_WAIT_V(6); PG8_BAR; PG8_MMA(1, 1, At, B1); PG8_BAR;
;       PG8_LDB(B0, 1, 0); PG8_SCHED; PG8_LDA(At, 1, 0); PG8_STAGE(PG8_SA(0, 1), a2 + hstepA, voffA);
;       PG8_WAIT_L(8); PG8_BAR; PG8_WAIT_L(0); PG8_MMA(0, 0, At, B0); PG8_BAR; PG8_SCHED;
;       PG8_LDB(B1, 1, 1); PG8_STAGE(PG8_SB(1, 0), b3, voffB);
;       PG8_BAR; PG8_WAIT_L(0); PG8_MMA(0, 1, At, B1); PG8_BAR;
;       PG8_LDA(At, 1, 1); PG8_STAGE(PG8_SA(1, 0), a3, voffA);
;       PG8_BAR; PG8_WAIT_L(0); PG8_MMA(1, 0, At, B0); PG8_BAR; PG8_SCHED;
	s_add_u32 s20, s22, 0x40000
	s_addc_u32 s21, s23, 0
	s_add_i32 s0, s52, s37
	v_lshl_add_u64 v[130:131], s[20:21], 0, v[96:97]
	s_mov_b32 m0, s0
	s_nop 0
	global_load_lds_dwordx4 v[130:131], off
	v_lshl_add_u64 v[130:131], s[20:21], 0, v[190:191]
	s_add_i32 m0, s0, 0x2000
	s_nop 0
	global_load_lds_dwordx4 v[130:131], off
	s_waitcnt vmcnt(6)
	s_barrier
	v_mfma_f32_16x16x32_bf16 v[52:55], v[178:181], v[146:149], v[52:55]
	v_mfma_f32_16x16x32_bf16 v[48:51], v[196:199], v[146:149], v[48:51]
	v_mfma_f32_16x16x32_bf16 v[36:39], v[178:181], v[154:157], v[36:39]
	v_mfma_f32_16x16x32_bf16 v[32:35], v[196:199], v[154:157], v[32:35]
	v_mfma_f32_16x16x32_bf16 v[20:23], v[178:181], v[162:165], v[20:23]
	v_mfma_f32_16x16x32_bf16 v[16:19], v[196:199], v[162:165], v[16:19]
	v_mfma_f32_16x16x32_bf16 v[4:7], v[178:181], v[170:173], v[4:7]
	v_mfma_f32_16x16x32_bf16 v[0:3], v[196:199], v[170:173], v[0:3]
	v_mfma_f32_16x16x32_bf16 v[52:55], v[182:185], v[150:153], v[52:55]
	v_mfma_f32_16x16x32_bf16 v[48:51], v[200:203], v[150:153], v[48:51]
	v_mfma_f32_16x16x32_bf16 v[36:39], v[182:185], v[158:161], v[36:39]
	v_mfma_f32_16x16x32_bf16 v[32:35], v[200:203], v[158:161], v[32:35]
	v_mfma_f32_16x16x32_bf16 v[20:23], v[182:185], v[166:169], v[20:23]
	v_mfma_f32_16x16x32_bf16 v[16:19], v[200:203], v[166:169], v[16:19]
	v_mfma_f32_16x16x32_bf16 v[4:7], v[182:185], v[174:177], v[4:7]
	v_mfma_f32_16x16x32_bf16 v[0:3], v[200:203], v[174:177], v[0:3]
	s_add_i32 s0, 0, 0x18000
	v_add_u32_e32 v142, s0, v211
	s_barrier
	ds_read_b128 v[130:133], v142
	ds_read_b128 v[134:137], v142 offset:1024
	ds_read_b128 v[138:141], v142 offset:2048
	ds_read_b128 v[142:145], v142 offset:3072
	s_add_u32 s20, s24, 0x114000
	s_addc_u32 s21, s25, 0
	s_mov_b32 m0, s40
	v_lshl_add_u64 v[178:179], s[20:21], 0, v[186:187]
	ds_read_b128 v[146:149], v213 offset:32768
	ds_read_b128 v[150:153], v213 offset:33792
	ds_read_b128 v[154:157], v213 offset:34816
	ds_read_b128 v[158:161], v213 offset:35840
	ds_read_b128 v[162:165], v213 offset:36864
	ds_read_b128 v[166:169], v213 offset:37888
	ds_read_b128 v[170:173], v213 offset:38912
	ds_read_b128 v[174:177], v213 offset:39936
	global_load_lds_dwordx4 v[178:179], off
	v_lshl_add_u64 v[178:179], s[20:21], 0, v[188:189]
	s_mov_b32 m0, s41
	s_nop 0
	global_load_lds_dwordx4 v[178:179], off
	s_waitcnt lgkmcnt(8)
	s_barrier
	s_waitcnt lgkmcnt(0)
	s_waitcnt lgkmcnt(0)
	v_mfma_f32_16x16x32_bf16 v[126:129], v[130:133], v[146:149], v[126:129]
	v_mfma_f32_16x16x32_bf16 v[122:125], v[138:141], v[146:149], v[122:125]
	v_mfma_f32_16x16x32_bf16 v[110:113], v[130:133], v[154:157], v[110:113]
	v_mfma_f32_16x16x32_bf16 v[106:109], v[138:141], v[154:157], v[106:109]
	v_mfma_f32_16x16x32_bf16 v[92:95], v[130:133], v[162:165], v[92:95]
	v_mfma_f32_16x16x32_bf16 v[88:91], v[138:141], v[162:165], v[88:91]
	v_mfma_f32_16x16x32_bf16 v[76:79], v[130:133], v[170:173], v[76:79]
	v_mfma_f32_16x16x32_bf16 v[72:75], v[138:141], v[170:173], v[72:75]
	v_mfma_f32_16x16x32_bf16 v[126:129], v[134:137], v[150:153], v[126:129]
	v_mfma_f32_16x16x32_bf16 v[122:125], v[142:145], v[150:153], v[122:125]
	v_mfma_f32_16x16x32_bf16 v[110:113], v[134:137], v[158:161], v[110:113]
	v_mfma_f32_16x16x32_bf16 v[106:109], v[142:145], v[158:161], v[106:109]
	v_mfma_f32_16x16x32_bf16 v[92:95], v[134:137], v[166:169], v[92:95]
	v_mfma_f32_16x16x32_bf16 v[88:91], v[142:145], v[166:169], v[88:91]
	v_mfma_f32_16x16x32_bf16 v[76:79], v[134:137], v[174:177], v[76:79]
	v_mfma_f32_16x16x32_bf16 v[72:75], v[142:145], v[174:177], v[72:75]
	s_barrier
	s_add_i32 s24, 0, 0x1c000
	s_add_i32 s0, s0, s37
	v_add_u32_e32 v200, s24, v211
	v_lshl_add_u64 v[204:205], v[204:205], 0, s[72:73]
	s_mov_b32 m0, s0
	ds_read_b128 v[178:181], v200
	ds_read_b128 v[182:185], v200 offset:1024
	ds_read_b128 v[196:199], v200 offset:2048
	ds_read_b128 v[200:203], v200 offset:3072
	global_load_lds_dwordx4 v[204:205], off
	v_lshl_add_u64 v[204:205], v[206:207], 0, s[72:73]
	s_add_i32 m0, s0, 0x2000
	s_nop 0
	global_load_lds_dwordx4 v[204:205], off
	s_barrier
	s_waitcnt lgkmcnt(0)
	s_waitcnt lgkmcnt(0)
	v_mfma_f32_16x16x32_bf16 v[118:121], v[178:181], v[146:149], v[118:121]
	v_mfma_f32_16x16x32_bf16 v[114:117], v[196:199], v[146:149], v[114:117]
	v_mfma_f32_16x16x32_bf16 v[102:105], v[178:181], v[154:157], v[102:105]
	v_mfma_f32_16x16x32_bf16 v[98:101], v[196:199], v[154:157], v[98:101]
	v_mfma_f32_16x16x32_bf16 v[84:87], v[178:181], v[162:165], v[84:87]
	v_mfma_f32_16x16x32_bf16 v[80:83], v[196:199], v[162:165], v[80:83]
	v_mfma_f32_16x16x32_bf16 v[68:71], v[178:181], v[170:173], v[68:71]
	v_mfma_f32_16x16x32_bf16 v[64:67], v[196:199], v[170:173], v[64:67]
	v_mfma_f32_16x16x32_bf16 v[118:121], v[182:185], v[150:153], v[118:121]
	v_mfma_f32_16x16x32_bf16 v[114:117], v[200:203], v[150:153], v[114:117]
	v_mfma_f32_16x16x32_bf16 v[102:105], v[182:185], v[158:161], v[102:105]
	v_mfma_f32_16x16x32_bf16 v[98:101], v[200:203], v[158:161], v[98:101]
	v_mfma_f32_16x16x32_bf16 v[84:87], v[182:185], v[166:169], v[84:87]
	v_mfma_f32_16x16x32_bf16 v[80:83], v[200:203], v[166:169], v[80:83]
	v_mfma_f32_16x16x32_bf16 v[68:71], v[182:185], v[174:177], v[68:71]
	v_mfma_f32_16x16x32_bf16 v[64:67], v[200:203], v[174:177], v[64:67]
	s_mov_b32 m0, s42
	v_lshl_add_u64 v[204:205], v[208:209], 0, s[72:73]
	s_barrier
	ds_read_b128 v[146:149], v213 offset:49152
	ds_read_b128 v[150:153], v213 offset:50176
	ds_read_b128 v[154:157], v213 offset:51200
	ds_read_b128 v[158:161], v213 offset:52224
	ds_read_b128 v[162:165], v213 offset:53248
	ds_read_b128 v[166:169], v213 offset:54272
	ds_read_b128 v[170:173], v213 offset:55296
	ds_read_b128 v[174:177], v213 offset:56320
	global_load_lds_dwordx4 v[204:205], off
	v_lshl_add_u64 v[204:205], v[214:215], 0, s[72:73]
	s_mov_b32 m0, s43
	s_nop 0
	global_load_lds_dwordx4 v[204:205], off
	s_barrier
; __device__ __forceinline__ float bf_lo(unsigned u) { return __uint_as_float(u << 16); }
; __device__ __forceinline__ float bf_hi(unsigned u) { return __uint_as_float(u & 0xffff0000u); }
; #define PG8_STAGE(bufoff, gbase, voff) do { _Pragma("unroll") for (int _i = 0; _i < 2; ++_i) \
;     __builtin_amdgcn_global_load_lds((const unsigned*)((const char*)(gbase) + (voff)[_i]), (LAS unsigned*)(lds + (bufoff) + ldsw + _i * 8192), 16, 0, 0); } while (0)
; #define PG8_MMA(ai, bj, At, Bt) do { __builtin_amdgcn_s_setprio(1); _Pragma("unroll") for (int m = 0; m < 4; ++m) _Pragma("unroll") for (int n = 0; n < 2; ++n) _Pragma("unroll") for (int k = 0; k < 2; ++k) \
;     acc[ai][bj][m][n] = __builtin_amdgcn_mfma_f32_16x16x32_bf16(Bt[n][k], At[m][k], acc[ai][bj][m][n], 0, 0, 0); __builtin_amdgcn_s_setprio(0); } while (0)
; #define PG8_WAIT_V(n) asm volatile("s_waitcnt vmcnt(" #n ")" ::: "memory")
; #define PG8_BAR __builtin_amdgcn_s_barrier()
; template <class Epi>
; __device__ __forceinline__ void gemm_phase(LAS unsigned char* lds, const Gemm g, const StaticOrder& S, const Epi& E, int wv0) {
;     ...
;       PG8_STAGE(PG8_SB(1, 1), b3 + hstepB, voffB);
;       PG8_WAIT_V(6); PG8_BAR; PG8_MMA(1, 1, At, B1); PG8_BAR;
;     }
;     E(acc, cur, wr, wc, fr, fq);
;     if (!has_next) break;
;   __device__ __forceinline__ void emit(const EpiPre& q0, int row, int col, f32x4 a, f32x4 b, const f32x4 (&hb)[2][2], const float (&hs)[2][4], int ai_, int m_, int bj_) const {
;     ...
;     } else if (MODE == E_PROJ) {
;       const int br = e.aux; const u32x4 gw = q.u0;
;       v[0] *= bf_lo(gw.x); v[1] *= bf_hi(gw.x); v[2] *= bf_lo(gw.y); v[3] *= bf_hi(gw.y);
;       v[4] *= bf_lo(gw.z); v[5] *= bf_hi(gw.z); v[6] *= bf_lo(gw.w); v[7] *= bf_hi(gw.w);
;       bf16_t* fa = (bf16_t*)e.facc + (size_t)row * DM + col;
;       if (br > 0) { const u32x4 pw = q.u1;
;         v[0] += bf_lo(pw.x); v[1] += bf_hi(pw.x); v[2] += bf_lo(pw.y); v[3] += bf_hi(pw.y); v[4] += bf_lo(pw.z); v[5] += bf_hi(pw.z); v[6] += bf_lo(pw.w); v[7] += bf_hi(pw.w); }
;       if (br == 2) store8bf((bf16_t*)e.out + (size_t)row * DM + col, v);
;       else store8bf(fa, v);
	s_waitcnt lgkmcnt(0)
	s_waitcnt lgkmcnt(0)
	v_mfma_f32_16x16x32_bf16 v[60:63], v[130:133], v[146:149], v[60:63]
	v_mfma_f32_16x16x32_bf16 v[56:59], v[138:141], v[146:149], v[56:59]
	v_mfma_f32_16x16x32_bf16 v[44:47], v[130:133], v[154:157], v[44:47]
	v_mfma_f32_16x16x32_bf16 v[40:43], v[138:141], v[154:157], v[40:43]
	v_mfma_f32_16x16x32_bf16 v[28:31], v[130:133], v[162:165], v[28:31]
	v_mfma_f32_16x16x32_bf16 v[24:27], v[138:141], v[162:165], v[24:27]
	v_mfma_f32_16x16x32_bf16 v[12:15], v[130:133], v[170:173], v[12:15]
	v_mfma_f32_16x16x32_bf16 v[8:11], v[138:141], v[170:173], v[8:11]
	v_mfma_f32_16x16x32_bf16 v[60:63], v[134:137], v[150:153], v[60:63]
	v_mfma_f32_16x16x32_bf16 v[56:59], v[142:145], v[150:153], v[56:59]
	v_mfma_f32_16x16x32_bf16 v[44:47], v[134:137], v[158:161], v[44:47]
	v_mfma_f32_16x16x32_bf16 v[40:43], v[142:145], v[158:161], v[40:43]
	v_mfma_f32_16x16x32_bf16 v[28:31], v[134:137], v[166:169], v[28:31]
	v_mfma_f32_16x16x32_bf16 v[24:27], v[142:145], v[166:169], v[24:27]
	v_mfma_f32_16x16x32_bf16 v[12:15], v[134:137], v[174:177], v[12:15]
	v_mfma_f32_16x16x32_bf16 v[8:11], v[142:145], v[174:177], v[8:11]
	s_barrier
	s_add_u32 s20, s22, 0x40080
	s_addc_u32 s21, s23, 0
	s_add_i32 s0, s24, s37
	v_lshl_add_u64 v[130:131], s[20:21], 0, v[96:97]
	s_mov_b32 m0, s0
	s_nop 0
	global_load_lds_dwordx4 v[130:131], off
	v_lshl_add_u64 v[130:131], s[20:21], 0, v[190:191]
	s_add_i32 m0, s0, 0x2000
	s_nop 0
	global_load_lds_dwordx4 v[130:131], off
	s_waitcnt vmcnt(6)
	s_barrier
	v_mfma_f32_16x16x32_bf16 v[52:55], v[178:181], v[146:149], v[52:55]
	v_mfma_f32_16x16x32_bf16 v[48:51], v[196:199], v[146:149], v[48:51]
	v_mfma_f32_16x16x32_bf16 v[36:39], v[178:181], v[154:157], v[36:39]
	v_mfma_f32_16x16x32_bf16 v[32:35], v[196:199], v[154:157], v[32:35]
	v_mfma_f32_16x16x32_bf16 v[20:23], v[178:181], v[162:165], v[20:23]
	v_mfma_f32_16x16x32_bf16 v[16:19], v[196:199], v[162:165], v[16:19]
	v_mfma_f32_16x16x32_bf16 v[4:7], v[178:181], v[170:173], v[4:7]
	v_mfma_f32_16x16x32_bf16 v[0:3], v[196:199], v[170:173], v[0:3]
	v_mfma_f32_16x16x32_bf16 v[52:55], v[182:185], v[150:153], v[52:55]
	v_mfma_f32_16x16x32_bf16 v[48:51], v[200:203], v[150:153], v[48:51]
	v_mfma_f32_16x16x32_bf16 v[36:39], v[182:185], v[158:161], v[36:39]
	v_mfma_f32_16x16x32_bf16 v[32:35], v[200:203], v[158:161], v[32:35]
	v_mfma_f32_16x16x32_bf16 v[20:23], v[182:185], v[166:169], v[20:23]
	v_mfma_f32_16x16x32_bf16 v[16:19], v[200:203], v[166:169], v[16:19]
	v_mfma_f32_16x16x32_bf16 v[4:7], v[182:185], v[174:177], v[4:7]
	v_mfma_f32_16x16x32_bf16 v[0:3], v[200:203], v[174:177], v[0:3]
	s_add_i32 s51, s51, 2
	s_add_u32 s49, s49, 0x100
	s_addc_u32 s50, s50, 0
	s_cmp_gt_u32 s51, 13
	s_mov_b64 s[20:21], s[4:5]
	s_barrier
	s_cbranch_scc0 .LBB0_1025
	v_lshl_add_u32 v209, s1, 8, v210
	v_lshl_or_b32 v214, s47, 8, v212
	v_mul_u32_u24_e32 v208, 0x3000, v209
	v_lshlrev_b32_e32 v209, 12, v209
	v_lshl_add_u32 v208, v214, 1, v208
	v_lshl_add_u32 v209, v214, 1, v209
	v_add_u32_e32 v214, 0x0, v208
	global_load_dwordx4 v[130:133], v214, s[8:9]
	v_add_u32_e32 v215, 0x0, v209
	global_load_dwordx4 v[134:137], v215, s[6:7]
	global_load_dwordx4 v[138:141], v214, s[8:9] offset:256
	global_load_dwordx4 v[142:145], v215, s[6:7] offset:256
	v_add_u32_e32 v214, 0x30000, v208
	global_load_dwordx4 v[146:149], v214, s[8:9]
	v_add_u32_e32 v215, 0x10000, v209
	global_load_dwordx4 v[150:153], v215, s[6:7]
	global_load_dwordx4 v[154:157], v214, s[8:9] offset:256
	global_load_dwordx4 v[158:161], v215, s[6:7] offset:256
	v_add_u32_e32 v214, 0x60000, v208
	global_load_dwordx4 v[162:165], v214, s[8:9]
	v_add_u32_e32 v215, 0x20000, v209
	global_load_dwordx4 v[166:169], v215, s[6:7]
	global_load_dwordx4 v[170:173], v214, s[8:9] offset:256
	global_load_dwordx4 v[174:177], v215, s[6:7] offset:256
	v_add_u32_e32 v214, 0x90000, v208
	global_load_dwordx4 v[178:181], v214, s[8:9]
	v_add_u32_e32 v215, 0x30000, v209
	global_load_dwordx4 v[182:185], v215, s[6:7]
	global_load_dwordx4 v[196:199], v214, s[8:9] offset:256
	global_load_dwordx4 v[200:203], v215, s[6:7] offset:256
	s_waitcnt vmcnt(14)
	v_lshlrev_b32_e32 v204, 16, v130
	v_and_b32_e32 v205, 0xffff0000, v130
	v_lshlrev_b32_e32 v206, 16, v134
	v_and_b32_e32 v207, 0xffff0000, v134
	v_pk_fma_f32 v[126:127], v[126:127], v[204:205], v[206:207]
	v_lshlrev_b32_e32 v204, 16, v131
	v_and_b32_e32 v205, 0xffff0000, v131
	v_lshlrev_b32_e32 v206, 16, v135
	v_and_b32_e32 v207, 0xffff0000, v135
	v_pk_fma_f32 v[128:129], v[128:129], v[204:205], v[206:207]
	v_lshlrev_b32_e32 v204, 16, v132
	v_and_b32_e32 v205, 0xffff0000, v132
	v_lshlrev_b32_e32 v206, 16, v136
	v_and_b32_e32 v207, 0xffff0000, v136
	v_pk_fma_f32 v[122:123], v[122:123], v[204:205], v[206:207]
	v_lshlrev_b32_e32 v204, 16, v133
	v_and_b32_e32 v205, 0xffff0000, v133
	v_lshlrev_b32_e32 v206, 16, v137
	v_and_b32_e32 v207, 0xffff0000, v137
	v_pk_fma_f32 v[124:125], v[124:125], v[204:205], v[206:207]
	v_cvt_pk_bf16_f32 v126, v126, v127
	v_cvt_pk_bf16_f32 v127, v128, v129
	v_cvt_pk_bf16_f32 v128, v122, v123
	v_cvt_pk_bf16_f32 v129, v124, v125
	v_add_u32_e32 v214, 0x180000, v208
	global_load_dwordx4 v[130:133], v214, s[8:9]
	v_add_u32_e32 v215, 0x80000, v209
	global_load_dwordx4 v[134:137], v215, s[6:7]
	s_waitcnt vmcnt(14)
; __device__ __forceinline__ float bf_lo(unsigned u) { return __uint_as_float(u << 16); }
; __device__ __forceinline__ float bf_hi(unsigned u) { return __uint_as_float(u & 0xffff0000u); }
;   __device__ __forceinline__ void emit(const EpiPre& q0, int row, int col, f32x4 a, f32x4 b, const f32x4 (&hb)[2][2], const float (&hs)[2][4], int ai_, int m_, int bj_) const {
;     ...
;     } else if (MODE == E_PROJ) {
;       const int br = e.aux; const u32x4 gw = q.u0;
;       v[0] *= bf_lo(gw.x); v[1] *= bf_hi(gw.x); v[2] *= bf_lo(gw.y); v[3] *= bf_hi(gw.y);
;       v[4] *= bf_lo(gw.z); v[5] *= bf_hi(gw.z); v[6] *= bf_lo(gw.w); v[7] *= bf_hi(gw.w);
;       bf16_t* fa = (bf16_t*)e.facc + (size_t)row * DM + col;
;       if (br > 0) { const u32x4 pw = q.u1;
;         v[0] += bf_lo(pw.x); v[1] += bf_hi(pw.x); v[2] += bf_lo(pw.y); v[3] += bf_hi(pw.y); v[4] += bf_lo(pw.z); v[5] += bf_hi(pw.z); v[6] += bf_lo(pw.w); v[7] += bf_hi(pw.w); }
;       if (br == 2) store8bf((bf16_t*)e.out + (size_t)row * DM + col, v);
;       else store8bf(fa, v);
	v_lshlrev_b32_e32 v204, 16, v138
	v_and_b32_e32 v205, 0xffff0000, v138
	v_lshlrev_b32_e32 v206, 16, v142
	v_and_b32_e32 v207, 0xffff0000, v142
	v_pk_fma_f32 v[118:119], v[118:119], v[204:205], v[206:207]
	v_lshlrev_b32_e32 v204, 16, v139
	v_and_b32_e32 v205, 0xffff0000, v139
	v_lshlrev_b32_e32 v206, 16, v143
	v_and_b32_e32 v207, 0xffff0000, v143
	v_pk_fma_f32 v[120:121], v[120:121], v[204:205], v[206:207]
	v_lshlrev_b32_e32 v204, 16, v140
	v_and_b32_e32 v205, 0xffff0000, v140
	v_lshlrev_b32_e32 v206, 16, v144
	v_and_b32_e32 v207, 0xffff0000, v144
	v_pk_fma_f32 v[114:115], v[114:115], v[204:205], v[206:207]
	v_lshlrev_b32_e32 v204, 16, v141
	v_and_b32_e32 v205, 0xffff0000, v141
	v_lshlrev_b32_e32 v206, 16, v145
	v_and_b32_e32 v207, 0xffff0000, v145
	v_pk_fma_f32 v[116:117], v[116:117], v[204:205], v[206:207]
	v_cvt_pk_bf16_f32 v118, v118, v119
	v_cvt_pk_bf16_f32 v119, v120, v121
	v_cvt_pk_bf16_f32 v120, v114, v115
	v_cvt_pk_bf16_f32 v121, v116, v117
	global_load_dwordx4 v[138:141], v214, s[8:9] offset:256
	global_load_dwordx4 v[142:145], v215, s[6:7] offset:256
	s_waitcnt vmcnt(14)
	v_lshlrev_b32_e32 v204, 16, v146
	v_and_b32_e32 v205, 0xffff0000, v146
	v_lshlrev_b32_e32 v206, 16, v150
	v_and_b32_e32 v207, 0xffff0000, v150
	v_pk_fma_f32 v[110:111], v[110:111], v[204:205], v[206:207]
	v_lshlrev_b32_e32 v204, 16, v147
	v_and_b32_e32 v205, 0xffff0000, v147
	v_lshlrev_b32_e32 v206, 16, v151
	v_and_b32_e32 v207, 0xffff0000, v151
	v_pk_fma_f32 v[112:113], v[112:113], v[204:205], v[206:207]
	v_lshlrev_b32_e32 v204, 16, v148
	v_and_b32_e32 v205, 0xffff0000, v148
	v_lshlrev_b32_e32 v206, 16, v152
	v_and_b32_e32 v207, 0xffff0000, v152
	v_pk_fma_f32 v[106:107], v[106:107], v[204:205], v[206:207]
	v_lshlrev_b32_e32 v204, 16, v149
	v_and_b32_e32 v205, 0xffff0000, v149
	v_lshlrev_b32_e32 v206, 16, v153
	v_and_b32_e32 v207, 0xffff0000, v153
	v_pk_fma_f32 v[108:109], v[108:109], v[204:205], v[206:207]
	v_cvt_pk_bf16_f32 v110, v110, v111
	v_cvt_pk_bf16_f32 v111, v112, v113
	v_cvt_pk_bf16_f32 v112, v106, v107
	v_cvt_pk_bf16_f32 v113, v108, v109
	v_add_u32_e32 v214, 0x1b0000, v208
	global_load_dwordx4 v[146:149], v214, s[8:9]
	v_add_u32_e32 v215, 0x90000, v209
	global_load_dwordx4 v[150:153], v215, s[6:7]
	s_waitcnt vmcnt(14)
	v_lshlrev_b32_e32 v204, 16, v154
	v_and_b32_e32 v205, 0xffff0000, v154
	v_lshlrev_b32_e32 v206, 16, v158
	v_and_b32_e32 v207, 0xffff0000, v158
	v_pk_fma_f32 v[102:103], v[102:103], v[204:205], v[206:207]
	v_lshlrev_b32_e32 v204, 16, v155
	v_and_b32_e32 v205, 0xffff0000, v155
	v_lshlrev_b32_e32 v206, 16, v159
	v_and_b32_e32 v207, 0xffff0000, v159
	v_pk_fma_f32 v[104:105], v[104:105], v[204:205], v[206:207]
	v_lshlrev_b32_e32 v204, 16, v156
	v_and_b32_e32 v205, 0xffff0000, v156
	v_lshlrev_b32_e32 v206, 16, v160
	v_and_b32_e32 v207, 0xffff0000, v160
	v_pk_fma_f32 v[98:99], v[98:99], v[204:205], v[206:207]
	v_lshlrev_b32_e32 v204, 16, v157
	v_and_b32_e32 v205, 0xffff0000, v157
	v_lshlrev_b32_e32 v206, 16, v161
	v_and_b32_e32 v207, 0xffff0000, v161
	v_pk_fma_f32 v[100:101], v[100:101], v[204:205], v[206:207]
	v_cvt_pk_bf16_f32 v102, v102, v103
	v_cvt_pk_bf16_f32 v103, v104, v105
	v_cvt_pk_bf16_f32 v104, v98, v99
	v_cvt_pk_bf16_f32 v105, v100, v101
	global_load_dwordx4 v[154:157], v214, s[8:9] offset:256
	global_load_dwordx4 v[158:161], v215, s[6:7] offset:256
	s_waitcnt vmcnt(14)
	v_lshlrev_b32_e32 v204, 16, v162
	v_and_b32_e32 v205, 0xffff0000, v162
	v_lshlrev_b32_e32 v206, 16, v166
	v_and_b32_e32 v207, 0xffff0000, v166
	v_pk_fma_f32 v[92:93], v[92:93], v[204:205], v[206:207]
	v_lshlrev_b32_e32 v204, 16, v163
	v_and_b32_e32 v205, 0xffff0000, v163
	v_lshlrev_b32_e32 v206, 16, v167
	v_and_b32_e32 v207, 0xffff0000, v167
	v_pk_fma_f32 v[94:95], v[94:95], v[204:205], v[206:207]
	v_lshlrev_b32_e32 v204, 16, v164
	v_and_b32_e32 v205, 0xffff0000, v164
	v_lshlrev_b32_e32 v206, 16, v168
	v_and_b32_e32 v207, 0xffff0000, v168
	v_pk_fma_f32 v[88:89], v[88:89], v[204:205], v[206:207]
	v_lshlrev_b32_e32 v204, 16, v165
	v_and_b32_e32 v205, 0xffff0000, v165
	v_lshlrev_b32_e32 v206, 16, v169
	v_and_b32_e32 v207, 0xffff0000, v169
	v_pk_fma_f32 v[90:91], v[90:91], v[204:205], v[206:207]
	v_cvt_pk_bf16_f32 v92, v92, v93
	v_cvt_pk_bf16_f32 v93, v94, v95
	v_cvt_pk_bf16_f32 v94, v88, v89
	v_cvt_pk_bf16_f32 v95, v90, v91
	v_add_u32_e32 v214, 0x1e0000, v208
	global_load_dwordx4 v[162:165], v214, s[8:9]
	v_add_u32_e32 v215, 0xa0000, v209
	global_load_dwordx4 v[166:169], v215, s[6:7]
	s_waitcnt vmcnt(14)
	v_lshlrev_b32_e32 v204, 16, v170
	v_and_b32_e32 v205, 0xffff0000, v170
	v_lshlrev_b32_e32 v206, 16, v174
	v_and_b32_e32 v207, 0xffff0000, v174
	v_pk_fma_f32 v[84:85], v[84:85], v[204:205], v[206:207]
	v_lshlrev_b32_e32 v204, 16, v171
	v_and_b32_e32 v205, 0xffff0000, v171
	v_lshlrev_b32_e32 v206, 16, v175
	v_and_b32_e32 v207, 0xffff0000, v175
	v_pk_fma_f32 v[86:87], v[86:87], v[204:205], v[206:207]
	v_lshlrev_b32_e32 v204, 16, v172
	v_and_b32_e32 v205, 0xffff0000, v172
	v_lshlrev_b32_e32 v206, 16, v176
	v_and_b32_e32 v207, 0xffff0000, v176
	v_pk_fma_f32 v[80:81], v[80:81], v[204:205], v[206:207]
	v_lshlrev_b32_e32 v204, 16, v173
	v_and_b32_e32 v205, 0xffff0000, v173
	v_lshlrev_b32_e32 v206, 16, v177
	v_and_b32_e32 v207, 0xffff0000, v177
	v_pk_fma_f32 v[82:83], v[82:83], v[204:205], v[206:207]
	v_cvt_pk_bf16_f32 v84, v84, v85
	v_cvt_pk_bf16_f32 v85, v86, v87
	v_cvt_pk_bf16_f32 v86, v80, v81
	v_cvt_pk_bf16_f32 v87, v82, v83
	global_load_dwordx4 v[170:173], v214, s[8:9] offset:256
	global_load_dwordx4 v[174:177], v215, s[6:7] offset:256
	s_waitcnt vmcnt(14)
; __device__ __forceinline__ float bf_lo(unsigned u) { return __uint_as_float(u << 16); }
; __device__ __forceinline__ float bf_hi(unsigned u) { return __uint_as_float(u & 0xffff0000u); }
;   __device__ __forceinline__ void emit(const EpiPre& q0, int row, int col, f32x4 a, f32x4 b, const f32x4 (&hb)[2][2], const float (&hs)[2][4], int ai_, int m_, int bj_) const {
;     ...
;     } else if (MODE == E_PROJ) {
;       const int br = e.aux; const u32x4 gw = q.u0;
;       v[0] *= bf_lo(gw.x); v[1] *= bf_hi(gw.x); v[2] *= bf_lo(gw.y); v[3] *= bf_hi(gw.y);
;       v[4] *= bf_lo(gw.z); v[5] *= bf_hi(gw.z); v[6] *= bf_lo(gw.w); v[7] *= bf_hi(gw.w);
;       bf16_t* fa = (bf16_t*)e.facc + (size_t)row * DM + col;
;       if (br > 0) { const u32x4 pw = q.u1;
;         v[0] += bf_lo(pw.x); v[1] += bf_hi(pw.x); v[2] += bf_lo(pw.y); v[3] += bf_hi(pw.y); v[4] += bf_lo(pw.z); v[5] += bf_hi(pw.z); v[6] += bf_lo(pw.w); v[7] += bf_hi(pw.w); }
;       if (br == 2) store8bf((bf16_t*)e.out + (size_t)row * DM + col, v);
;       else store8bf(fa, v);
	v_lshlrev_b32_e32 v204, 16, v178
	v_and_b32_e32 v205, 0xffff0000, v178
	v_lshlrev_b32_e32 v206, 16, v182
	v_and_b32_e32 v207, 0xffff0000, v182
	v_pk_fma_f32 v[76:77], v[76:77], v[204:205], v[206:207]
	v_lshlrev_b32_e32 v204, 16, v179
	v_and_b32_e32 v205, 0xffff0000, v179
	v_lshlrev_b32_e32 v206, 16, v183
	v_and_b32_e32 v207, 0xffff0000, v183
	v_pk_fma_f32 v[78:79], v[78:79], v[204:205], v[206:207]
	v_lshlrev_b32_e32 v204, 16, v180
	v_and_b32_e32 v205, 0xffff0000, v180
	v_lshlrev_b32_e32 v206, 16, v184
	v_and_b32_e32 v207, 0xffff0000, v184
	v_pk_fma_f32 v[72:73], v[72:73], v[204:205], v[206:207]
	v_lshlrev_b32_e32 v204, 16, v181
	v_and_b32_e32 v205, 0xffff0000, v181
	v_lshlrev_b32_e32 v206, 16, v185
	v_and_b32_e32 v207, 0xffff0000, v185
	v_pk_fma_f32 v[74:75], v[74:75], v[204:205], v[206:207]
	v_cvt_pk_bf16_f32 v76, v76, v77
	v_cvt_pk_bf16_f32 v77, v78, v79
	v_cvt_pk_bf16_f32 v78, v72, v73
	v_cvt_pk_bf16_f32 v79, v74, v75
	v_add_u32_e32 v214, 0x210000, v208
	global_load_dwordx4 v[178:181], v214, s[8:9]
	v_add_u32_e32 v215, 0xb0000, v209
	global_load_dwordx4 v[182:185], v215, s[6:7]
	s_waitcnt vmcnt(14)
	v_lshlrev_b32_e32 v204, 16, v196
	v_and_b32_e32 v205, 0xffff0000, v196
	v_lshlrev_b32_e32 v206, 16, v200
	v_and_b32_e32 v207, 0xffff0000, v200
	v_pk_fma_f32 v[68:69], v[68:69], v[204:205], v[206:207]
	v_lshlrev_b32_e32 v204, 16, v197
	v_and_b32_e32 v205, 0xffff0000, v197
	v_lshlrev_b32_e32 v206, 16, v201
	v_and_b32_e32 v207, 0xffff0000, v201
	v_pk_fma_f32 v[70:71], v[70:71], v[204:205], v[206:207]
	v_lshlrev_b32_e32 v204, 16, v198
	v_and_b32_e32 v205, 0xffff0000, v198
	v_lshlrev_b32_e32 v206, 16, v202
	v_and_b32_e32 v207, 0xffff0000, v202
	v_pk_fma_f32 v[64:65], v[64:65], v[204:205], v[206:207]
	v_lshlrev_b32_e32 v204, 16, v199
	v_and_b32_e32 v205, 0xffff0000, v199
	v_lshlrev_b32_e32 v206, 16, v203
	v_and_b32_e32 v207, 0xffff0000, v203
	v_pk_fma_f32 v[66:67], v[66:67], v[204:205], v[206:207]
	v_cvt_pk_bf16_f32 v68, v68, v69
	v_cvt_pk_bf16_f32 v69, v70, v71
	v_cvt_pk_bf16_f32 v70, v64, v65
	v_cvt_pk_bf16_f32 v71, v66, v67
	global_load_dwordx4 v[196:199], v214, s[8:9] offset:256
	global_load_dwordx4 v[200:203], v215, s[6:7] offset:256
	v_add_u32_e32 v215, 0x0, v209
	global_store_dwordx4 v215, v[126:129], s[12:13]
	global_store_dwordx4 v215, v[118:121], s[12:13] offset:256
	v_add_u32_e32 v215, 0x10000, v209
	global_store_dwordx4 v215, v[110:113], s[12:13]
	global_store_dwordx4 v215, v[102:105], s[12:13] offset:256
	v_add_u32_e32 v215, 0x20000, v209
	global_store_dwordx4 v215, v[92:95], s[12:13]
	global_store_dwordx4 v215, v[84:87], s[12:13] offset:256
	v_add_u32_e32 v215, 0x30000, v209
	global_store_dwordx4 v215, v[76:79], s[12:13]
	global_store_dwordx4 v215, v[68:71], s[12:13] offset:256
	s_waitcnt vmcnt(22)
	v_lshlrev_b32_e32 v204, 16, v130
	v_and_b32_e32 v205, 0xffff0000, v130
	v_lshlrev_b32_e32 v206, 16, v134
	v_and_b32_e32 v207, 0xffff0000, v134
	v_pk_fma_f32 v[60:61], v[60:61], v[204:205], v[206:207]
	v_lshlrev_b32_e32 v204, 16, v131
	v_and_b32_e32 v205, 0xffff0000, v131
	v_lshlrev_b32_e32 v206, 16, v135
	v_and_b32_e32 v207, 0xffff0000, v135
	v_pk_fma_f32 v[62:63], v[62:63], v[204:205], v[206:207]
	v_lshlrev_b32_e32 v204, 16, v132
	v_and_b32_e32 v205, 0xffff0000, v132
	v_lshlrev_b32_e32 v206, 16, v136
	v_and_b32_e32 v207, 0xffff0000, v136
	v_pk_fma_f32 v[56:57], v[56:57], v[204:205], v[206:207]
	v_lshlrev_b32_e32 v204, 16, v133
	v_and_b32_e32 v205, 0xffff0000, v133
	v_lshlrev_b32_e32 v206, 16, v137
	v_and_b32_e32 v207, 0xffff0000, v137
	v_pk_fma_f32 v[58:59], v[58:59], v[204:205], v[206:207]
	v_cvt_pk_bf16_f32 v60, v60, v61
	v_cvt_pk_bf16_f32 v61, v62, v63
	v_cvt_pk_bf16_f32 v62, v56, v57
	v_cvt_pk_bf16_f32 v63, v58, v59
	v_add_u32_e32 v215, 0x80000, v209
	global_store_dwordx4 v215, v[60:63], s[12:13]
	s_waitcnt vmcnt(21)
	v_lshlrev_b32_e32 v204, 16, v138
	v_and_b32_e32 v205, 0xffff0000, v138
	v_lshlrev_b32_e32 v206, 16, v142
	v_and_b32_e32 v207, 0xffff0000, v142
	v_pk_fma_f32 v[52:53], v[52:53], v[204:205], v[206:207]
	v_lshlrev_b32_e32 v204, 16, v139
	v_and_b32_e32 v205, 0xffff0000, v139
	v_lshlrev_b32_e32 v206, 16, v143
	v_and_b32_e32 v207, 0xffff0000, v143
	v_pk_fma_f32 v[54:55], v[54:55], v[204:205], v[206:207]
	v_lshlrev_b32_e32 v204, 16, v140
	v_and_b32_e32 v205, 0xffff0000, v140
	v_lshlrev_b32_e32 v206, 16, v144
	v_and_b32_e32 v207, 0xffff0000, v144
	v_pk_fma_f32 v[48:49], v[48:49], v[204:205], v[206:207]
	v_lshlrev_b32_e32 v204, 16, v141
	v_and_b32_e32 v205, 0xffff0000, v141
	v_lshlrev_b32_e32 v206, 16, v145
	v_and_b32_e32 v207, 0xffff0000, v145
	v_pk_fma_f32 v[50:51], v[50:51], v[204:205], v[206:207]
	v_cvt_pk_bf16_f32 v52, v52, v53
	v_cvt_pk_bf16_f32 v53, v54, v55
	v_cvt_pk_bf16_f32 v54, v48, v49
	v_cvt_pk_bf16_f32 v55, v50, v51
	global_store_dwordx4 v215, v[52:55], s[12:13] offset:256
	s_waitcnt vmcnt(20)
	v_lshlrev_b32_e32 v204, 16, v146
	v_and_b32_e32 v205, 0xffff0000, v146
	v_lshlrev_b32_e32 v206, 16, v150
	v_and_b32_e32 v207, 0xffff0000, v150
	v_pk_fma_f32 v[44:45], v[44:45], v[204:205], v[206:207]
	v_lshlrev_b32_e32 v204, 16, v147
	v_and_b32_e32 v205, 0xffff0000, v147
	v_lshlrev_b32_e32 v206, 16, v151
	v_and_b32_e32 v207, 0xffff0000, v151
	v_pk_fma_f32 v[46:47], v[46:47], v[204:205], v[206:207]
	v_lshlrev_b32_e32 v204, 16, v148
	v_and_b32_e32 v205, 0xffff0000, v148
	v_lshlrev_b32_e32 v206, 16, v152
	v_and_b32_e32 v207, 0xffff0000, v152
	v_pk_fma_f32 v[40:41], v[40:41], v[204:205], v[206:207]
	v_lshlrev_b32_e32 v204, 16, v149
	v_and_b32_e32 v205, 0xffff0000, v149
	v_lshlrev_b32_e32 v206, 16, v153
	v_and_b32_e32 v207, 0xffff0000, v153
	v_pk_fma_f32 v[42:43], v[42:43], v[204:205], v[206:207]
	v_cvt_pk_bf16_f32 v44, v44, v45
	v_cvt_pk_bf16_f32 v45, v46, v47
	v_cvt_pk_bf16_f32 v46, v40, v41
	v_cvt_pk_bf16_f32 v47, v42, v43
	v_add_u32_e32 v215, 0x90000, v209
	global_store_dwordx4 v215, v[44:47], s[12:13]
	s_waitcnt vmcnt(19)
; __device__ __forceinline__ float bf_lo(unsigned u) { return __uint_as_float(u << 16); }
; __device__ __forceinline__ float bf_hi(unsigned u) { return __uint_as_float(u & 0xffff0000u); }
; #define PG8_WAIT_V(n) asm volatile("s_waitcnt vmcnt(" #n ")" ::: "memory")
; #define PG8_BAR __builtin_amdgcn_s_barrier()
; template <class Epi>
; __device__ __forceinline__ void gemm_phase(LAS unsigned char* lds, const Gemm g, const StaticOrder& S, const Epi& E, int wv0) {
;     ...
;     if (!has_next) break;
; #pragma unroll
;     for (int a = 0; a < 2; ++a)
; #pragma unroll
;       for (int b = 0; b < 2; ++b)
; #pragma unroll
;         for (int m = 0; m < 4; ++m)
; #pragma unroll
;           for (int n = 0; n < 2; ++n) acc[a][b][m][n] = (f32x4){0.f, 0.f, 0.f, 0.f};
;     cur = nxt; cA = nA; cB = nB; ++ui;
;   }
;   PG8_WAIT_V(0);
;   if (wr == 0) PG8_BAR;
;   PG8_BAR;
;   __device__ __forceinline__ void emit(const EpiPre& q0, int row, int col, f32x4 a, f32x4 b, const f32x4 (&hb)[2][2], const float (&hs)[2][4], int ai_, int m_, int bj_) const {
;     ...
;     } else if (MODE == E_PROJ) {
;       const int br = e.aux; const u32x4 gw = q.u0;
;       v[0] *= bf_lo(gw.x); v[1] *= bf_hi(gw.x); v[2] *= bf_lo(gw.y); v[3] *= bf_hi(gw.y);
;       v[4] *= bf_lo(gw.z); v[5] *= bf_hi(gw.z); v[6] *= bf_lo(gw.w); v[7] *= bf_hi(gw.w);
;       bf16_t* fa = (bf16_t*)e.facc + (size_t)row * DM + col;
;       if (br > 0) { const u32x4 pw = q.u1;
;         v[0] += bf_lo(pw.x); v[1] += bf_hi(pw.x); v[2] += bf_lo(pw.y); v[3] += bf_hi(pw.y); v[4] += bf_lo(pw.z); v[5] += bf_hi(pw.z); v[6] += bf_lo(pw.w); v[7] += bf_hi(pw.w); }
;       if (br == 2) store8bf((bf16_t*)e.out + (size_t)row * DM + col, v);
;       else store8bf(fa, v);
	v_lshlrev_b32_e32 v204, 16, v154
	v_and_b32_e32 v205, 0xffff0000, v154
	v_lshlrev_b32_e32 v206, 16, v158
	v_and_b32_e32 v207, 0xffff0000, v158
	v_pk_fma_f32 v[36:37], v[36:37], v[204:205], v[206:207]
	v_lshlrev_b32_e32 v204, 16, v155
	v_and_b32_e32 v205, 0xffff0000, v155
	v_lshlrev_b32_e32 v206, 16, v159
	v_and_b32_e32 v207, 0xffff0000, v159
	v_pk_fma_f32 v[38:39], v[38:39], v[204:205], v[206:207]
	v_lshlrev_b32_e32 v204, 16, v156
	v_and_b32_e32 v205, 0xffff0000, v156
	v_lshlrev_b32_e32 v206, 16, v160
	v_and_b32_e32 v207, 0xffff0000, v160
	v_pk_fma_f32 v[32:33], v[32:33], v[204:205], v[206:207]
	v_lshlrev_b32_e32 v204, 16, v157
	v_and_b32_e32 v205, 0xffff0000, v157
	v_lshlrev_b32_e32 v206, 16, v161
	v_and_b32_e32 v207, 0xffff0000, v161
	v_pk_fma_f32 v[34:35], v[34:35], v[204:205], v[206:207]
	v_cvt_pk_bf16_f32 v36, v36, v37
	v_cvt_pk_bf16_f32 v37, v38, v39
	v_cvt_pk_bf16_f32 v38, v32, v33
	v_cvt_pk_bf16_f32 v39, v34, v35
	global_store_dwordx4 v215, v[36:39], s[12:13] offset:256
	s_waitcnt vmcnt(18)
	v_lshlrev_b32_e32 v204, 16, v162
	v_and_b32_e32 v205, 0xffff0000, v162
	v_lshlrev_b32_e32 v206, 16, v166
	v_and_b32_e32 v207, 0xffff0000, v166
	v_pk_fma_f32 v[28:29], v[28:29], v[204:205], v[206:207]
	v_lshlrev_b32_e32 v204, 16, v163
	v_and_b32_e32 v205, 0xffff0000, v163
	v_lshlrev_b32_e32 v206, 16, v167
	v_and_b32_e32 v207, 0xffff0000, v167
	v_pk_fma_f32 v[30:31], v[30:31], v[204:205], v[206:207]
	v_lshlrev_b32_e32 v204, 16, v164
	v_and_b32_e32 v205, 0xffff0000, v164
	v_lshlrev_b32_e32 v206, 16, v168
	v_and_b32_e32 v207, 0xffff0000, v168
	v_pk_fma_f32 v[24:25], v[24:25], v[204:205], v[206:207]
	v_lshlrev_b32_e32 v204, 16, v165
	v_and_b32_e32 v205, 0xffff0000, v165
	v_lshlrev_b32_e32 v206, 16, v169
	v_and_b32_e32 v207, 0xffff0000, v169
	v_pk_fma_f32 v[26:27], v[26:27], v[204:205], v[206:207]
	v_cvt_pk_bf16_f32 v28, v28, v29
	v_cvt_pk_bf16_f32 v29, v30, v31
	v_cvt_pk_bf16_f32 v30, v24, v25
	v_cvt_pk_bf16_f32 v31, v26, v27
	v_add_u32_e32 v215, 0xa0000, v209
	global_store_dwordx4 v215, v[28:31], s[12:13]
	s_waitcnt vmcnt(17)
	v_lshlrev_b32_e32 v204, 16, v170
	v_and_b32_e32 v205, 0xffff0000, v170
	v_lshlrev_b32_e32 v206, 16, v174
	v_and_b32_e32 v207, 0xffff0000, v174
	v_pk_fma_f32 v[20:21], v[20:21], v[204:205], v[206:207]
	v_lshlrev_b32_e32 v204, 16, v171
	v_and_b32_e32 v205, 0xffff0000, v171
	v_lshlrev_b32_e32 v206, 16, v175
	v_and_b32_e32 v207, 0xffff0000, v175
	v_pk_fma_f32 v[22:23], v[22:23], v[204:205], v[206:207]
	v_lshlrev_b32_e32 v204, 16, v172
	v_and_b32_e32 v205, 0xffff0000, v172
	v_lshlrev_b32_e32 v206, 16, v176
	v_and_b32_e32 v207, 0xffff0000, v176
	v_pk_fma_f32 v[16:17], v[16:17], v[204:205], v[206:207]
	v_lshlrev_b32_e32 v204, 16, v173
	v_and_b32_e32 v205, 0xffff0000, v173
	v_lshlrev_b32_e32 v206, 16, v177
	v_and_b32_e32 v207, 0xffff0000, v177
	v_pk_fma_f32 v[18:19], v[18:19], v[204:205], v[206:207]
	v_cvt_pk_bf16_f32 v20, v20, v21
	v_cvt_pk_bf16_f32 v21, v22, v23
	v_cvt_pk_bf16_f32 v22, v16, v17
	v_cvt_pk_bf16_f32 v23, v18, v19
	global_store_dwordx4 v215, v[20:23], s[12:13] offset:256
	s_waitcnt vmcnt(16)
	v_lshlrev_b32_e32 v204, 16, v178
	v_and_b32_e32 v205, 0xffff0000, v178
	v_lshlrev_b32_e32 v206, 16, v182
	v_and_b32_e32 v207, 0xffff0000, v182
	v_pk_fma_f32 v[12:13], v[12:13], v[204:205], v[206:207]
	v_lshlrev_b32_e32 v204, 16, v179
	v_and_b32_e32 v205, 0xffff0000, v179
	v_lshlrev_b32_e32 v206, 16, v183
	v_and_b32_e32 v207, 0xffff0000, v183
	v_pk_fma_f32 v[14:15], v[14:15], v[204:205], v[206:207]
	v_lshlrev_b32_e32 v204, 16, v180
	v_and_b32_e32 v205, 0xffff0000, v180
	v_lshlrev_b32_e32 v206, 16, v184
	v_and_b32_e32 v207, 0xffff0000, v184
	v_pk_fma_f32 v[8:9], v[8:9], v[204:205], v[206:207]
	v_lshlrev_b32_e32 v204, 16, v181
	v_and_b32_e32 v205, 0xffff0000, v181
	v_lshlrev_b32_e32 v206, 16, v185
	v_and_b32_e32 v207, 0xffff0000, v185
	v_pk_fma_f32 v[10:11], v[10:11], v[204:205], v[206:207]
	v_cvt_pk_bf16_f32 v12, v12, v13
	v_cvt_pk_bf16_f32 v13, v14, v15
	v_cvt_pk_bf16_f32 v14, v8, v9
	v_cvt_pk_bf16_f32 v15, v10, v11
	v_add_u32_e32 v215, 0xb0000, v209
	global_store_dwordx4 v215, v[12:15], s[12:13]
	s_waitcnt vmcnt(15)
	v_lshlrev_b32_e32 v204, 16, v196
	v_and_b32_e32 v205, 0xffff0000, v196
	v_lshlrev_b32_e32 v206, 16, v200
	v_and_b32_e32 v207, 0xffff0000, v200
	v_pk_fma_f32 v[4:5], v[4:5], v[204:205], v[206:207]
	v_lshlrev_b32_e32 v204, 16, v197
	v_and_b32_e32 v205, 0xffff0000, v197
	v_lshlrev_b32_e32 v206, 16, v201
	v_and_b32_e32 v207, 0xffff0000, v201
	v_pk_fma_f32 v[6:7], v[6:7], v[204:205], v[206:207]
	v_lshlrev_b32_e32 v204, 16, v198
	v_and_b32_e32 v205, 0xffff0000, v198
	v_lshlrev_b32_e32 v206, 16, v202
	v_and_b32_e32 v207, 0xffff0000, v202
	v_pk_fma_f32 v[0:1], v[0:1], v[204:205], v[206:207]
	v_lshlrev_b32_e32 v204, 16, v199
	v_and_b32_e32 v205, 0xffff0000, v199
	v_lshlrev_b32_e32 v206, 16, v203
	v_and_b32_e32 v207, 0xffff0000, v203
	v_pk_fma_f32 v[2:3], v[2:3], v[204:205], v[206:207]
	v_cvt_pk_bf16_f32 v4, v4, v5
	v_cvt_pk_bf16_f32 v5, v6, v7
	v_cvt_pk_bf16_f32 v6, v0, v1
	v_cvt_pk_bf16_f32 v7, v2, v3
	global_store_dwordx4 v215, v[4:7], s[12:13] offset:256
	s_mov_b32 s47, s14
	s_mov_b64 s[22:23], s[18:19]
	s_mov_b64 s[20:21], s[16:17]
	s_and_b64 vcc, exec, s[2:3]
	s_mov_b32 s1, s46
	s_cbranch_vccz .LBB0_1016
	s_waitcnt vmcnt(0)
	s_cmpk_gt_u32 s29, 0xff
	s_cbranch_scc1 .LBB0_1029
	s_barrier

; #define PG8_STAGE(bufoff, gbase, voff) do { _Pragma("unroll") for (int _i = 0; _i < 2; ++_i) \
;     __builtin_amdgcn_global_load_lds((const unsigned*)((const char*)(gbase) + (voff)[_i]), (LAS unsigned*)(lds + (bufoff) + ldsw + _i * 8192), 16, 0, 0); } while (0)
; #define PG8_LDA(dst, b, h) do { _Pragma("unroll") for (int m = 0; m < 4; ++m) _Pragma("unroll") for (int k = 0; k < 2; ++k) dst[m][k] = *(const LAS bf16x8*)(lds + PG8_SA(b, h) + aoff + m * 2048 + k * 1024); } while (0)
; #define PG8_LDB(dst, b, h) do { _Pragma("unroll") for (int n = 0; n < 2; ++n) _Pragma("unroll") for (int k = 0; k < 2; ++k) dst[n][k] = *(const LAS bf16x8*)(lds + PG8_SB(b, h) + boff + n * 2048 + k * 1024); } while (0)
; #define PG8_MMA(ai, bj, At, Bt) do { __builtin_amdgcn_s_setprio(1); _Pragma("unroll") for (int m = 0; m < 4; ++m) _Pragma("unroll") for (int n = 0; n < 2; ++n) _Pragma("unroll") for (int k = 0; k < 2; ++k) \
;     acc[ai][bj][m][n] = __builtin_amdgcn_mfma_f32_16x16x32_bf16(Bt[n][k], At[m][k], acc[ai][bj][m][n], 0, 0, 0); __builtin_amdgcn_s_setprio(0); } while (0)
; #define PG8_WAIT_V(n) asm volatile("s_waitcnt vmcnt(" #n ")" ::: "memory")
; #define PG8_WAIT_L(n) asm volatile("s_waitcnt lgkmcnt(" #n ")" ::: "memory")
; #define PG8_BAR __builtin_amdgcn_s_barrier()
; #define PG8_SCHED __builtin_amdgcn_sched_barrier(0)
; template <class Epi>
; __device__ __forceinline__ void gemm_phase(LAS unsigned char* lds, const Gemm g, const StaticOrder& S, const Epi& E, int wv0) {
;     ...
;       PG8_LDB(B0, 0, 0); PG8_SCHED; PG8_LDA(At, 0, 0); PG8_STAGE(PG8_SA(1, 1), a1 + hstepA, voffA);
;       PG8_WAIT_L(8); PG8_BAR; PG8_WAIT_L(0); PG8_MMA(0, 0, At, B0); PG8_BAR; PG8_SCHED;
;       PG8_LDB(B1, 0, 1); PG8_STAGE(PG8_SB(0, 0), b2, voffB);
;       PG8_BAR; PG8_WAIT_L(0); PG8_MMA(0, 1, At, B1); PG8_BAR;
;       PG8_LDA(At, 0, 1); PG8_STAGE(PG8_SA(0, 0), a2, voffA);
;       PG8_BAR; PG8_WAIT_L(0); PG8_MMA(1, 0, At, B0); PG8_BAR; PG8_SCHED;
;       PG8_STAGE(PG8_SB(0, 1), b2 + hstepB, voffB);
;       PG8_WAIT_V(6); PG8_BAR; PG8_MMA(1, 1, At, B1); PG8_BAR;
.Lgprio7:
.LBB0_1100:
	s_add_u32 s0, s20, 0xfff80080
	s_addc_u32 s22, s21, -1
	s_add_i32 s50, 0, 0x10000
	v_add_u32_e32 v142, s50, v185
	ds_read_b128 v[130:133], v142
	ds_read_b128 v[134:137], v142 offset:1024
	ds_read_b128 v[138:141], v142 offset:2048
	ds_read_b128 v[142:145], v142 offset:3072
	s_cmp_eq_u32 s49, 28
	s_cselect_b32 s25, s13, s22
	s_cselect_b32 s24, s45, s0
	s_cselect_b32 s23, s11, s48
	s_cselect_b32 s22, s46, s47
	v_lshl_add_u64 v[192:193], s[20:21], 0, v[168:169]
	s_add_i32 m0, s19, 0xc000
	ds_read_b128 v[146:149], v187
	ds_read_b128 v[150:153], v187 offset:1024
	ds_read_b128 v[154:157], v187 offset:2048
	ds_read_b128 v[158:161], v187 offset:3072
	ds_read_b128 v[172:175], v187 offset:4096
	ds_read_b128 v[176:179], v187 offset:5120
	ds_read_b128 v[180:183], v187 offset:6144
	ds_read_b128 v[188:191], v187 offset:7168
	global_load_lds_dwordx4 v[192:193], off
	v_lshl_add_u64 v[192:193], s[20:21], 0, v[170:171]
	s_add_i32 m0, s19, 0xe000
	s_nop 0
	global_load_lds_dwordx4 v[192:193], off
	s_waitcnt lgkmcnt(8)
	s_barrier
	s_waitcnt lgkmcnt(0)
	s_waitcnt lgkmcnt(0)
	v_mfma_f32_16x16x32_bf16 v[126:129], v[130:133], v[146:149], v[126:129]
	v_mfma_f32_16x16x32_bf16 v[122:125], v[138:141], v[146:149], v[122:125]
	v_mfma_f32_16x16x32_bf16 v[118:121], v[130:133], v[154:157], v[118:121]
	v_mfma_f32_16x16x32_bf16 v[114:117], v[138:141], v[154:157], v[114:117]
	v_mfma_f32_16x16x32_bf16 v[92:95], v[130:133], v[172:175], v[92:95]
	v_mfma_f32_16x16x32_bf16 v[88:91], v[138:141], v[172:175], v[88:91]
	v_mfma_f32_16x16x32_bf16 v[84:87], v[130:133], v[180:183], v[84:87]
	v_mfma_f32_16x16x32_bf16 v[76:79], v[138:141], v[180:183], v[76:79]
	v_mfma_f32_16x16x32_bf16 v[126:129], v[134:137], v[150:153], v[126:129]
	v_mfma_f32_16x16x32_bf16 v[122:125], v[142:145], v[150:153], v[122:125]
	v_mfma_f32_16x16x32_bf16 v[118:121], v[134:137], v[158:161], v[118:121]
	v_mfma_f32_16x16x32_bf16 v[114:117], v[142:145], v[158:161], v[114:117]
	v_mfma_f32_16x16x32_bf16 v[92:95], v[134:137], v[176:179], v[92:95]
	v_mfma_f32_16x16x32_bf16 v[88:91], v[142:145], v[176:179], v[88:91]
	v_mfma_f32_16x16x32_bf16 v[84:87], v[134:137], v[188:191], v[84:87]
	v_mfma_f32_16x16x32_bf16 v[76:79], v[142:145], v[188:191], v[76:79]
	s_barrier
	s_add_i32 s0, 0, 0x14000
	s_add_i32 s50, s50, s31
	v_add_u32_e32 v204, s0, v185
	v_lshl_add_u64 v[208:209], s[22:23], 0, v[96:97]
	s_mov_b32 m0, s50
	ds_read_b128 v[192:195], v204
	ds_read_b128 v[196:199], v204 offset:1024
	ds_read_b128 v[200:203], v204 offset:2048
	ds_read_b128 v[204:207], v204 offset:3072
	global_load_lds_dwordx4 v[208:209], off
	v_lshl_add_u64 v[210:211], s[22:23], 0, v[166:167]
	s_add_i32 m0, s50, 0x2000
	s_nop 0
	global_load_lds_dwordx4 v[210:211], off
	s_barrier
	s_waitcnt lgkmcnt(0)
	s_waitcnt lgkmcnt(0)
	v_mfma_f32_16x16x32_bf16 v[110:113], v[192:195], v[146:149], v[110:113]
	v_mfma_f32_16x16x32_bf16 v[106:109], v[200:203], v[146:149], v[106:109]
	v_mfma_f32_16x16x32_bf16 v[102:105], v[192:195], v[154:157], v[102:105]
	v_mfma_f32_16x16x32_bf16 v[98:101], v[200:203], v[154:157], v[98:101]
	v_mfma_f32_16x16x32_bf16 v[80:83], v[192:195], v[172:175], v[80:83]
	v_mfma_f32_16x16x32_bf16 v[72:75], v[200:203], v[172:175], v[72:75]
	v_mfma_f32_16x16x32_bf16 v[68:71], v[192:195], v[180:183], v[68:71]
	v_mfma_f32_16x16x32_bf16 v[64:67], v[200:203], v[180:183], v[64:67]
	v_mfma_f32_16x16x32_bf16 v[110:113], v[196:199], v[150:153], v[110:113]
	v_mfma_f32_16x16x32_bf16 v[106:109], v[204:207], v[150:153], v[106:109]
	v_mfma_f32_16x16x32_bf16 v[102:105], v[196:199], v[158:161], v[102:105]
	v_mfma_f32_16x16x32_bf16 v[98:101], v[204:207], v[158:161], v[98:101]
	v_mfma_f32_16x16x32_bf16 v[80:83], v[196:199], v[176:179], v[80:83]
	v_mfma_f32_16x16x32_bf16 v[72:75], v[204:207], v[176:179], v[72:75]
	v_mfma_f32_16x16x32_bf16 v[68:71], v[196:199], v[188:191], v[68:71]
	v_mfma_f32_16x16x32_bf16 v[64:67], v[204:207], v[188:191], v[64:67]
	s_mov_b32 m0, s19
	v_lshl_add_u64 v[212:213], s[24:25], 0, v[162:163]
	s_barrier
	ds_read_b128 v[146:149], v187 offset:16384
	ds_read_b128 v[150:153], v187 offset:17408
	ds_read_b128 v[154:157], v187 offset:18432
	ds_read_b128 v[158:161], v187 offset:19456
	ds_read_b128 v[172:175], v187 offset:20480
	ds_read_b128 v[176:179], v187 offset:21504
	ds_read_b128 v[180:183], v187 offset:22528
	ds_read_b128 v[188:191], v187 offset:23552
	global_load_lds_dwordx4 v[212:213], off
	v_lshl_add_u64 v[214:215], s[24:25], 0, v[164:165]
	s_mov_b32 m0, s38
	s_nop 0
	global_load_lds_dwordx4 v[214:215], off
	s_barrier
	s_waitcnt lgkmcnt(0)
	s_waitcnt lgkmcnt(0)
	v_mfma_f32_16x16x32_bf16 v[60:63], v[130:133], v[146:149], v[60:63]
	v_mfma_f32_16x16x32_bf16 v[56:59], v[138:141], v[146:149], v[56:59]
	v_mfma_f32_16x16x32_bf16 v[44:47], v[130:133], v[154:157], v[44:47]
	v_mfma_f32_16x16x32_bf16 v[40:43], v[138:141], v[154:157], v[40:43]
	v_mfma_f32_16x16x32_bf16 v[28:31], v[130:133], v[172:175], v[28:31]
	v_mfma_f32_16x16x32_bf16 v[24:27], v[138:141], v[172:175], v[24:27]
	v_mfma_f32_16x16x32_bf16 v[20:23], v[130:133], v[180:183], v[20:23]
	v_mfma_f32_16x16x32_bf16 v[8:11], v[138:141], v[180:183], v[8:11]
	v_mfma_f32_16x16x32_bf16 v[60:63], v[134:137], v[150:153], v[60:63]
	v_mfma_f32_16x16x32_bf16 v[56:59], v[142:145], v[150:153], v[56:59]
	v_mfma_f32_16x16x32_bf16 v[44:47], v[134:137], v[158:161], v[44:47]
	v_mfma_f32_16x16x32_bf16 v[40:43], v[142:145], v[158:161], v[40:43]
	v_mfma_f32_16x16x32_bf16 v[28:31], v[134:137], v[176:179], v[28:31]
	v_mfma_f32_16x16x32_bf16 v[24:27], v[142:145], v[176:179], v[24:27]
	v_mfma_f32_16x16x32_bf16 v[20:23], v[134:137], v[188:191], v[20:23]
	v_mfma_f32_16x16x32_bf16 v[8:11], v[142:145], v[188:191], v[8:11]
	s_barrier
; #define PG8_STAGE(bufoff, gbase, voff) do { _Pragma("unroll") for (int _i = 0; _i < 2; ++_i) \
;     __builtin_amdgcn_global_load_lds((const unsigned*)((const char*)(gbase) + (voff)[_i]), (LAS unsigned*)(lds + (bufoff) + ldsw + _i * 8192), 16, 0, 0); } while (0)
; #define PG8_LDA(dst, b, h) do { _Pragma("unroll") for (int m = 0; m < 4; ++m) _Pragma("unroll") for (int k = 0; k < 2; ++k) dst[m][k] = *(const LAS bf16x8*)(lds + PG8_SA(b, h) + aoff + m * 2048 + k * 1024); } while (0)
; #define PG8_LDB(dst, b, h) do { _Pragma("unroll") for (int n = 0; n < 2; ++n) _Pragma("unroll") for (int k = 0; k < 2; ++k) dst[n][k] = *(const LAS bf16x8*)(lds + PG8_SB(b, h) + boff + n * 2048 + k * 1024); } while (0)
; #define PG8_MMA(ai, bj, At, Bt) do { __builtin_amdgcn_s_setprio(1); _Pragma("unroll") for (int m = 0; m < 4; ++m) _Pragma("unroll") for (int n = 0; n < 2; ++n) _Pragma("unroll") for (int k = 0; k < 2; ++k) \
;     acc[ai][bj][m][n] = __builtin_amdgcn_mfma_f32_16x16x32_bf16(Bt[n][k], At[m][k], acc[ai][bj][m][n], 0, 0, 0); __builtin_amdgcn_s_setprio(0); } while (0)
; #define PG8_WAIT_V(n) asm volatile("s_waitcnt vmcnt(" #n ")" ::: "memory")
; #define PG8_WAIT_L(n) asm volatile("s_waitcnt lgkmcnt(" #n ")" ::: "memory")
; #define PG8_BAR __builtin_amdgcn_s_barrier()
; #define PG8_SCHED __builtin_amdgcn_sched_barrier(0)
; template <class Epi>
; __device__ __forceinline__ void gemm_phase(LAS unsigned char* lds, const Gemm g, const StaticOrder& S, const Epi& E, int wv0) {
;     ...
;       PG8_WAIT_V(6); PG8_BAR; PG8_MMA(1, 1, At, B1); PG8_BAR;
;       PG8_LDB(B0, 1, 0); PG8_SCHED; PG8_LDA(At, 1, 0); PG8_STAGE(PG8_SA(0, 1), a2 + hstepA, voffA);
;       PG8_WAIT_L(8); PG8_BAR; PG8_WAIT_L(0); PG8_MMA(0, 0, At, B0); PG8_BAR; PG8_SCHED;
;       PG8_LDB(B1, 1, 1); PG8_STAGE(PG8_SB(1, 0), b3, voffB);
;       PG8_BAR; PG8_WAIT_L(0); PG8_MMA(0, 1, At, B1); PG8_BAR;
;       PG8_LDA(At, 1, 1); PG8_STAGE(PG8_SA(1, 0), a3, voffA);
;       PG8_BAR; PG8_WAIT_L(0); PG8_MMA(1, 0, At, B0); PG8_BAR; PG8_SCHED;
	s_add_u32 s50, s22, 0x80000
	s_addc_u32 s51, s23, 0
	s_add_i32 s0, s0, s31
	v_lshl_add_u64 v[130:131], s[50:51], 0, v[96:97]
	s_mov_b32 m0, s0
	s_nop 0
	global_load_lds_dwordx4 v[130:131], off
	v_lshl_add_u64 v[130:131], s[50:51], 0, v[166:167]
	s_add_i32 m0, s0, 0x2000
	s_nop 0
	global_load_lds_dwordx4 v[130:131], off
	s_waitcnt vmcnt(6)
	s_barrier
	v_mfma_f32_16x16x32_bf16 v[52:55], v[192:195], v[146:149], v[52:55]
	v_mfma_f32_16x16x32_bf16 v[48:51], v[200:203], v[146:149], v[48:51]
	v_mfma_f32_16x16x32_bf16 v[36:39], v[192:195], v[154:157], v[36:39]
	v_mfma_f32_16x16x32_bf16 v[32:35], v[200:203], v[154:157], v[32:35]
	v_mfma_f32_16x16x32_bf16 v[16:19], v[192:195], v[172:175], v[16:19]
	v_mfma_f32_16x16x32_bf16 v[12:15], v[200:203], v[172:175], v[12:15]
	v_mfma_f32_16x16x32_bf16 v[4:7], v[192:195], v[180:183], v[4:7]
	v_mfma_f32_16x16x32_bf16 v[0:3], v[200:203], v[180:183], v[0:3]
	v_mfma_f32_16x16x32_bf16 v[52:55], v[196:199], v[150:153], v[52:55]
	v_mfma_f32_16x16x32_bf16 v[48:51], v[204:207], v[150:153], v[48:51]
	v_mfma_f32_16x16x32_bf16 v[36:39], v[196:199], v[158:161], v[36:39]
	v_mfma_f32_16x16x32_bf16 v[32:35], v[204:207], v[158:161], v[32:35]
	v_mfma_f32_16x16x32_bf16 v[16:19], v[196:199], v[176:179], v[16:19]
	v_mfma_f32_16x16x32_bf16 v[12:15], v[204:207], v[176:179], v[12:15]
	v_mfma_f32_16x16x32_bf16 v[4:7], v[196:199], v[188:191], v[4:7]
	v_mfma_f32_16x16x32_bf16 v[0:3], v[204:207], v[188:191], v[0:3]
	s_add_i32 s0, 0, 0x18000
	v_add_u32_e32 v142, s0, v185
	s_barrier
	ds_read_b128 v[130:133], v142
	ds_read_b128 v[134:137], v142 offset:1024
	ds_read_b128 v[138:141], v142 offset:2048
	ds_read_b128 v[142:145], v142 offset:3072
	s_add_u32 s24, s24, 0x80000
	s_addc_u32 s25, s25, 0
	s_mov_b32 m0, s39
	v_lshl_add_u64 v[192:193], s[24:25], 0, v[162:163]
	ds_read_b128 v[146:149], v187 offset:32768
	ds_read_b128 v[150:153], v187 offset:33792
	ds_read_b128 v[154:157], v187 offset:34816
	ds_read_b128 v[158:161], v187 offset:35840
	ds_read_b128 v[172:175], v187 offset:36864
	ds_read_b128 v[176:179], v187 offset:37888
	ds_read_b128 v[180:183], v187 offset:38912
	ds_read_b128 v[188:191], v187 offset:39936
	global_load_lds_dwordx4 v[192:193], off
	v_lshl_add_u64 v[192:193], s[24:25], 0, v[164:165]
	s_mov_b32 m0, s40
	s_nop 0
	global_load_lds_dwordx4 v[192:193], off
	s_waitcnt lgkmcnt(8)
	s_barrier
	s_waitcnt lgkmcnt(0)
	s_waitcnt lgkmcnt(0)
	v_mfma_f32_16x16x32_bf16 v[126:129], v[130:133], v[146:149], v[126:129]
	v_mfma_f32_16x16x32_bf16 v[122:125], v[138:141], v[146:149], v[122:125]
	v_mfma_f32_16x16x32_bf16 v[118:121], v[130:133], v[154:157], v[118:121]
	v_mfma_f32_16x16x32_bf16 v[114:117], v[138:141], v[154:157], v[114:117]
	v_mfma_f32_16x16x32_bf16 v[92:95], v[130:133], v[172:175], v[92:95]
	v_mfma_f32_16x16x32_bf16 v[88:91], v[138:141], v[172:175], v[88:91]
	v_mfma_f32_16x16x32_bf16 v[84:87], v[130:133], v[180:183], v[84:87]
	v_mfma_f32_16x16x32_bf16 v[76:79], v[138:141], v[180:183], v[76:79]
	v_mfma_f32_16x16x32_bf16 v[126:129], v[134:137], v[150:153], v[126:129]
	v_mfma_f32_16x16x32_bf16 v[122:125], v[142:145], v[150:153], v[122:125]
	v_mfma_f32_16x16x32_bf16 v[118:121], v[134:137], v[158:161], v[118:121]
	v_mfma_f32_16x16x32_bf16 v[114:117], v[142:145], v[158:161], v[114:117]
	v_mfma_f32_16x16x32_bf16 v[92:95], v[134:137], v[176:179], v[92:95]
	v_mfma_f32_16x16x32_bf16 v[88:91], v[142:145], v[176:179], v[88:91]
	v_mfma_f32_16x16x32_bf16 v[84:87], v[134:137], v[188:191], v[84:87]
	v_mfma_f32_16x16x32_bf16 v[76:79], v[142:145], v[188:191], v[76:79]
	s_barrier
	s_add_i32 s24, 0, 0x1c000
	s_add_i32 s0, s0, s31
	v_add_u32_e32 v204, s24, v185
	v_lshl_add_u64 v[208:209], v[208:209], 0, s[72:73]
	s_mov_b32 m0, s0
	ds_read_b128 v[192:195], v204
	ds_read_b128 v[196:199], v204 offset:1024
	ds_read_b128 v[200:203], v204 offset:2048
	ds_read_b128 v[204:207], v204 offset:3072
	global_load_lds_dwordx4 v[208:209], off
	v_lshl_add_u64 v[208:209], v[210:211], 0, s[72:73]
	s_add_i32 m0, s0, 0x2000
	s_nop 0
	global_load_lds_dwordx4 v[208:209], off
	s_barrier
	s_waitcnt lgkmcnt(0)
	s_waitcnt lgkmcnt(0)
	v_mfma_f32_16x16x32_bf16 v[110:113], v[192:195], v[146:149], v[110:113]
	v_mfma_f32_16x16x32_bf16 v[106:109], v[200:203], v[146:149], v[106:109]
	v_mfma_f32_16x16x32_bf16 v[102:105], v[192:195], v[154:157], v[102:105]
	v_mfma_f32_16x16x32_bf16 v[98:101], v[200:203], v[154:157], v[98:101]
	v_mfma_f32_16x16x32_bf16 v[80:83], v[192:195], v[172:175], v[80:83]
	v_mfma_f32_16x16x32_bf16 v[72:75], v[200:203], v[172:175], v[72:75]
	v_mfma_f32_16x16x32_bf16 v[68:71], v[192:195], v[180:183], v[68:71]
	v_mfma_f32_16x16x32_bf16 v[64:67], v[200:203], v[180:183], v[64:67]
	v_mfma_f32_16x16x32_bf16 v[110:113], v[196:199], v[150:153], v[110:113]
	v_mfma_f32_16x16x32_bf16 v[106:109], v[204:207], v[150:153], v[106:109]
	v_mfma_f32_16x16x32_bf16 v[102:105], v[196:199], v[158:161], v[102:105]
	v_mfma_f32_16x16x32_bf16 v[98:101], v[204:207], v[158:161], v[98:101]
	v_mfma_f32_16x16x32_bf16 v[80:83], v[196:199], v[176:179], v[80:83]
	v_mfma_f32_16x16x32_bf16 v[72:75], v[204:207], v[176:179], v[72:75]
	v_mfma_f32_16x16x32_bf16 v[68:71], v[196:199], v[188:191], v[68:71]
	v_mfma_f32_16x16x32_bf16 v[64:67], v[204:207], v[188:191], v[64:67]
	s_mov_b32 m0, s41
	v_lshl_add_u64 v[208:209], v[212:213], 0, s[72:73]
	s_barrier
	ds_read_b128 v[146:149], v187 offset:49152
	ds_read_b128 v[150:153], v187 offset:50176
	ds_read_b128 v[154:157], v187 offset:51200
	ds_read_b128 v[158:161], v187 offset:52224
	ds_read_b128 v[172:175], v187 offset:53248
	ds_read_b128 v[176:179], v187 offset:54272
	ds_read_b128 v[180:183], v187 offset:55296
	ds_read_b128 v[188:191], v187 offset:56320
	global_load_lds_dwordx4 v[208:209], off
	v_lshl_add_u64 v[208:209], v[214:215], 0, s[72:73]
	s_mov_b32 m0, s42
	s_nop 0
	global_load_lds_dwordx4 v[208:209], off
	s_barrier
; #define PG8_STAGE(bufoff, gbase, voff) do { _Pragma("unroll") for (int _i = 0; _i < 2; ++_i) \
;     __builtin_amdgcn_global_load_lds((const unsigned*)((const char*)(gbase) + (voff)[_i]), (LAS unsigned*)(lds + (bufoff) + ldsw + _i * 8192), 16, 0, 0); } while (0)
; #define PG8_LDA(dst, b, h) do { _Pragma("unroll") for (int m = 0; m < 4; ++m) _Pragma("unroll") for (int k = 0; k < 2; ++k) dst[m][k] = *(const LAS bf16x8*)(lds + PG8_SA(b, h) + aoff + m * 2048 + k * 1024); } while (0)
; #define PG8_MMA(ai, bj, At, Bt) do { __builtin_amdgcn_s_setprio(1); _Pragma("unroll") for (int m = 0; m < 4; ++m) _Pragma("unroll") for (int n = 0; n < 2; ++n) _Pragma("unroll") for (int k = 0; k < 2; ++k) \
;     acc[ai][bj][m][n] = __builtin_amdgcn_mfma_f32_16x16x32_bf16(Bt[n][k], At[m][k], acc[ai][bj][m][n], 0, 0, 0); __builtin_amdgcn_s_setprio(0); } while (0)
; #define PG8_WAIT_V(n) asm volatile("s_waitcnt vmcnt(" #n ")" ::: "memory")
; #define PG8_WAIT_L(n) asm volatile("s_waitcnt lgkmcnt(" #n ")" ::: "memory")
; #define PG8_BAR __builtin_amdgcn_s_barrier()
; #define PG8_SCHED __builtin_amdgcn_sched_barrier(0)
; template <class Epi>
; __device__ __forceinline__ void gemm_phase(LAS unsigned char* lds, const Gemm g, const StaticOrder& S, const Epi& E, int wv0) {
;     ...
;       PG8_BAR; PG8_WAIT_L(0); PG8_MMA(0, 1, At, B1); PG8_BAR;
;       PG8_LDA(At, 1, 1); PG8_STAGE(PG8_SA(1, 0), a3, voffA);
;       PG8_BAR; PG8_WAIT_L(0); PG8_MMA(1, 0, At, B0); PG8_BAR; PG8_SCHED;
;       PG8_STAGE(PG8_SB(1, 1), b3 + hstepB, voffB);
;       PG8_WAIT_V(6); PG8_BAR; PG8_MMA(1, 1, At, B1); PG8_BAR;
;     }
;     E(acc, cur, wr, wc, fr, fq);
;     if (!has_next) break;
;   __device__ __forceinline__ void emit(const EpiPre& q0, int row, int col, f32x4 a, f32x4 b, const f32x4 (&hb)[2][2], const float (&hs)[2][4], int ai_, int m_, int bj_) const {
;     ...
;     } else if (MODE == E_RES) {
;       const f32x4 r0 = q.a0, r1 = q.a1;
;       float* o = (float*)e.out + (size_t)row * DM + col;
;       *(f32x4*)o = (f32x4){ALPHA * r0[0] + v[0], ALPHA * r0[1] + v[1], ALPHA * r0[2] + v[2], ALPHA * r0[3] + v[3]};
;       *(f32x4*)(o + 4) = (f32x4){ALPHA * r1[0] + v[4], ALPHA * r1[1] + v[5], ALPHA * r1[2] + v[6], ALPHA * r1[3] + v[7]};
	s_waitcnt lgkmcnt(0)
	s_waitcnt lgkmcnt(0)
	v_mfma_f32_16x16x32_bf16 v[60:63], v[130:133], v[146:149], v[60:63]
	v_mfma_f32_16x16x32_bf16 v[56:59], v[138:141], v[146:149], v[56:59]
	v_mfma_f32_16x16x32_bf16 v[44:47], v[130:133], v[154:157], v[44:47]
	v_mfma_f32_16x16x32_bf16 v[40:43], v[138:141], v[154:157], v[40:43]
	v_mfma_f32_16x16x32_bf16 v[28:31], v[130:133], v[172:175], v[28:31]
	v_mfma_f32_16x16x32_bf16 v[24:27], v[138:141], v[172:175], v[24:27]
	v_mfma_f32_16x16x32_bf16 v[20:23], v[130:133], v[180:183], v[20:23]
	v_mfma_f32_16x16x32_bf16 v[8:11], v[138:141], v[180:183], v[8:11]
	v_mfma_f32_16x16x32_bf16 v[60:63], v[134:137], v[150:153], v[60:63]
	v_mfma_f32_16x16x32_bf16 v[56:59], v[142:145], v[150:153], v[56:59]
	v_mfma_f32_16x16x32_bf16 v[44:47], v[134:137], v[158:161], v[44:47]
	v_mfma_f32_16x16x32_bf16 v[40:43], v[142:145], v[158:161], v[40:43]
	v_mfma_f32_16x16x32_bf16 v[28:31], v[134:137], v[176:179], v[28:31]
	v_mfma_f32_16x16x32_bf16 v[24:27], v[142:145], v[176:179], v[24:27]
	v_mfma_f32_16x16x32_bf16 v[20:23], v[134:137], v[188:191], v[20:23]
	v_mfma_f32_16x16x32_bf16 v[8:11], v[142:145], v[188:191], v[8:11]
	s_barrier
	s_add_u32 s22, s22, 0x80080
	s_addc_u32 s23, s23, 0
	s_add_i32 s0, s24, s31
	v_lshl_add_u64 v[130:131], s[22:23], 0, v[96:97]
	s_mov_b32 m0, s0
	s_nop 0
	global_load_lds_dwordx4 v[130:131], off
	v_lshl_add_u64 v[130:131], s[22:23], 0, v[166:167]
	s_add_i32 m0, s0, 0x2000
	s_nop 0
	global_load_lds_dwordx4 v[130:131], off
	s_waitcnt vmcnt(6)
	s_barrier
	v_mfma_f32_16x16x32_bf16 v[52:55], v[192:195], v[146:149], v[52:55]
	v_mfma_f32_16x16x32_bf16 v[48:51], v[200:203], v[146:149], v[48:51]
	v_mfma_f32_16x16x32_bf16 v[36:39], v[192:195], v[154:157], v[36:39]
	v_mfma_f32_16x16x32_bf16 v[32:35], v[200:203], v[154:157], v[32:35]
	v_mfma_f32_16x16x32_bf16 v[16:19], v[192:195], v[172:175], v[16:19]
	v_mfma_f32_16x16x32_bf16 v[12:15], v[200:203], v[172:175], v[12:15]
	v_mfma_f32_16x16x32_bf16 v[4:7], v[192:195], v[180:183], v[4:7]
	v_mfma_f32_16x16x32_bf16 v[0:3], v[200:203], v[180:183], v[0:3]
	v_mfma_f32_16x16x32_bf16 v[52:55], v[196:199], v[150:153], v[52:55]
	v_mfma_f32_16x16x32_bf16 v[48:51], v[204:207], v[150:153], v[48:51]
	v_mfma_f32_16x16x32_bf16 v[36:39], v[196:199], v[158:161], v[36:39]
	v_mfma_f32_16x16x32_bf16 v[32:35], v[204:207], v[158:161], v[32:35]
	v_mfma_f32_16x16x32_bf16 v[16:19], v[196:199], v[176:179], v[16:19]
	v_mfma_f32_16x16x32_bf16 v[12:15], v[204:207], v[176:179], v[12:15]
	v_mfma_f32_16x16x32_bf16 v[4:7], v[196:199], v[188:191], v[4:7]
	v_mfma_f32_16x16x32_bf16 v[0:3], v[204:207], v[188:191], v[0:3]
	s_add_i32 s49, s49, 2
	s_add_u32 s20, s20, 0x100
	s_addc_u32 s21, s21, 0
	s_add_u32 s47, s47, 0x100
	s_addc_u32 s48, s48, 0
	s_cmp_gt_u32 s49, 29
	s_barrier
	s_cbranch_scc0 .LBB0_1100
	s_cmp_eq_u32 s66, 0
	s_cbranch_scc1 .Lwo_plain
	s_load_dwordx4 s[48:51], s[54:55], 0xb8
	s_load_dwordx2 s[96:97], s[54:55], 0xc8
	v_lshl_add_u32 v243, s18, 8, v184
	v_lshl_or_b32 v247, s1, 8, v186
	v_lshlrev_b32_e32 v242, 13, v243
	v_lshlrev_b32_e32 v247, 2, v247
	v_lshlrev_b32_e32 v243, 3, v243
	v_add_u32_e32 v242, v242, v247
	s_waitcnt lgkmcnt(0)
	s_add_u32 s100, s96, 0x4000000
	s_addc_u32 s101, s97, 0
	s_add_u32 s20, s6, 0x0
	s_addc_u32 s21, s7, 0
	global_load_dwordx2 v[220:221], v243, s[100:101] offset:0
	global_load_dwordx4 v[130:133], v242, s[20:21]
	global_load_dwordx4 v[134:137], v242, s[20:21] offset:16
	global_load_dwordx4 v[138:141], v242, s[20:21] offset:512
	global_load_dwordx4 v[142:145], v242, s[20:21] offset:528
	s_add_u32 s22, s6, 0x20000
	s_addc_u32 s23, s7, 0
	global_load_dwordx2 v[238:239], v243, s[100:101] offset:128
	global_load_dwordx4 v[146:149], v242, s[22:23]
	global_load_dwordx4 v[150:153], v242, s[22:23] offset:16
	global_load_dwordx4 v[154:157], v242, s[22:23] offset:512
	global_load_dwordx4 v[158:161], v242, s[22:23] offset:528
	s_add_u32 s24, s6, 0x40000
	s_addc_u32 s25, s7, 0
	global_load_dwordx2 v[240:241], v243, s[100:101] offset:256
	global_load_dwordx4 v[172:175], v242, s[24:25]
	global_load_dwordx4 v[176:179], v242, s[24:25] offset:16
	global_load_dwordx4 v[180:183], v242, s[24:25] offset:512
	global_load_dwordx4 v[234:237], v242, s[24:25] offset:528
	global_load_dwordx4 v[188:191], v247, s[48:49]
	global_load_dwordx4 v[192:195], v247, s[48:49] offset:16
	global_load_dwordx4 v[196:199], v247, s[48:49] offset:512
	global_load_dwordx4 v[200:203], v247, s[48:49] offset:528
	global_load_dwordx4 v[204:207], v247, s[50:51]
	global_load_dwordx4 v[208:211], v247, s[50:51] offset:16
	global_load_dwordx4 v[212:215], v247, s[50:51] offset:512
	global_load_dwordx4 v[216:219], v247, s[50:51] offset:528
	s_waitcnt vmcnt(0)
;   __device__ __forceinline__ void emit(const EpiPre& q0, int row, int col, f32x4 a, f32x4 b, const f32x4 (&hb)[2][2], const float (&hs)[2][4], int ai_, int m_, int bj_) const {
;     ...
;     } else if (MODE == E_RES) {
;       const f32x4 r0 = q.a0, r1 = q.a1;
;       float* o = (float*)e.out + (size_t)row * DM + col;
;       *(f32x4*)o = (f32x4){ALPHA * r0[0] + v[0], ALPHA * r0[1] + v[1], ALPHA * r0[2] + v[2], ALPHA * r0[3] + v[3]};
;       *(f32x4*)(o + 4) = (f32x4){ALPHA * r1[0] + v[4], ALPHA * r1[1] + v[5], ALPHA * r1[2] + v[6], ALPHA * r1[3] + v[7]};
; __device__ __forceinline__ void ln_phase(const float* in, float* outf, bf16_t* outb, const float* g, const float* b, int wv0) {
;     ...
;     for (int i = 0; i < 8; ++i) { v[i] -= mu; sq += v[i][0] * v[i][0] + v[i][1] * v[i][1] + v[i][2] * v[i][2] + v[i][3] * v[i][3]; }
;     sq = wave_sum(sq); const float rstd = __builtin_amdgcn_rsqf(sq * (1.0f / 2048.0f) + EPS);
; #pragma unroll
;     for (int i = 0; i < 8; ++i) {
;       const f32x4 y = v[i] * rstd * gg[i] + bb[i];
	v_pk_add_f32 v[130:131], v[130:131], v[220:221] op_sel_hi:[1,0]
	v_pk_add_f32 v[132:133], v[132:133], v[220:221] op_sel_hi:[1,0]
	v_pk_add_f32 v[134:135], v[134:135], v[220:221] op_sel_hi:[1,0]
	v_pk_add_f32 v[136:137], v[136:137], v[220:221] op_sel_hi:[1,0]
	v_pk_add_f32 v[138:139], v[138:139], v[220:221] op_sel_hi:[1,0]
	v_pk_add_f32 v[140:141], v[140:141], v[220:221] op_sel_hi:[1,0]
	v_pk_add_f32 v[142:143], v[142:143], v[220:221] op_sel_hi:[1,0]
	v_pk_add_f32 v[144:145], v[144:145], v[220:221] op_sel_hi:[1,0]
	v_pk_mul_f32 v[130:131], v[130:131], v[220:221] op_sel:[0,1] op_sel_hi:[1,1]
	v_pk_mul_f32 v[132:133], v[132:133], v[220:221] op_sel:[0,1] op_sel_hi:[1,1]
	v_pk_mul_f32 v[134:135], v[134:135], v[220:221] op_sel:[0,1] op_sel_hi:[1,1]
	v_pk_mul_f32 v[136:137], v[136:137], v[220:221] op_sel:[0,1] op_sel_hi:[1,1]
	v_pk_mul_f32 v[138:139], v[138:139], v[220:221] op_sel:[0,1] op_sel_hi:[1,1]
	v_pk_mul_f32 v[140:141], v[140:141], v[220:221] op_sel:[0,1] op_sel_hi:[1,1]
	v_pk_mul_f32 v[142:143], v[142:143], v[220:221] op_sel:[0,1] op_sel_hi:[1,1]
	v_pk_mul_f32 v[144:145], v[144:145], v[220:221] op_sel:[0,1] op_sel_hi:[1,1]
	v_pk_fma_f32 v[130:131], v[188:189], v[130:131], v[204:205]
	v_pk_fma_f32 v[132:133], v[190:191], v[132:133], v[206:207]
	v_pk_fma_f32 v[134:135], v[192:193], v[134:135], v[208:209]
	v_pk_fma_f32 v[136:137], v[194:195], v[136:137], v[210:211]
	v_pk_fma_f32 v[138:139], v[196:197], v[138:139], v[212:213]
	v_pk_fma_f32 v[140:141], v[198:199], v[140:141], v[214:215]
	v_pk_fma_f32 v[142:143], v[200:201], v[142:143], v[216:217]
	v_pk_fma_f32 v[144:145], v[202:203], v[144:145], v[218:219]
	v_pk_fma_f32 v[126:127], v[130:131], s[90:91], v[126:127] op_sel_hi:[1,0,1]
	v_pk_fma_f32 v[128:129], v[132:133], s[90:91], v[128:129] op_sel_hi:[1,0,1]
	v_pk_fma_f32 v[122:123], v[134:135], s[90:91], v[122:123] op_sel_hi:[1,0,1]
	v_pk_fma_f32 v[124:125], v[136:137], s[90:91], v[124:125] op_sel_hi:[1,0,1]
	v_pk_fma_f32 v[110:111], v[138:139], s[90:91], v[110:111] op_sel_hi:[1,0,1]
	v_pk_fma_f32 v[112:113], v[140:141], s[90:91], v[112:113] op_sel_hi:[1,0,1]
	v_pk_fma_f32 v[106:107], v[142:143], s[90:91], v[106:107] op_sel_hi:[1,0,1]
	v_pk_fma_f32 v[108:109], v[144:145], s[90:91], v[108:109] op_sel_hi:[1,0,1]
	s_add_u32 s46, s6, 0x60000
	s_addc_u32 s47, s7, 0
	global_load_dwordx2 v[220:221], v243, s[100:101] offset:384
	global_load_dwordx4 v[130:133], v242, s[46:47]
	global_load_dwordx4 v[134:137], v242, s[46:47] offset:16
	global_load_dwordx4 v[138:141], v242, s[46:47] offset:512
	global_load_dwordx4 v[142:145], v242, s[46:47] offset:528
	s_waitcnt vmcnt(18)
	v_pk_add_f32 v[146:147], v[146:147], v[238:239] op_sel_hi:[1,0]
	v_pk_add_f32 v[148:149], v[148:149], v[238:239] op_sel_hi:[1,0]
	v_pk_add_f32 v[150:151], v[150:151], v[238:239] op_sel_hi:[1,0]
	v_pk_add_f32 v[152:153], v[152:153], v[238:239] op_sel_hi:[1,0]
	v_pk_add_f32 v[154:155], v[154:155], v[238:239] op_sel_hi:[1,0]
	v_pk_add_f32 v[156:157], v[156:157], v[238:239] op_sel_hi:[1,0]
	v_pk_add_f32 v[158:159], v[158:159], v[238:239] op_sel_hi:[1,0]
	v_pk_add_f32 v[160:161], v[160:161], v[238:239] op_sel_hi:[1,0]
	v_pk_mul_f32 v[146:147], v[146:147], v[238:239] op_sel:[0,1] op_sel_hi:[1,1]
	v_pk_mul_f32 v[148:149], v[148:149], v[238:239] op_sel:[0,1] op_sel_hi:[1,1]
	v_pk_mul_f32 v[150:151], v[150:151], v[238:239] op_sel:[0,1] op_sel_hi:[1,1]
	v_pk_mul_f32 v[152:153], v[152:153], v[238:239] op_sel:[0,1] op_sel_hi:[1,1]
	v_pk_mul_f32 v[154:155], v[154:155], v[238:239] op_sel:[0,1] op_sel_hi:[1,1]
	v_pk_mul_f32 v[156:157], v[156:157], v[238:239] op_sel:[0,1] op_sel_hi:[1,1]
	v_pk_mul_f32 v[158:159], v[158:159], v[238:239] op_sel:[0,1] op_sel_hi:[1,1]
	v_pk_mul_f32 v[160:161], v[160:161], v[238:239] op_sel:[0,1] op_sel_hi:[1,1]
	v_pk_fma_f32 v[146:147], v[188:189], v[146:147], v[204:205]
	v_pk_fma_f32 v[148:149], v[190:191], v[148:149], v[206:207]
	v_pk_fma_f32 v[150:151], v[192:193], v[150:151], v[208:209]
	v_pk_fma_f32 v[152:153], v[194:195], v[152:153], v[210:211]
	v_pk_fma_f32 v[154:155], v[196:197], v[154:155], v[212:213]
	v_pk_fma_f32 v[156:157], v[198:199], v[156:157], v[214:215]
	v_pk_fma_f32 v[158:159], v[200:201], v[158:159], v[216:217]
	v_pk_fma_f32 v[160:161], v[202:203], v[160:161], v[218:219]
	v_pk_fma_f32 v[118:119], v[146:147], s[90:91], v[118:119] op_sel_hi:[1,0,1]
	v_pk_fma_f32 v[120:121], v[148:149], s[90:91], v[120:121] op_sel_hi:[1,0,1]
	v_pk_fma_f32 v[114:115], v[150:151], s[90:91], v[114:115] op_sel_hi:[1,0,1]
	v_pk_fma_f32 v[116:117], v[152:153], s[90:91], v[116:117] op_sel_hi:[1,0,1]
	v_pk_fma_f32 v[102:103], v[154:155], s[90:91], v[102:103] op_sel_hi:[1,0,1]
	v_pk_fma_f32 v[104:105], v[156:157], s[90:91], v[104:105] op_sel_hi:[1,0,1]
	v_pk_fma_f32 v[98:99], v[158:159], s[90:91], v[98:99] op_sel_hi:[1,0,1]
	v_pk_fma_f32 v[100:101], v[160:161], s[90:91], v[100:101] op_sel_hi:[1,0,1]
	s_add_u32 s48, s6, 0x100000
	s_addc_u32 s49, s7, 0
	global_load_dwordx2 v[238:239], v243, s[100:101] offset:1024
	global_load_dwordx4 v[146:149], v242, s[48:49]
	global_load_dwordx4 v[150:153], v242, s[48:49] offset:16
	global_load_dwordx4 v[154:157], v242, s[48:49] offset:512
	global_load_dwordx4 v[158:161], v242, s[48:49] offset:528
	s_waitcnt vmcnt(18)
;   __device__ __forceinline__ void emit(const EpiPre& q0, int row, int col, f32x4 a, f32x4 b, const f32x4 (&hb)[2][2], const float (&hs)[2][4], int ai_, int m_, int bj_) const {
;     ...
;     } else if (MODE == E_RES) {
;       const f32x4 r0 = q.a0, r1 = q.a1;
;       float* o = (float*)e.out + (size_t)row * DM + col;
;       *(f32x4*)o = (f32x4){ALPHA * r0[0] + v[0], ALPHA * r0[1] + v[1], ALPHA * r0[2] + v[2], ALPHA * r0[3] + v[3]};
;       *(f32x4*)(o + 4) = (f32x4){ALPHA * r1[0] + v[4], ALPHA * r1[1] + v[5], ALPHA * r1[2] + v[6], ALPHA * r1[3] + v[7]};
; __device__ __forceinline__ void ln_phase(const float* in, float* outf, bf16_t* outb, const float* g, const float* b, int wv0) {
;     ...
;     for (int i = 0; i < 8; ++i) { v[i] -= mu; sq += v[i][0] * v[i][0] + v[i][1] * v[i][1] + v[i][2] * v[i][2] + v[i][3] * v[i][3]; }
;     sq = wave_sum(sq); const float rstd = __builtin_amdgcn_rsqf(sq * (1.0f / 2048.0f) + EPS);
; #pragma unroll
;     for (int i = 0; i < 8; ++i) {
;       const f32x4 y = v[i] * rstd * gg[i] + bb[i];
	v_pk_add_f32 v[172:173], v[172:173], v[240:241] op_sel_hi:[1,0]
	v_pk_add_f32 v[174:175], v[174:175], v[240:241] op_sel_hi:[1,0]
	v_pk_add_f32 v[176:177], v[176:177], v[240:241] op_sel_hi:[1,0]
	v_pk_add_f32 v[178:179], v[178:179], v[240:241] op_sel_hi:[1,0]
	v_pk_add_f32 v[180:181], v[180:181], v[240:241] op_sel_hi:[1,0]
	v_pk_add_f32 v[182:183], v[182:183], v[240:241] op_sel_hi:[1,0]
	v_pk_add_f32 v[234:235], v[234:235], v[240:241] op_sel_hi:[1,0]
	v_pk_add_f32 v[236:237], v[236:237], v[240:241] op_sel_hi:[1,0]
	v_pk_mul_f32 v[172:173], v[172:173], v[240:241] op_sel:[0,1] op_sel_hi:[1,1]
	v_pk_mul_f32 v[174:175], v[174:175], v[240:241] op_sel:[0,1] op_sel_hi:[1,1]
	v_pk_mul_f32 v[176:177], v[176:177], v[240:241] op_sel:[0,1] op_sel_hi:[1,1]
	v_pk_mul_f32 v[178:179], v[178:179], v[240:241] op_sel:[0,1] op_sel_hi:[1,1]
	v_pk_mul_f32 v[180:181], v[180:181], v[240:241] op_sel:[0,1] op_sel_hi:[1,1]
	v_pk_mul_f32 v[182:183], v[182:183], v[240:241] op_sel:[0,1] op_sel_hi:[1,1]
	v_pk_mul_f32 v[234:235], v[234:235], v[240:241] op_sel:[0,1] op_sel_hi:[1,1]
	v_pk_mul_f32 v[236:237], v[236:237], v[240:241] op_sel:[0,1] op_sel_hi:[1,1]
	v_pk_fma_f32 v[172:173], v[188:189], v[172:173], v[204:205]
	v_pk_fma_f32 v[174:175], v[190:191], v[174:175], v[206:207]
	v_pk_fma_f32 v[176:177], v[192:193], v[176:177], v[208:209]
	v_pk_fma_f32 v[178:179], v[194:195], v[178:179], v[210:211]
	v_pk_fma_f32 v[180:181], v[196:197], v[180:181], v[212:213]
	v_pk_fma_f32 v[182:183], v[198:199], v[182:183], v[214:215]
	v_pk_fma_f32 v[234:235], v[200:201], v[234:235], v[216:217]
	v_pk_fma_f32 v[236:237], v[202:203], v[236:237], v[218:219]
	v_pk_fma_f32 v[92:93], v[172:173], s[90:91], v[92:93] op_sel_hi:[1,0,1]
	v_pk_fma_f32 v[94:95], v[174:175], s[90:91], v[94:95] op_sel_hi:[1,0,1]
	v_pk_fma_f32 v[88:89], v[176:177], s[90:91], v[88:89] op_sel_hi:[1,0,1]
	v_pk_fma_f32 v[90:91], v[178:179], s[90:91], v[90:91] op_sel_hi:[1,0,1]
	v_pk_fma_f32 v[80:81], v[180:181], s[90:91], v[80:81] op_sel_hi:[1,0,1]
	v_pk_fma_f32 v[82:83], v[182:183], s[90:91], v[82:83] op_sel_hi:[1,0,1]
	v_pk_fma_f32 v[72:73], v[234:235], s[90:91], v[72:73] op_sel_hi:[1,0,1]
	v_pk_fma_f32 v[74:75], v[236:237], s[90:91], v[74:75] op_sel_hi:[1,0,1]
	s_add_u32 s50, s6, 0x120000
	s_addc_u32 s51, s7, 0
	global_load_dwordx2 v[240:241], v243, s[100:101] offset:1152
	global_load_dwordx4 v[172:175], v242, s[50:51]
	global_load_dwordx4 v[176:179], v242, s[50:51] offset:16
	global_load_dwordx4 v[180:183], v242, s[50:51] offset:512
	global_load_dwordx4 v[234:237], v242, s[50:51] offset:528
	global_store_dwordx4 v242, v[126:129], s[20:21]
	global_store_dwordx4 v242, v[122:125], s[20:21] offset:16
	global_store_dwordx4 v242, v[110:113], s[20:21] offset:512
	global_store_dwordx4 v242, v[106:109], s[20:21] offset:528
	global_store_dwordx4 v242, v[118:121], s[22:23]
	global_store_dwordx4 v242, v[114:117], s[22:23] offset:16
	global_store_dwordx4 v242, v[102:105], s[22:23] offset:512
	global_store_dwordx4 v242, v[98:101], s[22:23] offset:528
	global_store_dwordx4 v242, v[92:95], s[24:25]
	global_store_dwordx4 v242, v[88:91], s[24:25] offset:16
	global_store_dwordx4 v242, v[80:83], s[24:25] offset:512
	global_store_dwordx4 v242, v[72:75], s[24:25] offset:528
	s_add_u32 s20, s6, 0x140000
	s_addc_u32 s21, s7, 0
	global_load_dwordx2 v[92:93], v243, s[100:101] offset:1280
	global_load_dwordx4 v[126:129], v242, s[20:21]
	global_load_dwordx4 v[122:125], v242, s[20:21] offset:16
	global_load_dwordx4 v[110:113], v242, s[20:21] offset:512
	global_load_dwordx4 v[106:109], v242, s[20:21] offset:528
	s_add_u32 s22, s6, 0x160000
	s_addc_u32 s23, s7, 0
	global_load_dwordx2 v[88:89], v243, s[100:101] offset:1408
	global_load_dwordx4 v[118:121], v242, s[22:23]
	global_load_dwordx4 v[114:117], v242, s[22:23] offset:16
	global_load_dwordx4 v[102:105], v242, s[22:23] offset:512
	global_load_dwordx4 v[98:101], v242, s[22:23] offset:528
	s_waitcnt vmcnt(32)
	v_pk_add_f32 v[130:131], v[130:131], v[220:221] op_sel_hi:[1,0]
	v_pk_add_f32 v[132:133], v[132:133], v[220:221] op_sel_hi:[1,0]
	v_pk_add_f32 v[134:135], v[134:135], v[220:221] op_sel_hi:[1,0]
	v_pk_add_f32 v[136:137], v[136:137], v[220:221] op_sel_hi:[1,0]
	v_pk_add_f32 v[138:139], v[138:139], v[220:221] op_sel_hi:[1,0]
	v_pk_add_f32 v[140:141], v[140:141], v[220:221] op_sel_hi:[1,0]
	v_pk_add_f32 v[142:143], v[142:143], v[220:221] op_sel_hi:[1,0]
	v_pk_add_f32 v[144:145], v[144:145], v[220:221] op_sel_hi:[1,0]
	v_pk_mul_f32 v[130:131], v[130:131], v[220:221] op_sel:[0,1] op_sel_hi:[1,1]
	v_pk_mul_f32 v[132:133], v[132:133], v[220:221] op_sel:[0,1] op_sel_hi:[1,1]
	v_pk_mul_f32 v[134:135], v[134:135], v[220:221] op_sel:[0,1] op_sel_hi:[1,1]
	v_pk_mul_f32 v[136:137], v[136:137], v[220:221] op_sel:[0,1] op_sel_hi:[1,1]
	v_pk_mul_f32 v[138:139], v[138:139], v[220:221] op_sel:[0,1] op_sel_hi:[1,1]
	v_pk_mul_f32 v[140:141], v[140:141], v[220:221] op_sel:[0,1] op_sel_hi:[1,1]
	v_pk_mul_f32 v[142:143], v[142:143], v[220:221] op_sel:[0,1] op_sel_hi:[1,1]
	v_pk_mul_f32 v[144:145], v[144:145], v[220:221] op_sel:[0,1] op_sel_hi:[1,1]
	v_pk_fma_f32 v[130:131], v[188:189], v[130:131], v[204:205]
	v_pk_fma_f32 v[132:133], v[190:191], v[132:133], v[206:207]
	v_pk_fma_f32 v[134:135], v[192:193], v[134:135], v[208:209]
	v_pk_fma_f32 v[136:137], v[194:195], v[136:137], v[210:211]
	v_pk_fma_f32 v[138:139], v[196:197], v[138:139], v[212:213]
	v_pk_fma_f32 v[140:141], v[198:199], v[140:141], v[214:215]
	v_pk_fma_f32 v[142:143], v[200:201], v[142:143], v[216:217]
	v_pk_fma_f32 v[144:145], v[202:203], v[144:145], v[218:219]
	v_pk_fma_f32 v[84:85], v[130:131], s[90:91], v[84:85] op_sel_hi:[1,0,1]
	v_pk_fma_f32 v[86:87], v[132:133], s[90:91], v[86:87] op_sel_hi:[1,0,1]
	v_pk_fma_f32 v[76:77], v[134:135], s[90:91], v[76:77] op_sel_hi:[1,0,1]
	v_pk_fma_f32 v[78:79], v[136:137], s[90:91], v[78:79] op_sel_hi:[1,0,1]
	v_pk_fma_f32 v[68:69], v[138:139], s[90:91], v[68:69] op_sel_hi:[1,0,1]
	v_pk_fma_f32 v[70:71], v[140:141], s[90:91], v[70:71] op_sel_hi:[1,0,1]
	v_pk_fma_f32 v[64:65], v[142:143], s[90:91], v[64:65] op_sel_hi:[1,0,1]
	v_pk_fma_f32 v[66:67], v[144:145], s[90:91], v[66:67] op_sel_hi:[1,0,1]
	global_store_dwordx4 v242, v[84:87], s[46:47]
	global_store_dwordx4 v242, v[76:79], s[46:47] offset:16
	global_store_dwordx4 v242, v[68:71], s[46:47] offset:512
	global_store_dwordx4 v242, v[64:67], s[46:47] offset:528
	s_waitcnt vmcnt(31)
;   __device__ __forceinline__ void emit(const EpiPre& q0, int row, int col, f32x4 a, f32x4 b, const f32x4 (&hb)[2][2], const float (&hs)[2][4], int ai_, int m_, int bj_) const {
;     ...
;     } else if (MODE == E_RES) {
;       const f32x4 r0 = q.a0, r1 = q.a1;
;       float* o = (float*)e.out + (size_t)row * DM + col;
;       *(f32x4*)o = (f32x4){ALPHA * r0[0] + v[0], ALPHA * r0[1] + v[1], ALPHA * r0[2] + v[2], ALPHA * r0[3] + v[3]};
;       *(f32x4*)(o + 4) = (f32x4){ALPHA * r1[0] + v[4], ALPHA * r1[1] + v[5], ALPHA * r1[2] + v[6], ALPHA * r1[3] + v[7]};
; __device__ __forceinline__ void ln_phase(const float* in, float* outf, bf16_t* outb, const float* g, const float* b, int wv0) {
;     ...
;     for (int i = 0; i < 8; ++i) { v[i] -= mu; sq += v[i][0] * v[i][0] + v[i][1] * v[i][1] + v[i][2] * v[i][2] + v[i][3] * v[i][3]; }
;     sq = wave_sum(sq); const float rstd = __builtin_amdgcn_rsqf(sq * (1.0f / 2048.0f) + EPS);
; #pragma unroll
;     for (int i = 0; i < 8; ++i) {
;       const f32x4 y = v[i] * rstd * gg[i] + bb[i];
	v_pk_add_f32 v[146:147], v[146:147], v[238:239] op_sel_hi:[1,0]
	v_pk_add_f32 v[148:149], v[148:149], v[238:239] op_sel_hi:[1,0]
	v_pk_add_f32 v[150:151], v[150:151], v[238:239] op_sel_hi:[1,0]
	v_pk_add_f32 v[152:153], v[152:153], v[238:239] op_sel_hi:[1,0]
	v_pk_add_f32 v[154:155], v[154:155], v[238:239] op_sel_hi:[1,0]
	v_pk_add_f32 v[156:157], v[156:157], v[238:239] op_sel_hi:[1,0]
	v_pk_add_f32 v[158:159], v[158:159], v[238:239] op_sel_hi:[1,0]
	v_pk_add_f32 v[160:161], v[160:161], v[238:239] op_sel_hi:[1,0]
	v_pk_mul_f32 v[146:147], v[146:147], v[238:239] op_sel:[0,1] op_sel_hi:[1,1]
	v_pk_mul_f32 v[148:149], v[148:149], v[238:239] op_sel:[0,1] op_sel_hi:[1,1]
	v_pk_mul_f32 v[150:151], v[150:151], v[238:239] op_sel:[0,1] op_sel_hi:[1,1]
	v_pk_mul_f32 v[152:153], v[152:153], v[238:239] op_sel:[0,1] op_sel_hi:[1,1]
	v_pk_mul_f32 v[154:155], v[154:155], v[238:239] op_sel:[0,1] op_sel_hi:[1,1]
	v_pk_mul_f32 v[156:157], v[156:157], v[238:239] op_sel:[0,1] op_sel_hi:[1,1]
	v_pk_mul_f32 v[158:159], v[158:159], v[238:239] op_sel:[0,1] op_sel_hi:[1,1]
	v_pk_mul_f32 v[160:161], v[160:161], v[238:239] op_sel:[0,1] op_sel_hi:[1,1]
	v_pk_fma_f32 v[146:147], v[188:189], v[146:147], v[204:205]
	v_pk_fma_f32 v[148:149], v[190:191], v[148:149], v[206:207]
	v_pk_fma_f32 v[150:151], v[192:193], v[150:151], v[208:209]
	v_pk_fma_f32 v[152:153], v[194:195], v[152:153], v[210:211]
	v_pk_fma_f32 v[154:155], v[196:197], v[154:155], v[212:213]
	v_pk_fma_f32 v[156:157], v[198:199], v[156:157], v[214:215]
	v_pk_fma_f32 v[158:159], v[200:201], v[158:159], v[216:217]
	v_pk_fma_f32 v[160:161], v[202:203], v[160:161], v[218:219]
	v_pk_fma_f32 v[60:61], v[146:147], s[90:91], v[60:61] op_sel_hi:[1,0,1]
	v_pk_fma_f32 v[62:63], v[148:149], s[90:91], v[62:63] op_sel_hi:[1,0,1]
	v_pk_fma_f32 v[56:57], v[150:151], s[90:91], v[56:57] op_sel_hi:[1,0,1]
	v_pk_fma_f32 v[58:59], v[152:153], s[90:91], v[58:59] op_sel_hi:[1,0,1]
	v_pk_fma_f32 v[52:53], v[154:155], s[90:91], v[52:53] op_sel_hi:[1,0,1]
	v_pk_fma_f32 v[54:55], v[156:157], s[90:91], v[54:55] op_sel_hi:[1,0,1]
	v_pk_fma_f32 v[48:49], v[158:159], s[90:91], v[48:49] op_sel_hi:[1,0,1]
	v_pk_fma_f32 v[50:51], v[160:161], s[90:91], v[50:51] op_sel_hi:[1,0,1]
	global_store_dwordx4 v242, v[60:63], s[48:49]
	global_store_dwordx4 v242, v[56:59], s[48:49] offset:16
	global_store_dwordx4 v242, v[52:55], s[48:49] offset:512
	global_store_dwordx4 v242, v[48:51], s[48:49] offset:528
	s_waitcnt vmcnt(30)
	v_pk_add_f32 v[172:173], v[172:173], v[240:241] op_sel_hi:[1,0]
	v_pk_add_f32 v[174:175], v[174:175], v[240:241] op_sel_hi:[1,0]
	v_pk_add_f32 v[176:177], v[176:177], v[240:241] op_sel_hi:[1,0]
	v_pk_add_f32 v[178:179], v[178:179], v[240:241] op_sel_hi:[1,0]
	v_pk_add_f32 v[180:181], v[180:181], v[240:241] op_sel_hi:[1,0]
	v_pk_add_f32 v[182:183], v[182:183], v[240:241] op_sel_hi:[1,0]
	v_pk_add_f32 v[234:235], v[234:235], v[240:241] op_sel_hi:[1,0]
	v_pk_add_f32 v[236:237], v[236:237], v[240:241] op_sel_hi:[1,0]
	v_pk_mul_f32 v[172:173], v[172:173], v[240:241] op_sel:[0,1] op_sel_hi:[1,1]
	v_pk_mul_f32 v[174:175], v[174:175], v[240:241] op_sel:[0,1] op_sel_hi:[1,1]
	v_pk_mul_f32 v[176:177], v[176:177], v[240:241] op_sel:[0,1] op_sel_hi:[1,1]
	v_pk_mul_f32 v[178:179], v[178:179], v[240:241] op_sel:[0,1] op_sel_hi:[1,1]
	v_pk_mul_f32 v[180:181], v[180:181], v[240:241] op_sel:[0,1] op_sel_hi:[1,1]
	v_pk_mul_f32 v[182:183], v[182:183], v[240:241] op_sel:[0,1] op_sel_hi:[1,1]
	v_pk_mul_f32 v[234:235], v[234:235], v[240:241] op_sel:[0,1] op_sel_hi:[1,1]
	v_pk_mul_f32 v[236:237], v[236:237], v[240:241] op_sel:[0,1] op_sel_hi:[1,1]
	v_pk_fma_f32 v[172:173], v[188:189], v[172:173], v[204:205]
	v_pk_fma_f32 v[174:175], v[190:191], v[174:175], v[206:207]
	v_pk_fma_f32 v[176:177], v[192:193], v[176:177], v[208:209]
	v_pk_fma_f32 v[178:179], v[194:195], v[178:179], v[210:211]
	v_pk_fma_f32 v[180:181], v[196:197], v[180:181], v[212:213]
	v_pk_fma_f32 v[182:183], v[198:199], v[182:183], v[214:215]
	v_pk_fma_f32 v[234:235], v[200:201], v[234:235], v[216:217]
	v_pk_fma_f32 v[236:237], v[202:203], v[236:237], v[218:219]
	v_pk_fma_f32 v[44:45], v[172:173], s[90:91], v[44:45] op_sel_hi:[1,0,1]
	v_pk_fma_f32 v[46:47], v[174:175], s[90:91], v[46:47] op_sel_hi:[1,0,1]
	v_pk_fma_f32 v[40:41], v[176:177], s[90:91], v[40:41] op_sel_hi:[1,0,1]
	v_pk_fma_f32 v[42:43], v[178:179], s[90:91], v[42:43] op_sel_hi:[1,0,1]
	v_pk_fma_f32 v[36:37], v[180:181], s[90:91], v[36:37] op_sel_hi:[1,0,1]
	v_pk_fma_f32 v[38:39], v[182:183], s[90:91], v[38:39] op_sel_hi:[1,0,1]
	v_pk_fma_f32 v[32:33], v[234:235], s[90:91], v[32:33] op_sel_hi:[1,0,1]
	v_pk_fma_f32 v[34:35], v[236:237], s[90:91], v[34:35] op_sel_hi:[1,0,1]
	global_store_dwordx4 v242, v[44:47], s[50:51]
	global_store_dwordx4 v242, v[40:43], s[50:51] offset:16
	global_store_dwordx4 v242, v[36:39], s[50:51] offset:512
	global_store_dwordx4 v242, v[32:35], s[50:51] offset:528
	s_waitcnt vmcnt(17)
;   __device__ __forceinline__ void emit(const EpiPre& q0, int row, int col, f32x4 a, f32x4 b, const f32x4 (&hb)[2][2], const float (&hs)[2][4], int ai_, int m_, int bj_) const {
;     ...
;     } else if (MODE == E_RES) {
;       const f32x4 r0 = q.a0, r1 = q.a1;
;       float* o = (float*)e.out + (size_t)row * DM + col;
;       *(f32x4*)o = (f32x4){ALPHA * r0[0] + v[0], ALPHA * r0[1] + v[1], ALPHA * r0[2] + v[2], ALPHA * r0[3] + v[3]};
;       *(f32x4*)(o + 4) = (f32x4){ALPHA * r1[0] + v[4], ALPHA * r1[1] + v[5], ALPHA * r1[2] + v[6], ALPHA * r1[3] + v[7]};
; __device__ __forceinline__ void ln_phase(const float* in, float* outf, bf16_t* outb, const float* g, const float* b, int wv0) {
;     ...
;     for (int i = 0; i < 8; ++i) { v[i] -= mu; sq += v[i][0] * v[i][0] + v[i][1] * v[i][1] + v[i][2] * v[i][2] + v[i][3] * v[i][3]; }
;     sq = wave_sum(sq); const float rstd = __builtin_amdgcn_rsqf(sq * (1.0f / 2048.0f) + EPS);
; #pragma unroll
;     for (int i = 0; i < 8; ++i) {
;       const f32x4 y = v[i] * rstd * gg[i] + bb[i];
	v_pk_add_f32 v[126:127], v[126:127], v[92:93] op_sel_hi:[1,0]
	v_pk_add_f32 v[128:129], v[128:129], v[92:93] op_sel_hi:[1,0]
	v_pk_add_f32 v[122:123], v[122:123], v[92:93] op_sel_hi:[1,0]
	v_pk_add_f32 v[124:125], v[124:125], v[92:93] op_sel_hi:[1,0]
	v_pk_add_f32 v[110:111], v[110:111], v[92:93] op_sel_hi:[1,0]
	v_pk_add_f32 v[112:113], v[112:113], v[92:93] op_sel_hi:[1,0]
	v_pk_add_f32 v[106:107], v[106:107], v[92:93] op_sel_hi:[1,0]
	v_pk_add_f32 v[108:109], v[108:109], v[92:93] op_sel_hi:[1,0]
	v_pk_mul_f32 v[126:127], v[126:127], v[92:93] op_sel:[0,1] op_sel_hi:[1,1]
	v_pk_mul_f32 v[128:129], v[128:129], v[92:93] op_sel:[0,1] op_sel_hi:[1,1]
	v_pk_mul_f32 v[122:123], v[122:123], v[92:93] op_sel:[0,1] op_sel_hi:[1,1]
	v_pk_mul_f32 v[124:125], v[124:125], v[92:93] op_sel:[0,1] op_sel_hi:[1,1]
	v_pk_mul_f32 v[110:111], v[110:111], v[92:93] op_sel:[0,1] op_sel_hi:[1,1]
	v_pk_mul_f32 v[112:113], v[112:113], v[92:93] op_sel:[0,1] op_sel_hi:[1,1]
	v_pk_mul_f32 v[106:107], v[106:107], v[92:93] op_sel:[0,1] op_sel_hi:[1,1]
	v_pk_mul_f32 v[108:109], v[108:109], v[92:93] op_sel:[0,1] op_sel_hi:[1,1]
	v_pk_fma_f32 v[126:127], v[188:189], v[126:127], v[204:205]
	v_pk_fma_f32 v[128:129], v[190:191], v[128:129], v[206:207]
	v_pk_fma_f32 v[122:123], v[192:193], v[122:123], v[208:209]
	v_pk_fma_f32 v[124:125], v[194:195], v[124:125], v[210:211]
	v_pk_fma_f32 v[110:111], v[196:197], v[110:111], v[212:213]
	v_pk_fma_f32 v[112:113], v[198:199], v[112:113], v[214:215]
	v_pk_fma_f32 v[106:107], v[200:201], v[106:107], v[216:217]
	v_pk_fma_f32 v[108:109], v[202:203], v[108:109], v[218:219]
	v_pk_fma_f32 v[28:29], v[126:127], s[90:91], v[28:29] op_sel_hi:[1,0,1]
	v_pk_fma_f32 v[30:31], v[128:129], s[90:91], v[30:31] op_sel_hi:[1,0,1]
	v_pk_fma_f32 v[24:25], v[122:123], s[90:91], v[24:25] op_sel_hi:[1,0,1]
	v_pk_fma_f32 v[26:27], v[124:125], s[90:91], v[26:27] op_sel_hi:[1,0,1]
	v_pk_fma_f32 v[16:17], v[110:111], s[90:91], v[16:17] op_sel_hi:[1,0,1]
	v_pk_fma_f32 v[18:19], v[112:113], s[90:91], v[18:19] op_sel_hi:[1,0,1]
	v_pk_fma_f32 v[12:13], v[106:107], s[90:91], v[12:13] op_sel_hi:[1,0,1]
	v_pk_fma_f32 v[14:15], v[108:109], s[90:91], v[14:15] op_sel_hi:[1,0,1]
	global_store_dwordx4 v242, v[28:31], s[20:21]
	global_store_dwordx4 v242, v[24:27], s[20:21] offset:16
	global_store_dwordx4 v242, v[16:19], s[20:21] offset:512
	global_store_dwordx4 v242, v[12:15], s[20:21] offset:528
	s_waitcnt vmcnt(16)
	v_pk_add_f32 v[118:119], v[118:119], v[88:89] op_sel_hi:[1,0]
	v_pk_add_f32 v[120:121], v[120:121], v[88:89] op_sel_hi:[1,0]
	v_pk_add_f32 v[114:115], v[114:115], v[88:89] op_sel_hi:[1,0]
	v_pk_add_f32 v[116:117], v[116:117], v[88:89] op_sel_hi:[1,0]
	v_pk_add_f32 v[102:103], v[102:103], v[88:89] op_sel_hi:[1,0]
	v_pk_add_f32 v[104:105], v[104:105], v[88:89] op_sel_hi:[1,0]
	v_pk_add_f32 v[98:99], v[98:99], v[88:89] op_sel_hi:[1,0]
	v_pk_add_f32 v[100:101], v[100:101], v[88:89] op_sel_hi:[1,0]
	v_pk_mul_f32 v[118:119], v[118:119], v[88:89] op_sel:[0,1] op_sel_hi:[1,1]
	v_pk_mul_f32 v[120:121], v[120:121], v[88:89] op_sel:[0,1] op_sel_hi:[1,1]
	v_pk_mul_f32 v[114:115], v[114:115], v[88:89] op_sel:[0,1] op_sel_hi:[1,1]
	v_pk_mul_f32 v[116:117], v[116:117], v[88:89] op_sel:[0,1] op_sel_hi:[1,1]
	v_pk_mul_f32 v[102:103], v[102:103], v[88:89] op_sel:[0,1] op_sel_hi:[1,1]
	v_pk_mul_f32 v[104:105], v[104:105], v[88:89] op_sel:[0,1] op_sel_hi:[1,1]
	v_pk_mul_f32 v[98:99], v[98:99], v[88:89] op_sel:[0,1] op_sel_hi:[1,1]
	v_pk_mul_f32 v[100:101], v[100:101], v[88:89] op_sel:[0,1] op_sel_hi:[1,1]
	v_pk_fma_f32 v[118:119], v[188:189], v[118:119], v[204:205]
	v_pk_fma_f32 v[120:121], v[190:191], v[120:121], v[206:207]
	v_pk_fma_f32 v[114:115], v[192:193], v[114:115], v[208:209]
	v_pk_fma_f32 v[116:117], v[194:195], v[116:117], v[210:211]
	v_pk_fma_f32 v[102:103], v[196:197], v[102:103], v[212:213]
	v_pk_fma_f32 v[104:105], v[198:199], v[104:105], v[214:215]
	v_pk_fma_f32 v[98:99], v[200:201], v[98:99], v[216:217]
	v_pk_fma_f32 v[100:101], v[202:203], v[100:101], v[218:219]
	v_pk_fma_f32 v[20:21], v[118:119], s[90:91], v[20:21] op_sel_hi:[1,0,1]
	v_pk_fma_f32 v[22:23], v[120:121], s[90:91], v[22:23] op_sel_hi:[1,0,1]
	v_pk_fma_f32 v[8:9], v[114:115], s[90:91], v[8:9] op_sel_hi:[1,0,1]
	v_pk_fma_f32 v[10:11], v[116:117], s[90:91], v[10:11] op_sel_hi:[1,0,1]
	v_pk_fma_f32 v[4:5], v[102:103], s[90:91], v[4:5] op_sel_hi:[1,0,1]
	v_pk_fma_f32 v[6:7], v[104:105], s[90:91], v[6:7] op_sel_hi:[1,0,1]
	v_pk_fma_f32 v[0:1], v[98:99], s[90:91], v[0:1] op_sel_hi:[1,0,1]
	v_pk_fma_f32 v[2:3], v[100:101], s[90:91], v[2:3] op_sel_hi:[1,0,1]
	global_store_dwordx4 v242, v[20:23], s[22:23]
	global_store_dwordx4 v242, v[8:11], s[22:23] offset:16
	global_store_dwordx4 v242, v[4:7], s[22:23] offset:512
	global_store_dwordx4 v242, v[0:3], s[22:23] offset:528
	s_mov_b32 s18, s12
	s_mov_b64 s[22:23], s[16:17]
	s_mov_b64 s[20:21], s[14:15]
	s_and_b64 vcc, exec, s[2:3]
	s_mov_b32 s1, s10
	s_branch .Lwo_join

; #define PG8_STAGE(bufoff, gbase, voff) do { _Pragma("unroll") for (int _i = 0; _i < 2; ++_i) \
;     __builtin_amdgcn_global_load_lds((const unsigned*)((const char*)(gbase) + (voff)[_i]), (LAS unsigned*)(lds + (bufoff) + ldsw + _i * 8192), 16, 0, 0); } while (0)
; #define PG8_LDA(dst, b, h) do { _Pragma("unroll") for (int m = 0; m < 4; ++m) _Pragma("unroll") for (int k = 0; k < 2; ++k) dst[m][k] = *(const LAS bf16x8*)(lds + PG8_SA(b, h) + aoff + m * 2048 + k * 1024); } while (0)
; #define PG8_LDB(dst, b, h) do { _Pragma("unroll") for (int n = 0; n < 2; ++n) _Pragma("unroll") for (int k = 0; k < 2; ++k) dst[n][k] = *(const LAS bf16x8*)(lds + PG8_SB(b, h) + boff + n * 2048 + k * 1024); } while (0)
; #define PG8_MMA(ai, bj, At, Bt) do { __builtin_amdgcn_s_setprio(1); _Pragma("unroll") for (int m = 0; m < 4; ++m) _Pragma("unroll") for (int n = 0; n < 2; ++n) _Pragma("unroll") for (int k = 0; k < 2; ++k) \
;     acc[ai][bj][m][n] = __builtin_amdgcn_mfma_f32_16x16x32_bf16(Bt[n][k], At[m][k], acc[ai][bj][m][n], 0, 0, 0); __builtin_amdgcn_s_setprio(0); } while (0)
; #define PG8_WAIT_V(n) asm volatile("s_waitcnt vmcnt(" #n ")" ::: "memory")
; #define PG8_WAIT_L(n) asm volatile("s_waitcnt lgkmcnt(" #n ")" ::: "memory")
; #define PG8_BAR __builtin_amdgcn_s_barrier()
; #define PG8_SCHED __builtin_amdgcn_sched_barrier(0)
; template <class Epi>
; __device__ __forceinline__ void gemm_phase(LAS unsigned char* lds, const Gemm g, const StaticOrder& S, const Epi& E, int wv0) {
;     ...
;       PG8_LDB(B0, 0, 0); PG8_SCHED; PG8_LDA(At, 0, 0); PG8_STAGE(PG8_SA(1, 1), a1 + hstepA, voffA);
;       PG8_WAIT_L(8); PG8_BAR; PG8_WAIT_L(0); PG8_MMA(0, 0, At, B0); PG8_BAR; PG8_SCHED;
;       PG8_LDB(B1, 0, 1); PG8_STAGE(PG8_SB(0, 0), b2, voffB);
;       PG8_BAR; PG8_WAIT_L(0); PG8_MMA(0, 1, At, B1); PG8_BAR;
;       PG8_LDA(At, 0, 1); PG8_STAGE(PG8_SA(0, 0), a2, voffA);
;       PG8_BAR; PG8_WAIT_L(0); PG8_MMA(1, 0, At, B0); PG8_BAR; PG8_SCHED;
;       PG8_STAGE(PG8_SB(0, 1), b2 + hstepB, voffB);
;       PG8_WAIT_V(6); PG8_BAR; PG8_MMA(1, 1, At, B1); PG8_BAR;
.Lgprio8:
.LBB0_1270:
	s_add_u32 s0, s60, 0xfff80080
	s_addc_u32 s62, s61, -1
	s_add_i32 s80, 0, 0x10000
	v_add_u32_e32 v134, s80, v213
	ds_read_b128 v[122:125], v134
	ds_read_b128 v[126:129], v134 offset:1024
	ds_read_b128 v[130:133], v134 offset:2048
	ds_read_b128 v[134:137], v134 offset:3072
	s_cmp_eq_u32 s78, 28
	s_cselect_b32 s65, s1, s62
	s_cselect_b32 s64, s51, s0
	s_cselect_b32 s63, s49, s75
	s_cselect_b32 s62, s57, s59
	v_lshl_add_u64 v[192:193], s[60:61], 0, v[172:173]
	s_add_i32 m0, s77, 0xc000
	ds_read_b128 v[138:141], v225
	ds_read_b128 v[142:145], v225 offset:1024
	ds_read_b128 v[146:149], v225 offset:2048
	ds_read_b128 v[150:153], v225 offset:3072
	ds_read_b128 v[176:179], v225 offset:4096
	ds_read_b128 v[180:183], v225 offset:5120
	ds_read_b128 v[184:187], v225 offset:6144
	ds_read_b128 v[188:191], v225 offset:7168
	global_load_lds_dwordx4 v[192:193], off
	v_lshl_add_u64 v[192:193], s[60:61], 0, v[174:175]
	s_add_i32 m0, s77, 0xe000
	s_nop 0
	global_load_lds_dwordx4 v[192:193], off
	s_waitcnt lgkmcnt(8)
	s_barrier
	s_waitcnt lgkmcnt(0)
	s_waitcnt lgkmcnt(0)
	v_mfma_f32_16x16x32_bf16 v[158:161], v[122:125], v[138:141], v[158:161]
	v_mfma_f32_16x16x32_bf16 v[60:63], v[130:133], v[138:141], v[60:63]
	v_mfma_f32_16x16x32_bf16 v[118:121], v[122:125], v[146:149], v[118:121]
	v_mfma_f32_16x16x32_bf16 v[52:55], v[130:133], v[146:149], v[52:55]
	v_mfma_f32_16x16x32_bf16 v[110:113], v[122:125], v[176:179], v[110:113]
	v_mfma_f32_16x16x32_bf16 v[44:47], v[130:133], v[176:179], v[44:47]
	v_mfma_f32_16x16x32_bf16 v[106:109], v[122:125], v[184:187], v[106:109]
	v_mfma_f32_16x16x32_bf16 v[40:43], v[130:133], v[184:187], v[40:43]
	v_mfma_f32_16x16x32_bf16 v[158:161], v[126:129], v[142:145], v[158:161]
	v_mfma_f32_16x16x32_bf16 v[60:63], v[134:137], v[142:145], v[60:63]
	v_mfma_f32_16x16x32_bf16 v[118:121], v[126:129], v[150:153], v[118:121]
	v_mfma_f32_16x16x32_bf16 v[52:55], v[134:137], v[150:153], v[52:55]
	v_mfma_f32_16x16x32_bf16 v[110:113], v[126:129], v[180:183], v[110:113]
	v_mfma_f32_16x16x32_bf16 v[44:47], v[134:137], v[180:183], v[44:47]
	v_mfma_f32_16x16x32_bf16 v[106:109], v[126:129], v[188:191], v[106:109]
	v_mfma_f32_16x16x32_bf16 v[40:43], v[134:137], v[188:191], v[40:43]
	s_barrier
	s_add_i32 s0, 0, 0x14000
	s_add_i32 s80, s80, s76
	v_add_u32_e32 v204, s0, v213
	v_lshl_add_u64 v[208:209], s[62:63], 0, v[96:97]
	s_mov_b32 m0, s80
	ds_read_b128 v[192:195], v204
	ds_read_b128 v[196:199], v204 offset:1024
	ds_read_b128 v[200:203], v204 offset:2048
	ds_read_b128 v[204:207], v204 offset:3072
	global_load_lds_dwordx4 v[208:209], off
	v_lshl_add_u64 v[210:211], s[62:63], 0, v[166:167]
	s_add_i32 m0, s80, 0x2000
	s_nop 0
	global_load_lds_dwordx4 v[210:211], off
	s_barrier
	s_waitcnt lgkmcnt(0)
	s_waitcnt lgkmcnt(0)
	v_mfma_f32_16x16x32_bf16 v[154:157], v[192:195], v[138:141], v[154:157]
	v_mfma_f32_16x16x32_bf16 v[56:59], v[200:203], v[138:141], v[56:59]
	v_mfma_f32_16x16x32_bf16 v[114:117], v[192:195], v[146:149], v[114:117]
	v_mfma_f32_16x16x32_bf16 v[48:51], v[200:203], v[146:149], v[48:51]
	v_mfma_f32_16x16x32_bf16 v[102:105], v[192:195], v[176:179], v[102:105]
	v_mfma_f32_16x16x32_bf16 v[36:39], v[200:203], v[176:179], v[36:39]
	v_mfma_f32_16x16x32_bf16 v[98:101], v[192:195], v[184:187], v[98:101]
	v_mfma_f32_16x16x32_bf16 v[32:35], v[200:203], v[184:187], v[32:35]
	v_mfma_f32_16x16x32_bf16 v[154:157], v[196:199], v[142:145], v[154:157]
	v_mfma_f32_16x16x32_bf16 v[56:59], v[204:207], v[142:145], v[56:59]
	v_mfma_f32_16x16x32_bf16 v[114:117], v[196:199], v[150:153], v[114:117]
	v_mfma_f32_16x16x32_bf16 v[48:51], v[204:207], v[150:153], v[48:51]
	v_mfma_f32_16x16x32_bf16 v[102:105], v[196:199], v[180:183], v[102:105]
	v_mfma_f32_16x16x32_bf16 v[36:39], v[204:207], v[180:183], v[36:39]
	v_mfma_f32_16x16x32_bf16 v[98:101], v[196:199], v[188:191], v[98:101]
	v_mfma_f32_16x16x32_bf16 v[32:35], v[204:207], v[188:191], v[32:35]
	s_mov_b32 m0, s77
	v_lshl_add_u64 v[220:221], s[64:65], 0, v[162:163]
	s_barrier
	ds_read_b128 v[138:141], v225 offset:16384
	ds_read_b128 v[142:145], v225 offset:17408
	ds_read_b128 v[146:149], v225 offset:18432
	ds_read_b128 v[150:153], v225 offset:19456
	ds_read_b128 v[176:179], v225 offset:20480
	ds_read_b128 v[180:183], v225 offset:21504
	ds_read_b128 v[184:187], v225 offset:22528
	ds_read_b128 v[188:191], v225 offset:23552
	global_load_lds_dwordx4 v[220:221], off
	v_lshl_add_u64 v[222:223], s[64:65], 0, v[164:165]
	s_mov_b32 m0, s86
	s_nop 0
	global_load_lds_dwordx4 v[222:223], off
	s_barrier
	s_waitcnt lgkmcnt(0)
	s_waitcnt lgkmcnt(0)
	v_mfma_f32_16x16x32_bf16 v[92:95], v[122:125], v[138:141], v[92:95]
	v_mfma_f32_16x16x32_bf16 v[28:31], v[130:133], v[138:141], v[28:31]
	v_mfma_f32_16x16x32_bf16 v[84:87], v[122:125], v[146:149], v[84:87]
	v_mfma_f32_16x16x32_bf16 v[20:23], v[130:133], v[146:149], v[20:23]
	v_mfma_f32_16x16x32_bf16 v[76:79], v[122:125], v[176:179], v[76:79]
	v_mfma_f32_16x16x32_bf16 v[12:15], v[130:133], v[176:179], v[12:15]
	v_mfma_f32_16x16x32_bf16 v[72:75], v[122:125], v[184:187], v[72:75]
	v_mfma_f32_16x16x32_bf16 v[8:11], v[130:133], v[184:187], v[8:11]
	v_mfma_f32_16x16x32_bf16 v[92:95], v[126:129], v[142:145], v[92:95]
	v_mfma_f32_16x16x32_bf16 v[28:31], v[134:137], v[142:145], v[28:31]
	v_mfma_f32_16x16x32_bf16 v[84:87], v[126:129], v[150:153], v[84:87]
	v_mfma_f32_16x16x32_bf16 v[20:23], v[134:137], v[150:153], v[20:23]
	v_mfma_f32_16x16x32_bf16 v[76:79], v[126:129], v[180:183], v[76:79]
	v_mfma_f32_16x16x32_bf16 v[12:15], v[134:137], v[180:183], v[12:15]
	v_mfma_f32_16x16x32_bf16 v[72:75], v[126:129], v[188:191], v[72:75]
	v_mfma_f32_16x16x32_bf16 v[8:11], v[134:137], v[188:191], v[8:11]
	s_barrier
; #define PG8_STAGE(bufoff, gbase, voff) do { _Pragma("unroll") for (int _i = 0; _i < 2; ++_i) \
;     __builtin_amdgcn_global_load_lds((const unsigned*)((const char*)(gbase) + (voff)[_i]), (LAS unsigned*)(lds + (bufoff) + ldsw + _i * 8192), 16, 0, 0); } while (0)
; #define PG8_LDA(dst, b, h) do { _Pragma("unroll") for (int m = 0; m < 4; ++m) _Pragma("unroll") for (int k = 0; k < 2; ++k) dst[m][k] = *(const LAS bf16x8*)(lds + PG8_SA(b, h) + aoff + m * 2048 + k * 1024); } while (0)
; #define PG8_LDB(dst, b, h) do { _Pragma("unroll") for (int n = 0; n < 2; ++n) _Pragma("unroll") for (int k = 0; k < 2; ++k) dst[n][k] = *(const LAS bf16x8*)(lds + PG8_SB(b, h) + boff + n * 2048 + k * 1024); } while (0)
; #define PG8_MMA(ai, bj, At, Bt) do { __builtin_amdgcn_s_setprio(1); _Pragma("unroll") for (int m = 0; m < 4; ++m) _Pragma("unroll") for (int n = 0; n < 2; ++n) _Pragma("unroll") for (int k = 0; k < 2; ++k) \
;     acc[ai][bj][m][n] = __builtin_amdgcn_mfma_f32_16x16x32_bf16(Bt[n][k], At[m][k], acc[ai][bj][m][n], 0, 0, 0); __builtin_amdgcn_s_setprio(0); } while (0)
; #define PG8_WAIT_V(n) asm volatile("s_waitcnt vmcnt(" #n ")" ::: "memory")
; #define PG8_WAIT_L(n) asm volatile("s_waitcnt lgkmcnt(" #n ")" ::: "memory")
; #define PG8_BAR __builtin_amdgcn_s_barrier()
; #define PG8_SCHED __builtin_amdgcn_sched_barrier(0)
; template <class Epi>
; __device__ __forceinline__ void gemm_phase(LAS unsigned char* lds, const Gemm g, const StaticOrder& S, const Epi& E, int wv0) {
;     ...
;       PG8_STAGE(PG8_SB(0, 1), b2 + hstepB, voffB);
;       PG8_WAIT_V(6); PG8_BAR; PG8_MMA(1, 1, At, B1); PG8_BAR;
;       PG8_LDB(B0, 1, 0); PG8_SCHED; PG8_LDA(At, 1, 0); PG8_STAGE(PG8_SA(0, 1), a2 + hstepA, voffA);
;       PG8_WAIT_L(8); PG8_BAR; PG8_WAIT_L(0); PG8_MMA(0, 0, At, B0); PG8_BAR; PG8_SCHED;
;       PG8_LDB(B1, 1, 1); PG8_STAGE(PG8_SB(1, 0), b3, voffB);
;       PG8_BAR; PG8_WAIT_L(0); PG8_MMA(0, 1, At, B1); PG8_BAR;
;       PG8_LDA(At, 1, 1); PG8_STAGE(PG8_SA(1, 0), a3, voffA);
	s_add_u32 vcc_lo, s62, 0x80000
	s_addc_u32 vcc_hi, s63, 0
	s_add_i32 s0, s0, s76
	v_lshl_add_u64 v[122:123], vcc, 0, v[96:97]
	s_mov_b32 m0, s0
	s_nop 0
	global_load_lds_dwordx4 v[122:123], off
	v_lshl_add_u64 v[122:123], vcc, 0, v[166:167]
	s_add_i32 m0, s0, 0x2000
	s_nop 0
	global_load_lds_dwordx4 v[122:123], off
	s_waitcnt vmcnt(6)
	s_barrier
	v_mfma_f32_16x16x32_bf16 v[88:91], v[192:195], v[138:141], v[88:91]
	v_mfma_f32_16x16x32_bf16 v[24:27], v[200:203], v[138:141], v[24:27]
	v_mfma_f32_16x16x32_bf16 v[80:83], v[192:195], v[146:149], v[80:83]
	v_mfma_f32_16x16x32_bf16 v[16:19], v[200:203], v[146:149], v[16:19]
	v_mfma_f32_16x16x32_bf16 v[68:71], v[192:195], v[176:179], v[68:71]
	v_mfma_f32_16x16x32_bf16 v[4:7], v[200:203], v[176:179], v[4:7]
	v_mfma_f32_16x16x32_bf16 v[64:67], v[192:195], v[184:187], v[64:67]
	v_mfma_f32_16x16x32_bf16 v[0:3], v[200:203], v[184:187], v[0:3]
	v_mfma_f32_16x16x32_bf16 v[88:91], v[196:199], v[142:145], v[88:91]
	v_mfma_f32_16x16x32_bf16 v[24:27], v[204:207], v[142:145], v[24:27]
	v_mfma_f32_16x16x32_bf16 v[80:83], v[196:199], v[150:153], v[80:83]
	v_mfma_f32_16x16x32_bf16 v[16:19], v[204:207], v[150:153], v[16:19]
	v_mfma_f32_16x16x32_bf16 v[68:71], v[196:199], v[180:183], v[68:71]
	v_mfma_f32_16x16x32_bf16 v[4:7], v[204:207], v[180:183], v[4:7]
	v_mfma_f32_16x16x32_bf16 v[64:67], v[196:199], v[188:191], v[64:67]
	v_mfma_f32_16x16x32_bf16 v[0:3], v[204:207], v[188:191], v[0:3]
	s_add_i32 s0, 0, 0x18000
	v_add_u32_e32 v134, s0, v213
	s_barrier
	ds_read_b128 v[122:125], v134
	ds_read_b128 v[126:129], v134 offset:1024
	ds_read_b128 v[130:133], v134 offset:2048
	ds_read_b128 v[134:137], v134 offset:3072
	s_add_u32 s64, s64, 0x80000
	s_addc_u32 s65, s65, 0
	s_mov_b32 m0, s87
	v_lshl_add_u64 v[192:193], s[64:65], 0, v[162:163]
	ds_read_b128 v[138:141], v225 offset:32768
	ds_read_b128 v[142:145], v225 offset:33792
	ds_read_b128 v[146:149], v225 offset:34816
	ds_read_b128 v[150:153], v225 offset:35840
	ds_read_b128 v[176:179], v225 offset:36864
	ds_read_b128 v[180:183], v225 offset:37888
	ds_read_b128 v[184:187], v225 offset:38912
	ds_read_b128 v[188:191], v225 offset:39936
	global_load_lds_dwordx4 v[192:193], off
	v_lshl_add_u64 v[192:193], s[64:65], 0, v[164:165]
	s_mov_b32 m0, s88
	s_nop 0
	global_load_lds_dwordx4 v[192:193], off
	s_waitcnt lgkmcnt(8)
	s_barrier
	s_waitcnt lgkmcnt(0)
	s_waitcnt lgkmcnt(0)
	v_mfma_f32_16x16x32_bf16 v[158:161], v[122:125], v[138:141], v[158:161]
	v_mfma_f32_16x16x32_bf16 v[60:63], v[130:133], v[138:141], v[60:63]
	v_mfma_f32_16x16x32_bf16 v[118:121], v[122:125], v[146:149], v[118:121]
	v_mfma_f32_16x16x32_bf16 v[52:55], v[130:133], v[146:149], v[52:55]
	v_mfma_f32_16x16x32_bf16 v[110:113], v[122:125], v[176:179], v[110:113]
	v_mfma_f32_16x16x32_bf16 v[44:47], v[130:133], v[176:179], v[44:47]
	v_mfma_f32_16x16x32_bf16 v[106:109], v[122:125], v[184:187], v[106:109]
	v_mfma_f32_16x16x32_bf16 v[40:43], v[130:133], v[184:187], v[40:43]
	v_mfma_f32_16x16x32_bf16 v[158:161], v[126:129], v[142:145], v[158:161]
	v_mfma_f32_16x16x32_bf16 v[60:63], v[134:137], v[142:145], v[60:63]
	v_mfma_f32_16x16x32_bf16 v[118:121], v[126:129], v[150:153], v[118:121]
	v_mfma_f32_16x16x32_bf16 v[52:55], v[134:137], v[150:153], v[52:55]
	v_mfma_f32_16x16x32_bf16 v[110:113], v[126:129], v[180:183], v[110:113]
	v_mfma_f32_16x16x32_bf16 v[44:47], v[134:137], v[180:183], v[44:47]
	v_mfma_f32_16x16x32_bf16 v[106:109], v[126:129], v[188:191], v[106:109]
	v_mfma_f32_16x16x32_bf16 v[40:43], v[134:137], v[188:191], v[40:43]
	s_barrier
	s_add_i32 s64, 0, 0x1c000
	s_add_i32 s0, s0, s76
	v_add_u32_e32 v204, s64, v213
	v_lshl_add_u64 v[208:209], v[208:209], 0, s[72:73]
	s_mov_b32 m0, s0
	ds_read_b128 v[192:195], v204
	ds_read_b128 v[196:199], v204 offset:1024
	ds_read_b128 v[200:203], v204 offset:2048
	ds_read_b128 v[204:207], v204 offset:3072
	global_load_lds_dwordx4 v[208:209], off
	v_lshl_add_u64 v[208:209], v[210:211], 0, s[72:73]
	s_add_i32 m0, s0, 0x2000
	s_nop 0
	global_load_lds_dwordx4 v[208:209], off
	s_barrier
	s_waitcnt lgkmcnt(0)
	s_waitcnt lgkmcnt(0)
	v_mfma_f32_16x16x32_bf16 v[154:157], v[192:195], v[138:141], v[154:157]
	v_mfma_f32_16x16x32_bf16 v[56:59], v[200:203], v[138:141], v[56:59]
	v_mfma_f32_16x16x32_bf16 v[114:117], v[192:195], v[146:149], v[114:117]
	v_mfma_f32_16x16x32_bf16 v[48:51], v[200:203], v[146:149], v[48:51]
	v_mfma_f32_16x16x32_bf16 v[102:105], v[192:195], v[176:179], v[102:105]
	v_mfma_f32_16x16x32_bf16 v[36:39], v[200:203], v[176:179], v[36:39]
	v_mfma_f32_16x16x32_bf16 v[98:101], v[192:195], v[184:187], v[98:101]
	v_mfma_f32_16x16x32_bf16 v[32:35], v[200:203], v[184:187], v[32:35]
	v_mfma_f32_16x16x32_bf16 v[154:157], v[196:199], v[142:145], v[154:157]
	v_mfma_f32_16x16x32_bf16 v[56:59], v[204:207], v[142:145], v[56:59]
	v_mfma_f32_16x16x32_bf16 v[114:117], v[196:199], v[150:153], v[114:117]
	v_mfma_f32_16x16x32_bf16 v[48:51], v[204:207], v[150:153], v[48:51]
	v_mfma_f32_16x16x32_bf16 v[102:105], v[196:199], v[180:183], v[102:105]
	v_mfma_f32_16x16x32_bf16 v[36:39], v[204:207], v[180:183], v[36:39]
	v_mfma_f32_16x16x32_bf16 v[98:101], v[196:199], v[188:191], v[98:101]
	v_mfma_f32_16x16x32_bf16 v[32:35], v[204:207], v[188:191], v[32:35]
	s_mov_b32 m0, s89
	v_lshl_add_u64 v[208:209], v[220:221], 0, s[72:73]
	s_barrier
; #define LAS __attribute__((address_space(3)))
; #define PG8_STAGE(bufoff, gbase, voff) do { _Pragma("unroll") for (int _i = 0; _i < 2; ++_i) \
;     __builtin_amdgcn_global_load_lds((const unsigned*)((const char*)(gbase) + (voff)[_i]), (LAS unsigned*)(lds + (bufoff) + ldsw + _i * 8192), 16, 0, 0); } while (0)
; #define PG8_LDA(dst, b, h) do { _Pragma("unroll") for (int m = 0; m < 4; ++m) _Pragma("unroll") for (int k = 0; k < 2; ++k) dst[m][k] = *(const LAS bf16x8*)(lds + PG8_SA(b, h) + aoff + m * 2048 + k * 1024); } while (0)
; #define PG8_MMA(ai, bj, At, Bt) do { __builtin_amdgcn_s_setprio(1); _Pragma("unroll") for (int m = 0; m < 4; ++m) _Pragma("unroll") for (int n = 0; n < 2; ++n) _Pragma("unroll") for (int k = 0; k < 2; ++k) \
;     acc[ai][bj][m][n] = __builtin_amdgcn_mfma_f32_16x16x32_bf16(Bt[n][k], At[m][k], acc[ai][bj][m][n], 0, 0, 0); __builtin_amdgcn_s_setprio(0); } while (0)
; #define PG8_WAIT_V(n) asm volatile("s_waitcnt vmcnt(" #n ")" ::: "memory")
; #define PG8_WAIT_L(n) asm volatile("s_waitcnt lgkmcnt(" #n ")" ::: "memory")
; #define PG8_BAR __builtin_amdgcn_s_barrier()
; template <class Epi>
; __device__ __forceinline__ void gemm_phase(LAS unsigned char* lds, const Gemm g, const StaticOrder& S, const Epi& E, int wv0) {
;     ...
;       PG8_BAR; PG8_WAIT_L(0); PG8_MMA(0, 1, At, B1); PG8_BAR;
;       PG8_LDA(At, 1, 1); PG8_STAGE(PG8_SA(1, 0), a3, voffA);
;       PG8_BAR; PG8_WAIT_L(0); PG8_MMA(1, 0, At, B0); PG8_BAR; PG8_SCHED;
;       PG8_STAGE(PG8_SB(1, 1), b3 + hstepB, voffB);
;       PG8_WAIT_V(6); PG8_BAR; PG8_MMA(1, 1, At, B1); PG8_BAR;
; __device__ __forceinline__ void epi_upc(const EpiP& e, const f32x4 (&acc)[2][2][4][2], const pg8::Unit& u, int wr, int wc, int fr, int fq) {
;     ...
;       for (int bj = 0; bj < 2; ++bj) {
;         u32x4 w; w.x = pk2(acc[ai][bj][m][0][0], acc[ai][bj][m][0][1]); w.y = pk2(acc[ai][bj][m][0][2], acc[ai][bj][m][0][3]);
;         w.z = pk2(acc[ai][bj][m][1][0], acc[ai][bj][m][1][1]); w.w = pk2(acc[ai][bj][m][1][2], acc[ai][bj][m][1][3]);
;         if (m == 3 && fr >= 14) *(LAS u32x4*)(ex + ((g * 2 + (fr - 14)) * 256 + bj * 128 + lc0) * 2) = w;
;         const int ucol = bj * DFF + 128 * u.pn + lc0;
;         if (g == 15 && fr >= 14) *(u32x4*)(side + ((size_t)u.pm * 4 + 2 + (fr - 14)) * NUP + ucol) = w;
;         if (g == 0 && fr < 2) *(u32x4*)(side + ((size_t)u.pm * 4 + fr) * NUP + ucol) = w;
	ds_read_b128 v[138:141], v225 offset:49152
	ds_read_b128 v[142:145], v225 offset:50176
	ds_read_b128 v[146:149], v225 offset:51200
	ds_read_b128 v[150:153], v225 offset:52224
	ds_read_b128 v[176:179], v225 offset:53248
	ds_read_b128 v[180:183], v225 offset:54272
	ds_read_b128 v[184:187], v225 offset:55296
	ds_read_b128 v[188:191], v225 offset:56320
	global_load_lds_dwordx4 v[208:209], off
	v_lshl_add_u64 v[208:209], v[222:223], 0, s[72:73]
	s_mov_b32 m0, s92
	s_nop 0
	global_load_lds_dwordx4 v[208:209], off
	s_barrier
	s_waitcnt lgkmcnt(0)
	s_waitcnt lgkmcnt(0)
	v_mfma_f32_16x16x32_bf16 v[92:95], v[122:125], v[138:141], v[92:95]
	v_mfma_f32_16x16x32_bf16 v[28:31], v[130:133], v[138:141], v[28:31]
	v_mfma_f32_16x16x32_bf16 v[84:87], v[122:125], v[146:149], v[84:87]
	v_mfma_f32_16x16x32_bf16 v[20:23], v[130:133], v[146:149], v[20:23]
	v_mfma_f32_16x16x32_bf16 v[76:79], v[122:125], v[176:179], v[76:79]
	v_mfma_f32_16x16x32_bf16 v[12:15], v[130:133], v[176:179], v[12:15]
	v_mfma_f32_16x16x32_bf16 v[72:75], v[122:125], v[184:187], v[72:75]
	v_mfma_f32_16x16x32_bf16 v[8:11], v[130:133], v[184:187], v[8:11]
	v_mfma_f32_16x16x32_bf16 v[92:95], v[126:129], v[142:145], v[92:95]
	v_mfma_f32_16x16x32_bf16 v[28:31], v[134:137], v[142:145], v[28:31]
	v_mfma_f32_16x16x32_bf16 v[84:87], v[126:129], v[150:153], v[84:87]
	v_mfma_f32_16x16x32_bf16 v[20:23], v[134:137], v[150:153], v[20:23]
	v_mfma_f32_16x16x32_bf16 v[76:79], v[126:129], v[180:183], v[76:79]
	v_mfma_f32_16x16x32_bf16 v[12:15], v[134:137], v[180:183], v[12:15]
	v_mfma_f32_16x16x32_bf16 v[72:75], v[126:129], v[188:191], v[72:75]
	v_mfma_f32_16x16x32_bf16 v[8:11], v[134:137], v[188:191], v[8:11]
	s_barrier
	s_add_u32 s62, s62, 0x80080
	s_addc_u32 s63, s63, 0
	s_add_i32 s0, s64, s76
	v_lshl_add_u64 v[122:123], s[62:63], 0, v[96:97]
	s_mov_b32 m0, s0
	s_nop 0
	global_load_lds_dwordx4 v[122:123], off
	v_lshl_add_u64 v[122:123], s[62:63], 0, v[166:167]
	s_add_i32 m0, s0, 0x2000
	s_nop 0
	global_load_lds_dwordx4 v[122:123], off
	s_waitcnt vmcnt(6)
	s_barrier
	v_mfma_f32_16x16x32_bf16 v[88:91], v[192:195], v[138:141], v[88:91]
	v_mfma_f32_16x16x32_bf16 v[24:27], v[200:203], v[138:141], v[24:27]
	v_mfma_f32_16x16x32_bf16 v[80:83], v[192:195], v[146:149], v[80:83]
	v_mfma_f32_16x16x32_bf16 v[16:19], v[200:203], v[146:149], v[16:19]
	v_mfma_f32_16x16x32_bf16 v[68:71], v[192:195], v[176:179], v[68:71]
	v_mfma_f32_16x16x32_bf16 v[4:7], v[200:203], v[176:179], v[4:7]
	v_mfma_f32_16x16x32_bf16 v[64:67], v[192:195], v[184:187], v[64:67]
	v_mfma_f32_16x16x32_bf16 v[0:3], v[200:203], v[184:187], v[0:3]
	v_mfma_f32_16x16x32_bf16 v[88:91], v[196:199], v[142:145], v[88:91]
	v_mfma_f32_16x16x32_bf16 v[24:27], v[204:207], v[142:145], v[24:27]
	v_mfma_f32_16x16x32_bf16 v[80:83], v[196:199], v[150:153], v[80:83]
	v_mfma_f32_16x16x32_bf16 v[16:19], v[204:207], v[150:153], v[16:19]
	v_mfma_f32_16x16x32_bf16 v[68:71], v[196:199], v[180:183], v[68:71]
	v_mfma_f32_16x16x32_bf16 v[4:7], v[204:207], v[180:183], v[4:7]
	v_mfma_f32_16x16x32_bf16 v[64:67], v[196:199], v[188:191], v[64:67]
	v_mfma_f32_16x16x32_bf16 v[0:3], v[204:207], v[188:191], v[0:3]
	s_add_i32 s78, s78, 2
	s_add_u32 s60, s60, 0x100
	s_addc_u32 s61, s61, 0
	s_add_u32 s59, s59, 0x100
	s_addc_u32 s75, s75, 0
	s_cmp_gt_u32 s78, 29
	s_barrier
	s_cbranch_scc0 .LBB0_1270
	s_and_saveexec_b64 s[60:61], s[36:37]
	s_movk_i32 s78, 0x5800
	s_cbranch_execz .LBB0_1273
	s_ashr_i32 s57, s56, 31
	s_lshl_b64 s[0:1], s[56:57], 2
	s_lshl_b32 s49, s58, 7
	v_or_b32_e32 v127, s0, v168
	v_mov_b64_e32 v[128:129], s[14:15]
	v_or_b32_e32 v126, s49, v214
	v_mad_u64_u32 v[128:129], s[62:63], v127, s78, v[128:129]
	v_mov_b32_e32 v127, 0x5800
	v_mad_i32_i24 v129, s1, v127, v129
	v_ashrrev_i32_e32 v127, 31, v126
	v_cvt_pk_bf16_f32 v122, v158, v159
	v_cvt_pk_bf16_f32 v123, v160, v161
	v_cvt_pk_bf16_f32 v124, v60, v61
	v_cvt_pk_bf16_f32 v125, v62, v63
	v_lshl_add_u64 v[126:127], v[126:127], 1, v[128:129]
	global_store_dwordx4 v[126:127], v[122:125], off
	v_add_u32_e32 v126, s49, v169
	v_ashrrev_i32_e32 v127, 31, v126
	v_cvt_pk_bf16_f32 v122, v154, v155
	v_cvt_pk_bf16_f32 v123, v156, v157
	v_cvt_pk_bf16_f32 v124, v56, v57
	v_cvt_pk_bf16_f32 v125, v58, v59
	v_lshl_add_u64 v[126:127], v[126:127], 1, v[128:129]
	global_store_dwordx4 v[126:127], v[122:125], off

; #define PG8_STAGE(bufoff, gbase, voff) do { _Pragma("unroll") for (int _i = 0; _i < 2; ++_i) \
;     __builtin_amdgcn_global_load_lds((const unsigned*)((const char*)(gbase) + (voff)[_i]), (LAS unsigned*)(lds + (bufoff) + ldsw + _i * 8192), 16, 0, 0); } while (0)
; #define PG8_LDA(dst, b, h) do { _Pragma("unroll") for (int m = 0; m < 4; ++m) _Pragma("unroll") for (int k = 0; k < 2; ++k) dst[m][k] = *(const LAS bf16x8*)(lds + PG8_SA(b, h) + aoff + m * 2048 + k * 1024); } while (0)
; #define PG8_LDB(dst, b, h) do { _Pragma("unroll") for (int n = 0; n < 2; ++n) _Pragma("unroll") for (int k = 0; k < 2; ++k) dst[n][k] = *(const LAS bf16x8*)(lds + PG8_SB(b, h) + boff + n * 2048 + k * 1024); } while (0)
; #define PG8_MMA(ai, bj, At, Bt) do { __builtin_amdgcn_s_setprio(1); _Pragma("unroll") for (int m = 0; m < 4; ++m) _Pragma("unroll") for (int n = 0; n < 2; ++n) _Pragma("unroll") for (int k = 0; k < 2; ++k) \
;     acc[ai][bj][m][n] = __builtin_amdgcn_mfma_f32_16x16x32_bf16(Bt[n][k], At[m][k], acc[ai][bj][m][n], 0, 0, 0); __builtin_amdgcn_s_setprio(0); } while (0)
; #define PG8_WAIT_V(n) asm volatile("s_waitcnt vmcnt(" #n ")" ::: "memory")
; #define PG8_WAIT_L(n) asm volatile("s_waitcnt lgkmcnt(" #n ")" ::: "memory")
; #define PG8_BAR __builtin_amdgcn_s_barrier()
; #define PG8_SCHED __builtin_amdgcn_sched_barrier(0)
; template <class Epi>
; __device__ __forceinline__ void gemm_phase(LAS unsigned char* lds, const Gemm g, const StaticOrder& S, const Epi& E, int wv0) {
;     ...
;       PG8_LDB(B0, 0, 0); PG8_SCHED; PG8_LDA(At, 0, 0); PG8_STAGE(PG8_SA(1, 1), a1 + hstepA, voffA);
;       PG8_WAIT_L(8); PG8_BAR; PG8_WAIT_L(0); PG8_MMA(0, 0, At, B0); PG8_BAR; PG8_SCHED;
;       PG8_LDB(B1, 0, 1); PG8_STAGE(PG8_SB(0, 0), b2, voffB);
;       PG8_BAR; PG8_WAIT_L(0); PG8_MMA(0, 1, At, B1); PG8_BAR;
;       PG8_LDA(At, 0, 1); PG8_STAGE(PG8_SA(0, 0), a2, voffA);
;       PG8_BAR; PG8_WAIT_L(0); PG8_MMA(1, 0, At, B0); PG8_BAR; PG8_SCHED;
;       PG8_STAGE(PG8_SB(0, 1), b2 + hstepB, voffB);
;       PG8_WAIT_V(6); PG8_BAR; PG8_MMA(1, 1, At, B1); PG8_BAR;
.Lgprio9:
.LBB0_1429:
	s_add_u32 s14, s12, 0x100
	s_addc_u32 s15, s13, 0
	s_add_i32 s0, 0, 0x10000
	v_add_u32_e32 v142, s0, v187
	ds_read_b128 v[130:133], v142
	ds_read_b128 v[134:137], v142 offset:1024
	ds_read_b128 v[138:141], v142 offset:2048
	ds_read_b128 v[142:145], v142 offset:3072
	s_cmpk_eq_i32 s45, 0x54
	s_cselect_b32 s19, s5, s15
	s_cselect_b32 s18, s4, s14
	s_cselect_b32 s17, s7, s44
	s_cselect_b32 s16, s6, s43
	v_lshl_add_u64 v[184:185], s[12:13], 0, v[168:169]
	s_add_i32 m0, s30, 0xc000
	ds_read_b128 v[146:149], v189
	ds_read_b128 v[150:153], v189 offset:1024
	ds_read_b128 v[154:157], v189 offset:2048
	ds_read_b128 v[158:161], v189 offset:3072
	ds_read_b128 v[172:175], v189 offset:4096
	ds_read_b128 v[176:179], v189 offset:5120
	ds_read_b128 v[180:183], v189 offset:6144
	ds_read_b128 v[190:193], v189 offset:7168
	global_load_lds_dwordx4 v[184:185], off
	v_lshl_add_u64 v[184:185], s[12:13], 0, v[170:171]
	s_add_i32 m0, s30, 0xe000
	s_nop 0
	global_load_lds_dwordx4 v[184:185], off
	s_waitcnt lgkmcnt(8)
	s_barrier
	s_waitcnt lgkmcnt(0)
	s_waitcnt lgkmcnt(0)
	v_mfma_f32_16x16x32_bf16 v[126:129], v[130:133], v[146:149], v[126:129]
	v_mfma_f32_16x16x32_bf16 v[122:125], v[138:141], v[146:149], v[122:125]
	v_mfma_f32_16x16x32_bf16 v[118:121], v[130:133], v[154:157], v[118:121]
	v_mfma_f32_16x16x32_bf16 v[114:117], v[138:141], v[154:157], v[114:117]
	v_mfma_f32_16x16x32_bf16 v[92:95], v[130:133], v[172:175], v[92:95]
	v_mfma_f32_16x16x32_bf16 v[88:91], v[138:141], v[172:175], v[88:91]
	v_mfma_f32_16x16x32_bf16 v[84:87], v[130:133], v[180:183], v[84:87]
	v_mfma_f32_16x16x32_bf16 v[76:79], v[138:141], v[180:183], v[76:79]
	v_mfma_f32_16x16x32_bf16 v[126:129], v[134:137], v[150:153], v[126:129]
	v_mfma_f32_16x16x32_bf16 v[122:125], v[142:145], v[150:153], v[122:125]
	v_mfma_f32_16x16x32_bf16 v[118:121], v[134:137], v[158:161], v[118:121]
	v_mfma_f32_16x16x32_bf16 v[114:117], v[142:145], v[158:161], v[114:117]
	v_mfma_f32_16x16x32_bf16 v[92:95], v[134:137], v[176:179], v[92:95]
	v_mfma_f32_16x16x32_bf16 v[88:91], v[142:145], v[176:179], v[88:91]
	v_mfma_f32_16x16x32_bf16 v[84:87], v[134:137], v[190:193], v[84:87]
	v_mfma_f32_16x16x32_bf16 v[76:79], v[142:145], v[190:193], v[76:79]
	s_barrier
	s_add_i32 s46, 0, 0x14000
	v_add_u32_e32 v184, s46, v187
	s_add_i32 s0, s0, s29
	ds_read_b128 v[194:197], v184
	ds_read_b128 v[198:201], v184 offset:1024
	ds_read_b128 v[202:205], v184 offset:2048
	ds_read_b128 v[206:209], v184 offset:3072
	v_lshl_add_u64 v[184:185], s[16:17], 0, v[96:97]
	s_mov_b32 m0, s0
	v_lshl_add_u64 v[210:211], s[16:17], 0, v[166:167]
	global_load_lds_dwordx4 v[184:185], off
	s_add_i32 m0, s0, 0x2000
	s_nop 0
	global_load_lds_dwordx4 v[210:211], off
	s_barrier
	s_waitcnt lgkmcnt(0)
	s_waitcnt lgkmcnt(0)
	v_mfma_f32_16x16x32_bf16 v[110:113], v[194:197], v[146:149], v[110:113]
	v_mfma_f32_16x16x32_bf16 v[106:109], v[202:205], v[146:149], v[106:109]
	v_mfma_f32_16x16x32_bf16 v[102:105], v[194:197], v[154:157], v[102:105]
	v_mfma_f32_16x16x32_bf16 v[98:101], v[202:205], v[154:157], v[98:101]
	v_mfma_f32_16x16x32_bf16 v[80:83], v[194:197], v[172:175], v[80:83]
	v_mfma_f32_16x16x32_bf16 v[72:75], v[202:205], v[172:175], v[72:75]
	v_mfma_f32_16x16x32_bf16 v[68:71], v[194:197], v[180:183], v[68:71]
	v_mfma_f32_16x16x32_bf16 v[64:67], v[202:205], v[180:183], v[64:67]
	v_mfma_f32_16x16x32_bf16 v[110:113], v[198:201], v[150:153], v[110:113]
	v_mfma_f32_16x16x32_bf16 v[106:109], v[206:209], v[150:153], v[106:109]
	v_mfma_f32_16x16x32_bf16 v[102:105], v[198:201], v[158:161], v[102:105]
	v_mfma_f32_16x16x32_bf16 v[98:101], v[206:209], v[158:161], v[98:101]
	v_mfma_f32_16x16x32_bf16 v[80:83], v[198:201], v[176:179], v[80:83]
	v_mfma_f32_16x16x32_bf16 v[72:75], v[206:209], v[176:179], v[72:75]
	v_mfma_f32_16x16x32_bf16 v[68:71], v[198:201], v[190:193], v[68:71]
	v_mfma_f32_16x16x32_bf16 v[64:67], v[206:209], v[190:193], v[64:67]
	s_mov_b32 m0, s30
	v_lshl_add_u64 v[212:213], s[18:19], 0, v[162:163]
	s_barrier
	ds_read_b128 v[146:149], v189 offset:16384
	ds_read_b128 v[150:153], v189 offset:17408
	ds_read_b128 v[154:157], v189 offset:18432
	ds_read_b128 v[158:161], v189 offset:19456
	ds_read_b128 v[172:175], v189 offset:20480
	ds_read_b128 v[176:179], v189 offset:21504
	ds_read_b128 v[180:183], v189 offset:22528
	ds_read_b128 v[190:193], v189 offset:23552
	global_load_lds_dwordx4 v[212:213], off
	v_lshl_add_u64 v[214:215], s[18:19], 0, v[164:165]
	s_mov_b32 m0, s31
	s_nop 0
	global_load_lds_dwordx4 v[214:215], off
	s_barrier
	s_waitcnt lgkmcnt(0)
	s_waitcnt lgkmcnt(0)
	v_mfma_f32_16x16x32_bf16 v[60:63], v[130:133], v[146:149], v[60:63]
	v_mfma_f32_16x16x32_bf16 v[56:59], v[138:141], v[146:149], v[56:59]
	v_mfma_f32_16x16x32_bf16 v[48:51], v[130:133], v[154:157], v[48:51]
	v_mfma_f32_16x16x32_bf16 v[40:43], v[138:141], v[154:157], v[40:43]
	v_mfma_f32_16x16x32_bf16 v[28:31], v[130:133], v[172:175], v[28:31]
	v_mfma_f32_16x16x32_bf16 v[24:27], v[138:141], v[172:175], v[24:27]
	v_mfma_f32_16x16x32_bf16 v[16:19], v[130:133], v[180:183], v[16:19]
	v_mfma_f32_16x16x32_bf16 v[8:11], v[138:141], v[180:183], v[8:11]
	v_mfma_f32_16x16x32_bf16 v[60:63], v[134:137], v[150:153], v[60:63]
	v_mfma_f32_16x16x32_bf16 v[56:59], v[142:145], v[150:153], v[56:59]
	v_mfma_f32_16x16x32_bf16 v[48:51], v[134:137], v[158:161], v[48:51]
	v_mfma_f32_16x16x32_bf16 v[40:43], v[142:145], v[158:161], v[40:43]
	v_mfma_f32_16x16x32_bf16 v[28:31], v[134:137], v[176:179], v[28:31]
	v_mfma_f32_16x16x32_bf16 v[24:27], v[142:145], v[176:179], v[24:27]
	v_mfma_f32_16x16x32_bf16 v[16:19], v[134:137], v[190:193], v[16:19]
	v_mfma_f32_16x16x32_bf16 v[8:11], v[142:145], v[190:193], v[8:11]
	s_barrier
; #define PG8_STAGE(bufoff, gbase, voff) do { _Pragma("unroll") for (int _i = 0; _i < 2; ++_i) \
;     __builtin_amdgcn_global_load_lds((const unsigned*)((const char*)(gbase) + (voff)[_i]), (LAS unsigned*)(lds + (bufoff) + ldsw + _i * 8192), 16, 0, 0); } while (0)
; #define PG8_LDA(dst, b, h) do { _Pragma("unroll") for (int m = 0; m < 4; ++m) _Pragma("unroll") for (int k = 0; k < 2; ++k) dst[m][k] = *(const LAS bf16x8*)(lds + PG8_SA(b, h) + aoff + m * 2048 + k * 1024); } while (0)
; #define PG8_LDB(dst, b, h) do { _Pragma("unroll") for (int n = 0; n < 2; ++n) _Pragma("unroll") for (int k = 0; k < 2; ++k) dst[n][k] = *(const LAS bf16x8*)(lds + PG8_SB(b, h) + boff + n * 2048 + k * 1024); } while (0)
; #define PG8_MMA(ai, bj, At, Bt) do { __builtin_amdgcn_s_setprio(1); _Pragma("unroll") for (int m = 0; m < 4; ++m) _Pragma("unroll") for (int n = 0; n < 2; ++n) _Pragma("unroll") for (int k = 0; k < 2; ++k) \
;     acc[ai][bj][m][n] = __builtin_amdgcn_mfma_f32_16x16x32_bf16(Bt[n][k], At[m][k], acc[ai][bj][m][n], 0, 0, 0); __builtin_amdgcn_s_setprio(0); } while (0)
; #define PG8_WAIT_V(n) asm volatile("s_waitcnt vmcnt(" #n ")" ::: "memory")
; #define PG8_WAIT_L(n) asm volatile("s_waitcnt lgkmcnt(" #n ")" ::: "memory")
; #define PG8_BAR __builtin_amdgcn_s_barrier()
; #define PG8_SCHED __builtin_amdgcn_sched_barrier(0)
; template <class Epi>
; __device__ __forceinline__ void gemm_phase(LAS unsigned char* lds, const Gemm g, const StaticOrder& S, const Epi& E, int wv0) {
;     ...
;       PG8_STAGE(PG8_SB(0, 1), b2 + hstepB, voffB);
;       PG8_WAIT_V(6); PG8_BAR; PG8_MMA(1, 1, At, B1); PG8_BAR;
;       PG8_LDB(B0, 1, 0); PG8_SCHED; PG8_LDA(At, 1, 0); PG8_STAGE(PG8_SA(0, 1), a2 + hstepA, voffA);
;       PG8_WAIT_L(8); PG8_BAR; PG8_WAIT_L(0); PG8_MMA(0, 0, At, B0); PG8_BAR; PG8_SCHED;
;       PG8_LDB(B1, 1, 1); PG8_STAGE(PG8_SB(1, 0), b3, voffB);
;       PG8_BAR; PG8_WAIT_L(0); PG8_MMA(0, 1, At, B1); PG8_BAR;
;       PG8_LDA(At, 1, 1); PG8_STAGE(PG8_SA(1, 0), a3, voffA);
	s_add_u32 s12, s16, 0x160000
	s_addc_u32 s13, s17, 0
	s_add_i32 s0, s46, s29
	v_lshl_add_u64 v[130:131], s[12:13], 0, v[96:97]
	s_mov_b32 m0, s0
	s_nop 0
	global_load_lds_dwordx4 v[130:131], off
	v_lshl_add_u64 v[130:131], s[12:13], 0, v[166:167]
	s_add_i32 m0, s0, 0x2000
	s_nop 0
	global_load_lds_dwordx4 v[130:131], off
	s_waitcnt vmcnt(6)
	s_barrier
	v_mfma_f32_16x16x32_bf16 v[52:55], v[194:197], v[146:149], v[52:55]
	v_mfma_f32_16x16x32_bf16 v[44:47], v[202:205], v[146:149], v[44:47]
	v_mfma_f32_16x16x32_bf16 v[36:39], v[194:197], v[154:157], v[36:39]
	v_mfma_f32_16x16x32_bf16 v[32:35], v[202:205], v[154:157], v[32:35]
	v_mfma_f32_16x16x32_bf16 v[20:23], v[194:197], v[172:175], v[20:23]
	v_mfma_f32_16x16x32_bf16 v[12:15], v[202:205], v[172:175], v[12:15]
	v_mfma_f32_16x16x32_bf16 v[4:7], v[194:197], v[180:183], v[4:7]
	v_mfma_f32_16x16x32_bf16 v[0:3], v[202:205], v[180:183], v[0:3]
	v_mfma_f32_16x16x32_bf16 v[52:55], v[198:201], v[150:153], v[52:55]
	v_mfma_f32_16x16x32_bf16 v[44:47], v[206:209], v[150:153], v[44:47]
	v_mfma_f32_16x16x32_bf16 v[36:39], v[198:201], v[158:161], v[36:39]
	v_mfma_f32_16x16x32_bf16 v[32:35], v[206:209], v[158:161], v[32:35]
	v_mfma_f32_16x16x32_bf16 v[20:23], v[198:201], v[176:179], v[20:23]
	v_mfma_f32_16x16x32_bf16 v[12:15], v[206:209], v[176:179], v[12:15]
	v_mfma_f32_16x16x32_bf16 v[4:7], v[198:201], v[190:193], v[4:7]
	v_mfma_f32_16x16x32_bf16 v[0:3], v[206:209], v[190:193], v[0:3]
	s_add_i32 s0, 0, 0x18000
	v_add_u32_e32 v142, s0, v187
	s_barrier
	ds_read_b128 v[130:133], v142
	ds_read_b128 v[134:137], v142 offset:1024
	ds_read_b128 v[138:141], v142 offset:2048
	ds_read_b128 v[142:145], v142 offset:3072
	s_add_u32 s12, s18, 0x160000
	s_addc_u32 s13, s19, 0
	s_mov_b32 m0, s34
	v_lshl_add_u64 v[194:195], s[12:13], 0, v[162:163]
	ds_read_b128 v[146:149], v189 offset:32768
	ds_read_b128 v[150:153], v189 offset:33792
	ds_read_b128 v[154:157], v189 offset:34816
	ds_read_b128 v[158:161], v189 offset:35840
	ds_read_b128 v[172:175], v189 offset:36864
	ds_read_b128 v[176:179], v189 offset:37888
	ds_read_b128 v[180:183], v189 offset:38912
	ds_read_b128 v[190:193], v189 offset:39936
	global_load_lds_dwordx4 v[194:195], off
	v_lshl_add_u64 v[194:195], s[12:13], 0, v[164:165]
	s_mov_b32 m0, s35
	s_nop 0
	global_load_lds_dwordx4 v[194:195], off
	s_waitcnt lgkmcnt(8)
	s_barrier
	s_waitcnt lgkmcnt(0)
	s_waitcnt lgkmcnt(0)
	v_mfma_f32_16x16x32_bf16 v[126:129], v[130:133], v[146:149], v[126:129]
	v_mfma_f32_16x16x32_bf16 v[122:125], v[138:141], v[146:149], v[122:125]
	v_mfma_f32_16x16x32_bf16 v[118:121], v[130:133], v[154:157], v[118:121]
	v_mfma_f32_16x16x32_bf16 v[114:117], v[138:141], v[154:157], v[114:117]
	v_mfma_f32_16x16x32_bf16 v[92:95], v[130:133], v[172:175], v[92:95]
	v_mfma_f32_16x16x32_bf16 v[88:91], v[138:141], v[172:175], v[88:91]
	v_mfma_f32_16x16x32_bf16 v[84:87], v[130:133], v[180:183], v[84:87]
	v_mfma_f32_16x16x32_bf16 v[76:79], v[138:141], v[180:183], v[76:79]
	v_mfma_f32_16x16x32_bf16 v[126:129], v[134:137], v[150:153], v[126:129]
	v_mfma_f32_16x16x32_bf16 v[122:125], v[142:145], v[150:153], v[122:125]
	v_mfma_f32_16x16x32_bf16 v[118:121], v[134:137], v[158:161], v[118:121]
	v_mfma_f32_16x16x32_bf16 v[114:117], v[142:145], v[158:161], v[114:117]
	v_mfma_f32_16x16x32_bf16 v[92:95], v[134:137], v[176:179], v[92:95]
	v_mfma_f32_16x16x32_bf16 v[88:91], v[142:145], v[176:179], v[88:91]
	v_mfma_f32_16x16x32_bf16 v[84:87], v[134:137], v[190:193], v[84:87]
	v_mfma_f32_16x16x32_bf16 v[76:79], v[142:145], v[190:193], v[76:79]
	s_barrier
	s_add_i32 s18, 0, 0x1c000
	s_add_i32 s0, s0, s29
	v_add_u32_e32 v206, s18, v187
	v_lshl_add_u64 v[184:185], v[184:185], 0, s[72:73]
	s_mov_b32 m0, s0
	ds_read_b128 v[194:197], v206
	ds_read_b128 v[198:201], v206 offset:1024
	ds_read_b128 v[202:205], v206 offset:2048
	ds_read_b128 v[206:209], v206 offset:3072
	global_load_lds_dwordx4 v[184:185], off
	v_lshl_add_u64 v[184:185], v[210:211], 0, s[72:73]
	s_add_i32 m0, s0, 0x2000
	s_nop 0
	global_load_lds_dwordx4 v[184:185], off
	s_barrier
	s_waitcnt lgkmcnt(0)
	s_waitcnt lgkmcnt(0)
	v_mfma_f32_16x16x32_bf16 v[110:113], v[194:197], v[146:149], v[110:113]
	v_mfma_f32_16x16x32_bf16 v[106:109], v[202:205], v[146:149], v[106:109]
	v_mfma_f32_16x16x32_bf16 v[102:105], v[194:197], v[154:157], v[102:105]
	v_mfma_f32_16x16x32_bf16 v[98:101], v[202:205], v[154:157], v[98:101]
	v_mfma_f32_16x16x32_bf16 v[80:83], v[194:197], v[172:175], v[80:83]
	v_mfma_f32_16x16x32_bf16 v[72:75], v[202:205], v[172:175], v[72:75]
	v_mfma_f32_16x16x32_bf16 v[68:71], v[194:197], v[180:183], v[68:71]
	v_mfma_f32_16x16x32_bf16 v[64:67], v[202:205], v[180:183], v[64:67]
	v_mfma_f32_16x16x32_bf16 v[110:113], v[198:201], v[150:153], v[110:113]
	v_mfma_f32_16x16x32_bf16 v[106:109], v[206:209], v[150:153], v[106:109]
	v_mfma_f32_16x16x32_bf16 v[102:105], v[198:201], v[158:161], v[102:105]
	v_mfma_f32_16x16x32_bf16 v[98:101], v[206:209], v[158:161], v[98:101]
	v_mfma_f32_16x16x32_bf16 v[80:83], v[198:201], v[176:179], v[80:83]
	v_mfma_f32_16x16x32_bf16 v[72:75], v[206:209], v[176:179], v[72:75]
	v_mfma_f32_16x16x32_bf16 v[68:71], v[198:201], v[190:193], v[68:71]
	v_mfma_f32_16x16x32_bf16 v[64:67], v[206:209], v[190:193], v[64:67]
	s_mov_b32 m0, s36
	v_lshl_add_u64 v[184:185], v[212:213], 0, s[72:73]
	s_barrier
	ds_read_b128 v[146:149], v189 offset:49152
	ds_read_b128 v[150:153], v189 offset:50176
	ds_read_b128 v[154:157], v189 offset:51200
	ds_read_b128 v[158:161], v189 offset:52224
	ds_read_b128 v[172:175], v189 offset:53248
	ds_read_b128 v[176:179], v189 offset:54272
	ds_read_b128 v[180:183], v189 offset:55296
	ds_read_b128 v[190:193], v189 offset:56320
	global_load_lds_dwordx4 v[184:185], off
	v_lshl_add_u64 v[184:185], v[214:215], 0, s[72:73]
	s_mov_b32 m0, s37
	s_nop 0
	global_load_lds_dwordx4 v[184:185], off
	s_barrier
; #define PG8_STAGE(bufoff, gbase, voff) do { _Pragma("unroll") for (int _i = 0; _i < 2; ++_i) \
;     __builtin_amdgcn_global_load_lds((const unsigned*)((const char*)(gbase) + (voff)[_i]), (LAS unsigned*)(lds + (bufoff) + ldsw + _i * 8192), 16, 0, 0); } while (0)
; #define PG8_LDA(dst, b, h) do { _Pragma("unroll") for (int m = 0; m < 4; ++m) _Pragma("unroll") for (int k = 0; k < 2; ++k) dst[m][k] = *(const LAS bf16x8*)(lds + PG8_SA(b, h) + aoff + m * 2048 + k * 1024); } while (0)
; #define PG8_MMA(ai, bj, At, Bt) do { __builtin_amdgcn_s_setprio(1); _Pragma("unroll") for (int m = 0; m < 4; ++m) _Pragma("unroll") for (int n = 0; n < 2; ++n) _Pragma("unroll") for (int k = 0; k < 2; ++k) \
;     acc[ai][bj][m][n] = __builtin_amdgcn_mfma_f32_16x16x32_bf16(Bt[n][k], At[m][k], acc[ai][bj][m][n], 0, 0, 0); __builtin_amdgcn_s_setprio(0); } while (0)
; #define PG8_WAIT_V(n) asm volatile("s_waitcnt vmcnt(" #n ")" ::: "memory")
; #define PG8_WAIT_L(n) asm volatile("s_waitcnt lgkmcnt(" #n ")" ::: "memory")
; #define PG8_BAR __builtin_amdgcn_s_barrier()
; #define PG8_SCHED __builtin_amdgcn_sched_barrier(0)
; template <class Epi>
; __device__ __forceinline__ void gemm_phase(LAS unsigned char* lds, const Gemm g, const StaticOrder& S, const Epi& E, int wv0) {
;     ...
;       PG8_BAR; PG8_WAIT_L(0); PG8_MMA(0, 1, At, B1); PG8_BAR;
;       PG8_LDA(At, 1, 1); PG8_STAGE(PG8_SA(1, 0), a3, voffA);
;       PG8_BAR; PG8_WAIT_L(0); PG8_MMA(1, 0, At, B0); PG8_BAR; PG8_SCHED;
;       PG8_STAGE(PG8_SB(1, 1), b3 + hstepB, voffB);
;       PG8_WAIT_V(6); PG8_BAR; PG8_MMA(1, 1, At, B1); PG8_BAR;
;     }
;     E(acc, cur, wr, wc, fr, fq);
;   __device__ __forceinline__ void emit(const EpiPre& q0, int row, int col, f32x4 a, f32x4 b, const f32x4 (&hb)[2][2], const float (&hs)[2][4], int ai_, int m_, int bj_) const {
;     ...
;     } else if (MODE == E_RES) {
;       const f32x4 r0 = q.a0, r1 = q.a1;
;       float* o = (float*)e.out + (size_t)row * DM + col;
;       *(f32x4*)o = (f32x4){ALPHA * r0[0] + v[0], ALPHA * r0[1] + v[1], ALPHA * r0[2] + v[2], ALPHA * r0[3] + v[3]};
;       *(f32x4*)(o + 4) = (f32x4){ALPHA * r1[0] + v[4], ALPHA * r1[1] + v[5], ALPHA * r1[2] + v[6], ALPHA * r1[3] + v[7]};
	s_waitcnt lgkmcnt(0)
	s_waitcnt lgkmcnt(0)
	v_mfma_f32_16x16x32_bf16 v[60:63], v[130:133], v[146:149], v[60:63]
	v_mfma_f32_16x16x32_bf16 v[56:59], v[138:141], v[146:149], v[56:59]
	v_mfma_f32_16x16x32_bf16 v[48:51], v[130:133], v[154:157], v[48:51]
	v_mfma_f32_16x16x32_bf16 v[40:43], v[138:141], v[154:157], v[40:43]
	v_mfma_f32_16x16x32_bf16 v[28:31], v[130:133], v[172:175], v[28:31]
	v_mfma_f32_16x16x32_bf16 v[24:27], v[138:141], v[172:175], v[24:27]
	v_mfma_f32_16x16x32_bf16 v[16:19], v[130:133], v[180:183], v[16:19]
	v_mfma_f32_16x16x32_bf16 v[8:11], v[138:141], v[180:183], v[8:11]
	v_mfma_f32_16x16x32_bf16 v[60:63], v[134:137], v[150:153], v[60:63]
	v_mfma_f32_16x16x32_bf16 v[56:59], v[142:145], v[150:153], v[56:59]
	v_mfma_f32_16x16x32_bf16 v[48:51], v[134:137], v[158:161], v[48:51]
	v_mfma_f32_16x16x32_bf16 v[40:43], v[142:145], v[158:161], v[40:43]
	v_mfma_f32_16x16x32_bf16 v[28:31], v[134:137], v[176:179], v[28:31]
	v_mfma_f32_16x16x32_bf16 v[24:27], v[142:145], v[176:179], v[24:27]
	v_mfma_f32_16x16x32_bf16 v[16:19], v[134:137], v[190:193], v[16:19]
	v_mfma_f32_16x16x32_bf16 v[8:11], v[142:145], v[190:193], v[8:11]
	s_barrier
	s_add_u32 s12, s16, 0x160080
	s_addc_u32 s13, s17, 0
	s_add_i32 s0, s18, s29
	v_lshl_add_u64 v[130:131], s[12:13], 0, v[96:97]
	s_mov_b32 m0, s0
	s_nop 0
	global_load_lds_dwordx4 v[130:131], off
	v_lshl_add_u64 v[130:131], s[12:13], 0, v[166:167]
	s_add_i32 m0, s0, 0x2000
	s_nop 0
	global_load_lds_dwordx4 v[130:131], off
	s_waitcnt vmcnt(6)
	s_barrier
	v_mfma_f32_16x16x32_bf16 v[52:55], v[194:197], v[146:149], v[52:55]
	v_mfma_f32_16x16x32_bf16 v[44:47], v[202:205], v[146:149], v[44:47]
	v_mfma_f32_16x16x32_bf16 v[36:39], v[194:197], v[154:157], v[36:39]
	v_mfma_f32_16x16x32_bf16 v[32:35], v[202:205], v[154:157], v[32:35]
	v_mfma_f32_16x16x32_bf16 v[20:23], v[194:197], v[172:175], v[20:23]
	v_mfma_f32_16x16x32_bf16 v[12:15], v[202:205], v[172:175], v[12:15]
	v_mfma_f32_16x16x32_bf16 v[4:7], v[194:197], v[180:183], v[4:7]
	v_mfma_f32_16x16x32_bf16 v[0:3], v[202:205], v[180:183], v[0:3]
	v_mfma_f32_16x16x32_bf16 v[52:55], v[198:201], v[150:153], v[52:55]
	v_mfma_f32_16x16x32_bf16 v[44:47], v[206:209], v[150:153], v[44:47]
	v_mfma_f32_16x16x32_bf16 v[36:39], v[198:201], v[158:161], v[36:39]
	v_mfma_f32_16x16x32_bf16 v[32:35], v[206:209], v[158:161], v[32:35]
	v_mfma_f32_16x16x32_bf16 v[20:23], v[198:201], v[176:179], v[20:23]
	v_mfma_f32_16x16x32_bf16 v[12:15], v[206:209], v[176:179], v[12:15]
	v_mfma_f32_16x16x32_bf16 v[4:7], v[198:201], v[190:193], v[4:7]
	v_mfma_f32_16x16x32_bf16 v[0:3], v[206:209], v[190:193], v[0:3]
	s_add_i32 s45, s45, 2
	s_add_u32 s43, s43, 0x100
	s_addc_u32 s44, s44, 0
	s_cmpk_gt_u32 s45, 0x55
	s_mov_b64 s[12:13], s[14:15]
	s_barrier
	s_cbranch_scc0 .LBB0_1429
	s_load_dwordx4 s[16:19], s[54:55], 0x88
	v_lshl_add_u32 v252, s1, 8, v186
	v_lshl_or_b32 v218, s42, 8, v188
	v_lshlrev_b32_e32 v247, 13, v252
	v_lshlrev_b32_e32 v218, 2, v218
	v_lshlrev_b32_e32 v252, 3, v252
	v_add_u32_e32 v247, v247, v218
	s_add_u32 s12, s8, 0x27700000
	s_addc_u32 s13, s9, 0
	s_add_u32 s14, s10, 0x0
	s_addc_u32 s15, s11, 0
	global_load_dwordx2 v[184:185], v252, s[12:13] offset:0
	global_load_dwordx4 v[130:133], v247, s[14:15]
	global_load_dwordx4 v[134:137], v247, s[14:15] offset:16
	global_load_dwordx4 v[138:141], v247, s[14:15] offset:512
	global_load_dwordx4 v[142:145], v247, s[14:15] offset:528
	s_add_u32 s44, s10, 0x20000
	s_addc_u32 s45, s11, 0
	global_load_dwordx2 v[242:243], v252, s[12:13] offset:128
	global_load_dwordx4 v[146:149], v247, s[44:45]
	global_load_dwordx4 v[150:153], v247, s[44:45] offset:16
	global_load_dwordx4 v[154:157], v247, s[44:45] offset:512
	global_load_dwordx4 v[158:161], v247, s[44:45] offset:528
	s_add_u32 s46, s10, 0x40000
	s_addc_u32 s47, s11, 0
	global_load_dwordx2 v[248:249], v252, s[12:13] offset:256
	global_load_dwordx4 v[172:175], v247, s[46:47]
	global_load_dwordx4 v[176:179], v247, s[46:47] offset:16
	global_load_dwordx4 v[180:183], v247, s[46:47] offset:512
	global_load_dwordx4 v[238:241], v247, s[46:47] offset:528
	s_lshl_b32 s0, s66, 13
	s_waitcnt lgkmcnt(0)
	s_add_u32 s16, s16, s0
	s_addc_u32 s17, s17, 0
	s_add_u32 s18, s18, s0
	s_addc_u32 s19, s19, 0
	global_load_dwordx4 v[190:193], v218, s[16:17]
	global_load_dwordx4 v[194:197], v218, s[16:17] offset:16
	global_load_dwordx4 v[198:201], v218, s[16:17] offset:512
	global_load_dwordx4 v[202:205], v218, s[16:17] offset:528
	global_load_dwordx4 v[206:209], v218, s[18:19]
	global_load_dwordx4 v[210:213], v218, s[18:19] offset:16
	global_load_dwordx4 v[214:217], v218, s[18:19] offset:512
	global_load_dwordx4 v[234:237], v218, s[18:19] offset:528
	s_waitcnt vmcnt(0)
;   __device__ __forceinline__ void emit(const EpiPre& q0, int row, int col, f32x4 a, f32x4 b, const f32x4 (&hb)[2][2], const float (&hs)[2][4], int ai_, int m_, int bj_) const {
;     ...
;     } else if (MODE == E_RES) {
;       const f32x4 r0 = q.a0, r1 = q.a1;
;       float* o = (float*)e.out + (size_t)row * DM + col;
;       *(f32x4*)o = (f32x4){ALPHA * r0[0] + v[0], ALPHA * r0[1] + v[1], ALPHA * r0[2] + v[2], ALPHA * r0[3] + v[3]};
;       *(f32x4*)(o + 4) = (f32x4){ALPHA * r1[0] + v[4], ALPHA * r1[1] + v[5], ALPHA * r1[2] + v[6], ALPHA * r1[3] + v[7]};
; __device__ __forceinline__ void ln_phase(const float* in, float* outf, bf16_t* outb, const float* g, const float* b, int wv0) {
;     ...
;     for (int i = 0; i < 8; ++i) { v[i] -= mu; sq += v[i][0] * v[i][0] + v[i][1] * v[i][1] + v[i][2] * v[i][2] + v[i][3] * v[i][3]; }
;     sq = wave_sum(sq); const float rstd = __builtin_amdgcn_rsqf(sq * (1.0f / 2048.0f) + EPS);
; #pragma unroll
;     for (int i = 0; i < 8; ++i) {
;       const f32x4 y = v[i] * rstd * gg[i] + bb[i];
	v_pk_add_f32 v[130:131], v[130:131], v[184:185] op_sel_hi:[1,0]
	v_pk_add_f32 v[132:133], v[132:133], v[184:185] op_sel_hi:[1,0]
	v_pk_add_f32 v[134:135], v[134:135], v[184:185] op_sel_hi:[1,0]
	v_pk_add_f32 v[136:137], v[136:137], v[184:185] op_sel_hi:[1,0]
	v_pk_add_f32 v[138:139], v[138:139], v[184:185] op_sel_hi:[1,0]
	v_pk_add_f32 v[140:141], v[140:141], v[184:185] op_sel_hi:[1,0]
	v_pk_add_f32 v[142:143], v[142:143], v[184:185] op_sel_hi:[1,0]
	v_pk_add_f32 v[144:145], v[144:145], v[184:185] op_sel_hi:[1,0]
	v_pk_mul_f32 v[130:131], v[130:131], v[184:185] op_sel:[0,1] op_sel_hi:[1,1]
	v_pk_mul_f32 v[132:133], v[132:133], v[184:185] op_sel:[0,1] op_sel_hi:[1,1]
	v_pk_mul_f32 v[134:135], v[134:135], v[184:185] op_sel:[0,1] op_sel_hi:[1,1]
	v_pk_mul_f32 v[136:137], v[136:137], v[184:185] op_sel:[0,1] op_sel_hi:[1,1]
	v_pk_mul_f32 v[138:139], v[138:139], v[184:185] op_sel:[0,1] op_sel_hi:[1,1]
	v_pk_mul_f32 v[140:141], v[140:141], v[184:185] op_sel:[0,1] op_sel_hi:[1,1]
	v_pk_mul_f32 v[142:143], v[142:143], v[184:185] op_sel:[0,1] op_sel_hi:[1,1]
	v_pk_mul_f32 v[144:145], v[144:145], v[184:185] op_sel:[0,1] op_sel_hi:[1,1]
	v_pk_fma_f32 v[130:131], v[190:191], v[130:131], v[206:207]
	v_pk_fma_f32 v[132:133], v[192:193], v[132:133], v[208:209]
	v_pk_fma_f32 v[134:135], v[194:195], v[134:135], v[210:211]
	v_pk_fma_f32 v[136:137], v[196:197], v[136:137], v[212:213]
	v_pk_fma_f32 v[138:139], v[198:199], v[138:139], v[214:215]
	v_pk_fma_f32 v[140:141], v[200:201], v[140:141], v[216:217]
	v_pk_fma_f32 v[142:143], v[202:203], v[142:143], v[234:235]
	v_pk_fma_f32 v[144:145], v[204:205], v[144:145], v[236:237]
	v_pk_fma_f32 v[126:127], v[130:131], s[90:91], v[126:127] op_sel_hi:[1,0,1]
	v_pk_fma_f32 v[128:129], v[132:133], s[90:91], v[128:129] op_sel_hi:[1,0,1]
	v_pk_fma_f32 v[122:123], v[134:135], s[90:91], v[122:123] op_sel_hi:[1,0,1]
	v_pk_fma_f32 v[124:125], v[136:137], s[90:91], v[124:125] op_sel_hi:[1,0,1]
	v_pk_fma_f32 v[110:111], v[138:139], s[90:91], v[110:111] op_sel_hi:[1,0,1]
	v_pk_fma_f32 v[112:113], v[140:141], s[90:91], v[112:113] op_sel_hi:[1,0,1]
	v_pk_fma_f32 v[106:107], v[142:143], s[90:91], v[106:107] op_sel_hi:[1,0,1]
	v_pk_fma_f32 v[108:109], v[144:145], s[90:91], v[108:109] op_sel_hi:[1,0,1]
	s_add_u32 s48, s10, 0x60000
	s_addc_u32 s49, s11, 0
	global_load_dwordx2 v[184:185], v252, s[12:13] offset:384
	global_load_dwordx4 v[130:133], v247, s[48:49]
	global_load_dwordx4 v[134:137], v247, s[48:49] offset:16
	global_load_dwordx4 v[138:141], v247, s[48:49] offset:512
	global_load_dwordx4 v[142:145], v247, s[48:49] offset:528
	s_waitcnt vmcnt(18)
	v_pk_add_f32 v[146:147], v[146:147], v[242:243] op_sel_hi:[1,0]
	v_pk_add_f32 v[148:149], v[148:149], v[242:243] op_sel_hi:[1,0]
	v_pk_add_f32 v[150:151], v[150:151], v[242:243] op_sel_hi:[1,0]
	v_pk_add_f32 v[152:153], v[152:153], v[242:243] op_sel_hi:[1,0]
	v_pk_add_f32 v[154:155], v[154:155], v[242:243] op_sel_hi:[1,0]
	v_pk_add_f32 v[156:157], v[156:157], v[242:243] op_sel_hi:[1,0]
	v_pk_add_f32 v[158:159], v[158:159], v[242:243] op_sel_hi:[1,0]
	v_pk_add_f32 v[160:161], v[160:161], v[242:243] op_sel_hi:[1,0]
	v_pk_mul_f32 v[146:147], v[146:147], v[242:243] op_sel:[0,1] op_sel_hi:[1,1]
	v_pk_mul_f32 v[148:149], v[148:149], v[242:243] op_sel:[0,1] op_sel_hi:[1,1]
	v_pk_mul_f32 v[150:151], v[150:151], v[242:243] op_sel:[0,1] op_sel_hi:[1,1]
	v_pk_mul_f32 v[152:153], v[152:153], v[242:243] op_sel:[0,1] op_sel_hi:[1,1]
	v_pk_mul_f32 v[154:155], v[154:155], v[242:243] op_sel:[0,1] op_sel_hi:[1,1]
	v_pk_mul_f32 v[156:157], v[156:157], v[242:243] op_sel:[0,1] op_sel_hi:[1,1]
	v_pk_mul_f32 v[158:159], v[158:159], v[242:243] op_sel:[0,1] op_sel_hi:[1,1]
	v_pk_mul_f32 v[160:161], v[160:161], v[242:243] op_sel:[0,1] op_sel_hi:[1,1]
	v_pk_fma_f32 v[146:147], v[190:191], v[146:147], v[206:207]
	v_pk_fma_f32 v[148:149], v[192:193], v[148:149], v[208:209]
	v_pk_fma_f32 v[150:151], v[194:195], v[150:151], v[210:211]
	v_pk_fma_f32 v[152:153], v[196:197], v[152:153], v[212:213]
	v_pk_fma_f32 v[154:155], v[198:199], v[154:155], v[214:215]
	v_pk_fma_f32 v[156:157], v[200:201], v[156:157], v[216:217]
	v_pk_fma_f32 v[158:159], v[202:203], v[158:159], v[234:235]
	v_pk_fma_f32 v[160:161], v[204:205], v[160:161], v[236:237]
	v_pk_fma_f32 v[118:119], v[146:147], s[90:91], v[118:119] op_sel_hi:[1,0,1]
	v_pk_fma_f32 v[120:121], v[148:149], s[90:91], v[120:121] op_sel_hi:[1,0,1]
	v_pk_fma_f32 v[114:115], v[150:151], s[90:91], v[114:115] op_sel_hi:[1,0,1]
	v_pk_fma_f32 v[116:117], v[152:153], s[90:91], v[116:117] op_sel_hi:[1,0,1]
	v_pk_fma_f32 v[102:103], v[154:155], s[90:91], v[102:103] op_sel_hi:[1,0,1]
	v_pk_fma_f32 v[104:105], v[156:157], s[90:91], v[104:105] op_sel_hi:[1,0,1]
	v_pk_fma_f32 v[98:99], v[158:159], s[90:91], v[98:99] op_sel_hi:[1,0,1]
	v_pk_fma_f32 v[100:101], v[160:161], s[90:91], v[100:101] op_sel_hi:[1,0,1]
	s_add_u32 s16, s10, 0x100000
	s_addc_u32 s17, s11, 0
	global_load_dwordx2 v[242:243], v252, s[12:13] offset:1024
	global_load_dwordx4 v[146:149], v247, s[16:17]
	global_load_dwordx4 v[150:153], v247, s[16:17] offset:16
	global_load_dwordx4 v[154:157], v247, s[16:17] offset:512
	global_load_dwordx4 v[158:161], v247, s[16:17] offset:528
	s_waitcnt vmcnt(18)
;   __device__ __forceinline__ void emit(const EpiPre& q0, int row, int col, f32x4 a, f32x4 b, const f32x4 (&hb)[2][2], const float (&hs)[2][4], int ai_, int m_, int bj_) const {
;     ...
;     } else if (MODE == E_RES) {
;       const f32x4 r0 = q.a0, r1 = q.a1;
;       float* o = (float*)e.out + (size_t)row * DM + col;
;       *(f32x4*)o = (f32x4){ALPHA * r0[0] + v[0], ALPHA * r0[1] + v[1], ALPHA * r0[2] + v[2], ALPHA * r0[3] + v[3]};
;       *(f32x4*)(o + 4) = (f32x4){ALPHA * r1[0] + v[4], ALPHA * r1[1] + v[5], ALPHA * r1[2] + v[6], ALPHA * r1[3] + v[7]};
; __device__ __forceinline__ void ln_phase(const float* in, float* outf, bf16_t* outb, const float* g, const float* b, int wv0) {
;     ...
;     for (int i = 0; i < 8; ++i) { v[i] -= mu; sq += v[i][0] * v[i][0] + v[i][1] * v[i][1] + v[i][2] * v[i][2] + v[i][3] * v[i][3]; }
;     sq = wave_sum(sq); const float rstd = __builtin_amdgcn_rsqf(sq * (1.0f / 2048.0f) + EPS);
; #pragma unroll
;     for (int i = 0; i < 8; ++i) {
;       const f32x4 y = v[i] * rstd * gg[i] + bb[i];
	v_pk_add_f32 v[172:173], v[172:173], v[248:249] op_sel_hi:[1,0]
	v_pk_add_f32 v[174:175], v[174:175], v[248:249] op_sel_hi:[1,0]
	v_pk_add_f32 v[176:177], v[176:177], v[248:249] op_sel_hi:[1,0]
	v_pk_add_f32 v[178:179], v[178:179], v[248:249] op_sel_hi:[1,0]
	v_pk_add_f32 v[180:181], v[180:181], v[248:249] op_sel_hi:[1,0]
	v_pk_add_f32 v[182:183], v[182:183], v[248:249] op_sel_hi:[1,0]
	v_pk_add_f32 v[238:239], v[238:239], v[248:249] op_sel_hi:[1,0]
	v_pk_add_f32 v[240:241], v[240:241], v[248:249] op_sel_hi:[1,0]
	v_pk_mul_f32 v[172:173], v[172:173], v[248:249] op_sel:[0,1] op_sel_hi:[1,1]
	v_pk_mul_f32 v[174:175], v[174:175], v[248:249] op_sel:[0,1] op_sel_hi:[1,1]
	v_pk_mul_f32 v[176:177], v[176:177], v[248:249] op_sel:[0,1] op_sel_hi:[1,1]
	v_pk_mul_f32 v[178:179], v[178:179], v[248:249] op_sel:[0,1] op_sel_hi:[1,1]
	v_pk_mul_f32 v[180:181], v[180:181], v[248:249] op_sel:[0,1] op_sel_hi:[1,1]
	v_pk_mul_f32 v[182:183], v[182:183], v[248:249] op_sel:[0,1] op_sel_hi:[1,1]
	v_pk_mul_f32 v[238:239], v[238:239], v[248:249] op_sel:[0,1] op_sel_hi:[1,1]
	v_pk_mul_f32 v[240:241], v[240:241], v[248:249] op_sel:[0,1] op_sel_hi:[1,1]
	v_pk_fma_f32 v[172:173], v[190:191], v[172:173], v[206:207]
	v_pk_fma_f32 v[174:175], v[192:193], v[174:175], v[208:209]
	v_pk_fma_f32 v[176:177], v[194:195], v[176:177], v[210:211]
	v_pk_fma_f32 v[178:179], v[196:197], v[178:179], v[212:213]
	v_pk_fma_f32 v[180:181], v[198:199], v[180:181], v[214:215]
	v_pk_fma_f32 v[182:183], v[200:201], v[182:183], v[216:217]
	v_pk_fma_f32 v[238:239], v[202:203], v[238:239], v[234:235]
	v_pk_fma_f32 v[240:241], v[204:205], v[240:241], v[236:237]
	v_pk_fma_f32 v[92:93], v[172:173], s[90:91], v[92:93] op_sel_hi:[1,0,1]
	v_pk_fma_f32 v[94:95], v[174:175], s[90:91], v[94:95] op_sel_hi:[1,0,1]
	v_pk_fma_f32 v[88:89], v[176:177], s[90:91], v[88:89] op_sel_hi:[1,0,1]
	v_pk_fma_f32 v[90:91], v[178:179], s[90:91], v[90:91] op_sel_hi:[1,0,1]
	v_pk_fma_f32 v[80:81], v[180:181], s[90:91], v[80:81] op_sel_hi:[1,0,1]
	v_pk_fma_f32 v[82:83], v[182:183], s[90:91], v[82:83] op_sel_hi:[1,0,1]
	v_pk_fma_f32 v[72:73], v[238:239], s[90:91], v[72:73] op_sel_hi:[1,0,1]
	v_pk_fma_f32 v[74:75], v[240:241], s[90:91], v[74:75] op_sel_hi:[1,0,1]
	s_add_u32 s18, s10, 0x120000
	s_addc_u32 s19, s11, 0
	global_load_dwordx2 v[248:249], v252, s[12:13] offset:1152
	global_load_dwordx4 v[172:175], v247, s[18:19]
	global_load_dwordx4 v[176:179], v247, s[18:19] offset:16
	global_load_dwordx4 v[180:183], v247, s[18:19] offset:512
	global_load_dwordx4 v[238:241], v247, s[18:19] offset:528
	global_store_dwordx4 v247, v[126:129], s[14:15]
	global_store_dwordx4 v247, v[122:125], s[14:15] offset:16
	global_store_dwordx4 v247, v[110:113], s[14:15] offset:512
	global_store_dwordx4 v247, v[106:109], s[14:15] offset:528
	global_store_dwordx4 v247, v[118:121], s[44:45]
	global_store_dwordx4 v247, v[114:117], s[44:45] offset:16
	global_store_dwordx4 v247, v[102:105], s[44:45] offset:512
	global_store_dwordx4 v247, v[98:101], s[44:45] offset:528
	global_store_dwordx4 v247, v[92:95], s[46:47]
	global_store_dwordx4 v247, v[88:91], s[46:47] offset:16
	global_store_dwordx4 v247, v[80:83], s[46:47] offset:512
	global_store_dwordx4 v247, v[72:75], s[46:47] offset:528
	s_add_u32 s14, s10, 0x140000
	s_addc_u32 s15, s11, 0
	global_load_dwordx2 v[92:93], v252, s[12:13] offset:1280
	global_load_dwordx4 v[126:129], v247, s[14:15]
	global_load_dwordx4 v[122:125], v247, s[14:15] offset:16
	global_load_dwordx4 v[110:113], v247, s[14:15] offset:512
	global_load_dwordx4 v[106:109], v247, s[14:15] offset:528
	s_add_u32 s44, s10, 0x160000
	s_addc_u32 s45, s11, 0
	global_load_dwordx2 v[88:89], v252, s[12:13] offset:1408
	global_load_dwordx4 v[118:121], v247, s[44:45]
	global_load_dwordx4 v[114:117], v247, s[44:45] offset:16
	global_load_dwordx4 v[102:105], v247, s[44:45] offset:512
	global_load_dwordx4 v[98:101], v247, s[44:45] offset:528
	s_waitcnt vmcnt(32)
	v_pk_add_f32 v[130:131], v[130:131], v[184:185] op_sel_hi:[1,0]
	v_pk_add_f32 v[132:133], v[132:133], v[184:185] op_sel_hi:[1,0]
	v_pk_add_f32 v[134:135], v[134:135], v[184:185] op_sel_hi:[1,0]
	v_pk_add_f32 v[136:137], v[136:137], v[184:185] op_sel_hi:[1,0]
	v_pk_add_f32 v[138:139], v[138:139], v[184:185] op_sel_hi:[1,0]
	v_pk_add_f32 v[140:141], v[140:141], v[184:185] op_sel_hi:[1,0]
	v_pk_add_f32 v[142:143], v[142:143], v[184:185] op_sel_hi:[1,0]
	v_pk_add_f32 v[144:145], v[144:145], v[184:185] op_sel_hi:[1,0]
	v_pk_mul_f32 v[130:131], v[130:131], v[184:185] op_sel:[0,1] op_sel_hi:[1,1]
	v_pk_mul_f32 v[132:133], v[132:133], v[184:185] op_sel:[0,1] op_sel_hi:[1,1]
	v_pk_mul_f32 v[134:135], v[134:135], v[184:185] op_sel:[0,1] op_sel_hi:[1,1]
	v_pk_mul_f32 v[136:137], v[136:137], v[184:185] op_sel:[0,1] op_sel_hi:[1,1]
	v_pk_mul_f32 v[138:139], v[138:139], v[184:185] op_sel:[0,1] op_sel_hi:[1,1]
	v_pk_mul_f32 v[140:141], v[140:141], v[184:185] op_sel:[0,1] op_sel_hi:[1,1]
	v_pk_mul_f32 v[142:143], v[142:143], v[184:185] op_sel:[0,1] op_sel_hi:[1,1]
	v_pk_mul_f32 v[144:145], v[144:145], v[184:185] op_sel:[0,1] op_sel_hi:[1,1]
	v_pk_fma_f32 v[130:131], v[190:191], v[130:131], v[206:207]
	v_pk_fma_f32 v[132:133], v[192:193], v[132:133], v[208:209]
	v_pk_fma_f32 v[134:135], v[194:195], v[134:135], v[210:211]
	v_pk_fma_f32 v[136:137], v[196:197], v[136:137], v[212:213]
	v_pk_fma_f32 v[138:139], v[198:199], v[138:139], v[214:215]
	v_pk_fma_f32 v[140:141], v[200:201], v[140:141], v[216:217]
	v_pk_fma_f32 v[142:143], v[202:203], v[142:143], v[234:235]
	v_pk_fma_f32 v[144:145], v[204:205], v[144:145], v[236:237]
	v_pk_fma_f32 v[84:85], v[130:131], s[90:91], v[84:85] op_sel_hi:[1,0,1]
	v_pk_fma_f32 v[86:87], v[132:133], s[90:91], v[86:87] op_sel_hi:[1,0,1]
	v_pk_fma_f32 v[76:77], v[134:135], s[90:91], v[76:77] op_sel_hi:[1,0,1]
	v_pk_fma_f32 v[78:79], v[136:137], s[90:91], v[78:79] op_sel_hi:[1,0,1]
	v_pk_fma_f32 v[68:69], v[138:139], s[90:91], v[68:69] op_sel_hi:[1,0,1]
	v_pk_fma_f32 v[70:71], v[140:141], s[90:91], v[70:71] op_sel_hi:[1,0,1]
	v_pk_fma_f32 v[64:65], v[142:143], s[90:91], v[64:65] op_sel_hi:[1,0,1]
	v_pk_fma_f32 v[66:67], v[144:145], s[90:91], v[66:67] op_sel_hi:[1,0,1]
	global_store_dwordx4 v247, v[84:87], s[48:49]
	global_store_dwordx4 v247, v[76:79], s[48:49] offset:16
	global_store_dwordx4 v247, v[68:71], s[48:49] offset:512
	global_store_dwordx4 v247, v[64:67], s[48:49] offset:528
	s_waitcnt vmcnt(31)
;   __device__ __forceinline__ void emit(const EpiPre& q0, int row, int col, f32x4 a, f32x4 b, const f32x4 (&hb)[2][2], const float (&hs)[2][4], int ai_, int m_, int bj_) const {
;     ...
;     } else if (MODE == E_RES) {
;       const f32x4 r0 = q.a0, r1 = q.a1;
;       float* o = (float*)e.out + (size_t)row * DM + col;
;       *(f32x4*)o = (f32x4){ALPHA * r0[0] + v[0], ALPHA * r0[1] + v[1], ALPHA * r0[2] + v[2], ALPHA * r0[3] + v[3]};
;       *(f32x4*)(o + 4) = (f32x4){ALPHA * r1[0] + v[4], ALPHA * r1[1] + v[5], ALPHA * r1[2] + v[6], ALPHA * r1[3] + v[7]};
; __device__ __forceinline__ void ln_phase(const float* in, float* outf, bf16_t* outb, const float* g, const float* b, int wv0) {
;     ...
;     for (int i = 0; i < 8; ++i) { v[i] -= mu; sq += v[i][0] * v[i][0] + v[i][1] * v[i][1] + v[i][2] * v[i][2] + v[i][3] * v[i][3]; }
;     sq = wave_sum(sq); const float rstd = __builtin_amdgcn_rsqf(sq * (1.0f / 2048.0f) + EPS);
; #pragma unroll
;     for (int i = 0; i < 8; ++i) {
;       const f32x4 y = v[i] * rstd * gg[i] + bb[i];
	v_pk_add_f32 v[146:147], v[146:147], v[242:243] op_sel_hi:[1,0]
	v_pk_add_f32 v[148:149], v[148:149], v[242:243] op_sel_hi:[1,0]
	v_pk_add_f32 v[150:151], v[150:151], v[242:243] op_sel_hi:[1,0]
	v_pk_add_f32 v[152:153], v[152:153], v[242:243] op_sel_hi:[1,0]
	v_pk_add_f32 v[154:155], v[154:155], v[242:243] op_sel_hi:[1,0]
	v_pk_add_f32 v[156:157], v[156:157], v[242:243] op_sel_hi:[1,0]
	v_pk_add_f32 v[158:159], v[158:159], v[242:243] op_sel_hi:[1,0]
	v_pk_add_f32 v[160:161], v[160:161], v[242:243] op_sel_hi:[1,0]
	v_pk_mul_f32 v[146:147], v[146:147], v[242:243] op_sel:[0,1] op_sel_hi:[1,1]
	v_pk_mul_f32 v[148:149], v[148:149], v[242:243] op_sel:[0,1] op_sel_hi:[1,1]
	v_pk_mul_f32 v[150:151], v[150:151], v[242:243] op_sel:[0,1] op_sel_hi:[1,1]
	v_pk_mul_f32 v[152:153], v[152:153], v[242:243] op_sel:[0,1] op_sel_hi:[1,1]
	v_pk_mul_f32 v[154:155], v[154:155], v[242:243] op_sel:[0,1] op_sel_hi:[1,1]
	v_pk_mul_f32 v[156:157], v[156:157], v[242:243] op_sel:[0,1] op_sel_hi:[1,1]
	v_pk_mul_f32 v[158:159], v[158:159], v[242:243] op_sel:[0,1] op_sel_hi:[1,1]
	v_pk_mul_f32 v[160:161], v[160:161], v[242:243] op_sel:[0,1] op_sel_hi:[1,1]
	v_pk_fma_f32 v[146:147], v[190:191], v[146:147], v[206:207]
	v_pk_fma_f32 v[148:149], v[192:193], v[148:149], v[208:209]
	v_pk_fma_f32 v[150:151], v[194:195], v[150:151], v[210:211]
	v_pk_fma_f32 v[152:153], v[196:197], v[152:153], v[212:213]
	v_pk_fma_f32 v[154:155], v[198:199], v[154:155], v[214:215]
	v_pk_fma_f32 v[156:157], v[200:201], v[156:157], v[216:217]
	v_pk_fma_f32 v[158:159], v[202:203], v[158:159], v[234:235]
	v_pk_fma_f32 v[160:161], v[204:205], v[160:161], v[236:237]
	v_pk_fma_f32 v[60:61], v[146:147], s[90:91], v[60:61] op_sel_hi:[1,0,1]
	v_pk_fma_f32 v[62:63], v[148:149], s[90:91], v[62:63] op_sel_hi:[1,0,1]
	v_pk_fma_f32 v[56:57], v[150:151], s[90:91], v[56:57] op_sel_hi:[1,0,1]
	v_pk_fma_f32 v[58:59], v[152:153], s[90:91], v[58:59] op_sel_hi:[1,0,1]
	v_pk_fma_f32 v[52:53], v[154:155], s[90:91], v[52:53] op_sel_hi:[1,0,1]
	v_pk_fma_f32 v[54:55], v[156:157], s[90:91], v[54:55] op_sel_hi:[1,0,1]
	v_pk_fma_f32 v[44:45], v[158:159], s[90:91], v[44:45] op_sel_hi:[1,0,1]
	v_pk_fma_f32 v[46:47], v[160:161], s[90:91], v[46:47] op_sel_hi:[1,0,1]
	global_store_dwordx4 v247, v[60:63], s[16:17]
	global_store_dwordx4 v247, v[56:59], s[16:17] offset:16
	global_store_dwordx4 v247, v[52:55], s[16:17] offset:512
	global_store_dwordx4 v247, v[44:47], s[16:17] offset:528
	s_waitcnt vmcnt(30)
	v_pk_add_f32 v[172:173], v[172:173], v[248:249] op_sel_hi:[1,0]
	v_pk_add_f32 v[174:175], v[174:175], v[248:249] op_sel_hi:[1,0]
	v_pk_add_f32 v[176:177], v[176:177], v[248:249] op_sel_hi:[1,0]
	v_pk_add_f32 v[178:179], v[178:179], v[248:249] op_sel_hi:[1,0]
	v_pk_add_f32 v[180:181], v[180:181], v[248:249] op_sel_hi:[1,0]
	v_pk_add_f32 v[182:183], v[182:183], v[248:249] op_sel_hi:[1,0]
	v_pk_add_f32 v[238:239], v[238:239], v[248:249] op_sel_hi:[1,0]
	v_pk_add_f32 v[240:241], v[240:241], v[248:249] op_sel_hi:[1,0]
	v_pk_mul_f32 v[172:173], v[172:173], v[248:249] op_sel:[0,1] op_sel_hi:[1,1]
	v_pk_mul_f32 v[174:175], v[174:175], v[248:249] op_sel:[0,1] op_sel_hi:[1,1]
	v_pk_mul_f32 v[176:177], v[176:177], v[248:249] op_sel:[0,1] op_sel_hi:[1,1]
	v_pk_mul_f32 v[178:179], v[178:179], v[248:249] op_sel:[0,1] op_sel_hi:[1,1]
	v_pk_mul_f32 v[180:181], v[180:181], v[248:249] op_sel:[0,1] op_sel_hi:[1,1]
	v_pk_mul_f32 v[182:183], v[182:183], v[248:249] op_sel:[0,1] op_sel_hi:[1,1]
	v_pk_mul_f32 v[238:239], v[238:239], v[248:249] op_sel:[0,1] op_sel_hi:[1,1]
	v_pk_mul_f32 v[240:241], v[240:241], v[248:249] op_sel:[0,1] op_sel_hi:[1,1]
	v_pk_fma_f32 v[172:173], v[190:191], v[172:173], v[206:207]
	v_pk_fma_f32 v[174:175], v[192:193], v[174:175], v[208:209]
	v_pk_fma_f32 v[176:177], v[194:195], v[176:177], v[210:211]
	v_pk_fma_f32 v[178:179], v[196:197], v[178:179], v[212:213]
	v_pk_fma_f32 v[180:181], v[198:199], v[180:181], v[214:215]
	v_pk_fma_f32 v[182:183], v[200:201], v[182:183], v[216:217]
	v_pk_fma_f32 v[238:239], v[202:203], v[238:239], v[234:235]
	v_pk_fma_f32 v[240:241], v[204:205], v[240:241], v[236:237]
	v_pk_fma_f32 v[48:49], v[172:173], s[90:91], v[48:49] op_sel_hi:[1,0,1]
	v_pk_fma_f32 v[50:51], v[174:175], s[90:91], v[50:51] op_sel_hi:[1,0,1]
	v_pk_fma_f32 v[40:41], v[176:177], s[90:91], v[40:41] op_sel_hi:[1,0,1]
	v_pk_fma_f32 v[42:43], v[178:179], s[90:91], v[42:43] op_sel_hi:[1,0,1]
	v_pk_fma_f32 v[36:37], v[180:181], s[90:91], v[36:37] op_sel_hi:[1,0,1]
	v_pk_fma_f32 v[38:39], v[182:183], s[90:91], v[38:39] op_sel_hi:[1,0,1]
	v_pk_fma_f32 v[32:33], v[238:239], s[90:91], v[32:33] op_sel_hi:[1,0,1]
	v_pk_fma_f32 v[34:35], v[240:241], s[90:91], v[34:35] op_sel_hi:[1,0,1]
	global_store_dwordx4 v247, v[48:51], s[18:19]
	global_store_dwordx4 v247, v[40:43], s[18:19] offset:16
	global_store_dwordx4 v247, v[36:39], s[18:19] offset:512
	global_store_dwordx4 v247, v[32:35], s[18:19] offset:528
	s_waitcnt vmcnt(17)
; #define PG8_WAIT_V(n) asm volatile("s_waitcnt vmcnt(" #n ")" ::: "memory")
; #define PG8_BAR __builtin_amdgcn_s_barrier()
; template <class Epi>
; __device__ __forceinline__ void gemm_phase(LAS unsigned char* lds, const Gemm g, const StaticOrder& S, const Epi& E, int wv0) {
;     ...
;     if (!has_next) break;
; #pragma unroll
;     for (int a = 0; a < 2; ++a)
; #pragma unroll
;       for (int b = 0; b < 2; ++b)
; #pragma unroll
;         for (int m = 0; m < 4; ++m)
; #pragma unroll
;           for (int n = 0; n < 2; ++n) acc[a][b][m][n] = (f32x4){0.f, 0.f, 0.f, 0.f};
;     cur = nxt; cA = nA; cB = nB; ++ui;
;   }
;   PG8_WAIT_V(0);
;   if (wr == 0) PG8_BAR;
;   PG8_BAR;
;   __device__ __forceinline__ void emit(const EpiPre& q0, int row, int col, f32x4 a, f32x4 b, const f32x4 (&hb)[2][2], const float (&hs)[2][4], int ai_, int m_, int bj_) const {
;     ...
;     } else if (MODE == E_RES) {
;       const f32x4 r0 = q.a0, r1 = q.a1;
;       float* o = (float*)e.out + (size_t)row * DM + col;
;       *(f32x4*)o = (f32x4){ALPHA * r0[0] + v[0], ALPHA * r0[1] + v[1], ALPHA * r0[2] + v[2], ALPHA * r0[3] + v[3]};
;       *(f32x4*)(o + 4) = (f32x4){ALPHA * r1[0] + v[4], ALPHA * r1[1] + v[5], ALPHA * r1[2] + v[6], ALPHA * r1[3] + v[7]};
	v_pk_add_f32 v[126:127], v[126:127], v[92:93] op_sel_hi:[1,0]
	v_pk_add_f32 v[128:129], v[128:129], v[92:93] op_sel_hi:[1,0]
	v_pk_add_f32 v[122:123], v[122:123], v[92:93] op_sel_hi:[1,0]
	v_pk_add_f32 v[124:125], v[124:125], v[92:93] op_sel_hi:[1,0]
	v_pk_add_f32 v[110:111], v[110:111], v[92:93] op_sel_hi:[1,0]
	v_pk_add_f32 v[112:113], v[112:113], v[92:93] op_sel_hi:[1,0]
	v_pk_add_f32 v[106:107], v[106:107], v[92:93] op_sel_hi:[1,0]
	v_pk_add_f32 v[108:109], v[108:109], v[92:93] op_sel_hi:[1,0]
	v_pk_mul_f32 v[126:127], v[126:127], v[92:93] op_sel:[0,1] op_sel_hi:[1,1]
	v_pk_mul_f32 v[128:129], v[128:129], v[92:93] op_sel:[0,1] op_sel_hi:[1,1]
	v_pk_mul_f32 v[122:123], v[122:123], v[92:93] op_sel:[0,1] op_sel_hi:[1,1]
	v_pk_mul_f32 v[124:125], v[124:125], v[92:93] op_sel:[0,1] op_sel_hi:[1,1]
	v_pk_mul_f32 v[110:111], v[110:111], v[92:93] op_sel:[0,1] op_sel_hi:[1,1]
	v_pk_mul_f32 v[112:113], v[112:113], v[92:93] op_sel:[0,1] op_sel_hi:[1,1]
	v_pk_mul_f32 v[106:107], v[106:107], v[92:93] op_sel:[0,1] op_sel_hi:[1,1]
	v_pk_mul_f32 v[108:109], v[108:109], v[92:93] op_sel:[0,1] op_sel_hi:[1,1]
	v_pk_fma_f32 v[126:127], v[190:191], v[126:127], v[206:207]
	v_pk_fma_f32 v[128:129], v[192:193], v[128:129], v[208:209]
	v_pk_fma_f32 v[122:123], v[194:195], v[122:123], v[210:211]
	v_pk_fma_f32 v[124:125], v[196:197], v[124:125], v[212:213]
	v_pk_fma_f32 v[110:111], v[198:199], v[110:111], v[214:215]
	v_pk_fma_f32 v[112:113], v[200:201], v[112:113], v[216:217]
	v_pk_fma_f32 v[106:107], v[202:203], v[106:107], v[234:235]
	v_pk_fma_f32 v[108:109], v[204:205], v[108:109], v[236:237]
	v_pk_fma_f32 v[28:29], v[126:127], s[90:91], v[28:29] op_sel_hi:[1,0,1]
	v_pk_fma_f32 v[30:31], v[128:129], s[90:91], v[30:31] op_sel_hi:[1,0,1]
	v_pk_fma_f32 v[24:25], v[122:123], s[90:91], v[24:25] op_sel_hi:[1,0,1]
	v_pk_fma_f32 v[26:27], v[124:125], s[90:91], v[26:27] op_sel_hi:[1,0,1]
	v_pk_fma_f32 v[20:21], v[110:111], s[90:91], v[20:21] op_sel_hi:[1,0,1]
	v_pk_fma_f32 v[22:23], v[112:113], s[90:91], v[22:23] op_sel_hi:[1,0,1]
	v_pk_fma_f32 v[12:13], v[106:107], s[90:91], v[12:13] op_sel_hi:[1,0,1]
	v_pk_fma_f32 v[14:15], v[108:109], s[90:91], v[14:15] op_sel_hi:[1,0,1]
	global_store_dwordx4 v247, v[28:31], s[14:15]
	global_store_dwordx4 v247, v[24:27], s[14:15] offset:16
	global_store_dwordx4 v247, v[20:23], s[14:15] offset:512
	global_store_dwordx4 v247, v[12:15], s[14:15] offset:528
	s_waitcnt vmcnt(16)
	v_pk_add_f32 v[118:119], v[118:119], v[88:89] op_sel_hi:[1,0]
	v_pk_add_f32 v[120:121], v[120:121], v[88:89] op_sel_hi:[1,0]
	v_pk_add_f32 v[114:115], v[114:115], v[88:89] op_sel_hi:[1,0]
	v_pk_add_f32 v[116:117], v[116:117], v[88:89] op_sel_hi:[1,0]
	v_pk_add_f32 v[102:103], v[102:103], v[88:89] op_sel_hi:[1,0]
	v_pk_add_f32 v[104:105], v[104:105], v[88:89] op_sel_hi:[1,0]
	v_pk_add_f32 v[98:99], v[98:99], v[88:89] op_sel_hi:[1,0]
	v_pk_add_f32 v[100:101], v[100:101], v[88:89] op_sel_hi:[1,0]
	v_pk_mul_f32 v[118:119], v[118:119], v[88:89] op_sel:[0,1] op_sel_hi:[1,1]
	v_pk_mul_f32 v[120:121], v[120:121], v[88:89] op_sel:[0,1] op_sel_hi:[1,1]
	v_pk_mul_f32 v[114:115], v[114:115], v[88:89] op_sel:[0,1] op_sel_hi:[1,1]
	v_pk_mul_f32 v[116:117], v[116:117], v[88:89] op_sel:[0,1] op_sel_hi:[1,1]
	v_pk_mul_f32 v[102:103], v[102:103], v[88:89] op_sel:[0,1] op_sel_hi:[1,1]
	v_pk_mul_f32 v[104:105], v[104:105], v[88:89] op_sel:[0,1] op_sel_hi:[1,1]
	v_pk_mul_f32 v[98:99], v[98:99], v[88:89] op_sel:[0,1] op_sel_hi:[1,1]
	v_pk_mul_f32 v[100:101], v[100:101], v[88:89] op_sel:[0,1] op_sel_hi:[1,1]
	v_pk_fma_f32 v[118:119], v[190:191], v[118:119], v[206:207]
	v_pk_fma_f32 v[120:121], v[192:193], v[120:121], v[208:209]
	v_pk_fma_f32 v[114:115], v[194:195], v[114:115], v[210:211]
	v_pk_fma_f32 v[116:117], v[196:197], v[116:117], v[212:213]
	v_pk_fma_f32 v[102:103], v[198:199], v[102:103], v[214:215]
	v_pk_fma_f32 v[104:105], v[200:201], v[104:105], v[216:217]
	v_pk_fma_f32 v[98:99], v[202:203], v[98:99], v[234:235]
	v_pk_fma_f32 v[100:101], v[204:205], v[100:101], v[236:237]
	v_pk_fma_f32 v[16:17], v[118:119], s[90:91], v[16:17] op_sel_hi:[1,0,1]
	v_pk_fma_f32 v[18:19], v[120:121], s[90:91], v[18:19] op_sel_hi:[1,0,1]
	v_pk_fma_f32 v[8:9], v[114:115], s[90:91], v[8:9] op_sel_hi:[1,0,1]
	v_pk_fma_f32 v[10:11], v[116:117], s[90:91], v[10:11] op_sel_hi:[1,0,1]
	v_pk_fma_f32 v[4:5], v[102:103], s[90:91], v[4:5] op_sel_hi:[1,0,1]
	v_pk_fma_f32 v[6:7], v[104:105], s[90:91], v[6:7] op_sel_hi:[1,0,1]
	v_pk_fma_f32 v[0:1], v[98:99], s[90:91], v[0:1] op_sel_hi:[1,0,1]
	v_pk_fma_f32 v[2:3], v[100:101], s[90:91], v[2:3] op_sel_hi:[1,0,1]
	global_store_dwordx4 v247, v[16:19], s[44:45]
	global_store_dwordx4 v247, v[8:11], s[44:45] offset:16
	global_store_dwordx4 v247, v[4:7], s[44:45] offset:512
	global_store_dwordx4 v247, v[0:3], s[44:45] offset:528
	s_mov_b64 s[0:1], 0x100000
	s_mov_b32 s42, s40
	s_mov_b64 s[14:15], s[6:7]
	s_mov_b64 s[12:13], s[4:5]
	s_and_b64 vcc, exec, s[2:3]
	s_mov_b32 s1, s41
	s_cbranch_vccz .LBB0_1418
	s_waitcnt vmcnt(0)
	s_cmpk_gt_u32 s23, 0xff
	s_cbranch_scc1 .LBB0_1433
	s_barrier
